# stack1f + LDS-DMA staging sites: address VALU fills the m0 hazard slot instead of s_nop (110 sites)
# speedup vs baseline: 1.0140x; 1.0006x over previous
; #define PG8_STAGE(bufoff, gbase, voff) do { _Pragma("unroll") for (int _i = 0; _i < 2; ++_i) \
;         __builtin_amdgcn_global_load_lds((const unsigned*)((const char*)(gbase) + (voff)[_i]), (PG8_LAS unsigned*)(lds + (bufoff) + ldsw + _i * 8192), 16, 0, 0); } while (0)
; #define PG8_LDA(dst, b, h) do { _Pragma("unroll") for (int m = 0; m < 4; ++m) _Pragma("unroll") for (int k = 0; k < 2; ++k) dst[m][k] = *(const PG8_LAS bf16x8*)(lds + PG8_SA(b, h) + aoff + m * 2048 + k * 1024); } while (0)
; #define PG8_LDB(dst, b, h) do { _Pragma("unroll") for (int n = 0; n < 2; ++n) _Pragma("unroll") for (int k = 0; k < 2; ++k) dst[n][k] = *(const PG8_LAS bf16x8*)(lds + PG8_SB(b, h) + boff + n * 2048 + k * 1024); } while (0)
; template <class Epi, class Sched, bool ALIGN_EPI = false, bool SP2 = false>
; __device__ __forceinline__ void gemm_phase(PG8_LAS unsigned char* lds, const Gemm g, const Sched& S, const Epi& E) {
;     ...
;         for (int t = 0; t < nt; t += 2) {
;             const bool last = (t == nt - 2);
;             const char* a1 = cA + (size_t)(t + 1) * kstep;
;             const char* a2 = last ? nA : cA + (size_t)(t + 2) * kstep; const char* b2 = last ? nB : cB + (size_t)(t + 2) * kstep;
;             const char* a3 = a2 + kstep; const char* b3 = b2 + kstep;
;             if (last && has_next) S.a_ready(nxt);
;             if constexpr (SP2) {
;             PG8_LDB(B0, 0, 0); PG8_LDB(B1, 0, 1); PG8_SCHED; PG8_LDA(At, 0, 0); PG8_STAGE(PG8_SA(1, 1), a1 + hstep, voffA);
;             PG8_WAIT_V(8); PG8_WAIT_L(0); PG8_BAR; PG8_MMA(0, 0, At, B0); PG8_MMA(0, 1, At, B1); PG8_BAR; PG8_SCHED;
;             PG8_LDA(At, 0, 1); PG8_STAGE(PG8_SB(0, 0), b2, voffB); PG8_STAGE(PG8_SB(0, 1), b2 + hstep, voffB); PG8_STAGE(PG8_SA(0, 0), a2, voffA);
;             PG8_WAIT_V(8); PG8_WAIT_L(0); PG8_BAR; PG8_MMA(1, 0, At, B0); PG8_MMA(1, 1, At, B1); PG8_BAR; PG8_SCHED;
;             PG8_LDB(B0, 1, 0); PG8_LDB(B1, 1, 1); PG8_SCHED; PG8_LDA(At, 1, 0); PG8_STAGE(PG8_SA(0, 1), a2 + hstep, voffA);
;             PG8_WAIT_V(8); PG8_WAIT_L(0); PG8_BAR; PG8_MMA(0, 0, At, B0); PG8_MMA(0, 1, At, B1); PG8_BAR; PG8_SCHED;
;             PG8_LDA(At, 1, 1); PG8_STAGE(PG8_SB(1, 0), b3, voffB); PG8_STAGE(PG8_SB(1, 1), b3 + hstep, voffB); PG8_STAGE(PG8_SA(1, 0), a3, voffA);
;             PG8_WAIT_V(8); PG8_WAIT_L(0); PG8_BAR; PG8_MMA(1, 0, At, B0); PG8_MMA(1, 1, At, B1); PG8_BAR; PG8_SCHED;
.LBB0_304:
	v_add_u32_e32 v166, s54, v169
	v_add_u32_e32 v168, s55, v169
	ds_read_b128 v[162:165], v166
	ds_read_b128 v[182:185], v166 offset:1024
	ds_read_b128 v[186:189], v166 offset:2048
	ds_read_b128 v[190:193], v166 offset:3072
	ds_read_b128 v[194:197], v168
	ds_read_b128 v[198:201], v168 offset:1024
	ds_read_b128 v[202:205], v168 offset:2048
	ds_read_b128 v[206:209], v168 offset:3072
	s_cmp_eq_u32 s53, s10
	v_lshl_add_u64 v[172:173], v[160:161], 0, s[22:23]
	s_cselect_b64 vcc, -1, 0
	s_add_i32 s10, s10, 2
	v_cndmask_b32_e32 v173, v173, v153, vcc
	v_cndmask_b32_e32 v172, v172, v152, vcc
	v_cndmask_b32_e32 v245, v159, v155, vcc
	v_cndmask_b32_e32 v244, v158, v154, vcc
	s_mov_b32 m0, s56
	v_lshl_add_u64 v[246:247], v[160:161], 0, v[148:149]
	ds_read_b128 v[210:213], v179
	ds_read_b128 v[216:219], v179 offset:1024
	ds_read_b128 v[220:223], v179 offset:2048
	ds_read_b128 v[224:227], v179 offset:3072
	ds_read_b128 v[228:231], v179 offset:4096
	ds_read_b128 v[232:235], v179 offset:5120
	ds_read_b128 v[236:239], v179 offset:6144
	ds_read_b128 v[240:243], v179 offset:7168
	global_load_lds_dwordx4 v[246:247], off
	s_mov_b32 m0, s57
	v_lshl_add_u64 v[246:247], v[160:161], 0, v[146:147]
	global_load_lds_dwordx4 v[246:247], off
	s_waitcnt vmcnt(8)
	s_waitcnt lgkmcnt(0)
	s_setprio 1
	s_barrier
	v_mfma_f32_16x16x32_bf16 v[124:127], v[162:165], v[210:213], v[124:127]
	v_mfma_f32_16x16x32_bf16 v[116:119], v[186:189], v[210:213], v[116:119]
	v_mfma_f32_16x16x32_bf16 v[108:111], v[162:165], v[220:223], v[108:111]
	v_mfma_f32_16x16x32_bf16 v[100:103], v[186:189], v[220:223], v[100:103]
	v_mfma_f32_16x16x32_bf16 v[92:95], v[162:165], v[228:231], v[92:95]
	v_mfma_f32_16x16x32_bf16 v[84:87], v[186:189], v[228:231], v[84:87]
	v_mfma_f32_16x16x32_bf16 v[76:79], v[162:165], v[236:239], v[76:79]
	v_mfma_f32_16x16x32_bf16 v[68:71], v[186:189], v[236:239], v[68:71]
	v_mfma_f32_16x16x32_bf16 v[124:127], v[182:185], v[216:219], v[124:127]
	v_mfma_f32_16x16x32_bf16 v[116:119], v[190:193], v[216:219], v[116:119]
	v_mfma_f32_16x16x32_bf16 v[108:111], v[182:185], v[224:227], v[108:111]
	v_mfma_f32_16x16x32_bf16 v[100:103], v[190:193], v[224:227], v[100:103]
	v_mfma_f32_16x16x32_bf16 v[92:95], v[182:185], v[232:235], v[92:95]
	v_mfma_f32_16x16x32_bf16 v[84:87], v[190:193], v[232:235], v[84:87]
	v_mfma_f32_16x16x32_bf16 v[76:79], v[182:185], v[240:243], v[76:79]
	v_mfma_f32_16x16x32_bf16 v[68:71], v[190:193], v[240:243], v[68:71]
	v_mfma_f32_16x16x32_bf16 v[120:123], v[194:197], v[210:213], v[120:123]
	v_mfma_f32_16x16x32_bf16 v[112:115], v[202:205], v[210:213], v[112:115]
	v_mfma_f32_16x16x32_bf16 v[104:107], v[194:197], v[220:223], v[104:107]
	v_mfma_f32_16x16x32_bf16 v[96:99], v[202:205], v[220:223], v[96:99]
	v_mfma_f32_16x16x32_bf16 v[88:91], v[194:197], v[228:231], v[88:91]
	v_mfma_f32_16x16x32_bf16 v[80:83], v[202:205], v[228:231], v[80:83]
	v_mfma_f32_16x16x32_bf16 v[72:75], v[194:197], v[236:239], v[72:75]
	v_mfma_f32_16x16x32_bf16 v[64:67], v[202:205], v[236:239], v[64:67]
	v_mfma_f32_16x16x32_bf16 v[120:123], v[198:201], v[216:219], v[120:123]
	v_mfma_f32_16x16x32_bf16 v[112:115], v[206:209], v[216:219], v[112:115]
	v_mfma_f32_16x16x32_bf16 v[104:107], v[198:201], v[224:227], v[104:107]
	v_mfma_f32_16x16x32_bf16 v[96:99], v[206:209], v[224:227], v[96:99]
	v_mfma_f32_16x16x32_bf16 v[88:91], v[198:201], v[232:235], v[88:91]
	v_mfma_f32_16x16x32_bf16 v[80:83], v[206:209], v[232:235], v[80:83]
	v_mfma_f32_16x16x32_bf16 v[72:75], v[198:201], v[240:243], v[72:75]
	v_mfma_f32_16x16x32_bf16 v[64:67], v[206:209], v[240:243], v[64:67]
	s_setprio 0
	s_barrier
	s_mov_b32 m0, s60
	v_lshl_add_u64 v[246:247], v[244:245], 0, v[138:139]
	ds_read_b128 v[210:213], v179 offset:16384
	ds_read_b128 v[216:219], v179 offset:17408
	ds_read_b128 v[220:223], v179 offset:18432
	ds_read_b128 v[224:227], v179 offset:19456
	ds_read_b128 v[228:231], v179 offset:20480
	ds_read_b128 v[232:235], v179 offset:21504
	ds_read_b128 v[236:239], v179 offset:22528
	ds_read_b128 v[240:243], v179 offset:23552
	global_load_lds_dwordx4 v[246:247], off
	v_lshl_add_u64 v[248:249], v[244:245], 0, v[134:135]
	s_mov_b32 m0, s61
	v_lshl_add_u64 v[244:245], v[244:245], 0, s[14:15]
	global_load_lds_dwordx4 v[248:249], off
	v_lshl_add_u64 v[250:251], v[244:245], 0, v[138:139]
	s_mov_b32 m0, s62
	v_lshl_add_u64 v[244:245], v[244:245], 0, v[134:135]
	global_load_lds_dwordx4 v[250:251], off
	s_add_i32 m0, s62, 0x2000
	v_lshl_add_u64 v[252:253], v[172:173], 0, v[140:141]
	global_load_lds_dwordx4 v[244:245], off
	s_mov_b32 m0, s46
	v_lshl_add_u64 v[214:215], v[172:173], 0, v[136:137]
	global_load_lds_dwordx4 v[252:253], off
	s_mov_b32 m0, s47
	s_nop 0
	global_load_lds_dwordx4 v[214:215], off
	s_waitcnt vmcnt(8)
	s_waitcnt lgkmcnt(0)
	s_setprio 1
	s_barrier
; #define PG8_STAGE(bufoff, gbase, voff) do { _Pragma("unroll") for (int _i = 0; _i < 2; ++_i) \
;         __builtin_amdgcn_global_load_lds((const unsigned*)((const char*)(gbase) + (voff)[_i]), (PG8_LAS unsigned*)(lds + (bufoff) + ldsw + _i * 8192), 16, 0, 0); } while (0)
; #define PG8_LDA(dst, b, h) do { _Pragma("unroll") for (int m = 0; m < 4; ++m) _Pragma("unroll") for (int k = 0; k < 2; ++k) dst[m][k] = *(const PG8_LAS bf16x8*)(lds + PG8_SA(b, h) + aoff + m * 2048 + k * 1024); } while (0)
; #define PG8_LDB(dst, b, h) do { _Pragma("unroll") for (int n = 0; n < 2; ++n) _Pragma("unroll") for (int k = 0; k < 2; ++k) dst[n][k] = *(const PG8_LAS bf16x8*)(lds + PG8_SB(b, h) + boff + n * 2048 + k * 1024); } while (0)
; template <class Epi, class Sched, bool ALIGN_EPI = false, bool SP2 = false>
; __device__ __forceinline__ void gemm_phase(PG8_LAS unsigned char* lds, const Gemm g, const Sched& S, const Epi& E) {
;     ...
;         for (int t = 0; t < nt; t += 2) {
;             const bool last = (t == nt - 2);
;             const char* a1 = cA + (size_t)(t + 1) * kstep;
;             const char* a2 = last ? nA : cA + (size_t)(t + 2) * kstep; const char* b2 = last ? nB : cB + (size_t)(t + 2) * kstep;
;             const char* a3 = a2 + kstep; const char* b3 = b2 + kstep;
;             if (last && has_next) S.a_ready(nxt);
;             if constexpr (SP2) {
;             PG8_LDB(B0, 0, 0); PG8_LDB(B1, 0, 1); PG8_SCHED; PG8_LDA(At, 0, 0); PG8_STAGE(PG8_SA(1, 1), a1 + hstep, voffA);
;             PG8_WAIT_V(8); PG8_WAIT_L(0); PG8_BAR; PG8_MMA(0, 0, At, B0); PG8_MMA(0, 1, At, B1); PG8_BAR; PG8_SCHED;
;             PG8_LDA(At, 0, 1); PG8_STAGE(PG8_SB(0, 0), b2, voffB); PG8_STAGE(PG8_SB(0, 1), b2 + hstep, voffB); PG8_STAGE(PG8_SA(0, 0), a2, voffA);
;             PG8_WAIT_V(8); PG8_WAIT_L(0); PG8_BAR; PG8_MMA(1, 0, At, B0); PG8_MMA(1, 1, At, B1); PG8_BAR; PG8_SCHED;
;             PG8_LDB(B0, 1, 0); PG8_LDB(B1, 1, 1); PG8_SCHED; PG8_LDA(At, 1, 0); PG8_STAGE(PG8_SA(0, 1), a2 + hstep, voffA);
;             PG8_WAIT_V(8); PG8_WAIT_L(0); PG8_BAR; PG8_MMA(0, 0, At, B0); PG8_MMA(0, 1, At, B1); PG8_BAR; PG8_SCHED;
;             PG8_LDA(At, 1, 1); PG8_STAGE(PG8_SB(1, 0), b3, voffB); PG8_STAGE(PG8_SB(1, 1), b3 + hstep, voffB); PG8_STAGE(PG8_SA(1, 0), a3, voffA);
;             PG8_WAIT_V(8); PG8_WAIT_L(0); PG8_BAR; PG8_MMA(1, 0, At, B0); PG8_MMA(1, 1, At, B1); PG8_BAR; PG8_SCHED;
	v_mfma_f32_16x16x32_bf16 v[60:63], v[162:165], v[210:213], v[60:63]
	v_mfma_f32_16x16x32_bf16 v[52:55], v[186:189], v[210:213], v[52:55]
	v_mfma_f32_16x16x32_bf16 v[44:47], v[162:165], v[220:223], v[44:47]
	v_mfma_f32_16x16x32_bf16 v[36:39], v[186:189], v[220:223], v[36:39]
	v_mfma_f32_16x16x32_bf16 v[28:31], v[162:165], v[228:231], v[28:31]
	v_mfma_f32_16x16x32_bf16 v[20:23], v[186:189], v[228:231], v[20:23]
	v_mfma_f32_16x16x32_bf16 v[12:15], v[162:165], v[236:239], v[12:15]
	v_mfma_f32_16x16x32_bf16 v[4:7], v[186:189], v[236:239], v[4:7]
	v_mfma_f32_16x16x32_bf16 v[60:63], v[182:185], v[216:219], v[60:63]
	v_mfma_f32_16x16x32_bf16 v[52:55], v[190:193], v[216:219], v[52:55]
	v_mfma_f32_16x16x32_bf16 v[44:47], v[182:185], v[224:227], v[44:47]
	v_mfma_f32_16x16x32_bf16 v[36:39], v[190:193], v[224:227], v[36:39]
	v_mfma_f32_16x16x32_bf16 v[28:31], v[182:185], v[232:235], v[28:31]
	v_mfma_f32_16x16x32_bf16 v[20:23], v[190:193], v[232:235], v[20:23]
	v_mfma_f32_16x16x32_bf16 v[12:15], v[182:185], v[240:243], v[12:15]
	v_mfma_f32_16x16x32_bf16 v[4:7], v[190:193], v[240:243], v[4:7]
	v_mfma_f32_16x16x32_bf16 v[56:59], v[194:197], v[210:213], v[56:59]
	v_mfma_f32_16x16x32_bf16 v[48:51], v[202:205], v[210:213], v[48:51]
	v_mfma_f32_16x16x32_bf16 v[40:43], v[194:197], v[220:223], v[40:43]
	v_mfma_f32_16x16x32_bf16 v[32:35], v[202:205], v[220:223], v[32:35]
	v_mfma_f32_16x16x32_bf16 v[24:27], v[194:197], v[228:231], v[24:27]
	v_mfma_f32_16x16x32_bf16 v[16:19], v[202:205], v[228:231], v[16:19]
	v_mfma_f32_16x16x32_bf16 v[8:11], v[194:197], v[236:239], v[8:11]
	v_mfma_f32_16x16x32_bf16 v[0:3], v[202:205], v[236:239], v[0:3]
	v_mfma_f32_16x16x32_bf16 v[56:59], v[198:201], v[216:219], v[56:59]
	v_mfma_f32_16x16x32_bf16 v[48:51], v[206:209], v[216:219], v[48:51]
	v_mfma_f32_16x16x32_bf16 v[40:43], v[198:201], v[224:227], v[40:43]
	v_mfma_f32_16x16x32_bf16 v[32:35], v[206:209], v[224:227], v[32:35]
	v_mfma_f32_16x16x32_bf16 v[24:27], v[198:201], v[232:235], v[24:27]
	v_mfma_f32_16x16x32_bf16 v[16:19], v[206:209], v[232:235], v[16:19]
	v_mfma_f32_16x16x32_bf16 v[8:11], v[198:201], v[240:243], v[8:11]
	v_mfma_f32_16x16x32_bf16 v[0:3], v[206:209], v[240:243], v[0:3]
	s_setprio 0
	s_barrier
	s_add_i32 s11, 0, 0x18000
	v_add_u32_e32 v166, s11, v169
	s_add_i32 s13, 0, 0x1c000
	ds_read_b128 v[162:165], v166
	ds_read_b128 v[182:185], v166 offset:1024
	ds_read_b128 v[186:189], v166 offset:2048
	ds_read_b128 v[190:193], v166 offset:3072
	v_add_u32_e32 v166, s13, v169
	ds_read_b128 v[194:197], v166
	ds_read_b128 v[198:201], v166 offset:1024
	ds_read_b128 v[202:205], v166 offset:2048
	ds_read_b128 v[206:209], v166 offset:3072
	v_lshl_add_u64 v[172:173], v[172:173], 0, s[14:15]
	s_mov_b32 m0, s48
	v_lshl_add_u64 v[170:171], v[172:173], 0, v[140:141]
	ds_read_b128 v[210:213], v179 offset:32768
	ds_read_b128 v[216:219], v179 offset:33792
	ds_read_b128 v[220:223], v179 offset:34816
	ds_read_b128 v[224:227], v179 offset:35840
	ds_read_b128 v[228:231], v179 offset:36864
	ds_read_b128 v[232:235], v179 offset:37888
	ds_read_b128 v[236:239], v179 offset:38912
	ds_read_b128 v[240:243], v179 offset:39936
	global_load_lds_dwordx4 v[170:171], off
	s_mov_b32 m0, s49
	v_lshl_add_u64 v[170:171], v[172:173], 0, v[136:137]
	global_load_lds_dwordx4 v[170:171], off
	s_waitcnt vmcnt(8)
	s_waitcnt lgkmcnt(0)
	s_setprio 1
	s_barrier
	v_mfma_f32_16x16x32_bf16 v[124:127], v[162:165], v[210:213], v[124:127]
	v_mfma_f32_16x16x32_bf16 v[116:119], v[186:189], v[210:213], v[116:119]
	v_mfma_f32_16x16x32_bf16 v[108:111], v[162:165], v[220:223], v[108:111]
	v_mfma_f32_16x16x32_bf16 v[100:103], v[186:189], v[220:223], v[100:103]
	v_mfma_f32_16x16x32_bf16 v[92:95], v[162:165], v[228:231], v[92:95]
	v_mfma_f32_16x16x32_bf16 v[84:87], v[186:189], v[228:231], v[84:87]
	v_mfma_f32_16x16x32_bf16 v[76:79], v[162:165], v[236:239], v[76:79]
	v_mfma_f32_16x16x32_bf16 v[68:71], v[186:189], v[236:239], v[68:71]
	v_mfma_f32_16x16x32_bf16 v[124:127], v[182:185], v[216:219], v[124:127]
	v_mfma_f32_16x16x32_bf16 v[116:119], v[190:193], v[216:219], v[116:119]
	v_mfma_f32_16x16x32_bf16 v[108:111], v[182:185], v[224:227], v[108:111]
	v_mfma_f32_16x16x32_bf16 v[100:103], v[190:193], v[224:227], v[100:103]
	v_mfma_f32_16x16x32_bf16 v[92:95], v[182:185], v[232:235], v[92:95]
	v_mfma_f32_16x16x32_bf16 v[84:87], v[190:193], v[232:235], v[84:87]
	v_mfma_f32_16x16x32_bf16 v[76:79], v[182:185], v[240:243], v[76:79]
	v_mfma_f32_16x16x32_bf16 v[68:71], v[190:193], v[240:243], v[68:71]
	v_mfma_f32_16x16x32_bf16 v[120:123], v[194:197], v[210:213], v[120:123]
	v_mfma_f32_16x16x32_bf16 v[112:115], v[202:205], v[210:213], v[112:115]
	v_mfma_f32_16x16x32_bf16 v[104:107], v[194:197], v[220:223], v[104:107]
	v_mfma_f32_16x16x32_bf16 v[96:99], v[202:205], v[220:223], v[96:99]
	v_mfma_f32_16x16x32_bf16 v[88:91], v[194:197], v[228:231], v[88:91]
	v_mfma_f32_16x16x32_bf16 v[80:83], v[202:205], v[228:231], v[80:83]
	v_mfma_f32_16x16x32_bf16 v[72:75], v[194:197], v[236:239], v[72:75]
	v_mfma_f32_16x16x32_bf16 v[64:67], v[202:205], v[236:239], v[64:67]
	v_mfma_f32_16x16x32_bf16 v[120:123], v[198:201], v[216:219], v[120:123]
	v_mfma_f32_16x16x32_bf16 v[112:115], v[206:209], v[216:219], v[112:115]
	v_mfma_f32_16x16x32_bf16 v[104:107], v[198:201], v[224:227], v[104:107]
	v_mfma_f32_16x16x32_bf16 v[96:99], v[206:209], v[224:227], v[96:99]
	v_mfma_f32_16x16x32_bf16 v[88:91], v[198:201], v[232:235], v[88:91]
	v_mfma_f32_16x16x32_bf16 v[80:83], v[206:209], v[232:235], v[80:83]
	v_mfma_f32_16x16x32_bf16 v[72:75], v[198:201], v[240:243], v[72:75]
	v_mfma_f32_16x16x32_bf16 v[64:67], v[206:209], v[240:243], v[64:67]
	s_setprio 0
	s_barrier
; #define PG8_STAGE(bufoff, gbase, voff) do { _Pragma("unroll") for (int _i = 0; _i < 2; ++_i) \
;         __builtin_amdgcn_global_load_lds((const unsigned*)((const char*)(gbase) + (voff)[_i]), (PG8_LAS unsigned*)(lds + (bufoff) + ldsw + _i * 8192), 16, 0, 0); } while (0)
; #define PG8_LDA(dst, b, h) do { _Pragma("unroll") for (int m = 0; m < 4; ++m) _Pragma("unroll") for (int k = 0; k < 2; ++k) dst[m][k] = *(const PG8_LAS bf16x8*)(lds + PG8_SA(b, h) + aoff + m * 2048 + k * 1024); } while (0)
; #define PG8_LDB(dst, b, h) do { _Pragma("unroll") for (int n = 0; n < 2; ++n) _Pragma("unroll") for (int k = 0; k < 2; ++k) dst[n][k] = *(const PG8_LAS bf16x8*)(lds + PG8_SB(b, h) + boff + n * 2048 + k * 1024); } while (0)
; template <class Epi, class Sched, bool ALIGN_EPI = false, bool SP2 = false>
; __device__ __forceinline__ void gemm_phase(PG8_LAS unsigned char* lds, const Gemm g, const Sched& S, const Epi& E) {
;     ...
;         for (int t = 0; t < nt; t += 2) {
;             const bool last = (t == nt - 2);
;             const char* a1 = cA + (size_t)(t + 1) * kstep;
;             const char* a2 = last ? nA : cA + (size_t)(t + 2) * kstep; const char* b2 = last ? nB : cB + (size_t)(t + 2) * kstep;
;             const char* a3 = a2 + kstep; const char* b3 = b2 + kstep;
;             if (last && has_next) S.a_ready(nxt);
;             if constexpr (SP2) {
;             PG8_LDB(B0, 0, 0); PG8_LDB(B1, 0, 1); PG8_SCHED; PG8_LDA(At, 0, 0); PG8_STAGE(PG8_SA(1, 1), a1 + hstep, voffA);
;             PG8_WAIT_V(8); PG8_WAIT_L(0); PG8_BAR; PG8_MMA(0, 0, At, B0); PG8_MMA(0, 1, At, B1); PG8_BAR; PG8_SCHED;
;             PG8_LDA(At, 0, 1); PG8_STAGE(PG8_SB(0, 0), b2, voffB); PG8_STAGE(PG8_SB(0, 1), b2 + hstep, voffB); PG8_STAGE(PG8_SA(0, 0), a2, voffA);
;             PG8_WAIT_V(8); PG8_WAIT_L(0); PG8_BAR; PG8_MMA(1, 0, At, B0); PG8_MMA(1, 1, At, B1); PG8_BAR; PG8_SCHED;
;             PG8_LDB(B0, 1, 0); PG8_LDB(B1, 1, 1); PG8_SCHED; PG8_LDA(At, 1, 0); PG8_STAGE(PG8_SA(0, 1), a2 + hstep, voffA);
;             PG8_WAIT_V(8); PG8_WAIT_L(0); PG8_BAR; PG8_MMA(0, 0, At, B0); PG8_MMA(0, 1, At, B1); PG8_BAR; PG8_SCHED;
;             PG8_LDA(At, 1, 1); PG8_STAGE(PG8_SB(1, 0), b3, voffB); PG8_STAGE(PG8_SB(1, 1), b3 + hstep, voffB); PG8_STAGE(PG8_SA(1, 0), a3, voffA);
;             PG8_WAIT_V(8); PG8_WAIT_L(0); PG8_BAR; PG8_MMA(1, 0, At, B0); PG8_MMA(1, 1, At, B1); PG8_BAR; PG8_SCHED;
	s_add_i32 s11, s11, s29
	v_lshl_add_u64 v[170:171], v[246:247], 0, s[22:23]
	s_mov_b32 m0, s11
	ds_read_b128 v[210:213], v179 offset:49152
	ds_read_b128 v[216:219], v179 offset:50176
	ds_read_b128 v[220:223], v179 offset:51200
	ds_read_b128 v[224:227], v179 offset:52224
	ds_read_b128 v[228:231], v179 offset:53248
	ds_read_b128 v[232:235], v179 offset:54272
	ds_read_b128 v[236:239], v179 offset:55296
	ds_read_b128 v[240:243], v179 offset:56320
	global_load_lds_dwordx4 v[170:171], off
	v_lshl_add_u64 v[170:171], v[248:249], 0, s[22:23]
	s_add_i32 m0, s11, 0x2000
	s_add_i32 s11, s13, s29
	global_load_lds_dwordx4 v[170:171], off
	s_mov_b32 m0, s11
	v_lshl_add_u64 v[170:171], v[250:251], 0, s[22:23]
	global_load_lds_dwordx4 v[170:171], off
	s_add_i32 m0, s11, 0x2000
	v_lshl_add_u64 v[170:171], v[244:245], 0, s[22:23]
	global_load_lds_dwordx4 v[170:171], off
	s_mov_b32 m0, s50
	v_lshl_add_u64 v[170:171], v[252:253], 0, s[22:23]
	global_load_lds_dwordx4 v[170:171], off
	s_mov_b32 m0, s51
	v_lshl_add_u64 v[170:171], v[214:215], 0, s[22:23]
	global_load_lds_dwordx4 v[170:171], off
	s_waitcnt vmcnt(8)
	s_waitcnt lgkmcnt(0)
	s_setprio 1
	s_barrier
	v_mfma_f32_16x16x32_bf16 v[60:63], v[162:165], v[210:213], v[60:63]
	v_mfma_f32_16x16x32_bf16 v[52:55], v[186:189], v[210:213], v[52:55]
	v_mfma_f32_16x16x32_bf16 v[44:47], v[162:165], v[220:223], v[44:47]
	v_mfma_f32_16x16x32_bf16 v[36:39], v[186:189], v[220:223], v[36:39]
	v_mfma_f32_16x16x32_bf16 v[28:31], v[162:165], v[228:231], v[28:31]
	v_mfma_f32_16x16x32_bf16 v[20:23], v[186:189], v[228:231], v[20:23]
	v_mfma_f32_16x16x32_bf16 v[12:15], v[162:165], v[236:239], v[12:15]
	v_mfma_f32_16x16x32_bf16 v[4:7], v[186:189], v[236:239], v[4:7]
	v_mfma_f32_16x16x32_bf16 v[60:63], v[182:185], v[216:219], v[60:63]
	v_mfma_f32_16x16x32_bf16 v[52:55], v[190:193], v[216:219], v[52:55]
	v_mfma_f32_16x16x32_bf16 v[44:47], v[182:185], v[224:227], v[44:47]
	v_mfma_f32_16x16x32_bf16 v[36:39], v[190:193], v[224:227], v[36:39]
	v_mfma_f32_16x16x32_bf16 v[28:31], v[182:185], v[232:235], v[28:31]
	v_mfma_f32_16x16x32_bf16 v[20:23], v[190:193], v[232:235], v[20:23]
	v_mfma_f32_16x16x32_bf16 v[12:15], v[182:185], v[240:243], v[12:15]
	v_mfma_f32_16x16x32_bf16 v[4:7], v[190:193], v[240:243], v[4:7]
	v_mfma_f32_16x16x32_bf16 v[56:59], v[194:197], v[210:213], v[56:59]
	v_mfma_f32_16x16x32_bf16 v[48:51], v[202:205], v[210:213], v[48:51]
	v_mfma_f32_16x16x32_bf16 v[40:43], v[194:197], v[220:223], v[40:43]
	v_mfma_f32_16x16x32_bf16 v[32:35], v[202:205], v[220:223], v[32:35]
	v_mfma_f32_16x16x32_bf16 v[24:27], v[194:197], v[228:231], v[24:27]
	v_mfma_f32_16x16x32_bf16 v[16:19], v[202:205], v[228:231], v[16:19]
	v_mfma_f32_16x16x32_bf16 v[8:11], v[194:197], v[236:239], v[8:11]
	v_mfma_f32_16x16x32_bf16 v[0:3], v[202:205], v[236:239], v[0:3]
	v_mfma_f32_16x16x32_bf16 v[56:59], v[198:201], v[216:219], v[56:59]
	v_mfma_f32_16x16x32_bf16 v[48:51], v[206:209], v[216:219], v[48:51]
	v_mfma_f32_16x16x32_bf16 v[40:43], v[198:201], v[224:227], v[40:43]
	v_mfma_f32_16x16x32_bf16 v[32:35], v[206:209], v[224:227], v[32:35]
	v_mfma_f32_16x16x32_bf16 v[24:27], v[198:201], v[232:235], v[24:27]
	v_mfma_f32_16x16x32_bf16 v[16:19], v[206:209], v[232:235], v[16:19]
	v_mfma_f32_16x16x32_bf16 v[8:11], v[198:201], v[240:243], v[8:11]
	v_mfma_f32_16x16x32_bf16 v[0:3], v[206:209], v[240:243], v[0:3]
	s_setprio 0
	s_barrier
	v_lshl_add_u64 v[158:159], v[158:159], 0, s[26:27]
	s_cmp_ge_i32 s10, s52
	v_lshl_add_u64 v[160:161], v[160:161], 0, s[26:27]
	s_cbranch_scc0 .LBB0_304

; #define PG8_STAGE(bufoff, gbase, voff) do { _Pragma("unroll") for (int _i = 0; _i < 2; ++_i) \
;         __builtin_amdgcn_global_load_lds((const unsigned*)((const char*)(gbase) + (voff)[_i]), (PG8_LAS unsigned*)(lds + (bufoff) + ldsw + _i * 8192), 16, 0, 0); } while (0)
; #define PG8_LDA(dst, b, h) do { _Pragma("unroll") for (int m = 0; m < 4; ++m) _Pragma("unroll") for (int k = 0; k < 2; ++k) dst[m][k] = *(const PG8_LAS bf16x8*)(lds + PG8_SA(b, h) + aoff + m * 2048 + k * 1024); } while (0)
; #define PG8_LDB(dst, b, h) do { _Pragma("unroll") for (int n = 0; n < 2; ++n) _Pragma("unroll") for (int k = 0; k < 2; ++k) dst[n][k] = *(const PG8_LAS bf16x8*)(lds + PG8_SB(b, h) + boff + n * 2048 + k * 1024); } while (0)
; template <class Epi, class Sched, bool ALIGN_EPI = false, bool SP2 = false>
; __device__ __forceinline__ void gemm_phase(PG8_LAS unsigned char* lds, const Gemm g, const Sched& S, const Epi& E) {
;     ...
;         for (int t = 0; t < nt; t += 2) {
;             const bool last = (t == nt - 2);
;             const char* a1 = cA + (size_t)(t + 1) * kstep;
;             const char* a2 = last ? nA : cA + (size_t)(t + 2) * kstep; const char* b2 = last ? nB : cB + (size_t)(t + 2) * kstep;
;             const char* a3 = a2 + kstep; const char* b3 = b2 + kstep;
;             if (last && has_next) S.a_ready(nxt);
;             if constexpr (SP2) {
;             PG8_LDB(B0, 0, 0); PG8_LDB(B1, 0, 1); PG8_SCHED; PG8_LDA(At, 0, 0); PG8_STAGE(PG8_SA(1, 1), a1 + hstep, voffA);
;             PG8_WAIT_V(8); PG8_WAIT_L(0); PG8_BAR; PG8_MMA(0, 0, At, B0); PG8_MMA(0, 1, At, B1); PG8_BAR; PG8_SCHED;
;             PG8_LDA(At, 0, 1); PG8_STAGE(PG8_SB(0, 0), b2, voffB); PG8_STAGE(PG8_SB(0, 1), b2 + hstep, voffB); PG8_STAGE(PG8_SA(0, 0), a2, voffA);
;             PG8_WAIT_V(8); PG8_WAIT_L(0); PG8_BAR; PG8_MMA(1, 0, At, B0); PG8_MMA(1, 1, At, B1); PG8_BAR; PG8_SCHED;
;             PG8_LDB(B0, 1, 0); PG8_LDB(B1, 1, 1); PG8_SCHED; PG8_LDA(At, 1, 0); PG8_STAGE(PG8_SA(0, 1), a2 + hstep, voffA);
;             PG8_WAIT_V(8); PG8_WAIT_L(0); PG8_BAR; PG8_MMA(0, 0, At, B0); PG8_MMA(0, 1, At, B1); PG8_BAR; PG8_SCHED;
;             PG8_LDA(At, 1, 1); PG8_STAGE(PG8_SB(1, 0), b3, voffB); PG8_STAGE(PG8_SB(1, 1), b3 + hstep, voffB); PG8_STAGE(PG8_SA(1, 0), a3, voffA);
;             PG8_WAIT_V(8); PG8_WAIT_L(0); PG8_BAR; PG8_MMA(1, 0, At, B0); PG8_MMA(1, 1, At, B1); PG8_BAR; PG8_SCHED;
.LBB0_371:
	v_add_u32_e32 v148, s54, v201
	v_add_u32_e32 v190, s55, v201
	ds_read_b128 v[136:139], v148
	ds_read_b128 v[140:143], v148 offset:1024
	ds_read_b128 v[144:147], v148 offset:2048
	ds_read_b128 v[148:151], v148 offset:3072
	ds_read_b128 v[152:155], v190
	ds_read_b128 v[182:185], v190 offset:1024
	ds_read_b128 v[186:189], v190 offset:2048
	ds_read_b128 v[190:193], v190 offset:3072
	s_cmp_eq_u32 s48, s12
	v_lshl_add_u64 v[194:195], v[134:135], 0, s[22:23]
	s_cselect_b64 vcc, -1, 0
	s_add_i32 s12, s12, 2
	v_cndmask_b32_e32 v199, v195, v179, vcc
	v_cndmask_b32_e32 v198, v194, v178, vcc
	v_cndmask_b32_e32 v215, v133, v181, vcc
	v_cndmask_b32_e32 v214, v132, v180, vcc
	s_mov_b32 m0, s56
	v_lshl_add_u64 v[236:237], v[134:135], 0, v[174:175]
	ds_read_b128 v[194:197], v203
	ds_read_b128 v[206:209], v203 offset:1024
	ds_read_b128 v[210:213], v203 offset:2048
	ds_read_b128 v[216:219], v203 offset:3072
	ds_read_b128 v[220:223], v203 offset:4096
	ds_read_b128 v[224:227], v203 offset:5120
	ds_read_b128 v[228:231], v203 offset:6144
	ds_read_b128 v[232:235], v203 offset:7168
	global_load_lds_dwordx4 v[236:237], off
	s_mov_b32 m0, s57
	v_lshl_add_u64 v[236:237], v[134:135], 0, v[172:173]
	global_load_lds_dwordx4 v[236:237], off
	s_waitcnt vmcnt(8)
	s_waitcnt lgkmcnt(0)
	s_setprio 1
	s_barrier
	v_mfma_f32_16x16x32_bf16 v[124:127], v[136:139], v[194:197], v[124:127]
	v_mfma_f32_16x16x32_bf16 v[128:131], v[144:147], v[194:197], v[128:131]
	v_mfma_f32_16x16x32_bf16 v[112:115], v[136:139], v[210:213], v[112:115]
	v_mfma_f32_16x16x32_bf16 v[108:111], v[144:147], v[210:213], v[108:111]
	v_mfma_f32_16x16x32_bf16 v[96:99], v[136:139], v[220:223], v[96:99]
	v_mfma_f32_16x16x32_bf16 v[92:95], v[144:147], v[220:223], v[92:95]
	v_mfma_f32_16x16x32_bf16 v[80:83], v[136:139], v[228:231], v[80:83]
	v_mfma_f32_16x16x32_bf16 v[76:79], v[144:147], v[228:231], v[76:79]
	v_mfma_f32_16x16x32_bf16 v[124:127], v[140:143], v[206:209], v[124:127]
	v_mfma_f32_16x16x32_bf16 v[128:131], v[148:151], v[206:209], v[128:131]
	v_mfma_f32_16x16x32_bf16 v[112:115], v[140:143], v[216:219], v[112:115]
	v_mfma_f32_16x16x32_bf16 v[108:111], v[148:151], v[216:219], v[108:111]
	v_mfma_f32_16x16x32_bf16 v[96:99], v[140:143], v[224:227], v[96:99]
	v_mfma_f32_16x16x32_bf16 v[92:95], v[148:151], v[224:227], v[92:95]
	v_mfma_f32_16x16x32_bf16 v[80:83], v[140:143], v[232:235], v[80:83]
	v_mfma_f32_16x16x32_bf16 v[76:79], v[148:151], v[232:235], v[76:79]
	v_mfma_f32_16x16x32_bf16 v[120:123], v[152:155], v[194:197], v[120:123]
	v_mfma_f32_16x16x32_bf16 v[116:119], v[186:189], v[194:197], v[116:119]
	v_mfma_f32_16x16x32_bf16 v[104:107], v[152:155], v[210:213], v[104:107]
	v_mfma_f32_16x16x32_bf16 v[100:103], v[186:189], v[210:213], v[100:103]
	v_mfma_f32_16x16x32_bf16 v[88:91], v[152:155], v[220:223], v[88:91]
	v_mfma_f32_16x16x32_bf16 v[84:87], v[186:189], v[220:223], v[84:87]
	v_mfma_f32_16x16x32_bf16 v[72:75], v[152:155], v[228:231], v[72:75]
	v_mfma_f32_16x16x32_bf16 v[68:71], v[186:189], v[228:231], v[68:71]
	v_mfma_f32_16x16x32_bf16 v[120:123], v[182:185], v[206:209], v[120:123]
	v_mfma_f32_16x16x32_bf16 v[116:119], v[190:193], v[206:209], v[116:119]
	v_mfma_f32_16x16x32_bf16 v[104:107], v[182:185], v[216:219], v[104:107]
	v_mfma_f32_16x16x32_bf16 v[100:103], v[190:193], v[216:219], v[100:103]
	v_mfma_f32_16x16x32_bf16 v[88:91], v[182:185], v[224:227], v[88:91]
	v_mfma_f32_16x16x32_bf16 v[84:87], v[190:193], v[224:227], v[84:87]
	v_mfma_f32_16x16x32_bf16 v[72:75], v[182:185], v[232:235], v[72:75]
	v_mfma_f32_16x16x32_bf16 v[68:71], v[190:193], v[232:235], v[68:71]
	s_setprio 0
	s_barrier
	s_mov_b32 m0, s58
	v_lshl_add_u64 v[236:237], v[214:215], 0, v[166:167]
	ds_read_b128 v[194:197], v203 offset:16384
	ds_read_b128 v[206:209], v203 offset:17408
	ds_read_b128 v[210:213], v203 offset:18432
	ds_read_b128 v[216:219], v203 offset:19456
	ds_read_b128 v[220:223], v203 offset:20480
	ds_read_b128 v[224:227], v203 offset:21504
	ds_read_b128 v[228:231], v203 offset:22528
	ds_read_b128 v[232:235], v203 offset:23552
	global_load_lds_dwordx4 v[236:237], off
	v_lshl_add_u64 v[238:239], v[214:215], 0, v[170:171]
	s_mov_b32 m0, s59
	v_lshl_add_u64 v[214:215], v[214:215], 0, s[14:15]
	s_add_i32 s13, s55, s30
	global_load_lds_dwordx4 v[238:239], off
	v_lshl_add_u64 v[240:241], v[214:215], 0, v[166:167]
	s_mov_b32 m0, s13
	v_lshl_add_u64 v[214:215], v[214:215], 0, v[170:171]
	global_load_lds_dwordx4 v[240:241], off
	s_add_i32 m0, s13, 0x2000
	v_lshl_add_u64 v[242:243], v[198:199], 0, v[164:165]
	global_load_lds_dwordx4 v[214:215], off
	s_mov_b32 m0, s31
	v_lshl_add_u64 v[244:245], v[198:199], 0, v[168:169]
	global_load_lds_dwordx4 v[242:243], off
	s_mov_b32 m0, s34
	s_nop 0
	global_load_lds_dwordx4 v[244:245], off
	s_waitcnt vmcnt(8)
	s_waitcnt lgkmcnt(0)
	s_setprio 1
	s_barrier
; #define PG8_STAGE(bufoff, gbase, voff) do { _Pragma("unroll") for (int _i = 0; _i < 2; ++_i) \
;         __builtin_amdgcn_global_load_lds((const unsigned*)((const char*)(gbase) + (voff)[_i]), (PG8_LAS unsigned*)(lds + (bufoff) + ldsw + _i * 8192), 16, 0, 0); } while (0)
; #define PG8_LDA(dst, b, h) do { _Pragma("unroll") for (int m = 0; m < 4; ++m) _Pragma("unroll") for (int k = 0; k < 2; ++k) dst[m][k] = *(const PG8_LAS bf16x8*)(lds + PG8_SA(b, h) + aoff + m * 2048 + k * 1024); } while (0)
; #define PG8_LDB(dst, b, h) do { _Pragma("unroll") for (int n = 0; n < 2; ++n) _Pragma("unroll") for (int k = 0; k < 2; ++k) dst[n][k] = *(const PG8_LAS bf16x8*)(lds + PG8_SB(b, h) + boff + n * 2048 + k * 1024); } while (0)
; #define PG8_MMA(ai, bj, At, Bt) do { __builtin_amdgcn_s_setprio(1); _Pragma("unroll") for (int m = 0; m < 4; ++m) _Pragma("unroll") for (int n = 0; n < 2; ++n) _Pragma("unroll") for (int k = 0; k < 2; ++k) \
;         acc[ai][bj][m][n] = __builtin_amdgcn_mfma_f32_16x16x32_bf16(Bt[n][k], At[m][k], acc[ai][bj][m][n], 0, 0, 0); __builtin_amdgcn_s_setprio(0); } while (0)
; #define PG8_WAIT_V(n) asm volatile("s_waitcnt vmcnt(" #n ")" ::: "memory")
; #define PG8_WAIT_L(n) asm volatile("s_waitcnt lgkmcnt(" #n ")" ::: "memory")
; #define PG8_BAR __builtin_amdgcn_s_barrier()
; #define PG8_SCHED __builtin_amdgcn_sched_barrier(0)
; template <class Epi, class Sched, bool ALIGN_EPI = false, bool SP2 = false>
; __device__ __forceinline__ void gemm_phase(PG8_LAS unsigned char* lds, const Gemm g, const Sched& S, const Epi& E) {
;     ...
;             PG8_WAIT_V(8); PG8_WAIT_L(0); PG8_BAR; PG8_MMA(1, 0, At, B0); PG8_MMA(1, 1, At, B1); PG8_BAR; PG8_SCHED;
;             PG8_LDB(B0, 1, 0); PG8_LDB(B1, 1, 1); PG8_SCHED; PG8_LDA(At, 1, 0); PG8_STAGE(PG8_SA(0, 1), a2 + hstep, voffA);
;             PG8_WAIT_V(8); PG8_WAIT_L(0); PG8_BAR; PG8_MMA(0, 0, At, B0); PG8_MMA(0, 1, At, B1); PG8_BAR; PG8_SCHED;
	v_mfma_f32_16x16x32_bf16 v[64:67], v[136:139], v[194:197], v[64:67]
	v_mfma_f32_16x16x32_bf16 v[60:63], v[144:147], v[194:197], v[60:63]
	v_mfma_f32_16x16x32_bf16 v[48:51], v[136:139], v[210:213], v[48:51]
	v_mfma_f32_16x16x32_bf16 v[44:47], v[144:147], v[210:213], v[44:47]
	v_mfma_f32_16x16x32_bf16 v[32:35], v[136:139], v[220:223], v[32:35]
	v_mfma_f32_16x16x32_bf16 v[28:31], v[144:147], v[220:223], v[28:31]
	v_mfma_f32_16x16x32_bf16 v[16:19], v[136:139], v[228:231], v[16:19]
	v_mfma_f32_16x16x32_bf16 v[12:15], v[144:147], v[228:231], v[12:15]
	v_mfma_f32_16x16x32_bf16 v[64:67], v[140:143], v[206:209], v[64:67]
	v_mfma_f32_16x16x32_bf16 v[60:63], v[148:151], v[206:209], v[60:63]
	v_mfma_f32_16x16x32_bf16 v[48:51], v[140:143], v[216:219], v[48:51]
	v_mfma_f32_16x16x32_bf16 v[44:47], v[148:151], v[216:219], v[44:47]
	v_mfma_f32_16x16x32_bf16 v[32:35], v[140:143], v[224:227], v[32:35]
	v_mfma_f32_16x16x32_bf16 v[28:31], v[148:151], v[224:227], v[28:31]
	v_mfma_f32_16x16x32_bf16 v[16:19], v[140:143], v[232:235], v[16:19]
	v_mfma_f32_16x16x32_bf16 v[12:15], v[148:151], v[232:235], v[12:15]
	v_mfma_f32_16x16x32_bf16 v[56:59], v[152:155], v[194:197], v[56:59]
	v_mfma_f32_16x16x32_bf16 v[52:55], v[186:189], v[194:197], v[52:55]
	v_mfma_f32_16x16x32_bf16 v[40:43], v[152:155], v[210:213], v[40:43]
	v_mfma_f32_16x16x32_bf16 v[36:39], v[186:189], v[210:213], v[36:39]
	v_mfma_f32_16x16x32_bf16 v[24:27], v[152:155], v[220:223], v[24:27]
	v_mfma_f32_16x16x32_bf16 v[20:23], v[186:189], v[220:223], v[20:23]
	v_mfma_f32_16x16x32_bf16 v[8:11], v[152:155], v[228:231], v[8:11]
	v_mfma_f32_16x16x32_bf16 v[4:7], v[186:189], v[228:231], v[4:7]
	v_mfma_f32_16x16x32_bf16 v[56:59], v[182:185], v[206:209], v[56:59]
	v_mfma_f32_16x16x32_bf16 v[52:55], v[190:193], v[206:209], v[52:55]
	v_mfma_f32_16x16x32_bf16 v[40:43], v[182:185], v[216:219], v[40:43]
	v_mfma_f32_16x16x32_bf16 v[36:39], v[190:193], v[216:219], v[36:39]
	v_mfma_f32_16x16x32_bf16 v[24:27], v[182:185], v[224:227], v[24:27]
	v_mfma_f32_16x16x32_bf16 v[20:23], v[190:193], v[224:227], v[20:23]
	v_mfma_f32_16x16x32_bf16 v[8:11], v[182:185], v[232:235], v[8:11]
	v_mfma_f32_16x16x32_bf16 v[4:7], v[190:193], v[232:235], v[4:7]
	s_setprio 0
	s_barrier
	s_add_i32 s13, 0, 0x18000
	s_add_i32 s29, 0, 0x1c000
	v_add_u32_e32 v148, s13, v201
	v_add_u32_e32 v190, s29, v201
	ds_read_b128 v[136:139], v148
	ds_read_b128 v[140:143], v148 offset:1024
	ds_read_b128 v[144:147], v148 offset:2048
	ds_read_b128 v[148:151], v148 offset:3072
	ds_read_b128 v[152:155], v190
	ds_read_b128 v[182:185], v190 offset:1024
	ds_read_b128 v[186:189], v190 offset:2048
	ds_read_b128 v[190:193], v190 offset:3072
	v_lshl_add_u64 v[198:199], v[198:199], 0, s[14:15]
	s_mov_b32 m0, s35
	v_lshl_add_u64 v[246:247], v[198:199], 0, v[164:165]
	ds_read_b128 v[194:197], v203 offset:32768
	ds_read_b128 v[206:209], v203 offset:33792
	ds_read_b128 v[210:213], v203 offset:34816
	ds_read_b128 v[216:219], v203 offset:35840
	ds_read_b128 v[220:223], v203 offset:36864
	ds_read_b128 v[224:227], v203 offset:37888
	ds_read_b128 v[228:231], v203 offset:38912
	ds_read_b128 v[232:235], v203 offset:39936
	global_load_lds_dwordx4 v[246:247], off
	s_mov_b32 m0, s36
	v_lshl_add_u64 v[198:199], v[198:199], 0, v[168:169]
	global_load_lds_dwordx4 v[198:199], off
	s_waitcnt vmcnt(8)
	s_waitcnt lgkmcnt(0)
	s_setprio 1
	s_barrier
	v_mfma_f32_16x16x32_bf16 v[124:127], v[136:139], v[194:197], v[124:127]
	v_mfma_f32_16x16x32_bf16 v[128:131], v[144:147], v[194:197], v[128:131]
	v_mfma_f32_16x16x32_bf16 v[112:115], v[136:139], v[210:213], v[112:115]
	v_mfma_f32_16x16x32_bf16 v[108:111], v[144:147], v[210:213], v[108:111]
	v_mfma_f32_16x16x32_bf16 v[96:99], v[136:139], v[220:223], v[96:99]
	v_mfma_f32_16x16x32_bf16 v[92:95], v[144:147], v[220:223], v[92:95]
	v_mfma_f32_16x16x32_bf16 v[80:83], v[136:139], v[228:231], v[80:83]
	v_mfma_f32_16x16x32_bf16 v[76:79], v[144:147], v[228:231], v[76:79]
	v_mfma_f32_16x16x32_bf16 v[124:127], v[140:143], v[206:209], v[124:127]
	v_mfma_f32_16x16x32_bf16 v[128:131], v[148:151], v[206:209], v[128:131]
	v_mfma_f32_16x16x32_bf16 v[112:115], v[140:143], v[216:219], v[112:115]
	v_mfma_f32_16x16x32_bf16 v[108:111], v[148:151], v[216:219], v[108:111]
	v_mfma_f32_16x16x32_bf16 v[96:99], v[140:143], v[224:227], v[96:99]
	v_mfma_f32_16x16x32_bf16 v[92:95], v[148:151], v[224:227], v[92:95]
	v_mfma_f32_16x16x32_bf16 v[80:83], v[140:143], v[232:235], v[80:83]
	v_mfma_f32_16x16x32_bf16 v[76:79], v[148:151], v[232:235], v[76:79]
	v_mfma_f32_16x16x32_bf16 v[120:123], v[152:155], v[194:197], v[120:123]
	v_mfma_f32_16x16x32_bf16 v[116:119], v[186:189], v[194:197], v[116:119]
	v_mfma_f32_16x16x32_bf16 v[104:107], v[152:155], v[210:213], v[104:107]
	v_mfma_f32_16x16x32_bf16 v[100:103], v[186:189], v[210:213], v[100:103]
	v_mfma_f32_16x16x32_bf16 v[88:91], v[152:155], v[220:223], v[88:91]
	v_mfma_f32_16x16x32_bf16 v[84:87], v[186:189], v[220:223], v[84:87]
	v_mfma_f32_16x16x32_bf16 v[72:75], v[152:155], v[228:231], v[72:75]
	v_mfma_f32_16x16x32_bf16 v[68:71], v[186:189], v[228:231], v[68:71]
	v_mfma_f32_16x16x32_bf16 v[120:123], v[182:185], v[206:209], v[120:123]
	v_mfma_f32_16x16x32_bf16 v[116:119], v[190:193], v[206:209], v[116:119]
	v_mfma_f32_16x16x32_bf16 v[104:107], v[182:185], v[216:219], v[104:107]
	v_mfma_f32_16x16x32_bf16 v[100:103], v[190:193], v[216:219], v[100:103]
	v_mfma_f32_16x16x32_bf16 v[88:91], v[182:185], v[224:227], v[88:91]
	v_mfma_f32_16x16x32_bf16 v[84:87], v[190:193], v[224:227], v[84:87]
	v_mfma_f32_16x16x32_bf16 v[72:75], v[182:185], v[232:235], v[72:75]
	v_mfma_f32_16x16x32_bf16 v[68:71], v[190:193], v[232:235], v[68:71]
	s_setprio 0
	s_barrier
; #define PG8_STAGE(bufoff, gbase, voff) do { _Pragma("unroll") for (int _i = 0; _i < 2; ++_i) \
;         __builtin_amdgcn_global_load_lds((const unsigned*)((const char*)(gbase) + (voff)[_i]), (PG8_LAS unsigned*)(lds + (bufoff) + ldsw + _i * 8192), 16, 0, 0); } while (0)
; #define PG8_LDA(dst, b, h) do { _Pragma("unroll") for (int m = 0; m < 4; ++m) _Pragma("unroll") for (int k = 0; k < 2; ++k) dst[m][k] = *(const PG8_LAS bf16x8*)(lds + PG8_SA(b, h) + aoff + m * 2048 + k * 1024); } while (0)
; #define PG8_MMA(ai, bj, At, Bt) do { __builtin_amdgcn_s_setprio(1); _Pragma("unroll") for (int m = 0; m < 4; ++m) _Pragma("unroll") for (int n = 0; n < 2; ++n) _Pragma("unroll") for (int k = 0; k < 2; ++k) \
;         acc[ai][bj][m][n] = __builtin_amdgcn_mfma_f32_16x16x32_bf16(Bt[n][k], At[m][k], acc[ai][bj][m][n], 0, 0, 0); __builtin_amdgcn_s_setprio(0); } while (0)
; #define PG8_WAIT_V(n) asm volatile("s_waitcnt vmcnt(" #n ")" ::: "memory")
; #define PG8_WAIT_L(n) asm volatile("s_waitcnt lgkmcnt(" #n ")" ::: "memory")
; #define PG8_BAR __builtin_amdgcn_s_barrier()
; #define PG8_SCHED __builtin_amdgcn_sched_barrier(0)
; template <class Epi, class Sched, bool ALIGN_EPI = false, bool SP2 = false>
; __device__ __forceinline__ void gemm_phase(PG8_LAS unsigned char* lds, const Gemm g, const Sched& S, const Epi& E) {
;     ...
;         for (int t = 0; t < nt; t += 2) {
;     ...
;             PG8_LDA(At, 1, 1); PG8_STAGE(PG8_SB(1, 0), b3, voffB); PG8_STAGE(PG8_SB(1, 1), b3 + hstep, voffB); PG8_STAGE(PG8_SA(1, 0), a3, voffA);
;             PG8_WAIT_V(8); PG8_WAIT_L(0); PG8_BAR; PG8_MMA(1, 0, At, B0); PG8_MMA(1, 1, At, B1); PG8_BAR; PG8_SCHED;
	s_add_i32 s13, s13, s30
	v_lshl_add_u64 v[198:199], v[236:237], 0, s[22:23]
	s_mov_b32 m0, s13
	ds_read_b128 v[194:197], v203 offset:49152
	ds_read_b128 v[206:209], v203 offset:50176
	ds_read_b128 v[210:213], v203 offset:51200
	ds_read_b128 v[216:219], v203 offset:52224
	ds_read_b128 v[220:223], v203 offset:53248
	ds_read_b128 v[224:227], v203 offset:54272
	ds_read_b128 v[228:231], v203 offset:55296
	ds_read_b128 v[232:235], v203 offset:56320
	global_load_lds_dwordx4 v[198:199], off
	v_lshl_add_u64 v[198:199], v[238:239], 0, s[22:23]
	s_add_i32 m0, s13, 0x2000
	s_add_i32 s13, s29, s30
	global_load_lds_dwordx4 v[198:199], off
	s_mov_b32 m0, s13
	v_lshl_add_u64 v[198:199], v[240:241], 0, s[22:23]
	global_load_lds_dwordx4 v[198:199], off
	s_add_i32 m0, s13, 0x2000
	v_lshl_add_u64 v[198:199], v[214:215], 0, s[22:23]
	global_load_lds_dwordx4 v[198:199], off
	s_mov_b32 m0, s37
	v_lshl_add_u64 v[198:199], v[242:243], 0, s[22:23]
	global_load_lds_dwordx4 v[198:199], off
	s_mov_b32 m0, s41
	v_lshl_add_u64 v[198:199], v[244:245], 0, s[22:23]
	global_load_lds_dwordx4 v[198:199], off
	s_waitcnt vmcnt(8)
	s_waitcnt lgkmcnt(0)
	s_setprio 1
	s_barrier
	v_mfma_f32_16x16x32_bf16 v[64:67], v[136:139], v[194:197], v[64:67]
	v_mfma_f32_16x16x32_bf16 v[60:63], v[144:147], v[194:197], v[60:63]
	v_mfma_f32_16x16x32_bf16 v[48:51], v[136:139], v[210:213], v[48:51]
	v_mfma_f32_16x16x32_bf16 v[44:47], v[144:147], v[210:213], v[44:47]
	v_mfma_f32_16x16x32_bf16 v[32:35], v[136:139], v[220:223], v[32:35]
	v_mfma_f32_16x16x32_bf16 v[28:31], v[144:147], v[220:223], v[28:31]
	v_mfma_f32_16x16x32_bf16 v[16:19], v[136:139], v[228:231], v[16:19]
	v_mfma_f32_16x16x32_bf16 v[12:15], v[144:147], v[228:231], v[12:15]
	v_mfma_f32_16x16x32_bf16 v[64:67], v[140:143], v[206:209], v[64:67]
	v_mfma_f32_16x16x32_bf16 v[60:63], v[148:151], v[206:209], v[60:63]
	v_mfma_f32_16x16x32_bf16 v[48:51], v[140:143], v[216:219], v[48:51]
	v_mfma_f32_16x16x32_bf16 v[44:47], v[148:151], v[216:219], v[44:47]
	v_mfma_f32_16x16x32_bf16 v[32:35], v[140:143], v[224:227], v[32:35]
	v_mfma_f32_16x16x32_bf16 v[28:31], v[148:151], v[224:227], v[28:31]
	v_mfma_f32_16x16x32_bf16 v[16:19], v[140:143], v[232:235], v[16:19]
	v_mfma_f32_16x16x32_bf16 v[12:15], v[148:151], v[232:235], v[12:15]
	v_mfma_f32_16x16x32_bf16 v[56:59], v[152:155], v[194:197], v[56:59]
	v_mfma_f32_16x16x32_bf16 v[52:55], v[186:189], v[194:197], v[52:55]
	v_mfma_f32_16x16x32_bf16 v[40:43], v[152:155], v[210:213], v[40:43]
	v_mfma_f32_16x16x32_bf16 v[36:39], v[186:189], v[210:213], v[36:39]
	v_mfma_f32_16x16x32_bf16 v[24:27], v[152:155], v[220:223], v[24:27]
	v_mfma_f32_16x16x32_bf16 v[20:23], v[186:189], v[220:223], v[20:23]
	v_mfma_f32_16x16x32_bf16 v[8:11], v[152:155], v[228:231], v[8:11]
	v_mfma_f32_16x16x32_bf16 v[4:7], v[186:189], v[228:231], v[4:7]
	v_mfma_f32_16x16x32_bf16 v[56:59], v[182:185], v[206:209], v[56:59]
	v_mfma_f32_16x16x32_bf16 v[52:55], v[190:193], v[206:209], v[52:55]
	v_mfma_f32_16x16x32_bf16 v[40:43], v[182:185], v[216:219], v[40:43]
	v_mfma_f32_16x16x32_bf16 v[36:39], v[190:193], v[216:219], v[36:39]
	v_mfma_f32_16x16x32_bf16 v[24:27], v[182:185], v[224:227], v[24:27]
	v_mfma_f32_16x16x32_bf16 v[20:23], v[190:193], v[224:227], v[20:23]
	v_mfma_f32_16x16x32_bf16 v[8:11], v[182:185], v[232:235], v[8:11]
	v_mfma_f32_16x16x32_bf16 v[4:7], v[190:193], v[232:235], v[4:7]
	s_setprio 0
	s_barrier
	v_lshl_add_u64 v[132:133], v[132:133], 0, s[26:27]
	s_cmp_ge_i32 s12, s47
	v_lshl_add_u64 v[134:135], v[134:135], 0, s[26:27]
	s_cbranch_scc0 .LBB0_371

; #define PG8_STAGE(bufoff, gbase, voff) do { _Pragma("unroll") for (int _i = 0; _i < 2; ++_i) \
;         __builtin_amdgcn_global_load_lds((const unsigned*)((const char*)(gbase) + (voff)[_i]), (PG8_LAS unsigned*)(lds + (bufoff) + ldsw + _i * 8192), 16, 0, 0); } while (0)
; #define PG8_LDA(dst, b, h) do { _Pragma("unroll") for (int m = 0; m < 4; ++m) _Pragma("unroll") for (int k = 0; k < 2; ++k) dst[m][k] = *(const PG8_LAS bf16x8*)(lds + PG8_SA(b, h) + aoff + m * 2048 + k * 1024); } while (0)
; #define PG8_LDB(dst, b, h) do { _Pragma("unroll") for (int n = 0; n < 2; ++n) _Pragma("unroll") for (int k = 0; k < 2; ++k) dst[n][k] = *(const PG8_LAS bf16x8*)(lds + PG8_SB(b, h) + boff + n * 2048 + k * 1024); } while (0)
; #define PG8_MMA(ai, bj, At, Bt) do { __builtin_amdgcn_s_setprio(1); _Pragma("unroll") for (int m = 0; m < 4; ++m) _Pragma("unroll") for (int n = 0; n < 2; ++n) _Pragma("unroll") for (int k = 0; k < 2; ++k) \
;         acc[ai][bj][m][n] = __builtin_amdgcn_mfma_f32_16x16x32_bf16(Bt[n][k], At[m][k], acc[ai][bj][m][n], 0, 0, 0); __builtin_amdgcn_s_setprio(0); } while (0)
; #define PG8_WAIT_V(n) asm volatile("s_waitcnt vmcnt(" #n ")" ::: "memory")
; #define PG8_WAIT_L(n) asm volatile("s_waitcnt lgkmcnt(" #n ")" ::: "memory")
; #define PG8_BAR __builtin_amdgcn_s_barrier()
; #define PG8_SCHED __builtin_amdgcn_sched_barrier(0)
; template <class Epi, class Sched, bool ALIGN_EPI = false, bool SP2 = false>
; __device__ __forceinline__ void gemm_phase(PG8_LAS unsigned char* lds, const Gemm g, const Sched& S, const Epi& E) {
;     ...
;             PG8_LDB(B0, 0, 0); PG8_LDB(B1, 0, 1); PG8_SCHED; PG8_LDA(At, 0, 0); PG8_STAGE(PG8_SA(1, 1), a1 + hstep, voffA);
;             PG8_WAIT_V(8); PG8_WAIT_L(0); PG8_BAR; PG8_MMA(0, 0, At, B0); PG8_MMA(0, 1, At, B1); PG8_BAR; PG8_SCHED;
.LBB0_454:
	v_add_u32_e32 v165, s69, v171
	v_add_u32_e32 v167, s70, v171
	ds_read_b128 v[132:135], v165
	ds_read_b128 v[136:139], v165 offset:1024
	ds_read_b128 v[176:179], v165 offset:2048
	ds_read_b128 v[180:183], v165 offset:3072
	ds_read_b128 v[184:187], v167
	ds_read_b128 v[188:191], v167 offset:1024
	ds_read_b128 v[192:195], v167 offset:2048
	ds_read_b128 v[196:199], v167 offset:3072
	s_cmp_eq_u32 s62, s12
	v_lshl_add_u64 v[200:201], v[130:131], 0, s[24:25]
	s_cselect_b64 vcc, -1, 0
	s_add_i32 s12, s12, 2
	v_cndmask_b32_e32 v209, v201, v173, vcc
	v_cndmask_b32_e32 v208, v200, v172, vcc
	v_cndmask_b32_e32 v213, v129, v175, vcc
	v_cndmask_b32_e32 v212, v128, v174, vcc
	v_lshl_add_u64 v[214:215], v[130:131], 0, v[160:161]
	s_add_i32 m0, s41, 0xc000
	ds_read_b128 v[200:203], v216
	ds_read_b128 v[204:207], v216 offset:1024
	ds_read_b128 v[218:221], v216 offset:2048
	ds_read_b128 v[222:225], v216 offset:3072
	ds_read_b128 v[226:229], v216 offset:4096
	ds_read_b128 v[230:233], v216 offset:5120
	ds_read_b128 v[234:237], v216 offset:6144
	ds_read_b128 v[238:241], v216 offset:7168
	global_load_lds_dwordx4 v[214:215], off
	s_add_i32 m0, s41, 0xe000
	v_lshl_add_u64 v[214:215], v[130:131], 0, v[158:159]
	global_load_lds_dwordx4 v[214:215], off
	s_waitcnt vmcnt(8)
	s_waitcnt lgkmcnt(0)
	s_setprio 1
	s_barrier
	v_mfma_f32_16x16x32_bf16 v[124:127], v[132:135], v[200:203], v[124:127]
	v_mfma_f32_16x16x32_bf16 v[120:123], v[176:179], v[200:203], v[120:123]
	v_mfma_f32_16x16x32_bf16 v[108:111], v[132:135], v[218:221], v[108:111]
	v_mfma_f32_16x16x32_bf16 v[104:107], v[176:179], v[218:221], v[104:107]
	v_mfma_f32_16x16x32_bf16 v[92:95], v[132:135], v[226:229], v[92:95]
	v_mfma_f32_16x16x32_bf16 v[88:91], v[176:179], v[226:229], v[88:91]
	v_mfma_f32_16x16x32_bf16 v[76:79], v[132:135], v[234:237], v[76:79]
	v_mfma_f32_16x16x32_bf16 v[72:75], v[176:179], v[234:237], v[72:75]
	v_mfma_f32_16x16x32_bf16 v[124:127], v[136:139], v[204:207], v[124:127]
	v_mfma_f32_16x16x32_bf16 v[120:123], v[180:183], v[204:207], v[120:123]
	v_mfma_f32_16x16x32_bf16 v[108:111], v[136:139], v[222:225], v[108:111]
	v_mfma_f32_16x16x32_bf16 v[104:107], v[180:183], v[222:225], v[104:107]
	v_mfma_f32_16x16x32_bf16 v[92:95], v[136:139], v[230:233], v[92:95]
	v_mfma_f32_16x16x32_bf16 v[88:91], v[180:183], v[230:233], v[88:91]
	v_mfma_f32_16x16x32_bf16 v[76:79], v[136:139], v[238:241], v[76:79]
	v_mfma_f32_16x16x32_bf16 v[72:75], v[180:183], v[238:241], v[72:75]
	s_cmp_gt_u32 s75, 3
	s_cbranch_scc1 .Lie_skipk0
	v_mfma_f32_16x16x32_bf16 v[116:119], v[184:187], v[200:203], v[116:119]
	v_mfma_f32_16x16x32_bf16 v[112:115], v[192:195], v[200:203], v[112:115]
	v_mfma_f32_16x16x32_bf16 v[100:103], v[184:187], v[218:221], v[100:103]
	v_mfma_f32_16x16x32_bf16 v[96:99], v[192:195], v[218:221], v[96:99]
	v_mfma_f32_16x16x32_bf16 v[84:87], v[184:187], v[226:229], v[84:87]
	v_mfma_f32_16x16x32_bf16 v[80:83], v[192:195], v[226:229], v[80:83]
	v_mfma_f32_16x16x32_bf16 v[68:71], v[184:187], v[234:237], v[68:71]
	v_mfma_f32_16x16x32_bf16 v[64:67], v[192:195], v[234:237], v[64:67]
	v_mfma_f32_16x16x32_bf16 v[116:119], v[188:191], v[204:207], v[116:119]
	v_mfma_f32_16x16x32_bf16 v[112:115], v[196:199], v[204:207], v[112:115]
	v_mfma_f32_16x16x32_bf16 v[100:103], v[188:191], v[222:225], v[100:103]
	v_mfma_f32_16x16x32_bf16 v[96:99], v[196:199], v[222:225], v[96:99]
	v_mfma_f32_16x16x32_bf16 v[84:87], v[188:191], v[230:233], v[84:87]
	v_mfma_f32_16x16x32_bf16 v[80:83], v[196:199], v[230:233], v[80:83]
	v_mfma_f32_16x16x32_bf16 v[68:71], v[188:191], v[238:241], v[68:71]
	v_mfma_f32_16x16x32_bf16 v[64:67], v[196:199], v[238:241], v[64:67]

; #define PG8_STAGE(bufoff, gbase, voff) do { _Pragma("unroll") for (int _i = 0; _i < 2; ++_i) \
;         __builtin_amdgcn_global_load_lds((const unsigned*)((const char*)(gbase) + (voff)[_i]), (PG8_LAS unsigned*)(lds + (bufoff) + ldsw + _i * 8192), 16, 0, 0); } while (0)
; #define PG8_LDA(dst, b, h) do { _Pragma("unroll") for (int m = 0; m < 4; ++m) _Pragma("unroll") for (int k = 0; k < 2; ++k) dst[m][k] = *(const PG8_LAS bf16x8*)(lds + PG8_SA(b, h) + aoff + m * 2048 + k * 1024); } while (0)
; #define PG8_LDB(dst, b, h) do { _Pragma("unroll") for (int n = 0; n < 2; ++n) _Pragma("unroll") for (int k = 0; k < 2; ++k) dst[n][k] = *(const PG8_LAS bf16x8*)(lds + PG8_SB(b, h) + boff + n * 2048 + k * 1024); } while (0)
; #define PG8_MMA(ai, bj, At, Bt) do { __builtin_amdgcn_s_setprio(1); _Pragma("unroll") for (int m = 0; m < 4; ++m) _Pragma("unroll") for (int n = 0; n < 2; ++n) _Pragma("unroll") for (int k = 0; k < 2; ++k) \
;         acc[ai][bj][m][n] = __builtin_amdgcn_mfma_f32_16x16x32_bf16(Bt[n][k], At[m][k], acc[ai][bj][m][n], 0, 0, 0); __builtin_amdgcn_s_setprio(0); } while (0)
; #define PG8_WAIT_V(n) asm volatile("s_waitcnt vmcnt(" #n ")" ::: "memory")
; #define PG8_WAIT_L(n) asm volatile("s_waitcnt lgkmcnt(" #n ")" ::: "memory")
; #define PG8_BAR __builtin_amdgcn_s_barrier()
; #define PG8_SCHED __builtin_amdgcn_sched_barrier(0)
; template <class Epi, class Sched, bool ALIGN_EPI = false, bool SP2 = false>
; __device__ __forceinline__ void gemm_phase(PG8_LAS unsigned char* lds, const Gemm g, const Sched& S, const Epi& E) {
;     ...
;         for (int t = 0; t < nt; t += 2) {
;     ...
;             PG8_WAIT_V(8); PG8_WAIT_L(0); PG8_BAR; PG8_MMA(1, 0, At, B0); PG8_MMA(1, 1, At, B1); PG8_BAR; PG8_SCHED;
;             PG8_LDB(B0, 1, 0); PG8_LDB(B1, 1, 1); PG8_SCHED; PG8_LDA(At, 1, 0); PG8_STAGE(PG8_SA(0, 1), a2 + hstep, voffA);
;             PG8_WAIT_V(8); PG8_WAIT_L(0); PG8_BAR; PG8_MMA(0, 0, At, B0); PG8_MMA(0, 1, At, B1); PG8_BAR; PG8_SCHED;
;             PG8_LDA(At, 1, 1); PG8_STAGE(PG8_SB(1, 0), b3, voffB); PG8_STAGE(PG8_SB(1, 1), b3 + hstep, voffB); PG8_STAGE(PG8_SA(1, 0), a3, voffA);
;             PG8_WAIT_V(8); PG8_WAIT_L(0); PG8_BAR; PG8_MMA(1, 0, At, B0); PG8_MMA(1, 1, At, B1); PG8_BAR; PG8_SCHED;
.Lie_skipk1:
	s_setprio 0
	s_barrier
	s_add_i32 s13, 0, 0x18000
	v_add_u32_e32 v165, s13, v171
	s_add_i32 s15, 0, 0x1c000
	ds_read_b128 v[132:135], v165
	ds_read_b128 v[136:139], v165 offset:1024
	ds_read_b128 v[176:179], v165 offset:2048
	ds_read_b128 v[180:183], v165 offset:3072
	v_add_u32_e32 v165, s15, v171
	ds_read_b128 v[184:187], v165
	ds_read_b128 v[188:191], v165 offset:1024
	ds_read_b128 v[192:195], v165 offset:2048
	ds_read_b128 v[196:199], v165 offset:3072
	v_lshl_add_u64 v[208:209], v[208:209], 0, s[16:17]
	s_mov_b32 m0, s52
	v_lshl_add_u64 v[250:251], v[208:209], 0, v[144:145]
	ds_read_b128 v[200:203], v216 offset:32768
	ds_read_b128 v[204:207], v216 offset:33792
	ds_read_b128 v[218:221], v216 offset:34816
	ds_read_b128 v[222:225], v216 offset:35840
	ds_read_b128 v[226:229], v216 offset:36864
	ds_read_b128 v[230:233], v216 offset:37888
	ds_read_b128 v[234:237], v216 offset:38912
	ds_read_b128 v[238:241], v216 offset:39936
	global_load_lds_dwordx4 v[250:251], off
	s_mov_b32 m0, s53
	v_lshl_add_u64 v[208:209], v[208:209], 0, v[148:149]
	global_load_lds_dwordx4 v[208:209], off
	s_waitcnt vmcnt(8)
	s_waitcnt lgkmcnt(0)
	s_setprio 1
	s_barrier
	v_mfma_f32_16x16x32_bf16 v[124:127], v[132:135], v[200:203], v[124:127]
	v_mfma_f32_16x16x32_bf16 v[120:123], v[176:179], v[200:203], v[120:123]
	v_mfma_f32_16x16x32_bf16 v[108:111], v[132:135], v[218:221], v[108:111]
	v_mfma_f32_16x16x32_bf16 v[104:107], v[176:179], v[218:221], v[104:107]
	v_mfma_f32_16x16x32_bf16 v[92:95], v[132:135], v[226:229], v[92:95]
	v_mfma_f32_16x16x32_bf16 v[88:91], v[176:179], v[226:229], v[88:91]
	v_mfma_f32_16x16x32_bf16 v[76:79], v[132:135], v[234:237], v[76:79]
	v_mfma_f32_16x16x32_bf16 v[72:75], v[176:179], v[234:237], v[72:75]
	v_mfma_f32_16x16x32_bf16 v[124:127], v[136:139], v[204:207], v[124:127]
	v_mfma_f32_16x16x32_bf16 v[120:123], v[180:183], v[204:207], v[120:123]
	v_mfma_f32_16x16x32_bf16 v[108:111], v[136:139], v[222:225], v[108:111]
	v_mfma_f32_16x16x32_bf16 v[104:107], v[180:183], v[222:225], v[104:107]
	v_mfma_f32_16x16x32_bf16 v[92:95], v[136:139], v[230:233], v[92:95]
	v_mfma_f32_16x16x32_bf16 v[88:91], v[180:183], v[230:233], v[88:91]
	v_mfma_f32_16x16x32_bf16 v[76:79], v[136:139], v[238:241], v[76:79]
	v_mfma_f32_16x16x32_bf16 v[72:75], v[180:183], v[238:241], v[72:75]
	s_cmp_gt_u32 s75, 3
	s_cbranch_scc1 .Lie_skipk2
	v_mfma_f32_16x16x32_bf16 v[116:119], v[184:187], v[200:203], v[116:119]
	v_mfma_f32_16x16x32_bf16 v[112:115], v[192:195], v[200:203], v[112:115]
	v_mfma_f32_16x16x32_bf16 v[100:103], v[184:187], v[218:221], v[100:103]
	v_mfma_f32_16x16x32_bf16 v[96:99], v[192:195], v[218:221], v[96:99]
	v_mfma_f32_16x16x32_bf16 v[84:87], v[184:187], v[226:229], v[84:87]
	v_mfma_f32_16x16x32_bf16 v[80:83], v[192:195], v[226:229], v[80:83]
	v_mfma_f32_16x16x32_bf16 v[68:71], v[184:187], v[234:237], v[68:71]
	v_mfma_f32_16x16x32_bf16 v[64:67], v[192:195], v[234:237], v[64:67]
	v_mfma_f32_16x16x32_bf16 v[116:119], v[188:191], v[204:207], v[116:119]
	v_mfma_f32_16x16x32_bf16 v[112:115], v[196:199], v[204:207], v[112:115]
	v_mfma_f32_16x16x32_bf16 v[100:103], v[188:191], v[222:225], v[100:103]
	v_mfma_f32_16x16x32_bf16 v[96:99], v[196:199], v[222:225], v[96:99]
	v_mfma_f32_16x16x32_bf16 v[84:87], v[188:191], v[230:233], v[84:87]
	v_mfma_f32_16x16x32_bf16 v[80:83], v[196:199], v[230:233], v[80:83]
	v_mfma_f32_16x16x32_bf16 v[68:71], v[188:191], v[238:241], v[68:71]
	v_mfma_f32_16x16x32_bf16 v[64:67], v[196:199], v[238:241], v[64:67]
.Lie_skipk2:
	s_setprio 0
	s_barrier
	s_add_i32 s13, s13, s37
	v_lshl_add_u64 v[208:209], v[214:215], 0, s[24:25]
	s_mov_b32 m0, s13
	ds_read_b128 v[200:203], v216 offset:49152
	ds_read_b128 v[204:207], v216 offset:50176
	ds_read_b128 v[218:221], v216 offset:51200
	ds_read_b128 v[222:225], v216 offset:52224
	ds_read_b128 v[226:229], v216 offset:53248
	ds_read_b128 v[230:233], v216 offset:54272
	ds_read_b128 v[234:237], v216 offset:55296
	ds_read_b128 v[238:241], v216 offset:56320
	global_load_lds_dwordx4 v[208:209], off
	v_lshl_add_u64 v[208:209], v[242:243], 0, s[24:25]
	s_add_i32 m0, s13, 0x2000
	s_add_i32 s13, s15, s37
	global_load_lds_dwordx4 v[208:209], off
	s_mov_b32 m0, s13
	v_lshl_add_u64 v[208:209], v[244:245], 0, s[24:25]
	global_load_lds_dwordx4 v[208:209], off
	s_add_i32 m0, s13, 0x2000
	v_lshl_add_u64 v[208:209], v[212:213], 0, s[24:25]
	global_load_lds_dwordx4 v[208:209], off
	s_mov_b32 m0, s56
	v_lshl_add_u64 v[208:209], v[246:247], 0, s[24:25]
	global_load_lds_dwordx4 v[208:209], off
	s_mov_b32 m0, s57
	v_lshl_add_u64 v[208:209], v[248:249], 0, s[24:25]
	global_load_lds_dwordx4 v[208:209], off
	s_waitcnt vmcnt(8)
	s_waitcnt lgkmcnt(0)
	s_setprio 1
	s_barrier
	v_mfma_f32_16x16x32_bf16 v[60:63], v[132:135], v[200:203], v[60:63]
	v_mfma_f32_16x16x32_bf16 v[56:59], v[176:179], v[200:203], v[56:59]
	v_mfma_f32_16x16x32_bf16 v[44:47], v[132:135], v[218:221], v[44:47]
	v_mfma_f32_16x16x32_bf16 v[40:43], v[176:179], v[218:221], v[40:43]
	v_mfma_f32_16x16x32_bf16 v[28:31], v[132:135], v[226:229], v[28:31]
	v_mfma_f32_16x16x32_bf16 v[24:27], v[176:179], v[226:229], v[24:27]
	v_mfma_f32_16x16x32_bf16 v[12:15], v[132:135], v[234:237], v[12:15]
	v_mfma_f32_16x16x32_bf16 v[8:11], v[176:179], v[234:237], v[8:11]
	v_mfma_f32_16x16x32_bf16 v[60:63], v[136:139], v[204:207], v[60:63]
	v_mfma_f32_16x16x32_bf16 v[56:59], v[180:183], v[204:207], v[56:59]
	v_mfma_f32_16x16x32_bf16 v[44:47], v[136:139], v[222:225], v[44:47]
	v_mfma_f32_16x16x32_bf16 v[40:43], v[180:183], v[222:225], v[40:43]
	v_mfma_f32_16x16x32_bf16 v[28:31], v[136:139], v[230:233], v[28:31]
	v_mfma_f32_16x16x32_bf16 v[24:27], v[180:183], v[230:233], v[24:27]
	v_mfma_f32_16x16x32_bf16 v[12:15], v[136:139], v[238:241], v[12:15]
	v_mfma_f32_16x16x32_bf16 v[8:11], v[180:183], v[238:241], v[8:11]
	s_cmp_gt_u32 s75, 3
	s_cbranch_scc1 .Lie_skipk3
	v_mfma_f32_16x16x32_bf16 v[52:55], v[184:187], v[200:203], v[52:55]
	v_mfma_f32_16x16x32_bf16 v[48:51], v[192:195], v[200:203], v[48:51]
	v_mfma_f32_16x16x32_bf16 v[36:39], v[184:187], v[218:221], v[36:39]
	v_mfma_f32_16x16x32_bf16 v[32:35], v[192:195], v[218:221], v[32:35]
	v_mfma_f32_16x16x32_bf16 v[20:23], v[184:187], v[226:229], v[20:23]
	v_mfma_f32_16x16x32_bf16 v[16:19], v[192:195], v[226:229], v[16:19]
	v_mfma_f32_16x16x32_bf16 v[4:7], v[184:187], v[234:237], v[4:7]
	v_mfma_f32_16x16x32_bf16 v[0:3], v[192:195], v[234:237], v[0:3]
	v_mfma_f32_16x16x32_bf16 v[52:55], v[188:191], v[204:207], v[52:55]
	v_mfma_f32_16x16x32_bf16 v[48:51], v[196:199], v[204:207], v[48:51]
	v_mfma_f32_16x16x32_bf16 v[36:39], v[188:191], v[222:225], v[36:39]
	v_mfma_f32_16x16x32_bf16 v[32:35], v[196:199], v[222:225], v[32:35]
	v_mfma_f32_16x16x32_bf16 v[20:23], v[188:191], v[230:233], v[20:23]
	v_mfma_f32_16x16x32_bf16 v[16:19], v[196:199], v[230:233], v[16:19]
	v_mfma_f32_16x16x32_bf16 v[4:7], v[188:191], v[238:241], v[4:7]
	v_mfma_f32_16x16x32_bf16 v[0:3], v[196:199], v[238:241], v[0:3]

; #define PG8_STAGE(bufoff, gbase, voff) do { _Pragma("unroll") for (int _i = 0; _i < 2; ++_i) \
;         __builtin_amdgcn_global_load_lds((const unsigned*)((const char*)(gbase) + (voff)[_i]), (PG8_LAS unsigned*)(lds + (bufoff) + ldsw + _i * 8192), 16, 0, 0); } while (0)
; #define PG8_LDA(dst, b, h) do { _Pragma("unroll") for (int m = 0; m < 4; ++m) _Pragma("unroll") for (int k = 0; k < 2; ++k) dst[m][k] = *(const PG8_LAS bf16x8*)(lds + PG8_SA(b, h) + aoff + m * 2048 + k * 1024); } while (0)
; #define PG8_LDB(dst, b, h) do { _Pragma("unroll") for (int n = 0; n < 2; ++n) _Pragma("unroll") for (int k = 0; k < 2; ++k) dst[n][k] = *(const PG8_LAS bf16x8*)(lds + PG8_SB(b, h) + boff + n * 2048 + k * 1024); } while (0)
; #define PG8_MMA(ai, bj, At, Bt) do { __builtin_amdgcn_s_setprio(1); _Pragma("unroll") for (int m = 0; m < 4; ++m) _Pragma("unroll") for (int n = 0; n < 2; ++n) _Pragma("unroll") for (int k = 0; k < 2; ++k) \
;         acc[ai][bj][m][n] = __builtin_amdgcn_mfma_f32_16x16x32_bf16(Bt[n][k], At[m][k], acc[ai][bj][m][n], 0, 0, 0); __builtin_amdgcn_s_setprio(0); } while (0)
; #define PG8_WAIT_V(n) asm volatile("s_waitcnt vmcnt(" #n ")" ::: "memory")
; #define PG8_WAIT_L(n) asm volatile("s_waitcnt lgkmcnt(" #n ")" ::: "memory")
; #define PG8_BAR __builtin_amdgcn_s_barrier()
; #define PG8_SCHED __builtin_amdgcn_sched_barrier(0)
; template <class Epi, class Sched, bool ALIGN_EPI = false, bool SP2 = false>
; __device__ __forceinline__ void gemm_phase(PG8_LAS unsigned char* lds, const Gemm g, const Sched& S, const Epi& E) {
;     ...
;             PG8_LDB(B0, 0, 0); PG8_LDB(B1, 0, 1); PG8_SCHED; PG8_LDA(At, 0, 0); PG8_STAGE(PG8_SA(1, 1), a1 + hstep, voffA);
;             PG8_WAIT_V(8); PG8_WAIT_L(0); PG8_BAR; PG8_MMA(0, 0, At, B0); PG8_MMA(0, 1, At, B1); PG8_BAR; PG8_SCHED;
;             PG8_LDA(At, 0, 1); PG8_STAGE(PG8_SB(0, 0), b2, voffB); PG8_STAGE(PG8_SB(0, 1), b2 + hstep, voffB); PG8_STAGE(PG8_SA(0, 0), a2, voffA);
.LBB0_635:
	v_add_u32_e32 v144, s64, v209
	v_add_u32_e32 v194, s65, v209
	ds_read_b128 v[92:95], v144
	ds_read_b128 v[128:131], v144 offset:1024
	ds_read_b128 v[132:135], v144 offset:2048
	ds_read_b128 v[144:147], v144 offset:3072
	ds_read_b128 v[148:151], v194
	ds_read_b128 v[152:155], v194 offset:1024
	ds_read_b128 v[190:193], v194 offset:2048
	ds_read_b128 v[194:197], v194 offset:3072
	s_cmp_eq_u32 s58, s10
	v_lshl_add_u64 v[198:199], v[90:91], 0, s[24:25]
	s_cselect_b64 vcc, -1, 0
	s_add_i32 s10, s10, 2
	v_cndmask_b32_e32 v207, v199, v187, vcc
	v_cndmask_b32_e32 v206, v198, v186, vcc
	v_cndmask_b32_e32 v215, v89, v189, vcc
	v_cndmask_b32_e32 v214, v88, v188, vcc
	v_lshl_add_u64 v[238:239], v[90:91], 0, v[180:181]
	s_add_i32 m0, s41, 0xc000
	ds_read_b128 v[198:201], v216
	ds_read_b128 v[202:205], v216 offset:1024
	ds_read_b128 v[210:213], v216 offset:2048
	ds_read_b128 v[218:221], v216 offset:3072
	ds_read_b128 v[222:225], v216 offset:4096
	ds_read_b128 v[226:229], v216 offset:5120
	ds_read_b128 v[230:233], v216 offset:6144
	ds_read_b128 v[234:237], v216 offset:7168
	global_load_lds_dwordx4 v[238:239], off
	s_add_i32 m0, s41, 0xe000
	v_lshl_add_u64 v[238:239], v[90:91], 0, v[178:179]
	global_load_lds_dwordx4 v[238:239], off
	s_waitcnt vmcnt(8)
	s_waitcnt lgkmcnt(0)
	s_setprio 1
	s_barrier
	v_mfma_f32_16x16x32_bf16 v[140:143], v[92:95], v[198:201], v[140:143]
	v_mfma_f32_16x16x32_bf16 v[136:139], v[132:135], v[198:201], v[136:139]
	v_mfma_f32_16x16x32_bf16 v[116:119], v[92:95], v[210:213], v[116:119]
	v_mfma_f32_16x16x32_bf16 v[112:115], v[132:135], v[210:213], v[112:115]
	v_mfma_f32_16x16x32_bf16 v[100:103], v[92:95], v[222:225], v[100:103]
	v_mfma_f32_16x16x32_bf16 v[96:99], v[132:135], v[222:225], v[96:99]
	v_mfma_f32_16x16x32_bf16 v[76:79], v[92:95], v[230:233], v[76:79]
	v_mfma_f32_16x16x32_bf16 v[72:75], v[132:135], v[230:233], v[72:75]
	v_mfma_f32_16x16x32_bf16 v[140:143], v[128:131], v[202:205], v[140:143]
	v_mfma_f32_16x16x32_bf16 v[136:139], v[144:147], v[202:205], v[136:139]
	v_mfma_f32_16x16x32_bf16 v[116:119], v[128:131], v[218:221], v[116:119]
	v_mfma_f32_16x16x32_bf16 v[112:115], v[144:147], v[218:221], v[112:115]
	v_mfma_f32_16x16x32_bf16 v[100:103], v[128:131], v[226:229], v[100:103]
	v_mfma_f32_16x16x32_bf16 v[96:99], v[144:147], v[226:229], v[96:99]
	v_mfma_f32_16x16x32_bf16 v[76:79], v[128:131], v[234:237], v[76:79]
	v_mfma_f32_16x16x32_bf16 v[72:75], v[144:147], v[234:237], v[72:75]
	v_mfma_f32_16x16x32_bf16 v[124:127], v[148:151], v[198:201], v[124:127]
	v_mfma_f32_16x16x32_bf16 v[120:123], v[190:193], v[198:201], v[120:123]
	v_mfma_f32_16x16x32_bf16 v[108:111], v[148:151], v[210:213], v[108:111]
	v_mfma_f32_16x16x32_bf16 v[104:107], v[190:193], v[210:213], v[104:107]
	v_mfma_f32_16x16x32_bf16 v[84:87], v[148:151], v[222:225], v[84:87]
	v_mfma_f32_16x16x32_bf16 v[80:83], v[190:193], v[222:225], v[80:83]
	v_mfma_f32_16x16x32_bf16 v[68:71], v[148:151], v[230:233], v[68:71]
	v_mfma_f32_16x16x32_bf16 v[64:67], v[190:193], v[230:233], v[64:67]
	v_mfma_f32_16x16x32_bf16 v[124:127], v[152:155], v[202:205], v[124:127]
	v_mfma_f32_16x16x32_bf16 v[120:123], v[194:197], v[202:205], v[120:123]
	v_mfma_f32_16x16x32_bf16 v[108:111], v[152:155], v[218:221], v[108:111]
	v_mfma_f32_16x16x32_bf16 v[104:107], v[194:197], v[218:221], v[104:107]
	v_mfma_f32_16x16x32_bf16 v[84:87], v[152:155], v[226:229], v[84:87]
	v_mfma_f32_16x16x32_bf16 v[80:83], v[194:197], v[226:229], v[80:83]
	v_mfma_f32_16x16x32_bf16 v[68:71], v[152:155], v[234:237], v[68:71]
	v_mfma_f32_16x16x32_bf16 v[64:67], v[194:197], v[234:237], v[64:67]
	s_setprio 0
	s_barrier
	s_add_i32 s11, s64, s35
	v_lshl_add_u64 v[238:239], v[214:215], 0, v[168:169]
	s_mov_b32 m0, s11
	ds_read_b128 v[198:201], v216 offset:16384
	ds_read_b128 v[202:205], v216 offset:17408
	ds_read_b128 v[210:213], v216 offset:18432
	ds_read_b128 v[218:221], v216 offset:19456
	ds_read_b128 v[222:225], v216 offset:20480
	ds_read_b128 v[226:229], v216 offset:21504
	ds_read_b128 v[230:233], v216 offset:22528
	ds_read_b128 v[234:237], v216 offset:23552
	global_load_lds_dwordx4 v[238:239], off
	v_lshl_add_u64 v[240:241], v[214:215], 0, v[172:173]
	s_add_i32 m0, s11, 0x2000
	v_lshl_add_u64 v[214:215], v[214:215], 0, s[18:19]
	s_add_i32 s11, s65, s35
	global_load_lds_dwordx4 v[240:241], off
	v_lshl_add_u64 v[242:243], v[214:215], 0, v[168:169]
	s_mov_b32 m0, s11
	v_lshl_add_u64 v[214:215], v[214:215], 0, v[172:173]
	global_load_lds_dwordx4 v[242:243], off
	s_add_i32 m0, s11, 0x2000
	v_lshl_add_u64 v[244:245], v[206:207], 0, v[166:167]
	global_load_lds_dwordx4 v[214:215], off
	s_mov_b32 m0, s41
	v_lshl_add_u64 v[246:247], v[206:207], 0, v[170:171]
	global_load_lds_dwordx4 v[244:245], off
	s_mov_b32 m0, s50
	s_nop 0
	global_load_lds_dwordx4 v[246:247], off
	s_waitcnt vmcnt(8)
	s_waitcnt lgkmcnt(0)
	s_setprio 1
	s_barrier
; #define PG8_STAGE(bufoff, gbase, voff) do { _Pragma("unroll") for (int _i = 0; _i < 2; ++_i) \
;         __builtin_amdgcn_global_load_lds((const unsigned*)((const char*)(gbase) + (voff)[_i]), (PG8_LAS unsigned*)(lds + (bufoff) + ldsw + _i * 8192), 16, 0, 0); } while (0)
; #define PG8_LDA(dst, b, h) do { _Pragma("unroll") for (int m = 0; m < 4; ++m) _Pragma("unroll") for (int k = 0; k < 2; ++k) dst[m][k] = *(const PG8_LAS bf16x8*)(lds + PG8_SA(b, h) + aoff + m * 2048 + k * 1024); } while (0)
; #define PG8_LDB(dst, b, h) do { _Pragma("unroll") for (int n = 0; n < 2; ++n) _Pragma("unroll") for (int k = 0; k < 2; ++k) dst[n][k] = *(const PG8_LAS bf16x8*)(lds + PG8_SB(b, h) + boff + n * 2048 + k * 1024); } while (0)
; #define PG8_MMA(ai, bj, At, Bt) do { __builtin_amdgcn_s_setprio(1); _Pragma("unroll") for (int m = 0; m < 4; ++m) _Pragma("unroll") for (int n = 0; n < 2; ++n) _Pragma("unroll") for (int k = 0; k < 2; ++k) \
;         acc[ai][bj][m][n] = __builtin_amdgcn_mfma_f32_16x16x32_bf16(Bt[n][k], At[m][k], acc[ai][bj][m][n], 0, 0, 0); __builtin_amdgcn_s_setprio(0); } while (0)
; #define PG8_WAIT_V(n) asm volatile("s_waitcnt vmcnt(" #n ")" ::: "memory")
; #define PG8_WAIT_L(n) asm volatile("s_waitcnt lgkmcnt(" #n ")" ::: "memory")
; #define PG8_BAR __builtin_amdgcn_s_barrier()
; #define PG8_SCHED __builtin_amdgcn_sched_barrier(0)
; template <class Epi, class Sched, bool ALIGN_EPI = false, bool SP2 = false>
; __device__ __forceinline__ void gemm_phase(PG8_LAS unsigned char* lds, const Gemm g, const Sched& S, const Epi& E) {
;     ...
;             PG8_WAIT_V(8); PG8_WAIT_L(0); PG8_BAR; PG8_MMA(1, 0, At, B0); PG8_MMA(1, 1, At, B1); PG8_BAR; PG8_SCHED;
;             PG8_LDB(B0, 1, 0); PG8_LDB(B1, 1, 1); PG8_SCHED; PG8_LDA(At, 1, 0); PG8_STAGE(PG8_SA(0, 1), a2 + hstep, voffA);
;             PG8_WAIT_V(8); PG8_WAIT_L(0); PG8_BAR; PG8_MMA(0, 0, At, B0); PG8_MMA(0, 1, At, B1); PG8_BAR; PG8_SCHED;
	v_mfma_f32_16x16x32_bf16 v[60:63], v[92:95], v[198:201], v[60:63]
	v_mfma_f32_16x16x32_bf16 v[56:59], v[132:135], v[198:201], v[56:59]
	v_mfma_f32_16x16x32_bf16 v[44:47], v[92:95], v[210:213], v[44:47]
	v_mfma_f32_16x16x32_bf16 v[40:43], v[132:135], v[210:213], v[40:43]
	v_mfma_f32_16x16x32_bf16 v[28:31], v[92:95], v[222:225], v[28:31]
	v_mfma_f32_16x16x32_bf16 v[24:27], v[132:135], v[222:225], v[24:27]
	v_mfma_f32_16x16x32_bf16 v[12:15], v[92:95], v[230:233], v[12:15]
	v_mfma_f32_16x16x32_bf16 v[8:11], v[132:135], v[230:233], v[8:11]
	v_mfma_f32_16x16x32_bf16 v[60:63], v[128:131], v[202:205], v[60:63]
	v_mfma_f32_16x16x32_bf16 v[56:59], v[144:147], v[202:205], v[56:59]
	v_mfma_f32_16x16x32_bf16 v[44:47], v[128:131], v[218:221], v[44:47]
	v_mfma_f32_16x16x32_bf16 v[40:43], v[144:147], v[218:221], v[40:43]
	v_mfma_f32_16x16x32_bf16 v[28:31], v[128:131], v[226:229], v[28:31]
	v_mfma_f32_16x16x32_bf16 v[24:27], v[144:147], v[226:229], v[24:27]
	v_mfma_f32_16x16x32_bf16 v[12:15], v[128:131], v[234:237], v[12:15]
	v_mfma_f32_16x16x32_bf16 v[8:11], v[144:147], v[234:237], v[8:11]
	v_mfma_f32_16x16x32_bf16 v[52:55], v[148:151], v[198:201], v[52:55]
	v_mfma_f32_16x16x32_bf16 v[48:51], v[190:193], v[198:201], v[48:51]
	v_mfma_f32_16x16x32_bf16 v[36:39], v[148:151], v[210:213], v[36:39]
	v_mfma_f32_16x16x32_bf16 v[32:35], v[190:193], v[210:213], v[32:35]
	v_mfma_f32_16x16x32_bf16 v[20:23], v[148:151], v[222:225], v[20:23]
	v_mfma_f32_16x16x32_bf16 v[16:19], v[190:193], v[222:225], v[16:19]
	v_mfma_f32_16x16x32_bf16 v[4:7], v[148:151], v[230:233], v[4:7]
	v_mfma_f32_16x16x32_bf16 v[0:3], v[190:193], v[230:233], v[0:3]
	v_mfma_f32_16x16x32_bf16 v[52:55], v[152:155], v[202:205], v[52:55]
	v_mfma_f32_16x16x32_bf16 v[48:51], v[194:197], v[202:205], v[48:51]
	v_mfma_f32_16x16x32_bf16 v[36:39], v[152:155], v[218:221], v[36:39]
	v_mfma_f32_16x16x32_bf16 v[32:35], v[194:197], v[218:221], v[32:35]
	v_mfma_f32_16x16x32_bf16 v[20:23], v[152:155], v[226:229], v[20:23]
	v_mfma_f32_16x16x32_bf16 v[16:19], v[194:197], v[226:229], v[16:19]
	v_mfma_f32_16x16x32_bf16 v[4:7], v[152:155], v[234:237], v[4:7]
	v_mfma_f32_16x16x32_bf16 v[0:3], v[194:197], v[234:237], v[0:3]
	s_setprio 0
	s_barrier
	s_add_i32 s11, 0, 0x18000
	s_add_i32 s14, 0, 0x1c000
	v_add_u32_e32 v144, s11, v209
	v_add_u32_e32 v194, s14, v209
	ds_read_b128 v[92:95], v144
	ds_read_b128 v[128:131], v144 offset:1024
	ds_read_b128 v[132:135], v144 offset:2048
	ds_read_b128 v[144:147], v144 offset:3072
	ds_read_b128 v[148:151], v194
	ds_read_b128 v[152:155], v194 offset:1024
	ds_read_b128 v[190:193], v194 offset:2048
	ds_read_b128 v[194:197], v194 offset:3072
	v_lshl_add_u64 v[206:207], v[206:207], 0, s[18:19]
	s_mov_b32 m0, s51
	v_lshl_add_u64 v[248:249], v[206:207], 0, v[166:167]
	ds_read_b128 v[198:201], v216 offset:32768
	ds_read_b128 v[202:205], v216 offset:33792
	ds_read_b128 v[210:213], v216 offset:34816
	ds_read_b128 v[218:221], v216 offset:35840
	ds_read_b128 v[222:225], v216 offset:36864
	ds_read_b128 v[226:229], v216 offset:37888
	ds_read_b128 v[230:233], v216 offset:38912
	ds_read_b128 v[234:237], v216 offset:39936
	global_load_lds_dwordx4 v[248:249], off
	s_mov_b32 m0, s52
	v_lshl_add_u64 v[206:207], v[206:207], 0, v[170:171]
	global_load_lds_dwordx4 v[206:207], off
	s_waitcnt vmcnt(8)
	s_waitcnt lgkmcnt(0)
	s_setprio 1
	s_barrier
	v_mfma_f32_16x16x32_bf16 v[140:143], v[92:95], v[198:201], v[140:143]
	v_mfma_f32_16x16x32_bf16 v[136:139], v[132:135], v[198:201], v[136:139]
	v_mfma_f32_16x16x32_bf16 v[116:119], v[92:95], v[210:213], v[116:119]
	v_mfma_f32_16x16x32_bf16 v[112:115], v[132:135], v[210:213], v[112:115]
	v_mfma_f32_16x16x32_bf16 v[100:103], v[92:95], v[222:225], v[100:103]
	v_mfma_f32_16x16x32_bf16 v[96:99], v[132:135], v[222:225], v[96:99]
	v_mfma_f32_16x16x32_bf16 v[76:79], v[92:95], v[230:233], v[76:79]
	v_mfma_f32_16x16x32_bf16 v[72:75], v[132:135], v[230:233], v[72:75]
	v_mfma_f32_16x16x32_bf16 v[140:143], v[128:131], v[202:205], v[140:143]
	v_mfma_f32_16x16x32_bf16 v[136:139], v[144:147], v[202:205], v[136:139]
	v_mfma_f32_16x16x32_bf16 v[116:119], v[128:131], v[218:221], v[116:119]
	v_mfma_f32_16x16x32_bf16 v[112:115], v[144:147], v[218:221], v[112:115]
	v_mfma_f32_16x16x32_bf16 v[100:103], v[128:131], v[226:229], v[100:103]
	v_mfma_f32_16x16x32_bf16 v[96:99], v[144:147], v[226:229], v[96:99]
	v_mfma_f32_16x16x32_bf16 v[76:79], v[128:131], v[234:237], v[76:79]
	v_mfma_f32_16x16x32_bf16 v[72:75], v[144:147], v[234:237], v[72:75]
	v_mfma_f32_16x16x32_bf16 v[124:127], v[148:151], v[198:201], v[124:127]
	v_mfma_f32_16x16x32_bf16 v[120:123], v[190:193], v[198:201], v[120:123]
	v_mfma_f32_16x16x32_bf16 v[108:111], v[148:151], v[210:213], v[108:111]
	v_mfma_f32_16x16x32_bf16 v[104:107], v[190:193], v[210:213], v[104:107]
	v_mfma_f32_16x16x32_bf16 v[84:87], v[148:151], v[222:225], v[84:87]
	v_mfma_f32_16x16x32_bf16 v[80:83], v[190:193], v[222:225], v[80:83]
	v_mfma_f32_16x16x32_bf16 v[68:71], v[148:151], v[230:233], v[68:71]
	v_mfma_f32_16x16x32_bf16 v[64:67], v[190:193], v[230:233], v[64:67]
	v_mfma_f32_16x16x32_bf16 v[124:127], v[152:155], v[202:205], v[124:127]
	v_mfma_f32_16x16x32_bf16 v[120:123], v[194:197], v[202:205], v[120:123]
	v_mfma_f32_16x16x32_bf16 v[108:111], v[152:155], v[218:221], v[108:111]
	v_mfma_f32_16x16x32_bf16 v[104:107], v[194:197], v[218:221], v[104:107]
	v_mfma_f32_16x16x32_bf16 v[84:87], v[152:155], v[226:229], v[84:87]
	v_mfma_f32_16x16x32_bf16 v[80:83], v[194:197], v[226:229], v[80:83]
	v_mfma_f32_16x16x32_bf16 v[68:71], v[152:155], v[234:237], v[68:71]
	v_mfma_f32_16x16x32_bf16 v[64:67], v[194:197], v[234:237], v[64:67]
	s_setprio 0
	s_barrier
; #define PG8_STAGE(bufoff, gbase, voff) do { _Pragma("unroll") for (int _i = 0; _i < 2; ++_i) \
;         __builtin_amdgcn_global_load_lds((const unsigned*)((const char*)(gbase) + (voff)[_i]), (PG8_LAS unsigned*)(lds + (bufoff) + ldsw + _i * 8192), 16, 0, 0); } while (0)
; #define PG8_LDA(dst, b, h) do { _Pragma("unroll") for (int m = 0; m < 4; ++m) _Pragma("unroll") for (int k = 0; k < 2; ++k) dst[m][k] = *(const PG8_LAS bf16x8*)(lds + PG8_SA(b, h) + aoff + m * 2048 + k * 1024); } while (0)
; #define PG8_MMA(ai, bj, At, Bt) do { __builtin_amdgcn_s_setprio(1); _Pragma("unroll") for (int m = 0; m < 4; ++m) _Pragma("unroll") for (int n = 0; n < 2; ++n) _Pragma("unroll") for (int k = 0; k < 2; ++k) \
;         acc[ai][bj][m][n] = __builtin_amdgcn_mfma_f32_16x16x32_bf16(Bt[n][k], At[m][k], acc[ai][bj][m][n], 0, 0, 0); __builtin_amdgcn_s_setprio(0); } while (0)
; #define PG8_WAIT_V(n) asm volatile("s_waitcnt vmcnt(" #n ")" ::: "memory")
; #define PG8_WAIT_L(n) asm volatile("s_waitcnt lgkmcnt(" #n ")" ::: "memory")
; #define PG8_BAR __builtin_amdgcn_s_barrier()
; #define PG8_SCHED __builtin_amdgcn_sched_barrier(0)
; template <class Epi, class Sched, bool ALIGN_EPI = false, bool SP2 = false>
; __device__ __forceinline__ void gemm_phase(PG8_LAS unsigned char* lds, const Gemm g, const Sched& S, const Epi& E) {
;     ...
;         for (int t = 0; t < nt; t += 2) {
;     ...
;             PG8_LDA(At, 1, 1); PG8_STAGE(PG8_SB(1, 0), b3, voffB); PG8_STAGE(PG8_SB(1, 1), b3 + hstep, voffB); PG8_STAGE(PG8_SA(1, 0), a3, voffA);
;             PG8_WAIT_V(8); PG8_WAIT_L(0); PG8_BAR; PG8_MMA(1, 0, At, B0); PG8_MMA(1, 1, At, B1); PG8_BAR; PG8_SCHED;
	s_add_i32 s11, s11, s35
	v_lshl_add_u64 v[206:207], v[238:239], 0, s[24:25]
	s_mov_b32 m0, s11
	ds_read_b128 v[198:201], v216 offset:49152
	ds_read_b128 v[202:205], v216 offset:50176
	ds_read_b128 v[210:213], v216 offset:51200
	ds_read_b128 v[218:221], v216 offset:52224
	ds_read_b128 v[222:225], v216 offset:53248
	ds_read_b128 v[226:229], v216 offset:54272
	ds_read_b128 v[230:233], v216 offset:55296
	ds_read_b128 v[234:237], v216 offset:56320
	global_load_lds_dwordx4 v[206:207], off
	v_lshl_add_u64 v[206:207], v[240:241], 0, s[24:25]
	s_add_i32 m0, s11, 0x2000
	s_add_i32 s11, s14, s35
	global_load_lds_dwordx4 v[206:207], off
	s_mov_b32 m0, s11
	v_lshl_add_u64 v[206:207], v[242:243], 0, s[24:25]
	global_load_lds_dwordx4 v[206:207], off
	s_add_i32 m0, s11, 0x2000
	v_lshl_add_u64 v[206:207], v[214:215], 0, s[24:25]
	global_load_lds_dwordx4 v[206:207], off
	s_mov_b32 m0, s54
	v_lshl_add_u64 v[206:207], v[244:245], 0, s[24:25]
	global_load_lds_dwordx4 v[206:207], off
	s_mov_b32 m0, s55
	v_lshl_add_u64 v[206:207], v[246:247], 0, s[24:25]
	global_load_lds_dwordx4 v[206:207], off
	s_waitcnt vmcnt(8)
	s_waitcnt lgkmcnt(0)
	s_setprio 1
	s_barrier
	v_mfma_f32_16x16x32_bf16 v[60:63], v[92:95], v[198:201], v[60:63]
	v_mfma_f32_16x16x32_bf16 v[56:59], v[132:135], v[198:201], v[56:59]
	v_mfma_f32_16x16x32_bf16 v[44:47], v[92:95], v[210:213], v[44:47]
	v_mfma_f32_16x16x32_bf16 v[40:43], v[132:135], v[210:213], v[40:43]
	v_mfma_f32_16x16x32_bf16 v[28:31], v[92:95], v[222:225], v[28:31]
	v_mfma_f32_16x16x32_bf16 v[24:27], v[132:135], v[222:225], v[24:27]
	v_mfma_f32_16x16x32_bf16 v[12:15], v[92:95], v[230:233], v[12:15]
	v_mfma_f32_16x16x32_bf16 v[8:11], v[132:135], v[230:233], v[8:11]
	v_mfma_f32_16x16x32_bf16 v[60:63], v[128:131], v[202:205], v[60:63]
	v_mfma_f32_16x16x32_bf16 v[56:59], v[144:147], v[202:205], v[56:59]
	v_mfma_f32_16x16x32_bf16 v[44:47], v[128:131], v[218:221], v[44:47]
	v_mfma_f32_16x16x32_bf16 v[40:43], v[144:147], v[218:221], v[40:43]
	v_mfma_f32_16x16x32_bf16 v[28:31], v[128:131], v[226:229], v[28:31]
	v_mfma_f32_16x16x32_bf16 v[24:27], v[144:147], v[226:229], v[24:27]
	v_mfma_f32_16x16x32_bf16 v[12:15], v[128:131], v[234:237], v[12:15]
	v_mfma_f32_16x16x32_bf16 v[8:11], v[144:147], v[234:237], v[8:11]
	v_mfma_f32_16x16x32_bf16 v[52:55], v[148:151], v[198:201], v[52:55]
	v_mfma_f32_16x16x32_bf16 v[48:51], v[190:193], v[198:201], v[48:51]
	v_mfma_f32_16x16x32_bf16 v[36:39], v[148:151], v[210:213], v[36:39]
	v_mfma_f32_16x16x32_bf16 v[32:35], v[190:193], v[210:213], v[32:35]
	v_mfma_f32_16x16x32_bf16 v[20:23], v[148:151], v[222:225], v[20:23]
	v_mfma_f32_16x16x32_bf16 v[16:19], v[190:193], v[222:225], v[16:19]
	v_mfma_f32_16x16x32_bf16 v[4:7], v[148:151], v[230:233], v[4:7]
	v_mfma_f32_16x16x32_bf16 v[0:3], v[190:193], v[230:233], v[0:3]
	v_mfma_f32_16x16x32_bf16 v[52:55], v[152:155], v[202:205], v[52:55]
	v_mfma_f32_16x16x32_bf16 v[48:51], v[194:197], v[202:205], v[48:51]
	v_mfma_f32_16x16x32_bf16 v[36:39], v[152:155], v[218:221], v[36:39]
	v_mfma_f32_16x16x32_bf16 v[32:35], v[194:197], v[218:221], v[32:35]
	v_mfma_f32_16x16x32_bf16 v[20:23], v[152:155], v[226:229], v[20:23]
	v_mfma_f32_16x16x32_bf16 v[16:19], v[194:197], v[226:229], v[16:19]
	v_mfma_f32_16x16x32_bf16 v[4:7], v[152:155], v[234:237], v[4:7]
	v_mfma_f32_16x16x32_bf16 v[0:3], v[194:197], v[234:237], v[0:3]
	s_setprio 0
	s_barrier
	v_lshl_add_u64 v[88:89], v[88:89], 0, s[30:31]
	s_cmp_ge_i32 s10, s57
	v_lshl_add_u64 v[90:91], v[90:91], 0, s[30:31]
	s_cbranch_scc0 .LBB0_635

; #define PG8_STAGE(bufoff, gbase, voff) do { _Pragma("unroll") for (int _i = 0; _i < 2; ++_i) \
;         __builtin_amdgcn_global_load_lds((const unsigned*)((const char*)(gbase) + (voff)[_i]), (PG8_LAS unsigned*)(lds + (bufoff) + ldsw + _i * 8192), 16, 0, 0); } while (0)
; #define PG8_LDA(dst, b, h) do { _Pragma("unroll") for (int m = 0; m < 4; ++m) _Pragma("unroll") for (int k = 0; k < 2; ++k) dst[m][k] = *(const PG8_LAS bf16x8*)(lds + PG8_SA(b, h) + aoff + m * 2048 + k * 1024); } while (0)
; #define PG8_LDB(dst, b, h) do { _Pragma("unroll") for (int n = 0; n < 2; ++n) _Pragma("unroll") for (int k = 0; k < 2; ++k) dst[n][k] = *(const PG8_LAS bf16x8*)(lds + PG8_SB(b, h) + boff + n * 2048 + k * 1024); } while (0)
; #define PG8_MMA(ai, bj, At, Bt) do { __builtin_amdgcn_s_setprio(1); _Pragma("unroll") for (int m = 0; m < 4; ++m) _Pragma("unroll") for (int n = 0; n < 2; ++n) _Pragma("unroll") for (int k = 0; k < 2; ++k) \
;         acc[ai][bj][m][n] = __builtin_amdgcn_mfma_f32_16x16x32_bf16(Bt[n][k], At[m][k], acc[ai][bj][m][n], 0, 0, 0); __builtin_amdgcn_s_setprio(0); } while (0)
; #define PG8_WAIT_V(n) asm volatile("s_waitcnt vmcnt(" #n ")" ::: "memory")
; #define PG8_WAIT_L(n) asm volatile("s_waitcnt lgkmcnt(" #n ")" ::: "memory")
; #define PG8_BAR __builtin_amdgcn_s_barrier()
; #define PG8_SCHED __builtin_amdgcn_sched_barrier(0)
; template <class Epi, class Sched, bool ALIGN_EPI = false, bool SP2 = false>
; __device__ __forceinline__ void gemm_phase(PG8_LAS unsigned char* lds, const Gemm g, const Sched& S, const Epi& E) {
;     ...
;             PG8_LDB(B0, 0, 0); PG8_LDB(B1, 0, 1); PG8_SCHED; PG8_LDA(At, 0, 0); PG8_STAGE(PG8_SA(1, 1), a1 + hstep, voffA);
;             PG8_WAIT_V(8); PG8_WAIT_L(0); PG8_BAR; PG8_MMA(0, 0, At, B0); PG8_MMA(0, 1, At, B1); PG8_BAR; PG8_SCHED;
;             PG8_LDA(At, 0, 1); PG8_STAGE(PG8_SB(0, 0), b2, voffB); PG8_STAGE(PG8_SB(0, 1), b2 + hstep, voffB); PG8_STAGE(PG8_SA(0, 0), a2, voffA);
.LBB0_722:
	v_add_u32_e32 v144, s59, v183
	v_add_u32_e32 v170, s60, v183
	ds_read_b128 v[116:119], v144
	ds_read_b128 v[136:139], v144 offset:1024
	ds_read_b128 v[140:143], v144 offset:2048
	ds_read_b128 v[144:147], v144 offset:3072
	ds_read_b128 v[148:151], v170
	ds_read_b128 v[188:191], v170 offset:1024
	ds_read_b128 v[192:195], v170 offset:2048
	ds_read_b128 v[198:201], v170 offset:3072
	s_cmp_eq_u32 s53, s8
	v_lshl_add_u64 v[204:205], v[114:115], 0, s[18:19]
	s_cselect_b64 vcc, -1, 0
	s_add_i32 s8, s8, 2
	v_cndmask_b32_e32 v213, v205, v185, vcc
	v_cndmask_b32_e32 v212, v204, v184, vcc
	v_cndmask_b32_e32 v215, v113, v187, vcc
	v_cndmask_b32_e32 v214, v112, v186, vcc
	v_lshl_add_u64 v[240:241], v[114:115], 0, v[178:179]
	s_add_i32 m0, s34, 0xc000
	ds_read_b128 v[204:207], v202
	ds_read_b128 v[208:211], v202 offset:1024
	ds_read_b128 v[216:219], v202 offset:2048
	ds_read_b128 v[220:223], v202 offset:3072
	ds_read_b128 v[224:227], v202 offset:4096
	ds_read_b128 v[228:231], v202 offset:5120
	ds_read_b128 v[232:235], v202 offset:6144
	ds_read_b128 v[236:239], v202 offset:7168
	global_load_lds_dwordx4 v[240:241], off
	s_add_i32 m0, s34, 0xe000
	v_lshl_add_u64 v[240:241], v[114:115], 0, v[176:177]
	global_load_lds_dwordx4 v[240:241], off
	s_waitcnt vmcnt(8)
	s_waitcnt lgkmcnt(0)
	s_setprio 1
	s_barrier
	v_mfma_f32_16x16x32_bf16 v[132:135], v[116:119], v[204:207], v[132:135]
	v_mfma_f32_16x16x32_bf16 v[128:131], v[140:143], v[204:207], v[128:131]
	v_mfma_f32_16x16x32_bf16 v[108:111], v[116:119], v[216:219], v[108:111]
	v_mfma_f32_16x16x32_bf16 v[104:107], v[140:143], v[216:219], v[104:107]
	v_mfma_f32_16x16x32_bf16 v[92:95], v[116:119], v[224:227], v[92:95]
	v_mfma_f32_16x16x32_bf16 v[88:91], v[140:143], v[224:227], v[88:91]
	v_mfma_f32_16x16x32_bf16 v[76:79], v[116:119], v[232:235], v[76:79]
	v_mfma_f32_16x16x32_bf16 v[72:75], v[140:143], v[232:235], v[72:75]
	v_mfma_f32_16x16x32_bf16 v[132:135], v[136:139], v[208:211], v[132:135]
	v_mfma_f32_16x16x32_bf16 v[128:131], v[144:147], v[208:211], v[128:131]
	v_mfma_f32_16x16x32_bf16 v[108:111], v[136:139], v[220:223], v[108:111]
	v_mfma_f32_16x16x32_bf16 v[104:107], v[144:147], v[220:223], v[104:107]
	v_mfma_f32_16x16x32_bf16 v[92:95], v[136:139], v[228:231], v[92:95]
	v_mfma_f32_16x16x32_bf16 v[88:91], v[144:147], v[228:231], v[88:91]
	v_mfma_f32_16x16x32_bf16 v[76:79], v[136:139], v[236:239], v[76:79]
	v_mfma_f32_16x16x32_bf16 v[72:75], v[144:147], v[236:239], v[72:75]
	v_mfma_f32_16x16x32_bf16 v[124:127], v[148:151], v[204:207], v[124:127]
	v_mfma_f32_16x16x32_bf16 v[120:123], v[192:195], v[204:207], v[120:123]
	v_mfma_f32_16x16x32_bf16 v[100:103], v[148:151], v[216:219], v[100:103]
	v_mfma_f32_16x16x32_bf16 v[96:99], v[192:195], v[216:219], v[96:99]
	v_mfma_f32_16x16x32_bf16 v[84:87], v[148:151], v[224:227], v[84:87]
	v_mfma_f32_16x16x32_bf16 v[80:83], v[192:195], v[224:227], v[80:83]
	v_mfma_f32_16x16x32_bf16 v[68:71], v[148:151], v[232:235], v[68:71]
	v_mfma_f32_16x16x32_bf16 v[64:67], v[192:195], v[232:235], v[64:67]
	v_mfma_f32_16x16x32_bf16 v[124:127], v[188:191], v[208:211], v[124:127]
	v_mfma_f32_16x16x32_bf16 v[120:123], v[198:201], v[208:211], v[120:123]
	v_mfma_f32_16x16x32_bf16 v[100:103], v[188:191], v[220:223], v[100:103]
	v_mfma_f32_16x16x32_bf16 v[96:99], v[198:201], v[220:223], v[96:99]
	v_mfma_f32_16x16x32_bf16 v[84:87], v[188:191], v[228:231], v[84:87]
	v_mfma_f32_16x16x32_bf16 v[80:83], v[198:201], v[228:231], v[80:83]
	v_mfma_f32_16x16x32_bf16 v[68:71], v[188:191], v[236:239], v[68:71]
	v_mfma_f32_16x16x32_bf16 v[64:67], v[198:201], v[236:239], v[64:67]
	s_setprio 0
	s_barrier
	s_add_i32 s9, s59, s29
	v_lshl_add_u64 v[240:241], v[214:215], 0, v[164:165]
	s_mov_b32 m0, s9
	ds_read_b128 v[204:207], v202 offset:16384
	ds_read_b128 v[208:211], v202 offset:17408
	ds_read_b128 v[216:219], v202 offset:18432
	ds_read_b128 v[220:223], v202 offset:19456
	ds_read_b128 v[224:227], v202 offset:20480
	ds_read_b128 v[228:231], v202 offset:21504
	ds_read_b128 v[232:235], v202 offset:22528
	ds_read_b128 v[236:239], v202 offset:23552
	global_load_lds_dwordx4 v[240:241], off
	v_lshl_add_u64 v[242:243], v[214:215], 0, v[168:169]
	s_add_i32 m0, s9, 0x2000
	v_lshl_add_u64 v[214:215], v[214:215], 0, s[12:13]
	s_add_i32 s9, s60, s29
	global_load_lds_dwordx4 v[242:243], off
	v_lshl_add_u64 v[244:245], v[214:215], 0, v[164:165]
	s_mov_b32 m0, s9
	v_lshl_add_u64 v[214:215], v[214:215], 0, v[168:169]
	global_load_lds_dwordx4 v[244:245], off
	s_add_i32 m0, s9, 0x2000
	v_lshl_add_u64 v[246:247], v[212:213], 0, v[162:163]
	global_load_lds_dwordx4 v[214:215], off
	s_mov_b32 m0, s34
	v_lshl_add_u64 v[248:249], v[212:213], 0, v[166:167]
	global_load_lds_dwordx4 v[246:247], off
	s_mov_b32 m0, s36
	s_nop 0
	global_load_lds_dwordx4 v[248:249], off
	s_waitcnt vmcnt(8)
	s_waitcnt lgkmcnt(0)
	s_setprio 1
	s_barrier
; #define PG8_STAGE(bufoff, gbase, voff) do { _Pragma("unroll") for (int _i = 0; _i < 2; ++_i) \
;         __builtin_amdgcn_global_load_lds((const unsigned*)((const char*)(gbase) + (voff)[_i]), (PG8_LAS unsigned*)(lds + (bufoff) + ldsw + _i * 8192), 16, 0, 0); } while (0)
; #define PG8_LDA(dst, b, h) do { _Pragma("unroll") for (int m = 0; m < 4; ++m) _Pragma("unroll") for (int k = 0; k < 2; ++k) dst[m][k] = *(const PG8_LAS bf16x8*)(lds + PG8_SA(b, h) + aoff + m * 2048 + k * 1024); } while (0)
; #define PG8_LDB(dst, b, h) do { _Pragma("unroll") for (int n = 0; n < 2; ++n) _Pragma("unroll") for (int k = 0; k < 2; ++k) dst[n][k] = *(const PG8_LAS bf16x8*)(lds + PG8_SB(b, h) + boff + n * 2048 + k * 1024); } while (0)
; #define PG8_MMA(ai, bj, At, Bt) do { __builtin_amdgcn_s_setprio(1); _Pragma("unroll") for (int m = 0; m < 4; ++m) _Pragma("unroll") for (int n = 0; n < 2; ++n) _Pragma("unroll") for (int k = 0; k < 2; ++k) \
;         acc[ai][bj][m][n] = __builtin_amdgcn_mfma_f32_16x16x32_bf16(Bt[n][k], At[m][k], acc[ai][bj][m][n], 0, 0, 0); __builtin_amdgcn_s_setprio(0); } while (0)
; #define PG8_WAIT_V(n) asm volatile("s_waitcnt vmcnt(" #n ")" ::: "memory")
; #define PG8_WAIT_L(n) asm volatile("s_waitcnt lgkmcnt(" #n ")" ::: "memory")
; #define PG8_BAR __builtin_amdgcn_s_barrier()
; #define PG8_SCHED __builtin_amdgcn_sched_barrier(0)
; template <class Epi, class Sched, bool ALIGN_EPI = false, bool SP2 = false>
; __device__ __forceinline__ void gemm_phase(PG8_LAS unsigned char* lds, const Gemm g, const Sched& S, const Epi& E) {
;     ...
;             PG8_WAIT_V(8); PG8_WAIT_L(0); PG8_BAR; PG8_MMA(1, 0, At, B0); PG8_MMA(1, 1, At, B1); PG8_BAR; PG8_SCHED;
;             PG8_LDB(B0, 1, 0); PG8_LDB(B1, 1, 1); PG8_SCHED; PG8_LDA(At, 1, 0); PG8_STAGE(PG8_SA(0, 1), a2 + hstep, voffA);
;             PG8_WAIT_V(8); PG8_WAIT_L(0); PG8_BAR; PG8_MMA(0, 0, At, B0); PG8_MMA(0, 1, At, B1); PG8_BAR; PG8_SCHED;
	v_mfma_f32_16x16x32_bf16 v[60:63], v[116:119], v[204:207], v[60:63]
	v_mfma_f32_16x16x32_bf16 v[56:59], v[140:143], v[204:207], v[56:59]
	v_mfma_f32_16x16x32_bf16 v[44:47], v[116:119], v[216:219], v[44:47]
	v_mfma_f32_16x16x32_bf16 v[40:43], v[140:143], v[216:219], v[40:43]
	v_mfma_f32_16x16x32_bf16 v[28:31], v[116:119], v[224:227], v[28:31]
	v_mfma_f32_16x16x32_bf16 v[24:27], v[140:143], v[224:227], v[24:27]
	v_mfma_f32_16x16x32_bf16 v[12:15], v[116:119], v[232:235], v[12:15]
	v_mfma_f32_16x16x32_bf16 v[8:11], v[140:143], v[232:235], v[8:11]
	v_mfma_f32_16x16x32_bf16 v[60:63], v[136:139], v[208:211], v[60:63]
	v_mfma_f32_16x16x32_bf16 v[56:59], v[144:147], v[208:211], v[56:59]
	v_mfma_f32_16x16x32_bf16 v[44:47], v[136:139], v[220:223], v[44:47]
	v_mfma_f32_16x16x32_bf16 v[40:43], v[144:147], v[220:223], v[40:43]
	v_mfma_f32_16x16x32_bf16 v[28:31], v[136:139], v[228:231], v[28:31]
	v_mfma_f32_16x16x32_bf16 v[24:27], v[144:147], v[228:231], v[24:27]
	v_mfma_f32_16x16x32_bf16 v[12:15], v[136:139], v[236:239], v[12:15]
	v_mfma_f32_16x16x32_bf16 v[8:11], v[144:147], v[236:239], v[8:11]
	v_mfma_f32_16x16x32_bf16 v[52:55], v[148:151], v[204:207], v[52:55]
	v_mfma_f32_16x16x32_bf16 v[48:51], v[192:195], v[204:207], v[48:51]
	v_mfma_f32_16x16x32_bf16 v[36:39], v[148:151], v[216:219], v[36:39]
	v_mfma_f32_16x16x32_bf16 v[32:35], v[192:195], v[216:219], v[32:35]
	v_mfma_f32_16x16x32_bf16 v[20:23], v[148:151], v[224:227], v[20:23]
	v_mfma_f32_16x16x32_bf16 v[16:19], v[192:195], v[224:227], v[16:19]
	v_mfma_f32_16x16x32_bf16 v[4:7], v[148:151], v[232:235], v[4:7]
	v_mfma_f32_16x16x32_bf16 v[0:3], v[192:195], v[232:235], v[0:3]
	v_mfma_f32_16x16x32_bf16 v[52:55], v[188:191], v[208:211], v[52:55]
	v_mfma_f32_16x16x32_bf16 v[48:51], v[198:201], v[208:211], v[48:51]
	v_mfma_f32_16x16x32_bf16 v[36:39], v[188:191], v[220:223], v[36:39]
	v_mfma_f32_16x16x32_bf16 v[32:35], v[198:201], v[220:223], v[32:35]
	v_mfma_f32_16x16x32_bf16 v[20:23], v[188:191], v[228:231], v[20:23]
	v_mfma_f32_16x16x32_bf16 v[16:19], v[198:201], v[228:231], v[16:19]
	v_mfma_f32_16x16x32_bf16 v[4:7], v[188:191], v[236:239], v[4:7]
	v_mfma_f32_16x16x32_bf16 v[0:3], v[198:201], v[236:239], v[0:3]
	s_setprio 0
	s_barrier
	s_add_i32 s9, 0, 0x18000
	s_add_i32 s10, 0, 0x1c000
	v_add_u32_e32 v144, s9, v183
	v_add_u32_e32 v170, s10, v183
	ds_read_b128 v[116:119], v144
	ds_read_b128 v[136:139], v144 offset:1024
	ds_read_b128 v[140:143], v144 offset:2048
	ds_read_b128 v[144:147], v144 offset:3072
	ds_read_b128 v[148:151], v170
	ds_read_b128 v[188:191], v170 offset:1024
	ds_read_b128 v[192:195], v170 offset:2048
	ds_read_b128 v[198:201], v170 offset:3072
	v_lshl_add_u64 v[212:213], v[212:213], 0, s[12:13]
	s_mov_b32 m0, s37
	v_lshl_add_u64 v[250:251], v[212:213], 0, v[162:163]
	ds_read_b128 v[204:207], v202 offset:32768
	ds_read_b128 v[208:211], v202 offset:33792
	ds_read_b128 v[216:219], v202 offset:34816
	ds_read_b128 v[220:223], v202 offset:35840
	ds_read_b128 v[224:227], v202 offset:36864
	ds_read_b128 v[228:231], v202 offset:37888
	ds_read_b128 v[232:235], v202 offset:38912
	ds_read_b128 v[236:239], v202 offset:39936
	global_load_lds_dwordx4 v[250:251], off
	s_mov_b32 m0, s41
	v_lshl_add_u64 v[212:213], v[212:213], 0, v[166:167]
	global_load_lds_dwordx4 v[212:213], off
	s_waitcnt vmcnt(8)
	s_waitcnt lgkmcnt(0)
	s_setprio 1
	s_barrier
	v_mfma_f32_16x16x32_bf16 v[132:135], v[116:119], v[204:207], v[132:135]
	v_mfma_f32_16x16x32_bf16 v[128:131], v[140:143], v[204:207], v[128:131]
	v_mfma_f32_16x16x32_bf16 v[108:111], v[116:119], v[216:219], v[108:111]
	v_mfma_f32_16x16x32_bf16 v[104:107], v[140:143], v[216:219], v[104:107]
	v_mfma_f32_16x16x32_bf16 v[92:95], v[116:119], v[224:227], v[92:95]
	v_mfma_f32_16x16x32_bf16 v[88:91], v[140:143], v[224:227], v[88:91]
	v_mfma_f32_16x16x32_bf16 v[76:79], v[116:119], v[232:235], v[76:79]
	v_mfma_f32_16x16x32_bf16 v[72:75], v[140:143], v[232:235], v[72:75]
	v_mfma_f32_16x16x32_bf16 v[132:135], v[136:139], v[208:211], v[132:135]
	v_mfma_f32_16x16x32_bf16 v[128:131], v[144:147], v[208:211], v[128:131]
	v_mfma_f32_16x16x32_bf16 v[108:111], v[136:139], v[220:223], v[108:111]
	v_mfma_f32_16x16x32_bf16 v[104:107], v[144:147], v[220:223], v[104:107]
	v_mfma_f32_16x16x32_bf16 v[92:95], v[136:139], v[228:231], v[92:95]
	v_mfma_f32_16x16x32_bf16 v[88:91], v[144:147], v[228:231], v[88:91]
	v_mfma_f32_16x16x32_bf16 v[76:79], v[136:139], v[236:239], v[76:79]
	v_mfma_f32_16x16x32_bf16 v[72:75], v[144:147], v[236:239], v[72:75]
	v_mfma_f32_16x16x32_bf16 v[124:127], v[148:151], v[204:207], v[124:127]
	v_mfma_f32_16x16x32_bf16 v[120:123], v[192:195], v[204:207], v[120:123]
	v_mfma_f32_16x16x32_bf16 v[100:103], v[148:151], v[216:219], v[100:103]
	v_mfma_f32_16x16x32_bf16 v[96:99], v[192:195], v[216:219], v[96:99]
	v_mfma_f32_16x16x32_bf16 v[84:87], v[148:151], v[224:227], v[84:87]
	v_mfma_f32_16x16x32_bf16 v[80:83], v[192:195], v[224:227], v[80:83]
	v_mfma_f32_16x16x32_bf16 v[68:71], v[148:151], v[232:235], v[68:71]
	v_mfma_f32_16x16x32_bf16 v[64:67], v[192:195], v[232:235], v[64:67]
	v_mfma_f32_16x16x32_bf16 v[124:127], v[188:191], v[208:211], v[124:127]
	v_mfma_f32_16x16x32_bf16 v[120:123], v[198:201], v[208:211], v[120:123]
	v_mfma_f32_16x16x32_bf16 v[100:103], v[188:191], v[220:223], v[100:103]
	v_mfma_f32_16x16x32_bf16 v[96:99], v[198:201], v[220:223], v[96:99]
	v_mfma_f32_16x16x32_bf16 v[84:87], v[188:191], v[228:231], v[84:87]
	v_mfma_f32_16x16x32_bf16 v[80:83], v[198:201], v[228:231], v[80:83]
	v_mfma_f32_16x16x32_bf16 v[68:71], v[188:191], v[236:239], v[68:71]
	v_mfma_f32_16x16x32_bf16 v[64:67], v[198:201], v[236:239], v[64:67]
	s_setprio 0
	s_barrier
; #define PG8_STAGE(bufoff, gbase, voff) do { _Pragma("unroll") for (int _i = 0; _i < 2; ++_i) \
;         __builtin_amdgcn_global_load_lds((const unsigned*)((const char*)(gbase) + (voff)[_i]), (PG8_LAS unsigned*)(lds + (bufoff) + ldsw + _i * 8192), 16, 0, 0); } while (0)
; #define PG8_LDA(dst, b, h) do { _Pragma("unroll") for (int m = 0; m < 4; ++m) _Pragma("unroll") for (int k = 0; k < 2; ++k) dst[m][k] = *(const PG8_LAS bf16x8*)(lds + PG8_SA(b, h) + aoff + m * 2048 + k * 1024); } while (0)
; #define PG8_MMA(ai, bj, At, Bt) do { __builtin_amdgcn_s_setprio(1); _Pragma("unroll") for (int m = 0; m < 4; ++m) _Pragma("unroll") for (int n = 0; n < 2; ++n) _Pragma("unroll") for (int k = 0; k < 2; ++k) \
;         acc[ai][bj][m][n] = __builtin_amdgcn_mfma_f32_16x16x32_bf16(Bt[n][k], At[m][k], acc[ai][bj][m][n], 0, 0, 0); __builtin_amdgcn_s_setprio(0); } while (0)
; #define PG8_WAIT_V(n) asm volatile("s_waitcnt vmcnt(" #n ")" ::: "memory")
; #define PG8_WAIT_L(n) asm volatile("s_waitcnt lgkmcnt(" #n ")" ::: "memory")
; #define PG8_BAR __builtin_amdgcn_s_barrier()
; #define PG8_SCHED __builtin_amdgcn_sched_barrier(0)
; template <class Epi, class Sched, bool ALIGN_EPI = false, bool SP2 = false>
; __device__ __forceinline__ void gemm_phase(PG8_LAS unsigned char* lds, const Gemm g, const Sched& S, const Epi& E) {
;     ...
;         for (int t = 0; t < nt; t += 2) {
;     ...
;             PG8_LDA(At, 1, 1); PG8_STAGE(PG8_SB(1, 0), b3, voffB); PG8_STAGE(PG8_SB(1, 1), b3 + hstep, voffB); PG8_STAGE(PG8_SA(1, 0), a3, voffA);
;             PG8_WAIT_V(8); PG8_WAIT_L(0); PG8_BAR; PG8_MMA(1, 0, At, B0); PG8_MMA(1, 1, At, B1); PG8_BAR; PG8_SCHED;
	s_add_i32 s9, s9, s29
	v_lshl_add_u64 v[212:213], v[240:241], 0, s[18:19]
	s_mov_b32 m0, s9
	ds_read_b128 v[204:207], v202 offset:49152
	ds_read_b128 v[208:211], v202 offset:50176
	ds_read_b128 v[216:219], v202 offset:51200
	ds_read_b128 v[220:223], v202 offset:52224
	ds_read_b128 v[224:227], v202 offset:53248
	ds_read_b128 v[228:231], v202 offset:54272
	ds_read_b128 v[232:235], v202 offset:55296
	ds_read_b128 v[236:239], v202 offset:56320
	global_load_lds_dwordx4 v[212:213], off
	v_lshl_add_u64 v[212:213], v[242:243], 0, s[18:19]
	s_add_i32 m0, s9, 0x2000
	s_add_i32 s9, s10, s29
	global_load_lds_dwordx4 v[212:213], off
	s_mov_b32 m0, s9
	v_lshl_add_u64 v[212:213], v[244:245], 0, s[18:19]
	global_load_lds_dwordx4 v[212:213], off
	s_add_i32 m0, s9, 0x2000
	v_lshl_add_u64 v[212:213], v[214:215], 0, s[18:19]
	global_load_lds_dwordx4 v[212:213], off
	s_mov_b32 m0, s49
	v_lshl_add_u64 v[212:213], v[246:247], 0, s[18:19]
	global_load_lds_dwordx4 v[212:213], off
	s_mov_b32 m0, s50
	v_lshl_add_u64 v[212:213], v[248:249], 0, s[18:19]
	global_load_lds_dwordx4 v[212:213], off
	s_waitcnt vmcnt(8)
	s_waitcnt lgkmcnt(0)
	s_setprio 1
	s_barrier
	v_mfma_f32_16x16x32_bf16 v[60:63], v[116:119], v[204:207], v[60:63]
	v_mfma_f32_16x16x32_bf16 v[56:59], v[140:143], v[204:207], v[56:59]
	v_mfma_f32_16x16x32_bf16 v[44:47], v[116:119], v[216:219], v[44:47]
	v_mfma_f32_16x16x32_bf16 v[40:43], v[140:143], v[216:219], v[40:43]
	v_mfma_f32_16x16x32_bf16 v[28:31], v[116:119], v[224:227], v[28:31]
	v_mfma_f32_16x16x32_bf16 v[24:27], v[140:143], v[224:227], v[24:27]
	v_mfma_f32_16x16x32_bf16 v[12:15], v[116:119], v[232:235], v[12:15]
	v_mfma_f32_16x16x32_bf16 v[8:11], v[140:143], v[232:235], v[8:11]
	v_mfma_f32_16x16x32_bf16 v[60:63], v[136:139], v[208:211], v[60:63]
	v_mfma_f32_16x16x32_bf16 v[56:59], v[144:147], v[208:211], v[56:59]
	v_mfma_f32_16x16x32_bf16 v[44:47], v[136:139], v[220:223], v[44:47]
	v_mfma_f32_16x16x32_bf16 v[40:43], v[144:147], v[220:223], v[40:43]
	v_mfma_f32_16x16x32_bf16 v[28:31], v[136:139], v[228:231], v[28:31]
	v_mfma_f32_16x16x32_bf16 v[24:27], v[144:147], v[228:231], v[24:27]
	v_mfma_f32_16x16x32_bf16 v[12:15], v[136:139], v[236:239], v[12:15]
	v_mfma_f32_16x16x32_bf16 v[8:11], v[144:147], v[236:239], v[8:11]
	v_mfma_f32_16x16x32_bf16 v[52:55], v[148:151], v[204:207], v[52:55]
	v_mfma_f32_16x16x32_bf16 v[48:51], v[192:195], v[204:207], v[48:51]
	v_mfma_f32_16x16x32_bf16 v[36:39], v[148:151], v[216:219], v[36:39]
	v_mfma_f32_16x16x32_bf16 v[32:35], v[192:195], v[216:219], v[32:35]
	v_mfma_f32_16x16x32_bf16 v[20:23], v[148:151], v[224:227], v[20:23]
	v_mfma_f32_16x16x32_bf16 v[16:19], v[192:195], v[224:227], v[16:19]
	v_mfma_f32_16x16x32_bf16 v[4:7], v[148:151], v[232:235], v[4:7]
	v_mfma_f32_16x16x32_bf16 v[0:3], v[192:195], v[232:235], v[0:3]
	v_mfma_f32_16x16x32_bf16 v[52:55], v[188:191], v[208:211], v[52:55]
	v_mfma_f32_16x16x32_bf16 v[48:51], v[198:201], v[208:211], v[48:51]
	v_mfma_f32_16x16x32_bf16 v[36:39], v[188:191], v[220:223], v[36:39]
	v_mfma_f32_16x16x32_bf16 v[32:35], v[198:201], v[220:223], v[32:35]
	v_mfma_f32_16x16x32_bf16 v[20:23], v[188:191], v[228:231], v[20:23]
	v_mfma_f32_16x16x32_bf16 v[16:19], v[198:201], v[228:231], v[16:19]
	v_mfma_f32_16x16x32_bf16 v[4:7], v[188:191], v[236:239], v[4:7]
	v_mfma_f32_16x16x32_bf16 v[0:3], v[198:201], v[236:239], v[0:3]
	s_setprio 0
	s_barrier
	v_lshl_add_u64 v[112:113], v[112:113], 0, s[26:27]
	s_cmp_ge_i32 s8, s51
	v_lshl_add_u64 v[114:115], v[114:115], 0, s[26:27]
	s_cbranch_scc0 .LBB0_722

; #define PG8_STAGE(bufoff, gbase, voff) do { _Pragma("unroll") for (int _i = 0; _i < 2; ++_i) \
;         __builtin_amdgcn_global_load_lds((const unsigned*)((const char*)(gbase) + (voff)[_i]), (PG8_LAS unsigned*)(lds + (bufoff) + ldsw + _i * 8192), 16, 0, 0); } while (0)
; #define PG8_LDA(dst, b, h) do { _Pragma("unroll") for (int m = 0; m < 4; ++m) _Pragma("unroll") for (int k = 0; k < 2; ++k) dst[m][k] = *(const PG8_LAS bf16x8*)(lds + PG8_SA(b, h) + aoff + m * 2048 + k * 1024); } while (0)
; #define PG8_LDB(dst, b, h) do { _Pragma("unroll") for (int n = 0; n < 2; ++n) _Pragma("unroll") for (int k = 0; k < 2; ++k) dst[n][k] = *(const PG8_LAS bf16x8*)(lds + PG8_SB(b, h) + boff + n * 2048 + k * 1024); } while (0)
; #define PG8_MMA(ai, bj, At, Bt) do { __builtin_amdgcn_s_setprio(1); _Pragma("unroll") for (int m = 0; m < 4; ++m) _Pragma("unroll") for (int n = 0; n < 2; ++n) _Pragma("unroll") for (int k = 0; k < 2; ++k) \
;         acc[ai][bj][m][n] = __builtin_amdgcn_mfma_f32_16x16x32_bf16(Bt[n][k], At[m][k], acc[ai][bj][m][n], 0, 0, 0); __builtin_amdgcn_s_setprio(0); } while (0)
; #define PG8_WAIT_V(n) asm volatile("s_waitcnt vmcnt(" #n ")" ::: "memory")
; #define PG8_WAIT_L(n) asm volatile("s_waitcnt lgkmcnt(" #n ")" ::: "memory")
; #define PG8_BAR __builtin_amdgcn_s_barrier()
; #define PG8_SCHED __builtin_amdgcn_sched_barrier(0)
; template <class Epi, class Sched, bool ALIGN_EPI = false, bool SP2 = false>
; __device__ __forceinline__ void gemm_phase(PG8_LAS unsigned char* lds, const Gemm g, const Sched& S, const Epi& E) {
;     ...
;             PG8_LDB(B0, 0, 0); PG8_LDB(B1, 0, 1); PG8_SCHED; PG8_LDA(At, 0, 0); PG8_STAGE(PG8_SA(1, 1), a1 + hstep, voffA);
;             PG8_WAIT_V(8); PG8_WAIT_L(0); PG8_BAR; PG8_MMA(0, 0, At, B0); PG8_MMA(0, 1, At, B1); PG8_BAR; PG8_SCHED;
;             PG8_LDA(At, 0, 1); PG8_STAGE(PG8_SB(0, 0), b2, voffB); PG8_STAGE(PG8_SB(0, 1), b2 + hstep, voffB); PG8_STAGE(PG8_SA(0, 0), a2, voffA);
.LBB0_940:
	v_add_u32_e32 v188, s55, v199
	ds_read_b128 v[132:135], v201
	ds_read_b128 v[136:139], v201 offset:1024
	ds_read_b128 v[140:143], v201 offset:2048
	ds_read_b128 v[144:147], v201 offset:3072
	ds_read_b128 v[148:151], v188
	ds_read_b128 v[180:183], v188 offset:1024
	ds_read_b128 v[184:187], v188 offset:2048
	ds_read_b128 v[188:191], v188 offset:3072
	s_cmp_eq_u32 s48, s12
	v_lshl_add_u64 v[192:193], v[130:131], 0, s[22:23]
	s_cselect_b64 vcc, -1, 0
	s_add_i32 s12, s12, 2
	v_cndmask_b32_e32 v197, v193, v177, vcc
	v_cndmask_b32_e32 v196, v192, v176, vcc
	v_cndmask_b32_e32 v213, v129, v179, vcc
	v_cndmask_b32_e32 v212, v128, v178, vcc
	s_mov_b32 m0, s56
	v_lshl_add_u64 v[214:215], v[130:131], 0, v[172:173]
	ds_read_b128 v[192:195], v202
	ds_read_b128 v[204:207], v202 offset:1024
	ds_read_b128 v[208:211], v202 offset:2048
	ds_read_b128 v[216:219], v202 offset:3072
	ds_read_b128 v[220:223], v202 offset:4096
	ds_read_b128 v[224:227], v202 offset:5120
	ds_read_b128 v[228:231], v202 offset:6144
	ds_read_b128 v[232:235], v202 offset:7168
	global_load_lds_dwordx4 v[214:215], off
	s_mov_b32 m0, s57
	v_lshl_add_u64 v[214:215], v[130:131], 0, v[170:171]
	global_load_lds_dwordx4 v[214:215], off
	s_waitcnt vmcnt(8)
	s_waitcnt lgkmcnt(0)
	s_setprio 1
	s_barrier
	v_mfma_f32_16x16x32_bf16 v[120:123], v[132:135], v[192:195], v[120:123]
	v_mfma_f32_16x16x32_bf16 v[124:127], v[140:143], v[192:195], v[124:127]
	v_mfma_f32_16x16x32_bf16 v[108:111], v[132:135], v[208:211], v[108:111]
	v_mfma_f32_16x16x32_bf16 v[104:107], v[140:143], v[208:211], v[104:107]
	v_mfma_f32_16x16x32_bf16 v[92:95], v[132:135], v[220:223], v[92:95]
	v_mfma_f32_16x16x32_bf16 v[88:91], v[140:143], v[220:223], v[88:91]
	v_mfma_f32_16x16x32_bf16 v[76:79], v[132:135], v[228:231], v[76:79]
	v_mfma_f32_16x16x32_bf16 v[72:75], v[140:143], v[228:231], v[72:75]
	v_mfma_f32_16x16x32_bf16 v[120:123], v[136:139], v[204:207], v[120:123]
	v_mfma_f32_16x16x32_bf16 v[124:127], v[144:147], v[204:207], v[124:127]
	v_mfma_f32_16x16x32_bf16 v[108:111], v[136:139], v[216:219], v[108:111]
	v_mfma_f32_16x16x32_bf16 v[104:107], v[144:147], v[216:219], v[104:107]
	v_mfma_f32_16x16x32_bf16 v[92:95], v[136:139], v[224:227], v[92:95]
	v_mfma_f32_16x16x32_bf16 v[88:91], v[144:147], v[224:227], v[88:91]
	v_mfma_f32_16x16x32_bf16 v[76:79], v[136:139], v[232:235], v[76:79]
	v_mfma_f32_16x16x32_bf16 v[72:75], v[144:147], v[232:235], v[72:75]
	v_mfma_f32_16x16x32_bf16 v[116:119], v[148:151], v[192:195], v[116:119]
	v_mfma_f32_16x16x32_bf16 v[112:115], v[184:187], v[192:195], v[112:115]
	v_mfma_f32_16x16x32_bf16 v[100:103], v[148:151], v[208:211], v[100:103]
	v_mfma_f32_16x16x32_bf16 v[96:99], v[184:187], v[208:211], v[96:99]
	v_mfma_f32_16x16x32_bf16 v[84:87], v[148:151], v[220:223], v[84:87]
	v_mfma_f32_16x16x32_bf16 v[80:83], v[184:187], v[220:223], v[80:83]
	v_mfma_f32_16x16x32_bf16 v[68:71], v[148:151], v[228:231], v[68:71]
	v_mfma_f32_16x16x32_bf16 v[64:67], v[184:187], v[228:231], v[64:67]
	v_mfma_f32_16x16x32_bf16 v[116:119], v[180:183], v[204:207], v[116:119]
	v_mfma_f32_16x16x32_bf16 v[112:115], v[188:191], v[204:207], v[112:115]
	v_mfma_f32_16x16x32_bf16 v[100:103], v[180:183], v[216:219], v[100:103]
	v_mfma_f32_16x16x32_bf16 v[96:99], v[188:191], v[216:219], v[96:99]
	v_mfma_f32_16x16x32_bf16 v[84:87], v[180:183], v[224:227], v[84:87]
	v_mfma_f32_16x16x32_bf16 v[80:83], v[188:191], v[224:227], v[80:83]
	v_mfma_f32_16x16x32_bf16 v[68:71], v[180:183], v[232:235], v[68:71]
	v_mfma_f32_16x16x32_bf16 v[64:67], v[188:191], v[232:235], v[64:67]
	s_setprio 0
	s_barrier
	s_mov_b32 m0, s58
	v_lshl_add_u64 v[214:215], v[212:213], 0, v[164:165]
	ds_read_b128 v[192:195], v202 offset:16384
	ds_read_b128 v[204:207], v202 offset:17408
	ds_read_b128 v[208:211], v202 offset:18432
	ds_read_b128 v[216:219], v202 offset:19456
	ds_read_b128 v[220:223], v202 offset:20480
	ds_read_b128 v[224:227], v202 offset:21504
	ds_read_b128 v[228:231], v202 offset:22528
	ds_read_b128 v[232:235], v202 offset:23552
	global_load_lds_dwordx4 v[214:215], off
	v_lshl_add_u64 v[236:237], v[212:213], 0, v[168:169]
	s_mov_b32 m0, s59
	v_lshl_add_u64 v[212:213], v[212:213], 0, s[14:15]
	s_add_i32 s13, s55, s30
	global_load_lds_dwordx4 v[236:237], off
	v_lshl_add_u64 v[238:239], v[212:213], 0, v[164:165]
	s_mov_b32 m0, s13
	v_lshl_add_u64 v[212:213], v[212:213], 0, v[168:169]
	global_load_lds_dwordx4 v[238:239], off
	s_add_i32 m0, s13, 0x2000
	v_lshl_add_u64 v[240:241], v[196:197], 0, v[162:163]
	global_load_lds_dwordx4 v[212:213], off
	s_mov_b32 m0, s31
	v_lshl_add_u64 v[242:243], v[196:197], 0, v[166:167]
	global_load_lds_dwordx4 v[240:241], off
	s_mov_b32 m0, s34
	s_nop 0
	global_load_lds_dwordx4 v[242:243], off
	s_waitcnt vmcnt(8)
	s_waitcnt lgkmcnt(0)
	s_setprio 1
	s_barrier
; #define PG8_STAGE(bufoff, gbase, voff) do { _Pragma("unroll") for (int _i = 0; _i < 2; ++_i) \
;         __builtin_amdgcn_global_load_lds((const unsigned*)((const char*)(gbase) + (voff)[_i]), (PG8_LAS unsigned*)(lds + (bufoff) + ldsw + _i * 8192), 16, 0, 0); } while (0)
; #define PG8_LDA(dst, b, h) do { _Pragma("unroll") for (int m = 0; m < 4; ++m) _Pragma("unroll") for (int k = 0; k < 2; ++k) dst[m][k] = *(const PG8_LAS bf16x8*)(lds + PG8_SA(b, h) + aoff + m * 2048 + k * 1024); } while (0)
; #define PG8_LDB(dst, b, h) do { _Pragma("unroll") for (int n = 0; n < 2; ++n) _Pragma("unroll") for (int k = 0; k < 2; ++k) dst[n][k] = *(const PG8_LAS bf16x8*)(lds + PG8_SB(b, h) + boff + n * 2048 + k * 1024); } while (0)
; #define PG8_MMA(ai, bj, At, Bt) do { __builtin_amdgcn_s_setprio(1); _Pragma("unroll") for (int m = 0; m < 4; ++m) _Pragma("unroll") for (int n = 0; n < 2; ++n) _Pragma("unroll") for (int k = 0; k < 2; ++k) \
;         acc[ai][bj][m][n] = __builtin_amdgcn_mfma_f32_16x16x32_bf16(Bt[n][k], At[m][k], acc[ai][bj][m][n], 0, 0, 0); __builtin_amdgcn_s_setprio(0); } while (0)
; #define PG8_WAIT_V(n) asm volatile("s_waitcnt vmcnt(" #n ")" ::: "memory")
; #define PG8_WAIT_L(n) asm volatile("s_waitcnt lgkmcnt(" #n ")" ::: "memory")
; #define PG8_BAR __builtin_amdgcn_s_barrier()
; #define PG8_SCHED __builtin_amdgcn_sched_barrier(0)
; template <class Epi, class Sched, bool ALIGN_EPI = false, bool SP2 = false>
; __device__ __forceinline__ void gemm_phase(PG8_LAS unsigned char* lds, const Gemm g, const Sched& S, const Epi& E) {
;     ...
;             PG8_WAIT_V(8); PG8_WAIT_L(0); PG8_BAR; PG8_MMA(1, 0, At, B0); PG8_MMA(1, 1, At, B1); PG8_BAR; PG8_SCHED;
;             PG8_LDB(B0, 1, 0); PG8_LDB(B1, 1, 1); PG8_SCHED; PG8_LDA(At, 1, 0); PG8_STAGE(PG8_SA(0, 1), a2 + hstep, voffA);
;             PG8_WAIT_V(8); PG8_WAIT_L(0); PG8_BAR; PG8_MMA(0, 0, At, B0); PG8_MMA(0, 1, At, B1); PG8_BAR; PG8_SCHED;
	v_mfma_f32_16x16x32_bf16 v[60:63], v[132:135], v[192:195], v[60:63]
	v_mfma_f32_16x16x32_bf16 v[56:59], v[140:143], v[192:195], v[56:59]
	v_mfma_f32_16x16x32_bf16 v[44:47], v[132:135], v[208:211], v[44:47]
	v_mfma_f32_16x16x32_bf16 v[40:43], v[140:143], v[208:211], v[40:43]
	v_mfma_f32_16x16x32_bf16 v[28:31], v[132:135], v[220:223], v[28:31]
	v_mfma_f32_16x16x32_bf16 v[24:27], v[140:143], v[220:223], v[24:27]
	v_mfma_f32_16x16x32_bf16 v[12:15], v[132:135], v[228:231], v[12:15]
	v_mfma_f32_16x16x32_bf16 v[8:11], v[140:143], v[228:231], v[8:11]
	v_mfma_f32_16x16x32_bf16 v[60:63], v[136:139], v[204:207], v[60:63]
	v_mfma_f32_16x16x32_bf16 v[56:59], v[144:147], v[204:207], v[56:59]
	v_mfma_f32_16x16x32_bf16 v[44:47], v[136:139], v[216:219], v[44:47]
	v_mfma_f32_16x16x32_bf16 v[40:43], v[144:147], v[216:219], v[40:43]
	v_mfma_f32_16x16x32_bf16 v[28:31], v[136:139], v[224:227], v[28:31]
	v_mfma_f32_16x16x32_bf16 v[24:27], v[144:147], v[224:227], v[24:27]
	v_mfma_f32_16x16x32_bf16 v[12:15], v[136:139], v[232:235], v[12:15]
	v_mfma_f32_16x16x32_bf16 v[8:11], v[144:147], v[232:235], v[8:11]
	v_mfma_f32_16x16x32_bf16 v[52:55], v[148:151], v[192:195], v[52:55]
	v_mfma_f32_16x16x32_bf16 v[48:51], v[184:187], v[192:195], v[48:51]
	v_mfma_f32_16x16x32_bf16 v[36:39], v[148:151], v[208:211], v[36:39]
	v_mfma_f32_16x16x32_bf16 v[32:35], v[184:187], v[208:211], v[32:35]
	v_mfma_f32_16x16x32_bf16 v[20:23], v[148:151], v[220:223], v[20:23]
	v_mfma_f32_16x16x32_bf16 v[16:19], v[184:187], v[220:223], v[16:19]
	v_mfma_f32_16x16x32_bf16 v[4:7], v[148:151], v[228:231], v[4:7]
	v_mfma_f32_16x16x32_bf16 v[0:3], v[184:187], v[228:231], v[0:3]
	v_mfma_f32_16x16x32_bf16 v[52:55], v[180:183], v[204:207], v[52:55]
	v_mfma_f32_16x16x32_bf16 v[48:51], v[188:191], v[204:207], v[48:51]
	v_mfma_f32_16x16x32_bf16 v[36:39], v[180:183], v[216:219], v[36:39]
	v_mfma_f32_16x16x32_bf16 v[32:35], v[188:191], v[216:219], v[32:35]
	v_mfma_f32_16x16x32_bf16 v[20:23], v[180:183], v[224:227], v[20:23]
	v_mfma_f32_16x16x32_bf16 v[16:19], v[188:191], v[224:227], v[16:19]
	v_mfma_f32_16x16x32_bf16 v[4:7], v[180:183], v[232:235], v[4:7]
	v_mfma_f32_16x16x32_bf16 v[0:3], v[188:191], v[232:235], v[0:3]
	s_setprio 0
	s_barrier
	s_add_i32 s13, 0, 0x18000
	s_add_i32 s29, 0, 0x1c000
	v_add_u32_e32 v144, s13, v199
	v_add_u32_e32 v188, s29, v199
	ds_read_b128 v[132:135], v144
	ds_read_b128 v[136:139], v144 offset:1024
	ds_read_b128 v[140:143], v144 offset:2048
	ds_read_b128 v[144:147], v144 offset:3072
	ds_read_b128 v[148:151], v188
	ds_read_b128 v[180:183], v188 offset:1024
	ds_read_b128 v[184:187], v188 offset:2048
	ds_read_b128 v[188:191], v188 offset:3072
	v_lshl_add_u64 v[196:197], v[196:197], 0, s[14:15]
	s_mov_b32 m0, s35
	v_lshl_add_u64 v[244:245], v[196:197], 0, v[162:163]
	ds_read_b128 v[192:195], v202 offset:32768
	ds_read_b128 v[204:207], v202 offset:33792
	ds_read_b128 v[208:211], v202 offset:34816
	ds_read_b128 v[216:219], v202 offset:35840
	ds_read_b128 v[220:223], v202 offset:36864
	ds_read_b128 v[224:227], v202 offset:37888
	ds_read_b128 v[228:231], v202 offset:38912
	ds_read_b128 v[232:235], v202 offset:39936
	global_load_lds_dwordx4 v[244:245], off
	s_mov_b32 m0, s36
	v_lshl_add_u64 v[196:197], v[196:197], 0, v[166:167]
	global_load_lds_dwordx4 v[196:197], off
	s_waitcnt vmcnt(8)
	s_waitcnt lgkmcnt(0)
	s_setprio 1
	s_barrier
	v_mfma_f32_16x16x32_bf16 v[120:123], v[132:135], v[192:195], v[120:123]
	v_mfma_f32_16x16x32_bf16 v[124:127], v[140:143], v[192:195], v[124:127]
	v_mfma_f32_16x16x32_bf16 v[108:111], v[132:135], v[208:211], v[108:111]
	v_mfma_f32_16x16x32_bf16 v[104:107], v[140:143], v[208:211], v[104:107]
	v_mfma_f32_16x16x32_bf16 v[92:95], v[132:135], v[220:223], v[92:95]
	v_mfma_f32_16x16x32_bf16 v[88:91], v[140:143], v[220:223], v[88:91]
	v_mfma_f32_16x16x32_bf16 v[76:79], v[132:135], v[228:231], v[76:79]
	v_mfma_f32_16x16x32_bf16 v[72:75], v[140:143], v[228:231], v[72:75]
	v_mfma_f32_16x16x32_bf16 v[120:123], v[136:139], v[204:207], v[120:123]
	v_mfma_f32_16x16x32_bf16 v[124:127], v[144:147], v[204:207], v[124:127]
	v_mfma_f32_16x16x32_bf16 v[108:111], v[136:139], v[216:219], v[108:111]
	v_mfma_f32_16x16x32_bf16 v[104:107], v[144:147], v[216:219], v[104:107]
	v_mfma_f32_16x16x32_bf16 v[92:95], v[136:139], v[224:227], v[92:95]
	v_mfma_f32_16x16x32_bf16 v[88:91], v[144:147], v[224:227], v[88:91]
	v_mfma_f32_16x16x32_bf16 v[76:79], v[136:139], v[232:235], v[76:79]
	v_mfma_f32_16x16x32_bf16 v[72:75], v[144:147], v[232:235], v[72:75]
	v_mfma_f32_16x16x32_bf16 v[116:119], v[148:151], v[192:195], v[116:119]
	v_mfma_f32_16x16x32_bf16 v[112:115], v[184:187], v[192:195], v[112:115]
	v_mfma_f32_16x16x32_bf16 v[100:103], v[148:151], v[208:211], v[100:103]
	v_mfma_f32_16x16x32_bf16 v[96:99], v[184:187], v[208:211], v[96:99]
	v_mfma_f32_16x16x32_bf16 v[84:87], v[148:151], v[220:223], v[84:87]
	v_mfma_f32_16x16x32_bf16 v[80:83], v[184:187], v[220:223], v[80:83]
	v_mfma_f32_16x16x32_bf16 v[68:71], v[148:151], v[228:231], v[68:71]
	v_mfma_f32_16x16x32_bf16 v[64:67], v[184:187], v[228:231], v[64:67]
	v_mfma_f32_16x16x32_bf16 v[116:119], v[180:183], v[204:207], v[116:119]
	v_mfma_f32_16x16x32_bf16 v[112:115], v[188:191], v[204:207], v[112:115]
	v_mfma_f32_16x16x32_bf16 v[100:103], v[180:183], v[216:219], v[100:103]
	v_mfma_f32_16x16x32_bf16 v[96:99], v[188:191], v[216:219], v[96:99]
	v_mfma_f32_16x16x32_bf16 v[84:87], v[180:183], v[224:227], v[84:87]
	v_mfma_f32_16x16x32_bf16 v[80:83], v[188:191], v[224:227], v[80:83]
	v_mfma_f32_16x16x32_bf16 v[68:71], v[180:183], v[232:235], v[68:71]
	v_mfma_f32_16x16x32_bf16 v[64:67], v[188:191], v[232:235], v[64:67]
	s_setprio 0
	s_barrier
; #define PG8_STAGE(bufoff, gbase, voff) do { _Pragma("unroll") for (int _i = 0; _i < 2; ++_i) \
;         __builtin_amdgcn_global_load_lds((const unsigned*)((const char*)(gbase) + (voff)[_i]), (PG8_LAS unsigned*)(lds + (bufoff) + ldsw + _i * 8192), 16, 0, 0); } while (0)
; #define PG8_LDA(dst, b, h) do { _Pragma("unroll") for (int m = 0; m < 4; ++m) _Pragma("unroll") for (int k = 0; k < 2; ++k) dst[m][k] = *(const PG8_LAS bf16x8*)(lds + PG8_SA(b, h) + aoff + m * 2048 + k * 1024); } while (0)
; #define PG8_MMA(ai, bj, At, Bt) do { __builtin_amdgcn_s_setprio(1); _Pragma("unroll") for (int m = 0; m < 4; ++m) _Pragma("unroll") for (int n = 0; n < 2; ++n) _Pragma("unroll") for (int k = 0; k < 2; ++k) \
;         acc[ai][bj][m][n] = __builtin_amdgcn_mfma_f32_16x16x32_bf16(Bt[n][k], At[m][k], acc[ai][bj][m][n], 0, 0, 0); __builtin_amdgcn_s_setprio(0); } while (0)
; #define PG8_WAIT_V(n) asm volatile("s_waitcnt vmcnt(" #n ")" ::: "memory")
; #define PG8_WAIT_L(n) asm volatile("s_waitcnt lgkmcnt(" #n ")" ::: "memory")
; #define PG8_BAR __builtin_amdgcn_s_barrier()
; #define PG8_SCHED __builtin_amdgcn_sched_barrier(0)
; template <class Epi, class Sched, bool ALIGN_EPI = false, bool SP2 = false>
; __device__ __forceinline__ void gemm_phase(PG8_LAS unsigned char* lds, const Gemm g, const Sched& S, const Epi& E) {
;     ...
;         for (int t = 0; t < nt; t += 2) {
;     ...
;             PG8_LDA(At, 1, 1); PG8_STAGE(PG8_SB(1, 0), b3, voffB); PG8_STAGE(PG8_SB(1, 1), b3 + hstep, voffB); PG8_STAGE(PG8_SA(1, 0), a3, voffA);
;             PG8_WAIT_V(8); PG8_WAIT_L(0); PG8_BAR; PG8_MMA(1, 0, At, B0); PG8_MMA(1, 1, At, B1); PG8_BAR; PG8_SCHED;
	s_add_i32 s13, s13, s30
	v_lshl_add_u64 v[196:197], v[214:215], 0, s[22:23]
	s_mov_b32 m0, s13
	ds_read_b128 v[192:195], v202 offset:49152
	ds_read_b128 v[204:207], v202 offset:50176
	ds_read_b128 v[208:211], v202 offset:51200
	ds_read_b128 v[216:219], v202 offset:52224
	ds_read_b128 v[220:223], v202 offset:53248
	ds_read_b128 v[224:227], v202 offset:54272
	ds_read_b128 v[228:231], v202 offset:55296
	ds_read_b128 v[232:235], v202 offset:56320
	global_load_lds_dwordx4 v[196:197], off
	v_lshl_add_u64 v[196:197], v[236:237], 0, s[22:23]
	s_add_i32 m0, s13, 0x2000
	s_add_i32 s13, s29, s30
	global_load_lds_dwordx4 v[196:197], off
	s_mov_b32 m0, s13
	v_lshl_add_u64 v[196:197], v[238:239], 0, s[22:23]
	global_load_lds_dwordx4 v[196:197], off
	s_add_i32 m0, s13, 0x2000
	v_lshl_add_u64 v[196:197], v[212:213], 0, s[22:23]
	global_load_lds_dwordx4 v[196:197], off
	s_mov_b32 m0, s37
	v_lshl_add_u64 v[196:197], v[240:241], 0, s[22:23]
	global_load_lds_dwordx4 v[196:197], off
	s_mov_b32 m0, s41
	v_lshl_add_u64 v[196:197], v[242:243], 0, s[22:23]
	global_load_lds_dwordx4 v[196:197], off
	s_waitcnt vmcnt(8)
	s_waitcnt lgkmcnt(0)
	s_setprio 1
	s_barrier
	v_mfma_f32_16x16x32_bf16 v[60:63], v[132:135], v[192:195], v[60:63]
	v_mfma_f32_16x16x32_bf16 v[56:59], v[140:143], v[192:195], v[56:59]
	v_mfma_f32_16x16x32_bf16 v[44:47], v[132:135], v[208:211], v[44:47]
	v_mfma_f32_16x16x32_bf16 v[40:43], v[140:143], v[208:211], v[40:43]
	v_mfma_f32_16x16x32_bf16 v[28:31], v[132:135], v[220:223], v[28:31]
	v_mfma_f32_16x16x32_bf16 v[24:27], v[140:143], v[220:223], v[24:27]
	v_mfma_f32_16x16x32_bf16 v[12:15], v[132:135], v[228:231], v[12:15]
	v_mfma_f32_16x16x32_bf16 v[8:11], v[140:143], v[228:231], v[8:11]
	v_mfma_f32_16x16x32_bf16 v[60:63], v[136:139], v[204:207], v[60:63]
	v_mfma_f32_16x16x32_bf16 v[56:59], v[144:147], v[204:207], v[56:59]
	v_mfma_f32_16x16x32_bf16 v[44:47], v[136:139], v[216:219], v[44:47]
	v_mfma_f32_16x16x32_bf16 v[40:43], v[144:147], v[216:219], v[40:43]
	v_mfma_f32_16x16x32_bf16 v[28:31], v[136:139], v[224:227], v[28:31]
	v_mfma_f32_16x16x32_bf16 v[24:27], v[144:147], v[224:227], v[24:27]
	v_mfma_f32_16x16x32_bf16 v[12:15], v[136:139], v[232:235], v[12:15]
	v_mfma_f32_16x16x32_bf16 v[8:11], v[144:147], v[232:235], v[8:11]
	v_mfma_f32_16x16x32_bf16 v[52:55], v[148:151], v[192:195], v[52:55]
	v_mfma_f32_16x16x32_bf16 v[48:51], v[184:187], v[192:195], v[48:51]
	v_mfma_f32_16x16x32_bf16 v[36:39], v[148:151], v[208:211], v[36:39]
	v_mfma_f32_16x16x32_bf16 v[32:35], v[184:187], v[208:211], v[32:35]
	v_mfma_f32_16x16x32_bf16 v[20:23], v[148:151], v[220:223], v[20:23]
	v_mfma_f32_16x16x32_bf16 v[16:19], v[184:187], v[220:223], v[16:19]
	v_mfma_f32_16x16x32_bf16 v[4:7], v[148:151], v[228:231], v[4:7]
	v_mfma_f32_16x16x32_bf16 v[0:3], v[184:187], v[228:231], v[0:3]
	v_mfma_f32_16x16x32_bf16 v[52:55], v[180:183], v[204:207], v[52:55]
	v_mfma_f32_16x16x32_bf16 v[48:51], v[188:191], v[204:207], v[48:51]
	v_mfma_f32_16x16x32_bf16 v[36:39], v[180:183], v[216:219], v[36:39]
	v_mfma_f32_16x16x32_bf16 v[32:35], v[188:191], v[216:219], v[32:35]
	v_mfma_f32_16x16x32_bf16 v[20:23], v[180:183], v[224:227], v[20:23]
	v_mfma_f32_16x16x32_bf16 v[16:19], v[188:191], v[224:227], v[16:19]
	v_mfma_f32_16x16x32_bf16 v[4:7], v[180:183], v[232:235], v[4:7]
	v_mfma_f32_16x16x32_bf16 v[0:3], v[188:191], v[232:235], v[0:3]
	s_setprio 0
	s_barrier
	v_lshl_add_u64 v[128:129], v[128:129], 0, s[26:27]
	s_cmp_ge_i32 s12, s47
	v_lshl_add_u64 v[130:131], v[130:131], 0, s[26:27]
	s_cbranch_scc0 .LBB0_940

; #define PG8_STAGE(bufoff, gbase, voff) do { _Pragma("unroll") for (int _i = 0; _i < 2; ++_i) \
;         __builtin_amdgcn_global_load_lds((const unsigned*)((const char*)(gbase) + (voff)[_i]), (PG8_LAS unsigned*)(lds + (bufoff) + ldsw + _i * 8192), 16, 0, 0); } while (0)
; #define PG8_LDA(dst, b, h) do { _Pragma("unroll") for (int m = 0; m < 4; ++m) _Pragma("unroll") for (int k = 0; k < 2; ++k) dst[m][k] = *(const PG8_LAS bf16x8*)(lds + PG8_SA(b, h) + aoff + m * 2048 + k * 1024); } while (0)
; #define PG8_LDB(dst, b, h) do { _Pragma("unroll") for (int n = 0; n < 2; ++n) _Pragma("unroll") for (int k = 0; k < 2; ++k) dst[n][k] = *(const PG8_LAS bf16x8*)(lds + PG8_SB(b, h) + boff + n * 2048 + k * 1024); } while (0)
; #define PG8_MMA(ai, bj, At, Bt) do { __builtin_amdgcn_s_setprio(1); _Pragma("unroll") for (int m = 0; m < 4; ++m) _Pragma("unroll") for (int n = 0; n < 2; ++n) _Pragma("unroll") for (int k = 0; k < 2; ++k) \
;         acc[ai][bj][m][n] = __builtin_amdgcn_mfma_f32_16x16x32_bf16(Bt[n][k], At[m][k], acc[ai][bj][m][n], 0, 0, 0); __builtin_amdgcn_s_setprio(0); } while (0)
; #define PG8_WAIT_V(n) asm volatile("s_waitcnt vmcnt(" #n ")" ::: "memory")
; #define PG8_WAIT_L(n) asm volatile("s_waitcnt lgkmcnt(" #n ")" ::: "memory")
; #define PG8_BAR __builtin_amdgcn_s_barrier()
; #define PG8_SCHED __builtin_amdgcn_sched_barrier(0)
; template <class Epi, class Sched, bool ALIGN_EPI = false, bool SP2 = false>
; __device__ __forceinline__ void gemm_phase(PG8_LAS unsigned char* lds, const Gemm g, const Sched& S, const Epi& E) {
;     ...
;             PG8_LDB(B0, 0, 0); PG8_LDB(B1, 0, 1); PG8_SCHED; PG8_LDA(At, 0, 0); PG8_STAGE(PG8_SA(1, 1), a1 + hstep, voffA);
;             PG8_WAIT_V(8); PG8_WAIT_L(0); PG8_BAR; PG8_MMA(0, 0, At, B0); PG8_MMA(0, 1, At, B1); PG8_BAR; PG8_SCHED;
;             PG8_LDA(At, 0, 1); PG8_STAGE(PG8_SB(0, 0), b2, voffB); PG8_STAGE(PG8_SB(0, 1), b2 + hstep, voffB); PG8_STAGE(PG8_SA(0, 0), a2, voffA);
.LBB0_1021:
	v_add_u32_e32 v166, s55, v169
	v_add_u32_e32 v168, s56, v169
	ds_read_b128 v[162:165], v166
	ds_read_b128 v[182:185], v166 offset:1024
	ds_read_b128 v[186:189], v166 offset:2048
	ds_read_b128 v[190:193], v166 offset:3072
	ds_read_b128 v[194:197], v168
	ds_read_b128 v[198:201], v168 offset:1024
	ds_read_b128 v[202:205], v168 offset:2048
	ds_read_b128 v[206:209], v168 offset:3072
	s_cmp_eq_u32 s54, s10
	v_lshl_add_u64 v[172:173], v[160:161], 0, s[22:23]
	s_cselect_b64 vcc, -1, 0
	s_add_i32 s10, s10, 2
	v_cndmask_b32_e32 v173, v173, v153, vcc
	v_cndmask_b32_e32 v172, v172, v152, vcc
	v_cndmask_b32_e32 v215, v159, v155, vcc
	v_cndmask_b32_e32 v214, v158, v154, vcc
	s_mov_b32 m0, s57
	v_lshl_add_u64 v[244:245], v[160:161], 0, v[148:149]
	ds_read_b128 v[210:213], v179
	ds_read_b128 v[216:219], v179 offset:1024
	ds_read_b128 v[220:223], v179 offset:2048
	ds_read_b128 v[224:227], v179 offset:3072
	ds_read_b128 v[228:231], v179 offset:4096
	ds_read_b128 v[232:235], v179 offset:5120
	ds_read_b128 v[236:239], v179 offset:6144
	ds_read_b128 v[240:243], v179 offset:7168
	global_load_lds_dwordx4 v[244:245], off
	s_mov_b32 m0, s58
	v_lshl_add_u64 v[244:245], v[160:161], 0, v[146:147]
	global_load_lds_dwordx4 v[244:245], off
	s_waitcnt vmcnt(8)
	s_waitcnt lgkmcnt(0)
	s_setprio 1
	s_barrier
	v_mfma_f32_16x16x32_bf16 v[124:127], v[162:165], v[210:213], v[124:127]
	v_mfma_f32_16x16x32_bf16 v[116:119], v[186:189], v[210:213], v[116:119]
	v_mfma_f32_16x16x32_bf16 v[108:111], v[162:165], v[220:223], v[108:111]
	v_mfma_f32_16x16x32_bf16 v[100:103], v[186:189], v[220:223], v[100:103]
	v_mfma_f32_16x16x32_bf16 v[92:95], v[162:165], v[228:231], v[92:95]
	v_mfma_f32_16x16x32_bf16 v[84:87], v[186:189], v[228:231], v[84:87]
	v_mfma_f32_16x16x32_bf16 v[76:79], v[162:165], v[236:239], v[76:79]
	v_mfma_f32_16x16x32_bf16 v[68:71], v[186:189], v[236:239], v[68:71]
	v_mfma_f32_16x16x32_bf16 v[124:127], v[182:185], v[216:219], v[124:127]
	v_mfma_f32_16x16x32_bf16 v[116:119], v[190:193], v[216:219], v[116:119]
	v_mfma_f32_16x16x32_bf16 v[108:111], v[182:185], v[224:227], v[108:111]
	v_mfma_f32_16x16x32_bf16 v[100:103], v[190:193], v[224:227], v[100:103]
	v_mfma_f32_16x16x32_bf16 v[92:95], v[182:185], v[232:235], v[92:95]
	v_mfma_f32_16x16x32_bf16 v[84:87], v[190:193], v[232:235], v[84:87]
	v_mfma_f32_16x16x32_bf16 v[76:79], v[182:185], v[240:243], v[76:79]
	v_mfma_f32_16x16x32_bf16 v[68:71], v[190:193], v[240:243], v[68:71]
	v_mfma_f32_16x16x32_bf16 v[120:123], v[194:197], v[210:213], v[120:123]
	v_mfma_f32_16x16x32_bf16 v[112:115], v[202:205], v[210:213], v[112:115]
	v_mfma_f32_16x16x32_bf16 v[104:107], v[194:197], v[220:223], v[104:107]
	v_mfma_f32_16x16x32_bf16 v[96:99], v[202:205], v[220:223], v[96:99]
	v_mfma_f32_16x16x32_bf16 v[88:91], v[194:197], v[228:231], v[88:91]
	v_mfma_f32_16x16x32_bf16 v[80:83], v[202:205], v[228:231], v[80:83]
	v_mfma_f32_16x16x32_bf16 v[72:75], v[194:197], v[236:239], v[72:75]
	v_mfma_f32_16x16x32_bf16 v[64:67], v[202:205], v[236:239], v[64:67]
	v_mfma_f32_16x16x32_bf16 v[120:123], v[198:201], v[216:219], v[120:123]
	v_mfma_f32_16x16x32_bf16 v[112:115], v[206:209], v[216:219], v[112:115]
	v_mfma_f32_16x16x32_bf16 v[104:107], v[198:201], v[224:227], v[104:107]
	v_mfma_f32_16x16x32_bf16 v[96:99], v[206:209], v[224:227], v[96:99]
	v_mfma_f32_16x16x32_bf16 v[88:91], v[198:201], v[232:235], v[88:91]
	v_mfma_f32_16x16x32_bf16 v[80:83], v[206:209], v[232:235], v[80:83]
	v_mfma_f32_16x16x32_bf16 v[72:75], v[198:201], v[240:243], v[72:75]
	v_mfma_f32_16x16x32_bf16 v[64:67], v[206:209], v[240:243], v[64:67]
	s_setprio 0
	s_barrier
	s_mov_b32 m0, s61
	v_lshl_add_u64 v[244:245], v[214:215], 0, v[138:139]
	ds_read_b128 v[210:213], v179 offset:16384
	ds_read_b128 v[216:219], v179 offset:17408
	ds_read_b128 v[220:223], v179 offset:18432
	ds_read_b128 v[224:227], v179 offset:19456
	ds_read_b128 v[228:231], v179 offset:20480
	ds_read_b128 v[232:235], v179 offset:21504
	ds_read_b128 v[236:239], v179 offset:22528
	ds_read_b128 v[240:243], v179 offset:23552
	global_load_lds_dwordx4 v[244:245], off
	v_lshl_add_u64 v[246:247], v[214:215], 0, v[134:135]
	s_mov_b32 m0, s62
	v_lshl_add_u64 v[214:215], v[214:215], 0, s[14:15]
	global_load_lds_dwordx4 v[246:247], off
	v_lshl_add_u64 v[248:249], v[214:215], 0, v[138:139]
	s_mov_b32 m0, s63
	v_lshl_add_u64 v[214:215], v[214:215], 0, v[134:135]
	global_load_lds_dwordx4 v[248:249], off
	s_add_i32 m0, s63, 0x2000
	v_lshl_add_u64 v[250:251], v[172:173], 0, v[140:141]
	global_load_lds_dwordx4 v[214:215], off
	s_mov_b32 m0, s46
	v_lshl_add_u64 v[252:253], v[172:173], 0, v[136:137]
	global_load_lds_dwordx4 v[250:251], off
	s_mov_b32 m0, s47
	s_nop 0
	global_load_lds_dwordx4 v[252:253], off
	s_waitcnt vmcnt(8)
	s_waitcnt lgkmcnt(0)
	s_setprio 1
	s_barrier
; #define PG8_STAGE(bufoff, gbase, voff) do { _Pragma("unroll") for (int _i = 0; _i < 2; ++_i) \
;         __builtin_amdgcn_global_load_lds((const unsigned*)((const char*)(gbase) + (voff)[_i]), (PG8_LAS unsigned*)(lds + (bufoff) + ldsw + _i * 8192), 16, 0, 0); } while (0)
; #define PG8_LDA(dst, b, h) do { _Pragma("unroll") for (int m = 0; m < 4; ++m) _Pragma("unroll") for (int k = 0; k < 2; ++k) dst[m][k] = *(const PG8_LAS bf16x8*)(lds + PG8_SA(b, h) + aoff + m * 2048 + k * 1024); } while (0)
; #define PG8_LDB(dst, b, h) do { _Pragma("unroll") for (int n = 0; n < 2; ++n) _Pragma("unroll") for (int k = 0; k < 2; ++k) dst[n][k] = *(const PG8_LAS bf16x8*)(lds + PG8_SB(b, h) + boff + n * 2048 + k * 1024); } while (0)
; #define PG8_MMA(ai, bj, At, Bt) do { __builtin_amdgcn_s_setprio(1); _Pragma("unroll") for (int m = 0; m < 4; ++m) _Pragma("unroll") for (int n = 0; n < 2; ++n) _Pragma("unroll") for (int k = 0; k < 2; ++k) \
;         acc[ai][bj][m][n] = __builtin_amdgcn_mfma_f32_16x16x32_bf16(Bt[n][k], At[m][k], acc[ai][bj][m][n], 0, 0, 0); __builtin_amdgcn_s_setprio(0); } while (0)
; #define PG8_WAIT_V(n) asm volatile("s_waitcnt vmcnt(" #n ")" ::: "memory")
; #define PG8_WAIT_L(n) asm volatile("s_waitcnt lgkmcnt(" #n ")" ::: "memory")
; #define PG8_BAR __builtin_amdgcn_s_barrier()
; #define PG8_SCHED __builtin_amdgcn_sched_barrier(0)
; template <class Epi, class Sched, bool ALIGN_EPI = false, bool SP2 = false>
; __device__ __forceinline__ void gemm_phase(PG8_LAS unsigned char* lds, const Gemm g, const Sched& S, const Epi& E) {
;     ...
;             PG8_WAIT_V(8); PG8_WAIT_L(0); PG8_BAR; PG8_MMA(1, 0, At, B0); PG8_MMA(1, 1, At, B1); PG8_BAR; PG8_SCHED;
;             PG8_LDB(B0, 1, 0); PG8_LDB(B1, 1, 1); PG8_SCHED; PG8_LDA(At, 1, 0); PG8_STAGE(PG8_SA(0, 1), a2 + hstep, voffA);
;             PG8_WAIT_V(8); PG8_WAIT_L(0); PG8_BAR; PG8_MMA(0, 0, At, B0); PG8_MMA(0, 1, At, B1); PG8_BAR; PG8_SCHED;
	v_mfma_f32_16x16x32_bf16 v[60:63], v[162:165], v[210:213], v[60:63]
	v_mfma_f32_16x16x32_bf16 v[52:55], v[186:189], v[210:213], v[52:55]
	v_mfma_f32_16x16x32_bf16 v[44:47], v[162:165], v[220:223], v[44:47]
	v_mfma_f32_16x16x32_bf16 v[36:39], v[186:189], v[220:223], v[36:39]
	v_mfma_f32_16x16x32_bf16 v[28:31], v[162:165], v[228:231], v[28:31]
	v_mfma_f32_16x16x32_bf16 v[20:23], v[186:189], v[228:231], v[20:23]
	v_mfma_f32_16x16x32_bf16 v[12:15], v[162:165], v[236:239], v[12:15]
	v_mfma_f32_16x16x32_bf16 v[4:7], v[186:189], v[236:239], v[4:7]
	v_mfma_f32_16x16x32_bf16 v[60:63], v[182:185], v[216:219], v[60:63]
	v_mfma_f32_16x16x32_bf16 v[52:55], v[190:193], v[216:219], v[52:55]
	v_mfma_f32_16x16x32_bf16 v[44:47], v[182:185], v[224:227], v[44:47]
	v_mfma_f32_16x16x32_bf16 v[36:39], v[190:193], v[224:227], v[36:39]
	v_mfma_f32_16x16x32_bf16 v[28:31], v[182:185], v[232:235], v[28:31]
	v_mfma_f32_16x16x32_bf16 v[20:23], v[190:193], v[232:235], v[20:23]
	v_mfma_f32_16x16x32_bf16 v[12:15], v[182:185], v[240:243], v[12:15]
	v_mfma_f32_16x16x32_bf16 v[4:7], v[190:193], v[240:243], v[4:7]
	v_mfma_f32_16x16x32_bf16 v[56:59], v[194:197], v[210:213], v[56:59]
	v_mfma_f32_16x16x32_bf16 v[48:51], v[202:205], v[210:213], v[48:51]
	v_mfma_f32_16x16x32_bf16 v[40:43], v[194:197], v[220:223], v[40:43]
	v_mfma_f32_16x16x32_bf16 v[32:35], v[202:205], v[220:223], v[32:35]
	v_mfma_f32_16x16x32_bf16 v[24:27], v[194:197], v[228:231], v[24:27]
	v_mfma_f32_16x16x32_bf16 v[16:19], v[202:205], v[228:231], v[16:19]
	v_mfma_f32_16x16x32_bf16 v[8:11], v[194:197], v[236:239], v[8:11]
	v_mfma_f32_16x16x32_bf16 v[0:3], v[202:205], v[236:239], v[0:3]
	v_mfma_f32_16x16x32_bf16 v[56:59], v[198:201], v[216:219], v[56:59]
	v_mfma_f32_16x16x32_bf16 v[48:51], v[206:209], v[216:219], v[48:51]
	v_mfma_f32_16x16x32_bf16 v[40:43], v[198:201], v[224:227], v[40:43]
	v_mfma_f32_16x16x32_bf16 v[32:35], v[206:209], v[224:227], v[32:35]
	v_mfma_f32_16x16x32_bf16 v[24:27], v[198:201], v[232:235], v[24:27]
	v_mfma_f32_16x16x32_bf16 v[16:19], v[206:209], v[232:235], v[16:19]
	v_mfma_f32_16x16x32_bf16 v[8:11], v[198:201], v[240:243], v[8:11]
	v_mfma_f32_16x16x32_bf16 v[0:3], v[206:209], v[240:243], v[0:3]
	s_setprio 0
	s_barrier
	s_add_i32 s11, 0, 0x18000
	v_add_u32_e32 v166, s11, v169
	s_add_i32 s13, 0, 0x1c000
	ds_read_b128 v[162:165], v166
	ds_read_b128 v[182:185], v166 offset:1024
	ds_read_b128 v[186:189], v166 offset:2048
	ds_read_b128 v[190:193], v166 offset:3072
	v_add_u32_e32 v166, s13, v169
	ds_read_b128 v[194:197], v166
	ds_read_b128 v[198:201], v166 offset:1024
	ds_read_b128 v[202:205], v166 offset:2048
	ds_read_b128 v[206:209], v166 offset:3072
	v_lshl_add_u64 v[172:173], v[172:173], 0, s[14:15]
	s_mov_b32 m0, s48
	v_lshl_add_u64 v[170:171], v[172:173], 0, v[140:141]
	ds_read_b128 v[210:213], v179 offset:32768
	ds_read_b128 v[216:219], v179 offset:33792
	ds_read_b128 v[220:223], v179 offset:34816
	ds_read_b128 v[224:227], v179 offset:35840
	ds_read_b128 v[228:231], v179 offset:36864
	ds_read_b128 v[232:235], v179 offset:37888
	ds_read_b128 v[236:239], v179 offset:38912
	ds_read_b128 v[240:243], v179 offset:39936
	global_load_lds_dwordx4 v[170:171], off
	s_mov_b32 m0, s49
	v_lshl_add_u64 v[170:171], v[172:173], 0, v[136:137]
	global_load_lds_dwordx4 v[170:171], off
	s_waitcnt vmcnt(8)
	s_waitcnt lgkmcnt(0)
	s_setprio 1
	s_barrier
	v_mfma_f32_16x16x32_bf16 v[124:127], v[162:165], v[210:213], v[124:127]
	v_mfma_f32_16x16x32_bf16 v[116:119], v[186:189], v[210:213], v[116:119]
	v_mfma_f32_16x16x32_bf16 v[108:111], v[162:165], v[220:223], v[108:111]
	v_mfma_f32_16x16x32_bf16 v[100:103], v[186:189], v[220:223], v[100:103]
	v_mfma_f32_16x16x32_bf16 v[92:95], v[162:165], v[228:231], v[92:95]
	v_mfma_f32_16x16x32_bf16 v[84:87], v[186:189], v[228:231], v[84:87]
	v_mfma_f32_16x16x32_bf16 v[76:79], v[162:165], v[236:239], v[76:79]
	v_mfma_f32_16x16x32_bf16 v[68:71], v[186:189], v[236:239], v[68:71]
	v_mfma_f32_16x16x32_bf16 v[124:127], v[182:185], v[216:219], v[124:127]
	v_mfma_f32_16x16x32_bf16 v[116:119], v[190:193], v[216:219], v[116:119]
	v_mfma_f32_16x16x32_bf16 v[108:111], v[182:185], v[224:227], v[108:111]
	v_mfma_f32_16x16x32_bf16 v[100:103], v[190:193], v[224:227], v[100:103]
	v_mfma_f32_16x16x32_bf16 v[92:95], v[182:185], v[232:235], v[92:95]
	v_mfma_f32_16x16x32_bf16 v[84:87], v[190:193], v[232:235], v[84:87]
	v_mfma_f32_16x16x32_bf16 v[76:79], v[182:185], v[240:243], v[76:79]
	v_mfma_f32_16x16x32_bf16 v[68:71], v[190:193], v[240:243], v[68:71]
	v_mfma_f32_16x16x32_bf16 v[120:123], v[194:197], v[210:213], v[120:123]
	v_mfma_f32_16x16x32_bf16 v[112:115], v[202:205], v[210:213], v[112:115]
	v_mfma_f32_16x16x32_bf16 v[104:107], v[194:197], v[220:223], v[104:107]
	v_mfma_f32_16x16x32_bf16 v[96:99], v[202:205], v[220:223], v[96:99]
	v_mfma_f32_16x16x32_bf16 v[88:91], v[194:197], v[228:231], v[88:91]
	v_mfma_f32_16x16x32_bf16 v[80:83], v[202:205], v[228:231], v[80:83]
	v_mfma_f32_16x16x32_bf16 v[72:75], v[194:197], v[236:239], v[72:75]
	v_mfma_f32_16x16x32_bf16 v[64:67], v[202:205], v[236:239], v[64:67]
	v_mfma_f32_16x16x32_bf16 v[120:123], v[198:201], v[216:219], v[120:123]
	v_mfma_f32_16x16x32_bf16 v[112:115], v[206:209], v[216:219], v[112:115]
	v_mfma_f32_16x16x32_bf16 v[104:107], v[198:201], v[224:227], v[104:107]
	v_mfma_f32_16x16x32_bf16 v[96:99], v[206:209], v[224:227], v[96:99]
	v_mfma_f32_16x16x32_bf16 v[88:91], v[198:201], v[232:235], v[88:91]
	v_mfma_f32_16x16x32_bf16 v[80:83], v[206:209], v[232:235], v[80:83]
	v_mfma_f32_16x16x32_bf16 v[72:75], v[198:201], v[240:243], v[72:75]
	v_mfma_f32_16x16x32_bf16 v[64:67], v[206:209], v[240:243], v[64:67]
	s_setprio 0
	s_barrier
; #define PG8_STAGE(bufoff, gbase, voff) do { _Pragma("unroll") for (int _i = 0; _i < 2; ++_i) \
;         __builtin_amdgcn_global_load_lds((const unsigned*)((const char*)(gbase) + (voff)[_i]), (PG8_LAS unsigned*)(lds + (bufoff) + ldsw + _i * 8192), 16, 0, 0); } while (0)
; #define PG8_LDA(dst, b, h) do { _Pragma("unroll") for (int m = 0; m < 4; ++m) _Pragma("unroll") for (int k = 0; k < 2; ++k) dst[m][k] = *(const PG8_LAS bf16x8*)(lds + PG8_SA(b, h) + aoff + m * 2048 + k * 1024); } while (0)
; #define PG8_MMA(ai, bj, At, Bt) do { __builtin_amdgcn_s_setprio(1); _Pragma("unroll") for (int m = 0; m < 4; ++m) _Pragma("unroll") for (int n = 0; n < 2; ++n) _Pragma("unroll") for (int k = 0; k < 2; ++k) \
;         acc[ai][bj][m][n] = __builtin_amdgcn_mfma_f32_16x16x32_bf16(Bt[n][k], At[m][k], acc[ai][bj][m][n], 0, 0, 0); __builtin_amdgcn_s_setprio(0); } while (0)
; #define PG8_WAIT_V(n) asm volatile("s_waitcnt vmcnt(" #n ")" ::: "memory")
; #define PG8_WAIT_L(n) asm volatile("s_waitcnt lgkmcnt(" #n ")" ::: "memory")
; #define PG8_BAR __builtin_amdgcn_s_barrier()
; #define PG8_SCHED __builtin_amdgcn_sched_barrier(0)
; template <class Epi, class Sched, bool ALIGN_EPI = false, bool SP2 = false>
; __device__ __forceinline__ void gemm_phase(PG8_LAS unsigned char* lds, const Gemm g, const Sched& S, const Epi& E) {
;     ...
;         for (int t = 0; t < nt; t += 2) {
;     ...
;             PG8_LDA(At, 1, 1); PG8_STAGE(PG8_SB(1, 0), b3, voffB); PG8_STAGE(PG8_SB(1, 1), b3 + hstep, voffB); PG8_STAGE(PG8_SA(1, 0), a3, voffA);
;             PG8_WAIT_V(8); PG8_WAIT_L(0); PG8_BAR; PG8_MMA(1, 0, At, B0); PG8_MMA(1, 1, At, B1); PG8_BAR; PG8_SCHED;
	s_add_i32 s11, s11, s29
	v_lshl_add_u64 v[170:171], v[244:245], 0, s[22:23]
	s_mov_b32 m0, s11
	ds_read_b128 v[210:213], v179 offset:49152
	ds_read_b128 v[216:219], v179 offset:50176
	ds_read_b128 v[220:223], v179 offset:51200
	ds_read_b128 v[224:227], v179 offset:52224
	ds_read_b128 v[228:231], v179 offset:53248
	ds_read_b128 v[232:235], v179 offset:54272
	ds_read_b128 v[236:239], v179 offset:55296
	ds_read_b128 v[240:243], v179 offset:56320
	global_load_lds_dwordx4 v[170:171], off
	v_lshl_add_u64 v[170:171], v[246:247], 0, s[22:23]
	s_add_i32 m0, s11, 0x2000
	s_add_i32 s11, s13, s29
	global_load_lds_dwordx4 v[170:171], off
	s_mov_b32 m0, s11
	v_lshl_add_u64 v[170:171], v[248:249], 0, s[22:23]
	global_load_lds_dwordx4 v[170:171], off
	s_add_i32 m0, s11, 0x2000
	v_lshl_add_u64 v[170:171], v[214:215], 0, s[22:23]
	global_load_lds_dwordx4 v[170:171], off
	s_mov_b32 m0, s50
	v_lshl_add_u64 v[170:171], v[250:251], 0, s[22:23]
	global_load_lds_dwordx4 v[170:171], off
	s_mov_b32 m0, s51
	v_lshl_add_u64 v[170:171], v[252:253], 0, s[22:23]
	global_load_lds_dwordx4 v[170:171], off
	s_waitcnt vmcnt(8)
	s_waitcnt lgkmcnt(0)
	s_setprio 1
	s_barrier
	v_mfma_f32_16x16x32_bf16 v[60:63], v[162:165], v[210:213], v[60:63]
	v_mfma_f32_16x16x32_bf16 v[52:55], v[186:189], v[210:213], v[52:55]
	v_mfma_f32_16x16x32_bf16 v[44:47], v[162:165], v[220:223], v[44:47]
	v_mfma_f32_16x16x32_bf16 v[36:39], v[186:189], v[220:223], v[36:39]
	v_mfma_f32_16x16x32_bf16 v[28:31], v[162:165], v[228:231], v[28:31]
	v_mfma_f32_16x16x32_bf16 v[20:23], v[186:189], v[228:231], v[20:23]
	v_mfma_f32_16x16x32_bf16 v[12:15], v[162:165], v[236:239], v[12:15]
	v_mfma_f32_16x16x32_bf16 v[4:7], v[186:189], v[236:239], v[4:7]
	v_mfma_f32_16x16x32_bf16 v[60:63], v[182:185], v[216:219], v[60:63]
	v_mfma_f32_16x16x32_bf16 v[52:55], v[190:193], v[216:219], v[52:55]
	v_mfma_f32_16x16x32_bf16 v[44:47], v[182:185], v[224:227], v[44:47]
	v_mfma_f32_16x16x32_bf16 v[36:39], v[190:193], v[224:227], v[36:39]
	v_mfma_f32_16x16x32_bf16 v[28:31], v[182:185], v[232:235], v[28:31]
	v_mfma_f32_16x16x32_bf16 v[20:23], v[190:193], v[232:235], v[20:23]
	v_mfma_f32_16x16x32_bf16 v[12:15], v[182:185], v[240:243], v[12:15]
	v_mfma_f32_16x16x32_bf16 v[4:7], v[190:193], v[240:243], v[4:7]
	v_mfma_f32_16x16x32_bf16 v[56:59], v[194:197], v[210:213], v[56:59]
	v_mfma_f32_16x16x32_bf16 v[48:51], v[202:205], v[210:213], v[48:51]
	v_mfma_f32_16x16x32_bf16 v[40:43], v[194:197], v[220:223], v[40:43]
	v_mfma_f32_16x16x32_bf16 v[32:35], v[202:205], v[220:223], v[32:35]
	v_mfma_f32_16x16x32_bf16 v[24:27], v[194:197], v[228:231], v[24:27]
	v_mfma_f32_16x16x32_bf16 v[16:19], v[202:205], v[228:231], v[16:19]
	v_mfma_f32_16x16x32_bf16 v[8:11], v[194:197], v[236:239], v[8:11]
	v_mfma_f32_16x16x32_bf16 v[0:3], v[202:205], v[236:239], v[0:3]
	v_mfma_f32_16x16x32_bf16 v[56:59], v[198:201], v[216:219], v[56:59]
	v_mfma_f32_16x16x32_bf16 v[48:51], v[206:209], v[216:219], v[48:51]
	v_mfma_f32_16x16x32_bf16 v[40:43], v[198:201], v[224:227], v[40:43]
	v_mfma_f32_16x16x32_bf16 v[32:35], v[206:209], v[224:227], v[32:35]
	v_mfma_f32_16x16x32_bf16 v[24:27], v[198:201], v[232:235], v[24:27]
	v_mfma_f32_16x16x32_bf16 v[16:19], v[206:209], v[232:235], v[16:19]
	v_mfma_f32_16x16x32_bf16 v[8:11], v[198:201], v[240:243], v[8:11]
	v_mfma_f32_16x16x32_bf16 v[0:3], v[206:209], v[240:243], v[0:3]
	s_setprio 0
	s_barrier
	v_lshl_add_u64 v[158:159], v[158:159], 0, s[26:27]
	s_cmp_ge_i32 s10, s52
	v_lshl_add_u64 v[160:161], v[160:161], 0, s[26:27]
	s_cbranch_scc0 .LBB0_1021

; #define PG8_STAGE(bufoff, gbase, voff) do { _Pragma("unroll") for (int _i = 0; _i < 2; ++_i) \
;         __builtin_amdgcn_global_load_lds((const unsigned*)((const char*)(gbase) + (voff)[_i]), (PG8_LAS unsigned*)(lds + (bufoff) + ldsw + _i * 8192), 16, 0, 0); } while (0)
; #define PG8_LDA(dst, b, h) do { _Pragma("unroll") for (int m = 0; m < 4; ++m) _Pragma("unroll") for (int k = 0; k < 2; ++k) dst[m][k] = *(const PG8_LAS bf16x8*)(lds + PG8_SA(b, h) + aoff + m * 2048 + k * 1024); } while (0)
; #define PG8_LDB(dst, b, h) do { _Pragma("unroll") for (int n = 0; n < 2; ++n) _Pragma("unroll") for (int k = 0; k < 2; ++k) dst[n][k] = *(const PG8_LAS bf16x8*)(lds + PG8_SB(b, h) + boff + n * 2048 + k * 1024); } while (0)
; #define PG8_MMA(ai, bj, At, Bt) do { __builtin_amdgcn_s_setprio(1); _Pragma("unroll") for (int m = 0; m < 4; ++m) _Pragma("unroll") for (int n = 0; n < 2; ++n) _Pragma("unroll") for (int k = 0; k < 2; ++k) \
;         acc[ai][bj][m][n] = __builtin_amdgcn_mfma_f32_16x16x32_bf16(Bt[n][k], At[m][k], acc[ai][bj][m][n], 0, 0, 0); __builtin_amdgcn_s_setprio(0); } while (0)
; #define PG8_WAIT_V(n) asm volatile("s_waitcnt vmcnt(" #n ")" ::: "memory")
; #define PG8_WAIT_L(n) asm volatile("s_waitcnt lgkmcnt(" #n ")" ::: "memory")
; #define PG8_BAR __builtin_amdgcn_s_barrier()
; #define PG8_SCHED __builtin_amdgcn_sched_barrier(0)
; template <class Epi, class Sched, bool ALIGN_EPI = false, bool SP2 = false>
; __device__ __forceinline__ void gemm_phase(PG8_LAS unsigned char* lds, const Gemm g, const Sched& S, const Epi& E) {
;     ...
;             PG8_LDB(B0, 0, 0); PG8_LDB(B1, 0, 1); PG8_SCHED; PG8_LDA(At, 0, 0); PG8_STAGE(PG8_SA(1, 1), a1 + hstep, voffA);
;             PG8_WAIT_V(8); PG8_WAIT_L(0); PG8_BAR; PG8_MMA(0, 0, At, B0); PG8_MMA(0, 1, At, B1); PG8_BAR; PG8_SCHED;
;             PG8_LDA(At, 0, 1); PG8_STAGE(PG8_SB(0, 0), b2, voffB); PG8_STAGE(PG8_SB(0, 1), b2 + hstep, voffB); PG8_STAGE(PG8_SA(0, 0), a2, voffA);
.LBB0_1169:
	v_add_u32_e32 v192, s52, v161
	ds_read_b128 v[164:167], v162
	ds_read_b128 v[168:171], v162 offset:1024
	ds_read_b128 v[172:175], v162 offset:2048
	ds_read_b128 v[176:179], v162 offset:3072
	ds_read_b128 v[180:183], v192
	ds_read_b128 v[184:187], v192 offset:1024
	ds_read_b128 v[188:191], v192 offset:2048
	ds_read_b128 v[192:195], v192 offset:3072
	s_cmp_eq_u32 s51, s10
	v_lshl_add_u64 v[196:197], v[158:159], 0, s[24:25]
	s_cselect_b64 vcc, -1, 0
	s_add_i32 s10, s10, 2
	v_cndmask_b32_e32 v213, v197, v151, vcc
	v_cndmask_b32_e32 v212, v196, v150, vcc
	v_cndmask_b32_e32 v215, v155, v153, vcc
	v_cndmask_b32_e32 v214, v154, v152, vcc
	s_mov_b32 m0, s54
	v_lshl_add_u64 v[232:233], v[158:159], 0, v[146:147]
	ds_read_b128 v[196:199], v163
	ds_read_b128 v[200:203], v163 offset:1024
	ds_read_b128 v[204:207], v163 offset:2048
	ds_read_b128 v[208:211], v163 offset:3072
	ds_read_b128 v[216:219], v163 offset:4096
	ds_read_b128 v[220:223], v163 offset:5120
	ds_read_b128 v[224:227], v163 offset:6144
	ds_read_b128 v[228:231], v163 offset:7168
	global_load_lds_dwordx4 v[232:233], off
	s_mov_b32 m0, s55
	v_lshl_add_u64 v[232:233], v[158:159], 0, v[144:145]
	global_load_lds_dwordx4 v[232:233], off
	s_waitcnt vmcnt(8)
	s_waitcnt lgkmcnt(0)
	s_setprio 1
	s_barrier
	v_mfma_f32_16x16x32_bf16 v[124:127], v[164:167], v[196:199], v[124:127]
	v_mfma_f32_16x16x32_bf16 v[120:123], v[172:175], v[196:199], v[120:123]
	v_mfma_f32_16x16x32_bf16 v[108:111], v[164:167], v[204:207], v[108:111]
	v_mfma_f32_16x16x32_bf16 v[104:107], v[172:175], v[204:207], v[104:107]
	v_mfma_f32_16x16x32_bf16 v[92:95], v[164:167], v[216:219], v[92:95]
	v_mfma_f32_16x16x32_bf16 v[88:91], v[172:175], v[216:219], v[88:91]
	v_mfma_f32_16x16x32_bf16 v[76:79], v[164:167], v[224:227], v[76:79]
	v_mfma_f32_16x16x32_bf16 v[72:75], v[172:175], v[224:227], v[72:75]
	v_mfma_f32_16x16x32_bf16 v[124:127], v[168:171], v[200:203], v[124:127]
	v_mfma_f32_16x16x32_bf16 v[120:123], v[176:179], v[200:203], v[120:123]
	v_mfma_f32_16x16x32_bf16 v[108:111], v[168:171], v[208:211], v[108:111]
	v_mfma_f32_16x16x32_bf16 v[104:107], v[176:179], v[208:211], v[104:107]
	v_mfma_f32_16x16x32_bf16 v[92:95], v[168:171], v[220:223], v[92:95]
	v_mfma_f32_16x16x32_bf16 v[88:91], v[176:179], v[220:223], v[88:91]
	v_mfma_f32_16x16x32_bf16 v[76:79], v[168:171], v[228:231], v[76:79]
	v_mfma_f32_16x16x32_bf16 v[72:75], v[176:179], v[228:231], v[72:75]
	v_mfma_f32_16x16x32_bf16 v[116:119], v[180:183], v[196:199], v[116:119]
	v_mfma_f32_16x16x32_bf16 v[112:115], v[188:191], v[196:199], v[112:115]
	v_mfma_f32_16x16x32_bf16 v[100:103], v[180:183], v[204:207], v[100:103]
	v_mfma_f32_16x16x32_bf16 v[96:99], v[188:191], v[204:207], v[96:99]
	v_mfma_f32_16x16x32_bf16 v[84:87], v[180:183], v[216:219], v[84:87]
	v_mfma_f32_16x16x32_bf16 v[80:83], v[188:191], v[216:219], v[80:83]
	v_mfma_f32_16x16x32_bf16 v[68:71], v[180:183], v[224:227], v[68:71]
	v_mfma_f32_16x16x32_bf16 v[64:67], v[188:191], v[224:227], v[64:67]
	v_mfma_f32_16x16x32_bf16 v[116:119], v[184:187], v[200:203], v[116:119]
	v_mfma_f32_16x16x32_bf16 v[112:115], v[192:195], v[200:203], v[112:115]
	v_mfma_f32_16x16x32_bf16 v[100:103], v[184:187], v[208:211], v[100:103]
	v_mfma_f32_16x16x32_bf16 v[96:99], v[192:195], v[208:211], v[96:99]
	v_mfma_f32_16x16x32_bf16 v[84:87], v[184:187], v[220:223], v[84:87]
	v_mfma_f32_16x16x32_bf16 v[80:83], v[192:195], v[220:223], v[80:83]
	v_mfma_f32_16x16x32_bf16 v[68:71], v[184:187], v[228:231], v[68:71]
	v_mfma_f32_16x16x32_bf16 v[64:67], v[192:195], v[228:231], v[64:67]
	s_setprio 0
	s_barrier
	s_mov_b32 m0, s56
	v_lshl_add_u64 v[232:233], v[214:215], 0, v[138:139]
	ds_read_b128 v[196:199], v163 offset:16384
	ds_read_b128 v[200:203], v163 offset:17408
	ds_read_b128 v[204:207], v163 offset:18432
	ds_read_b128 v[208:211], v163 offset:19456
	ds_read_b128 v[216:219], v163 offset:20480
	ds_read_b128 v[220:223], v163 offset:21504
	ds_read_b128 v[224:227], v163 offset:22528
	ds_read_b128 v[228:231], v163 offset:23552
	global_load_lds_dwordx4 v[232:233], off
	v_lshl_add_u64 v[234:235], v[214:215], 0, v[134:135]
	s_mov_b32 m0, s57
	v_lshl_add_u64 v[214:215], v[214:215], 0, s[14:15]
	global_load_lds_dwordx4 v[234:235], off
	v_lshl_add_u64 v[236:237], v[214:215], 0, v[138:139]
	s_mov_b32 m0, s58
	v_lshl_add_u64 v[214:215], v[214:215], 0, v[134:135]
	global_load_lds_dwordx4 v[236:237], off
	s_mov_b32 m0, s59
	v_lshl_add_u64 v[238:239], v[212:213], 0, v[140:141]
	global_load_lds_dwordx4 v[214:215], off
	s_mov_b32 m0, s37
	v_lshl_add_u64 v[240:241], v[212:213], 0, v[136:137]
	global_load_lds_dwordx4 v[238:239], off
	s_mov_b32 m0, s41
	s_nop 0
	global_load_lds_dwordx4 v[240:241], off
	s_waitcnt vmcnt(8)
	s_waitcnt lgkmcnt(0)
	s_setprio 1
	s_barrier
; #define PG8_STAGE(bufoff, gbase, voff) do { _Pragma("unroll") for (int _i = 0; _i < 2; ++_i) \
;         __builtin_amdgcn_global_load_lds((const unsigned*)((const char*)(gbase) + (voff)[_i]), (PG8_LAS unsigned*)(lds + (bufoff) + ldsw + _i * 8192), 16, 0, 0); } while (0)
; #define PG8_LDA(dst, b, h) do { _Pragma("unroll") for (int m = 0; m < 4; ++m) _Pragma("unroll") for (int k = 0; k < 2; ++k) dst[m][k] = *(const PG8_LAS bf16x8*)(lds + PG8_SA(b, h) + aoff + m * 2048 + k * 1024); } while (0)
; #define PG8_LDB(dst, b, h) do { _Pragma("unroll") for (int n = 0; n < 2; ++n) _Pragma("unroll") for (int k = 0; k < 2; ++k) dst[n][k] = *(const PG8_LAS bf16x8*)(lds + PG8_SB(b, h) + boff + n * 2048 + k * 1024); } while (0)
; #define PG8_MMA(ai, bj, At, Bt) do { __builtin_amdgcn_s_setprio(1); _Pragma("unroll") for (int m = 0; m < 4; ++m) _Pragma("unroll") for (int n = 0; n < 2; ++n) _Pragma("unroll") for (int k = 0; k < 2; ++k) \
;         acc[ai][bj][m][n] = __builtin_amdgcn_mfma_f32_16x16x32_bf16(Bt[n][k], At[m][k], acc[ai][bj][m][n], 0, 0, 0); __builtin_amdgcn_s_setprio(0); } while (0)
; #define PG8_WAIT_V(n) asm volatile("s_waitcnt vmcnt(" #n ")" ::: "memory")
; #define PG8_WAIT_L(n) asm volatile("s_waitcnt lgkmcnt(" #n ")" ::: "memory")
; #define PG8_BAR __builtin_amdgcn_s_barrier()
; #define PG8_SCHED __builtin_amdgcn_sched_barrier(0)
; template <class Epi, class Sched, bool ALIGN_EPI = false, bool SP2 = false>
; __device__ __forceinline__ void gemm_phase(PG8_LAS unsigned char* lds, const Gemm g, const Sched& S, const Epi& E) {
;     ...
;             PG8_WAIT_V(8); PG8_WAIT_L(0); PG8_BAR; PG8_MMA(1, 0, At, B0); PG8_MMA(1, 1, At, B1); PG8_BAR; PG8_SCHED;
;             PG8_LDB(B0, 1, 0); PG8_LDB(B1, 1, 1); PG8_SCHED; PG8_LDA(At, 1, 0); PG8_STAGE(PG8_SA(0, 1), a2 + hstep, voffA);
;             PG8_WAIT_V(8); PG8_WAIT_L(0); PG8_BAR; PG8_MMA(0, 0, At, B0); PG8_MMA(0, 1, At, B1); PG8_BAR; PG8_SCHED;
	v_mfma_f32_16x16x32_bf16 v[60:63], v[164:167], v[196:199], v[60:63]
	v_mfma_f32_16x16x32_bf16 v[56:59], v[172:175], v[196:199], v[56:59]
	v_mfma_f32_16x16x32_bf16 v[44:47], v[164:167], v[204:207], v[44:47]
	v_mfma_f32_16x16x32_bf16 v[40:43], v[172:175], v[204:207], v[40:43]
	v_mfma_f32_16x16x32_bf16 v[28:31], v[164:167], v[216:219], v[28:31]
	v_mfma_f32_16x16x32_bf16 v[24:27], v[172:175], v[216:219], v[24:27]
	v_mfma_f32_16x16x32_bf16 v[12:15], v[164:167], v[224:227], v[12:15]
	v_mfma_f32_16x16x32_bf16 v[8:11], v[172:175], v[224:227], v[8:11]
	v_mfma_f32_16x16x32_bf16 v[60:63], v[168:171], v[200:203], v[60:63]
	v_mfma_f32_16x16x32_bf16 v[56:59], v[176:179], v[200:203], v[56:59]
	v_mfma_f32_16x16x32_bf16 v[44:47], v[168:171], v[208:211], v[44:47]
	v_mfma_f32_16x16x32_bf16 v[40:43], v[176:179], v[208:211], v[40:43]
	v_mfma_f32_16x16x32_bf16 v[28:31], v[168:171], v[220:223], v[28:31]
	v_mfma_f32_16x16x32_bf16 v[24:27], v[176:179], v[220:223], v[24:27]
	v_mfma_f32_16x16x32_bf16 v[12:15], v[168:171], v[228:231], v[12:15]
	v_mfma_f32_16x16x32_bf16 v[8:11], v[176:179], v[228:231], v[8:11]
	v_mfma_f32_16x16x32_bf16 v[52:55], v[180:183], v[196:199], v[52:55]
	v_mfma_f32_16x16x32_bf16 v[48:51], v[188:191], v[196:199], v[48:51]
	v_mfma_f32_16x16x32_bf16 v[36:39], v[180:183], v[204:207], v[36:39]
	v_mfma_f32_16x16x32_bf16 v[32:35], v[188:191], v[204:207], v[32:35]
	v_mfma_f32_16x16x32_bf16 v[20:23], v[180:183], v[216:219], v[20:23]
	v_mfma_f32_16x16x32_bf16 v[16:19], v[188:191], v[216:219], v[16:19]
	v_mfma_f32_16x16x32_bf16 v[4:7], v[180:183], v[224:227], v[4:7]
	v_mfma_f32_16x16x32_bf16 v[0:3], v[188:191], v[224:227], v[0:3]
	v_mfma_f32_16x16x32_bf16 v[52:55], v[184:187], v[200:203], v[52:55]
	v_mfma_f32_16x16x32_bf16 v[48:51], v[192:195], v[200:203], v[48:51]
	v_mfma_f32_16x16x32_bf16 v[36:39], v[184:187], v[208:211], v[36:39]
	v_mfma_f32_16x16x32_bf16 v[32:35], v[192:195], v[208:211], v[32:35]
	v_mfma_f32_16x16x32_bf16 v[20:23], v[184:187], v[220:223], v[20:23]
	v_mfma_f32_16x16x32_bf16 v[16:19], v[192:195], v[220:223], v[16:19]
	v_mfma_f32_16x16x32_bf16 v[4:7], v[184:187], v[228:231], v[4:7]
	v_mfma_f32_16x16x32_bf16 v[0:3], v[192:195], v[228:231], v[0:3]
	s_setprio 0
	s_barrier
	v_add_u32_e32 v176, s60, v161
	v_add_u32_e32 v192, s61, v161
	ds_read_b128 v[164:167], v176
	ds_read_b128 v[168:171], v176 offset:1024
	ds_read_b128 v[172:175], v176 offset:2048
	ds_read_b128 v[176:179], v176 offset:3072
	ds_read_b128 v[180:183], v192
	ds_read_b128 v[184:187], v192 offset:1024
	ds_read_b128 v[188:191], v192 offset:2048
	ds_read_b128 v[192:195], v192 offset:3072
	v_lshl_add_u64 v[212:213], v[212:213], 0, s[14:15]
	s_mov_b32 m0, s46
	v_lshl_add_u64 v[242:243], v[212:213], 0, v[140:141]
	ds_read_b128 v[196:199], v163 offset:32768
	ds_read_b128 v[200:203], v163 offset:33792
	ds_read_b128 v[204:207], v163 offset:34816
	ds_read_b128 v[208:211], v163 offset:35840
	ds_read_b128 v[216:219], v163 offset:36864
	ds_read_b128 v[220:223], v163 offset:37888
	ds_read_b128 v[224:227], v163 offset:38912
	ds_read_b128 v[228:231], v163 offset:39936
	global_load_lds_dwordx4 v[242:243], off
	s_mov_b32 m0, s47
	v_lshl_add_u64 v[212:213], v[212:213], 0, v[136:137]
	global_load_lds_dwordx4 v[212:213], off
	s_waitcnt vmcnt(8)
	s_waitcnt lgkmcnt(0)
	s_setprio 1
	s_barrier
	v_mfma_f32_16x16x32_bf16 v[124:127], v[164:167], v[196:199], v[124:127]
	v_mfma_f32_16x16x32_bf16 v[120:123], v[172:175], v[196:199], v[120:123]
	v_mfma_f32_16x16x32_bf16 v[108:111], v[164:167], v[204:207], v[108:111]
	v_mfma_f32_16x16x32_bf16 v[104:107], v[172:175], v[204:207], v[104:107]
	v_mfma_f32_16x16x32_bf16 v[92:95], v[164:167], v[216:219], v[92:95]
	v_mfma_f32_16x16x32_bf16 v[88:91], v[172:175], v[216:219], v[88:91]
	v_mfma_f32_16x16x32_bf16 v[76:79], v[164:167], v[224:227], v[76:79]
	v_mfma_f32_16x16x32_bf16 v[72:75], v[172:175], v[224:227], v[72:75]
	v_mfma_f32_16x16x32_bf16 v[124:127], v[168:171], v[200:203], v[124:127]
	v_mfma_f32_16x16x32_bf16 v[120:123], v[176:179], v[200:203], v[120:123]
	v_mfma_f32_16x16x32_bf16 v[108:111], v[168:171], v[208:211], v[108:111]
	v_mfma_f32_16x16x32_bf16 v[104:107], v[176:179], v[208:211], v[104:107]
	v_mfma_f32_16x16x32_bf16 v[92:95], v[168:171], v[220:223], v[92:95]
	v_mfma_f32_16x16x32_bf16 v[88:91], v[176:179], v[220:223], v[88:91]
	v_mfma_f32_16x16x32_bf16 v[76:79], v[168:171], v[228:231], v[76:79]
	v_mfma_f32_16x16x32_bf16 v[72:75], v[176:179], v[228:231], v[72:75]
	v_mfma_f32_16x16x32_bf16 v[116:119], v[180:183], v[196:199], v[116:119]
	v_mfma_f32_16x16x32_bf16 v[112:115], v[188:191], v[196:199], v[112:115]
	v_mfma_f32_16x16x32_bf16 v[100:103], v[180:183], v[204:207], v[100:103]
	v_mfma_f32_16x16x32_bf16 v[96:99], v[188:191], v[204:207], v[96:99]
	v_mfma_f32_16x16x32_bf16 v[84:87], v[180:183], v[216:219], v[84:87]
	v_mfma_f32_16x16x32_bf16 v[80:83], v[188:191], v[216:219], v[80:83]
	v_mfma_f32_16x16x32_bf16 v[68:71], v[180:183], v[224:227], v[68:71]
	v_mfma_f32_16x16x32_bf16 v[64:67], v[188:191], v[224:227], v[64:67]
	v_mfma_f32_16x16x32_bf16 v[116:119], v[184:187], v[200:203], v[116:119]
	v_mfma_f32_16x16x32_bf16 v[112:115], v[192:195], v[200:203], v[112:115]
	v_mfma_f32_16x16x32_bf16 v[100:103], v[184:187], v[208:211], v[100:103]
	v_mfma_f32_16x16x32_bf16 v[96:99], v[192:195], v[208:211], v[96:99]
	v_mfma_f32_16x16x32_bf16 v[84:87], v[184:187], v[220:223], v[84:87]
	v_mfma_f32_16x16x32_bf16 v[80:83], v[192:195], v[220:223], v[80:83]
	v_mfma_f32_16x16x32_bf16 v[68:71], v[184:187], v[228:231], v[68:71]
	v_mfma_f32_16x16x32_bf16 v[64:67], v[192:195], v[228:231], v[64:67]
	s_setprio 0
	s_barrier
; #define PG8_STAGE(bufoff, gbase, voff) do { _Pragma("unroll") for (int _i = 0; _i < 2; ++_i) \
;         __builtin_amdgcn_global_load_lds((const unsigned*)((const char*)(gbase) + (voff)[_i]), (PG8_LAS unsigned*)(lds + (bufoff) + ldsw + _i * 8192), 16, 0, 0); } while (0)
; #define PG8_LDA(dst, b, h) do { _Pragma("unroll") for (int m = 0; m < 4; ++m) _Pragma("unroll") for (int k = 0; k < 2; ++k) dst[m][k] = *(const PG8_LAS bf16x8*)(lds + PG8_SA(b, h) + aoff + m * 2048 + k * 1024); } while (0)
; #define PG8_MMA(ai, bj, At, Bt) do { __builtin_amdgcn_s_setprio(1); _Pragma("unroll") for (int m = 0; m < 4; ++m) _Pragma("unroll") for (int n = 0; n < 2; ++n) _Pragma("unroll") for (int k = 0; k < 2; ++k) \
;         acc[ai][bj][m][n] = __builtin_amdgcn_mfma_f32_16x16x32_bf16(Bt[n][k], At[m][k], acc[ai][bj][m][n], 0, 0, 0); __builtin_amdgcn_s_setprio(0); } while (0)
; #define PG8_WAIT_V(n) asm volatile("s_waitcnt vmcnt(" #n ")" ::: "memory")
; #define PG8_WAIT_L(n) asm volatile("s_waitcnt lgkmcnt(" #n ")" ::: "memory")
; #define PG8_BAR __builtin_amdgcn_s_barrier()
; #define PG8_SCHED __builtin_amdgcn_sched_barrier(0)
; template <class Epi, class Sched, bool ALIGN_EPI = false, bool SP2 = false>
; __device__ __forceinline__ void gemm_phase(PG8_LAS unsigned char* lds, const Gemm g, const Sched& S, const Epi& E) {
;     ...
;         for (int t = 0; t < nt; t += 2) {
;     ...
;             PG8_LDA(At, 1, 1); PG8_STAGE(PG8_SB(1, 0), b3, voffB); PG8_STAGE(PG8_SB(1, 1), b3 + hstep, voffB); PG8_STAGE(PG8_SA(1, 0), a3, voffA);
;             PG8_WAIT_V(8); PG8_WAIT_L(0); PG8_BAR; PG8_MMA(1, 0, At, B0); PG8_MMA(1, 1, At, B1); PG8_BAR; PG8_SCHED;
	s_mov_b32 m0, s62
	v_lshl_add_u64 v[212:213], v[232:233], 0, s[24:25]
	ds_read_b128 v[196:199], v163 offset:49152
	ds_read_b128 v[200:203], v163 offset:50176
	ds_read_b128 v[204:207], v163 offset:51200
	ds_read_b128 v[208:211], v163 offset:52224
	ds_read_b128 v[216:219], v163 offset:53248
	ds_read_b128 v[220:223], v163 offset:54272
	ds_read_b128 v[224:227], v163 offset:55296
	ds_read_b128 v[228:231], v163 offset:56320
	global_load_lds_dwordx4 v[212:213], off
	s_mov_b32 m0, s63
	v_lshl_add_u64 v[212:213], v[234:235], 0, s[24:25]
	global_load_lds_dwordx4 v[212:213], off
	s_mov_b32 m0, s64
	v_lshl_add_u64 v[212:213], v[236:237], 0, s[24:25]
	global_load_lds_dwordx4 v[212:213], off
	s_mov_b32 m0, s65
	v_lshl_add_u64 v[212:213], v[214:215], 0, s[24:25]
	global_load_lds_dwordx4 v[212:213], off
	s_mov_b32 m0, s48
	v_lshl_add_u64 v[212:213], v[238:239], 0, s[24:25]
	global_load_lds_dwordx4 v[212:213], off
	s_mov_b32 m0, s49
	v_lshl_add_u64 v[212:213], v[240:241], 0, s[24:25]
	global_load_lds_dwordx4 v[212:213], off
	s_waitcnt vmcnt(8)
	s_waitcnt lgkmcnt(0)
	s_setprio 1
	s_barrier
	v_mfma_f32_16x16x32_bf16 v[60:63], v[164:167], v[196:199], v[60:63]
	v_mfma_f32_16x16x32_bf16 v[56:59], v[172:175], v[196:199], v[56:59]
	v_mfma_f32_16x16x32_bf16 v[44:47], v[164:167], v[204:207], v[44:47]
	v_mfma_f32_16x16x32_bf16 v[40:43], v[172:175], v[204:207], v[40:43]
	v_mfma_f32_16x16x32_bf16 v[28:31], v[164:167], v[216:219], v[28:31]
	v_mfma_f32_16x16x32_bf16 v[24:27], v[172:175], v[216:219], v[24:27]
	v_mfma_f32_16x16x32_bf16 v[12:15], v[164:167], v[224:227], v[12:15]
	v_mfma_f32_16x16x32_bf16 v[8:11], v[172:175], v[224:227], v[8:11]
	v_mfma_f32_16x16x32_bf16 v[60:63], v[168:171], v[200:203], v[60:63]
	v_mfma_f32_16x16x32_bf16 v[56:59], v[176:179], v[200:203], v[56:59]
	v_mfma_f32_16x16x32_bf16 v[44:47], v[168:171], v[208:211], v[44:47]
	v_mfma_f32_16x16x32_bf16 v[40:43], v[176:179], v[208:211], v[40:43]
	v_mfma_f32_16x16x32_bf16 v[28:31], v[168:171], v[220:223], v[28:31]
	v_mfma_f32_16x16x32_bf16 v[24:27], v[176:179], v[220:223], v[24:27]
	v_mfma_f32_16x16x32_bf16 v[12:15], v[168:171], v[228:231], v[12:15]
	v_mfma_f32_16x16x32_bf16 v[8:11], v[176:179], v[228:231], v[8:11]
	v_mfma_f32_16x16x32_bf16 v[52:55], v[180:183], v[196:199], v[52:55]
	v_mfma_f32_16x16x32_bf16 v[48:51], v[188:191], v[196:199], v[48:51]
	v_mfma_f32_16x16x32_bf16 v[36:39], v[180:183], v[204:207], v[36:39]
	v_mfma_f32_16x16x32_bf16 v[32:35], v[188:191], v[204:207], v[32:35]
	v_mfma_f32_16x16x32_bf16 v[20:23], v[180:183], v[216:219], v[20:23]
	v_mfma_f32_16x16x32_bf16 v[16:19], v[188:191], v[216:219], v[16:19]
	v_mfma_f32_16x16x32_bf16 v[4:7], v[180:183], v[224:227], v[4:7]
	v_mfma_f32_16x16x32_bf16 v[0:3], v[188:191], v[224:227], v[0:3]
	v_mfma_f32_16x16x32_bf16 v[52:55], v[184:187], v[200:203], v[52:55]
	v_mfma_f32_16x16x32_bf16 v[48:51], v[192:195], v[200:203], v[48:51]
	v_mfma_f32_16x16x32_bf16 v[36:39], v[184:187], v[208:211], v[36:39]
	v_mfma_f32_16x16x32_bf16 v[32:35], v[192:195], v[208:211], v[32:35]
	v_mfma_f32_16x16x32_bf16 v[20:23], v[184:187], v[220:223], v[20:23]
	v_mfma_f32_16x16x32_bf16 v[16:19], v[192:195], v[220:223], v[16:19]
	v_mfma_f32_16x16x32_bf16 v[4:7], v[184:187], v[228:231], v[4:7]
	v_mfma_f32_16x16x32_bf16 v[0:3], v[192:195], v[228:231], v[0:3]
	s_setprio 0
	s_barrier
	v_lshl_add_u64 v[154:155], v[154:155], 0, s[28:29]
	s_cmp_ge_i32 s10, s50
	v_lshl_add_u64 v[158:159], v[158:159], 0, s[28:29]
	s_cbranch_scc0 .LBB0_1169

; #define PG8_STAGE(bufoff, gbase, voff) do { _Pragma("unroll") for (int _i = 0; _i < 2; ++_i) \
;         __builtin_amdgcn_global_load_lds((const unsigned*)((const char*)(gbase) + (voff)[_i]), (PG8_LAS unsigned*)(lds + (bufoff) + ldsw + _i * 8192), 16, 0, 0); } while (0)
; #define PG8_LDA(dst, b, h) do { _Pragma("unroll") for (int m = 0; m < 4; ++m) _Pragma("unroll") for (int k = 0; k < 2; ++k) dst[m][k] = *(const PG8_LAS bf16x8*)(lds + PG8_SA(b, h) + aoff + m * 2048 + k * 1024); } while (0)
; #define PG8_LDB(dst, b, h) do { _Pragma("unroll") for (int n = 0; n < 2; ++n) _Pragma("unroll") for (int k = 0; k < 2; ++k) dst[n][k] = *(const PG8_LAS bf16x8*)(lds + PG8_SB(b, h) + boff + n * 2048 + k * 1024); } while (0)
; #define PG8_MMA(ai, bj, At, Bt) do { __builtin_amdgcn_s_setprio(1); _Pragma("unroll") for (int m = 0; m < 4; ++m) _Pragma("unroll") for (int n = 0; n < 2; ++n) _Pragma("unroll") for (int k = 0; k < 2; ++k) \
;         acc[ai][bj][m][n] = __builtin_amdgcn_mfma_f32_16x16x32_bf16(Bt[n][k], At[m][k], acc[ai][bj][m][n], 0, 0, 0); __builtin_amdgcn_s_setprio(0); } while (0)
; #define PG8_WAIT_V(n) asm volatile("s_waitcnt vmcnt(" #n ")" ::: "memory")
; #define PG8_WAIT_L(n) asm volatile("s_waitcnt lgkmcnt(" #n ")" ::: "memory")
; #define PG8_BAR __builtin_amdgcn_s_barrier()
; #define PG8_SCHED __builtin_amdgcn_sched_barrier(0)
; template <class Epi, class Sched, bool ALIGN_EPI = false, bool SP2 = false>
; __device__ __forceinline__ void gemm_phase(PG8_LAS unsigned char* lds, const Gemm g, const Sched& S, const Epi& E) {
;     ...
;             PG8_LDB(B0, 0, 0); PG8_LDB(B1, 0, 1); PG8_SCHED; PG8_LDA(At, 0, 0); PG8_STAGE(PG8_SA(1, 1), a1 + hstep, voffA);
;             PG8_WAIT_V(8); PG8_WAIT_L(0); PG8_BAR; PG8_MMA(0, 0, At, B0); PG8_MMA(0, 1, At, B1); PG8_BAR; PG8_SCHED;
;             PG8_LDA(At, 0, 1); PG8_STAGE(PG8_SB(0, 0), b2, voffB); PG8_STAGE(PG8_SB(0, 1), b2 + hstep, voffB); PG8_STAGE(PG8_SA(0, 0), a2, voffA);
.LBB0_1192:
	v_add_u32_e32 v178, s56, v216
	v_add_u32_e32 v194, s57, v216
	ds_read_b128 v[138:141], v178
	ds_read_b128 v[142:145], v178 offset:1024
	ds_read_b128 v[146:149], v178 offset:2048
	ds_read_b128 v[178:181], v178 offset:3072
	ds_read_b128 v[182:185], v194
	ds_read_b128 v[186:189], v194 offset:1024
	ds_read_b128 v[190:193], v194 offset:2048
	ds_read_b128 v[194:197], v194 offset:3072
	s_cmp_eq_u32 s49, s10
	v_lshl_add_u64 v[198:199], v[136:137], 0, s[20:21]
	s_cselect_b64 vcc, -1, 0
	s_add_i32 s10, s10, 2
	v_cndmask_b32_e32 v215, v199, v175, vcc
	v_cndmask_b32_e32 v214, v198, v174, vcc
	v_cndmask_b32_e32 v237, v135, v177, vcc
	v_cndmask_b32_e32 v236, v134, v176, vcc
	v_lshl_add_u64 v[238:239], v[136:137], 0, v[168:169]
	s_add_i32 m0, s34, 0xc000
	ds_read_b128 v[198:201], v218
	ds_read_b128 v[202:205], v218 offset:1024
	ds_read_b128 v[206:209], v218 offset:2048
	ds_read_b128 v[210:213], v218 offset:3072
	ds_read_b128 v[220:223], v218 offset:4096
	ds_read_b128 v[224:227], v218 offset:5120
	ds_read_b128 v[228:231], v218 offset:6144
	ds_read_b128 v[232:235], v218 offset:7168
	global_load_lds_dwordx4 v[238:239], off
	s_add_i32 m0, s34, 0xe000
	v_lshl_add_u64 v[238:239], v[136:137], 0, v[166:167]
	global_load_lds_dwordx4 v[238:239], off
	s_waitcnt vmcnt(8)
	s_waitcnt lgkmcnt(0)
	s_setprio 1
	s_barrier
	v_mfma_f32_16x16x32_bf16 v[130:133], v[138:141], v[198:201], v[130:133]
	v_mfma_f32_16x16x32_bf16 v[126:129], v[146:149], v[198:201], v[126:129]
	v_mfma_f32_16x16x32_bf16 v[114:117], v[138:141], v[206:209], v[114:117]
	v_mfma_f32_16x16x32_bf16 v[110:113], v[146:149], v[206:209], v[110:113]
	v_mfma_f32_16x16x32_bf16 v[98:101], v[138:141], v[220:223], v[98:101]
	v_mfma_f32_16x16x32_bf16 v[94:97], v[146:149], v[220:223], v[94:97]
	v_mfma_f32_16x16x32_bf16 v[82:85], v[138:141], v[228:231], v[82:85]
	v_mfma_f32_16x16x32_bf16 v[78:81], v[146:149], v[228:231], v[78:81]
	v_mfma_f32_16x16x32_bf16 v[130:133], v[142:145], v[202:205], v[130:133]
	v_mfma_f32_16x16x32_bf16 v[126:129], v[178:181], v[202:205], v[126:129]
	v_mfma_f32_16x16x32_bf16 v[114:117], v[142:145], v[210:213], v[114:117]
	v_mfma_f32_16x16x32_bf16 v[110:113], v[178:181], v[210:213], v[110:113]
	v_mfma_f32_16x16x32_bf16 v[98:101], v[142:145], v[224:227], v[98:101]
	v_mfma_f32_16x16x32_bf16 v[94:97], v[178:181], v[224:227], v[94:97]
	v_mfma_f32_16x16x32_bf16 v[82:85], v[142:145], v[232:235], v[82:85]
	v_mfma_f32_16x16x32_bf16 v[78:81], v[178:181], v[232:235], v[78:81]
	v_mfma_f32_16x16x32_bf16 v[122:125], v[182:185], v[198:201], v[122:125]
	v_mfma_f32_16x16x32_bf16 v[118:121], v[190:193], v[198:201], v[118:121]
	v_mfma_f32_16x16x32_bf16 v[106:109], v[182:185], v[206:209], v[106:109]
	v_mfma_f32_16x16x32_bf16 v[102:105], v[190:193], v[206:209], v[102:105]
	v_mfma_f32_16x16x32_bf16 v[90:93], v[182:185], v[220:223], v[90:93]
	v_mfma_f32_16x16x32_bf16 v[86:89], v[190:193], v[220:223], v[86:89]
	v_mfma_f32_16x16x32_bf16 v[74:77], v[182:185], v[228:231], v[74:77]
	v_mfma_f32_16x16x32_bf16 v[70:73], v[190:193], v[228:231], v[70:73]
	v_mfma_f32_16x16x32_bf16 v[122:125], v[186:189], v[202:205], v[122:125]
	v_mfma_f32_16x16x32_bf16 v[118:121], v[194:197], v[202:205], v[118:121]
	v_mfma_f32_16x16x32_bf16 v[106:109], v[186:189], v[210:213], v[106:109]
	v_mfma_f32_16x16x32_bf16 v[102:105], v[194:197], v[210:213], v[102:105]
	v_mfma_f32_16x16x32_bf16 v[90:93], v[186:189], v[224:227], v[90:93]
	v_mfma_f32_16x16x32_bf16 v[86:89], v[194:197], v[224:227], v[86:89]
	v_mfma_f32_16x16x32_bf16 v[74:77], v[186:189], v[232:235], v[74:77]
	v_mfma_f32_16x16x32_bf16 v[70:73], v[194:197], v[232:235], v[70:73]
	s_setprio 0
	s_barrier
	s_add_i32 s11, s56, s29
	v_lshl_add_u64 v[238:239], v[236:237], 0, v[158:159]
	s_mov_b32 m0, s11
	ds_read_b128 v[198:201], v218 offset:16384
	ds_read_b128 v[202:205], v218 offset:17408
	ds_read_b128 v[206:209], v218 offset:18432
	ds_read_b128 v[210:213], v218 offset:19456
	ds_read_b128 v[220:223], v218 offset:20480
	ds_read_b128 v[224:227], v218 offset:21504
	ds_read_b128 v[228:231], v218 offset:22528
	ds_read_b128 v[232:235], v218 offset:23552
	global_load_lds_dwordx4 v[238:239], off
	v_lshl_add_u64 v[240:241], v[236:237], 0, v[162:163]
	s_add_i32 m0, s11, 0x2000
	v_lshl_add_u64 v[236:237], v[236:237], 0, s[12:13]
	s_add_i32 s11, s57, s29
	global_load_lds_dwordx4 v[240:241], off
	v_lshl_add_u64 v[242:243], v[236:237], 0, v[158:159]
	s_mov_b32 m0, s11
	v_lshl_add_u64 v[236:237], v[236:237], 0, v[162:163]
	global_load_lds_dwordx4 v[242:243], off
	s_add_i32 m0, s11, 0x2000
	v_lshl_add_u64 v[244:245], v[214:215], 0, v[154:155]
	global_load_lds_dwordx4 v[236:237], off
	s_mov_b32 m0, s34
	v_lshl_add_u64 v[246:247], v[214:215], 0, v[160:161]
	global_load_lds_dwordx4 v[244:245], off
	s_mov_b32 m0, s35
	s_nop 0
	global_load_lds_dwordx4 v[246:247], off
	s_waitcnt vmcnt(8)
	s_waitcnt lgkmcnt(0)
	s_setprio 1
	s_barrier
; #define PG8_STAGE(bufoff, gbase, voff) do { _Pragma("unroll") for (int _i = 0; _i < 2; ++_i) \
;         __builtin_amdgcn_global_load_lds((const unsigned*)((const char*)(gbase) + (voff)[_i]), (PG8_LAS unsigned*)(lds + (bufoff) + ldsw + _i * 8192), 16, 0, 0); } while (0)
; #define PG8_LDA(dst, b, h) do { _Pragma("unroll") for (int m = 0; m < 4; ++m) _Pragma("unroll") for (int k = 0; k < 2; ++k) dst[m][k] = *(const PG8_LAS bf16x8*)(lds + PG8_SA(b, h) + aoff + m * 2048 + k * 1024); } while (0)
; #define PG8_LDB(dst, b, h) do { _Pragma("unroll") for (int n = 0; n < 2; ++n) _Pragma("unroll") for (int k = 0; k < 2; ++k) dst[n][k] = *(const PG8_LAS bf16x8*)(lds + PG8_SB(b, h) + boff + n * 2048 + k * 1024); } while (0)
; #define PG8_MMA(ai, bj, At, Bt) do { __builtin_amdgcn_s_setprio(1); _Pragma("unroll") for (int m = 0; m < 4; ++m) _Pragma("unroll") for (int n = 0; n < 2; ++n) _Pragma("unroll") for (int k = 0; k < 2; ++k) \
;         acc[ai][bj][m][n] = __builtin_amdgcn_mfma_f32_16x16x32_bf16(Bt[n][k], At[m][k], acc[ai][bj][m][n], 0, 0, 0); __builtin_amdgcn_s_setprio(0); } while (0)
; #define PG8_WAIT_V(n) asm volatile("s_waitcnt vmcnt(" #n ")" ::: "memory")
; #define PG8_WAIT_L(n) asm volatile("s_waitcnt lgkmcnt(" #n ")" ::: "memory")
; #define PG8_BAR __builtin_amdgcn_s_barrier()
; #define PG8_SCHED __builtin_amdgcn_sched_barrier(0)
; template <class Epi, class Sched, bool ALIGN_EPI = false, bool SP2 = false>
; __device__ __forceinline__ void gemm_phase(PG8_LAS unsigned char* lds, const Gemm g, const Sched& S, const Epi& E) {
;     ...
;             PG8_WAIT_V(8); PG8_WAIT_L(0); PG8_BAR; PG8_MMA(1, 0, At, B0); PG8_MMA(1, 1, At, B1); PG8_BAR; PG8_SCHED;
;             PG8_LDB(B0, 1, 0); PG8_LDB(B1, 1, 1); PG8_SCHED; PG8_LDA(At, 1, 0); PG8_STAGE(PG8_SA(0, 1), a2 + hstep, voffA);
;             PG8_WAIT_V(8); PG8_WAIT_L(0); PG8_BAR; PG8_MMA(0, 0, At, B0); PG8_MMA(0, 1, At, B1); PG8_BAR; PG8_SCHED;
	v_mfma_f32_16x16x32_bf16 v[66:69], v[138:141], v[198:201], v[66:69]
	v_mfma_f32_16x16x32_bf16 v[62:65], v[146:149], v[198:201], v[62:65]
	v_mfma_f32_16x16x32_bf16 v[50:53], v[138:141], v[206:209], v[50:53]
	v_mfma_f32_16x16x32_bf16 v[46:49], v[146:149], v[206:209], v[46:49]
	v_mfma_f32_16x16x32_bf16 v[34:37], v[138:141], v[220:223], v[34:37]
	v_mfma_f32_16x16x32_bf16 v[30:33], v[146:149], v[220:223], v[30:33]
	v_mfma_f32_16x16x32_bf16 v[18:21], v[138:141], v[228:231], v[18:21]
	v_mfma_f32_16x16x32_bf16 v[14:17], v[146:149], v[228:231], v[14:17]
	v_mfma_f32_16x16x32_bf16 v[66:69], v[142:145], v[202:205], v[66:69]
	v_mfma_f32_16x16x32_bf16 v[62:65], v[178:181], v[202:205], v[62:65]
	v_mfma_f32_16x16x32_bf16 v[50:53], v[142:145], v[210:213], v[50:53]
	v_mfma_f32_16x16x32_bf16 v[46:49], v[178:181], v[210:213], v[46:49]
	v_mfma_f32_16x16x32_bf16 v[34:37], v[142:145], v[224:227], v[34:37]
	v_mfma_f32_16x16x32_bf16 v[30:33], v[178:181], v[224:227], v[30:33]
	v_mfma_f32_16x16x32_bf16 v[18:21], v[142:145], v[232:235], v[18:21]
	v_mfma_f32_16x16x32_bf16 v[14:17], v[178:181], v[232:235], v[14:17]
	v_mfma_f32_16x16x32_bf16 v[58:61], v[182:185], v[198:201], v[58:61]
	v_mfma_f32_16x16x32_bf16 v[54:57], v[190:193], v[198:201], v[54:57]
	v_mfma_f32_16x16x32_bf16 v[42:45], v[182:185], v[206:209], v[42:45]
	v_mfma_f32_16x16x32_bf16 v[38:41], v[190:193], v[206:209], v[38:41]
	v_mfma_f32_16x16x32_bf16 v[26:29], v[182:185], v[220:223], v[26:29]
	v_mfma_f32_16x16x32_bf16 v[22:25], v[190:193], v[220:223], v[22:25]
	v_mfma_f32_16x16x32_bf16 v[10:13], v[182:185], v[228:231], v[10:13]
	v_mfma_f32_16x16x32_bf16 v[6:9], v[190:193], v[228:231], v[6:9]
	v_mfma_f32_16x16x32_bf16 v[58:61], v[186:189], v[202:205], v[58:61]
	v_mfma_f32_16x16x32_bf16 v[54:57], v[194:197], v[202:205], v[54:57]
	v_mfma_f32_16x16x32_bf16 v[42:45], v[186:189], v[210:213], v[42:45]
	v_mfma_f32_16x16x32_bf16 v[38:41], v[194:197], v[210:213], v[38:41]
	v_mfma_f32_16x16x32_bf16 v[26:29], v[186:189], v[224:227], v[26:29]
	v_mfma_f32_16x16x32_bf16 v[22:25], v[194:197], v[224:227], v[22:25]
	v_mfma_f32_16x16x32_bf16 v[10:13], v[186:189], v[232:235], v[10:13]
	v_mfma_f32_16x16x32_bf16 v[6:9], v[194:197], v[232:235], v[6:9]
	s_setprio 0
	s_barrier
	s_add_i32 s11, 0, 0x18000
	s_add_i32 s31, 0, 0x1c000
	v_add_u32_e32 v178, s11, v216
	v_add_u32_e32 v194, s31, v216
	ds_read_b128 v[138:141], v178
	ds_read_b128 v[142:145], v178 offset:1024
	ds_read_b128 v[146:149], v178 offset:2048
	ds_read_b128 v[178:181], v178 offset:3072
	ds_read_b128 v[182:185], v194
	ds_read_b128 v[186:189], v194 offset:1024
	ds_read_b128 v[190:193], v194 offset:2048
	ds_read_b128 v[194:197], v194 offset:3072
	v_lshl_add_u64 v[214:215], v[214:215], 0, s[12:13]
	s_mov_b32 m0, s36
	v_lshl_add_u64 v[248:249], v[214:215], 0, v[154:155]
	ds_read_b128 v[198:201], v218 offset:32768
	ds_read_b128 v[202:205], v218 offset:33792
	ds_read_b128 v[206:209], v218 offset:34816
	ds_read_b128 v[210:213], v218 offset:35840
	ds_read_b128 v[220:223], v218 offset:36864
	ds_read_b128 v[224:227], v218 offset:37888
	ds_read_b128 v[228:231], v218 offset:38912
	ds_read_b128 v[232:235], v218 offset:39936
	global_load_lds_dwordx4 v[248:249], off
	s_mov_b32 m0, s37
	v_lshl_add_u64 v[214:215], v[214:215], 0, v[160:161]
	global_load_lds_dwordx4 v[214:215], off
	s_waitcnt vmcnt(8)
	s_waitcnt lgkmcnt(0)
	s_setprio 1
	s_barrier
	v_mfma_f32_16x16x32_bf16 v[130:133], v[138:141], v[198:201], v[130:133]
	v_mfma_f32_16x16x32_bf16 v[126:129], v[146:149], v[198:201], v[126:129]
	v_mfma_f32_16x16x32_bf16 v[114:117], v[138:141], v[206:209], v[114:117]
	v_mfma_f32_16x16x32_bf16 v[110:113], v[146:149], v[206:209], v[110:113]
	v_mfma_f32_16x16x32_bf16 v[98:101], v[138:141], v[220:223], v[98:101]
	v_mfma_f32_16x16x32_bf16 v[94:97], v[146:149], v[220:223], v[94:97]
	v_mfma_f32_16x16x32_bf16 v[82:85], v[138:141], v[228:231], v[82:85]
	v_mfma_f32_16x16x32_bf16 v[78:81], v[146:149], v[228:231], v[78:81]
	v_mfma_f32_16x16x32_bf16 v[130:133], v[142:145], v[202:205], v[130:133]
	v_mfma_f32_16x16x32_bf16 v[126:129], v[178:181], v[202:205], v[126:129]
	v_mfma_f32_16x16x32_bf16 v[114:117], v[142:145], v[210:213], v[114:117]
	v_mfma_f32_16x16x32_bf16 v[110:113], v[178:181], v[210:213], v[110:113]
	v_mfma_f32_16x16x32_bf16 v[98:101], v[142:145], v[224:227], v[98:101]
	v_mfma_f32_16x16x32_bf16 v[94:97], v[178:181], v[224:227], v[94:97]
	v_mfma_f32_16x16x32_bf16 v[82:85], v[142:145], v[232:235], v[82:85]
	v_mfma_f32_16x16x32_bf16 v[78:81], v[178:181], v[232:235], v[78:81]
	v_mfma_f32_16x16x32_bf16 v[122:125], v[182:185], v[198:201], v[122:125]
	v_mfma_f32_16x16x32_bf16 v[118:121], v[190:193], v[198:201], v[118:121]
	v_mfma_f32_16x16x32_bf16 v[106:109], v[182:185], v[206:209], v[106:109]
	v_mfma_f32_16x16x32_bf16 v[102:105], v[190:193], v[206:209], v[102:105]
	v_mfma_f32_16x16x32_bf16 v[90:93], v[182:185], v[220:223], v[90:93]
	v_mfma_f32_16x16x32_bf16 v[86:89], v[190:193], v[220:223], v[86:89]
	v_mfma_f32_16x16x32_bf16 v[74:77], v[182:185], v[228:231], v[74:77]
	v_mfma_f32_16x16x32_bf16 v[70:73], v[190:193], v[228:231], v[70:73]
	v_mfma_f32_16x16x32_bf16 v[122:125], v[186:189], v[202:205], v[122:125]
	v_mfma_f32_16x16x32_bf16 v[118:121], v[194:197], v[202:205], v[118:121]
	v_mfma_f32_16x16x32_bf16 v[106:109], v[186:189], v[210:213], v[106:109]
	v_mfma_f32_16x16x32_bf16 v[102:105], v[194:197], v[210:213], v[102:105]
	v_mfma_f32_16x16x32_bf16 v[90:93], v[186:189], v[224:227], v[90:93]
	v_mfma_f32_16x16x32_bf16 v[86:89], v[194:197], v[224:227], v[86:89]
	v_mfma_f32_16x16x32_bf16 v[74:77], v[186:189], v[232:235], v[74:77]
	v_mfma_f32_16x16x32_bf16 v[70:73], v[194:197], v[232:235], v[70:73]
	s_setprio 0
	s_barrier
; #define PG8_STAGE(bufoff, gbase, voff) do { _Pragma("unroll") for (int _i = 0; _i < 2; ++_i) \
;         __builtin_amdgcn_global_load_lds((const unsigned*)((const char*)(gbase) + (voff)[_i]), (PG8_LAS unsigned*)(lds + (bufoff) + ldsw + _i * 8192), 16, 0, 0); } while (0)
; #define PG8_LDA(dst, b, h) do { _Pragma("unroll") for (int m = 0; m < 4; ++m) _Pragma("unroll") for (int k = 0; k < 2; ++k) dst[m][k] = *(const PG8_LAS bf16x8*)(lds + PG8_SA(b, h) + aoff + m * 2048 + k * 1024); } while (0)
; #define PG8_MMA(ai, bj, At, Bt) do { __builtin_amdgcn_s_setprio(1); _Pragma("unroll") for (int m = 0; m < 4; ++m) _Pragma("unroll") for (int n = 0; n < 2; ++n) _Pragma("unroll") for (int k = 0; k < 2; ++k) \
;         acc[ai][bj][m][n] = __builtin_amdgcn_mfma_f32_16x16x32_bf16(Bt[n][k], At[m][k], acc[ai][bj][m][n], 0, 0, 0); __builtin_amdgcn_s_setprio(0); } while (0)
; #define PG8_WAIT_V(n) asm volatile("s_waitcnt vmcnt(" #n ")" ::: "memory")
; #define PG8_WAIT_L(n) asm volatile("s_waitcnt lgkmcnt(" #n ")" ::: "memory")
; #define PG8_BAR __builtin_amdgcn_s_barrier()
; #define PG8_SCHED __builtin_amdgcn_sched_barrier(0)
; template <class Epi, class Sched, bool ALIGN_EPI = false, bool SP2 = false>
; __device__ __forceinline__ void gemm_phase(PG8_LAS unsigned char* lds, const Gemm g, const Sched& S, const Epi& E) {
;     ...
;         for (int t = 0; t < nt; t += 2) {
;     ...
;             PG8_LDA(At, 1, 1); PG8_STAGE(PG8_SB(1, 0), b3, voffB); PG8_STAGE(PG8_SB(1, 1), b3 + hstep, voffB); PG8_STAGE(PG8_SA(1, 0), a3, voffA);
;             PG8_WAIT_V(8); PG8_WAIT_L(0); PG8_BAR; PG8_MMA(1, 0, At, B0); PG8_MMA(1, 1, At, B1); PG8_BAR; PG8_SCHED;
	s_add_i32 s11, s11, s29
	v_lshl_add_u64 v[214:215], v[238:239], 0, s[20:21]
	s_mov_b32 m0, s11
	ds_read_b128 v[198:201], v218 offset:49152
	ds_read_b128 v[202:205], v218 offset:50176
	ds_read_b128 v[206:209], v218 offset:51200
	ds_read_b128 v[210:213], v218 offset:52224
	ds_read_b128 v[220:223], v218 offset:53248
	ds_read_b128 v[224:227], v218 offset:54272
	ds_read_b128 v[228:231], v218 offset:55296
	ds_read_b128 v[232:235], v218 offset:56320
	global_load_lds_dwordx4 v[214:215], off
	v_lshl_add_u64 v[214:215], v[240:241], 0, s[20:21]
	s_add_i32 m0, s11, 0x2000
	s_add_i32 s11, s31, s29
	global_load_lds_dwordx4 v[214:215], off
	s_mov_b32 m0, s11
	v_lshl_add_u64 v[214:215], v[242:243], 0, s[20:21]
	global_load_lds_dwordx4 v[214:215], off
	s_add_i32 m0, s11, 0x2000
	v_lshl_add_u64 v[214:215], v[236:237], 0, s[20:21]
	global_load_lds_dwordx4 v[214:215], off
	s_mov_b32 m0, s41
	v_lshl_add_u64 v[214:215], v[244:245], 0, s[20:21]
	global_load_lds_dwordx4 v[214:215], off
	s_mov_b32 m0, s46
	v_lshl_add_u64 v[214:215], v[246:247], 0, s[20:21]
	global_load_lds_dwordx4 v[214:215], off
	s_waitcnt vmcnt(8)
	s_waitcnt lgkmcnt(0)
	s_setprio 1
	s_barrier
	v_mfma_f32_16x16x32_bf16 v[66:69], v[138:141], v[198:201], v[66:69]
	v_mfma_f32_16x16x32_bf16 v[62:65], v[146:149], v[198:201], v[62:65]
	v_mfma_f32_16x16x32_bf16 v[50:53], v[138:141], v[206:209], v[50:53]
	v_mfma_f32_16x16x32_bf16 v[46:49], v[146:149], v[206:209], v[46:49]
	v_mfma_f32_16x16x32_bf16 v[34:37], v[138:141], v[220:223], v[34:37]
	v_mfma_f32_16x16x32_bf16 v[30:33], v[146:149], v[220:223], v[30:33]
	v_mfma_f32_16x16x32_bf16 v[18:21], v[138:141], v[228:231], v[18:21]
	v_mfma_f32_16x16x32_bf16 v[14:17], v[146:149], v[228:231], v[14:17]
	v_mfma_f32_16x16x32_bf16 v[66:69], v[142:145], v[202:205], v[66:69]
	v_mfma_f32_16x16x32_bf16 v[62:65], v[178:181], v[202:205], v[62:65]
	v_mfma_f32_16x16x32_bf16 v[50:53], v[142:145], v[210:213], v[50:53]
	v_mfma_f32_16x16x32_bf16 v[46:49], v[178:181], v[210:213], v[46:49]
	v_mfma_f32_16x16x32_bf16 v[34:37], v[142:145], v[224:227], v[34:37]
	v_mfma_f32_16x16x32_bf16 v[30:33], v[178:181], v[224:227], v[30:33]
	v_mfma_f32_16x16x32_bf16 v[18:21], v[142:145], v[232:235], v[18:21]
	v_mfma_f32_16x16x32_bf16 v[14:17], v[178:181], v[232:235], v[14:17]
	v_mfma_f32_16x16x32_bf16 v[58:61], v[182:185], v[198:201], v[58:61]
	v_mfma_f32_16x16x32_bf16 v[54:57], v[190:193], v[198:201], v[54:57]
	v_mfma_f32_16x16x32_bf16 v[42:45], v[182:185], v[206:209], v[42:45]
	v_mfma_f32_16x16x32_bf16 v[38:41], v[190:193], v[206:209], v[38:41]
	v_mfma_f32_16x16x32_bf16 v[26:29], v[182:185], v[220:223], v[26:29]
	v_mfma_f32_16x16x32_bf16 v[22:25], v[190:193], v[220:223], v[22:25]
	v_mfma_f32_16x16x32_bf16 v[10:13], v[182:185], v[228:231], v[10:13]
	v_mfma_f32_16x16x32_bf16 v[6:9], v[190:193], v[228:231], v[6:9]
	v_mfma_f32_16x16x32_bf16 v[58:61], v[186:189], v[202:205], v[58:61]
	v_mfma_f32_16x16x32_bf16 v[54:57], v[194:197], v[202:205], v[54:57]
	v_mfma_f32_16x16x32_bf16 v[42:45], v[186:189], v[210:213], v[42:45]
	v_mfma_f32_16x16x32_bf16 v[38:41], v[194:197], v[210:213], v[38:41]
	v_mfma_f32_16x16x32_bf16 v[26:29], v[186:189], v[224:227], v[26:29]
	v_mfma_f32_16x16x32_bf16 v[22:25], v[194:197], v[224:227], v[22:25]
	v_mfma_f32_16x16x32_bf16 v[10:13], v[186:189], v[232:235], v[10:13]
	v_mfma_f32_16x16x32_bf16 v[6:9], v[194:197], v[232:235], v[6:9]
	s_setprio 0
	s_barrier
	v_lshl_add_u64 v[134:135], v[134:135], 0, s[26:27]
	s_cmp_ge_i32 s10, s48
	v_lshl_add_u64 v[136:137], v[136:137], 0, s[26:27]
	s_cbranch_scc0 .LBB0_1192

; #define PG8_STAGE(bufoff, gbase, voff) do { _Pragma("unroll") for (int _i = 0; _i < 2; ++_i) \
;         __builtin_amdgcn_global_load_lds((const unsigned*)((const char*)(gbase) + (voff)[_i]), (PG8_LAS unsigned*)(lds + (bufoff) + ldsw + _i * 8192), 16, 0, 0); } while (0)
; #define PG8_LDA(dst, b, h) do { _Pragma("unroll") for (int m = 0; m < 4; ++m) _Pragma("unroll") for (int k = 0; k < 2; ++k) dst[m][k] = *(const PG8_LAS bf16x8*)(lds + PG8_SA(b, h) + aoff + m * 2048 + k * 1024); } while (0)
; #define PG8_LDB(dst, b, h) do { _Pragma("unroll") for (int n = 0; n < 2; ++n) _Pragma("unroll") for (int k = 0; k < 2; ++k) dst[n][k] = *(const PG8_LAS bf16x8*)(lds + PG8_SB(b, h) + boff + n * 2048 + k * 1024); } while (0)
; #define PG8_MMA(ai, bj, At, Bt) do { __builtin_amdgcn_s_setprio(1); _Pragma("unroll") for (int m = 0; m < 4; ++m) _Pragma("unroll") for (int n = 0; n < 2; ++n) _Pragma("unroll") for (int k = 0; k < 2; ++k) \
;         acc[ai][bj][m][n] = __builtin_amdgcn_mfma_f32_16x16x32_bf16(Bt[n][k], At[m][k], acc[ai][bj][m][n], 0, 0, 0); __builtin_amdgcn_s_setprio(0); } while (0)
; #define PG8_WAIT_V(n) asm volatile("s_waitcnt vmcnt(" #n ")" ::: "memory")
; #define PG8_WAIT_L(n) asm volatile("s_waitcnt lgkmcnt(" #n ")" ::: "memory")
; #define PG8_BAR __builtin_amdgcn_s_barrier()
; #define PG8_SCHED __builtin_amdgcn_sched_barrier(0)
; template <class Epi, class Sched, bool ALIGN_EPI = false, bool SP2 = false>
; __device__ __forceinline__ void gemm_phase(PG8_LAS unsigned char* lds, const Gemm g, const Sched& S, const Epi& E) {
;     ...
;             PG8_LDB(B0, 0, 0); PG8_LDB(B1, 0, 1); PG8_SCHED; PG8_LDA(At, 0, 0); PG8_STAGE(PG8_SA(1, 1), a1 + hstep, voffA);
;             PG8_WAIT_V(8); PG8_WAIT_L(0); PG8_BAR; PG8_MMA(0, 0, At, B0); PG8_MMA(0, 1, At, B1); PG8_BAR; PG8_SCHED;
;             PG8_LDA(At, 0, 1); PG8_STAGE(PG8_SB(0, 0), b2, voffB); PG8_STAGE(PG8_SB(0, 1), b2 + hstep, voffB); PG8_STAGE(PG8_SA(0, 0), a2, voffA);
.LBB0_1340:
	v_add_u32_e32 v148, s55, v201
	v_add_u32_e32 v190, s56, v201
	ds_read_b128 v[136:139], v148
	ds_read_b128 v[140:143], v148 offset:1024
	ds_read_b128 v[144:147], v148 offset:2048
	ds_read_b128 v[148:151], v148 offset:3072
	ds_read_b128 v[152:155], v190
	ds_read_b128 v[182:185], v190 offset:1024
	ds_read_b128 v[186:189], v190 offset:2048
	ds_read_b128 v[190:193], v190 offset:3072
	s_cmp_eq_u32 s48, s12
	v_lshl_add_u64 v[194:195], v[134:135], 0, s[22:23]
	s_cselect_b64 vcc, -1, 0
	s_add_i32 s12, s12, 2
	v_cndmask_b32_e32 v199, v195, v179, vcc
	v_cndmask_b32_e32 v198, v194, v178, vcc
	v_cndmask_b32_e32 v215, v133, v181, vcc
	v_cndmask_b32_e32 v214, v132, v180, vcc
	s_mov_b32 m0, s57
	v_lshl_add_u64 v[236:237], v[134:135], 0, v[174:175]
	ds_read_b128 v[194:197], v203
	ds_read_b128 v[206:209], v203 offset:1024
	ds_read_b128 v[210:213], v203 offset:2048
	ds_read_b128 v[216:219], v203 offset:3072
	ds_read_b128 v[220:223], v203 offset:4096
	ds_read_b128 v[224:227], v203 offset:5120
	ds_read_b128 v[228:231], v203 offset:6144
	ds_read_b128 v[232:235], v203 offset:7168
	global_load_lds_dwordx4 v[236:237], off
	s_mov_b32 m0, s58
	v_lshl_add_u64 v[236:237], v[134:135], 0, v[172:173]
	global_load_lds_dwordx4 v[236:237], off
	s_waitcnt vmcnt(8)
	s_waitcnt lgkmcnt(0)
	s_setprio 1
	s_barrier
	v_mfma_f32_16x16x32_bf16 v[124:127], v[136:139], v[194:197], v[124:127]
	v_mfma_f32_16x16x32_bf16 v[128:131], v[144:147], v[194:197], v[128:131]
	v_mfma_f32_16x16x32_bf16 v[112:115], v[136:139], v[210:213], v[112:115]
	v_mfma_f32_16x16x32_bf16 v[108:111], v[144:147], v[210:213], v[108:111]
	v_mfma_f32_16x16x32_bf16 v[96:99], v[136:139], v[220:223], v[96:99]
	v_mfma_f32_16x16x32_bf16 v[92:95], v[144:147], v[220:223], v[92:95]
	v_mfma_f32_16x16x32_bf16 v[80:83], v[136:139], v[228:231], v[80:83]
	v_mfma_f32_16x16x32_bf16 v[76:79], v[144:147], v[228:231], v[76:79]
	v_mfma_f32_16x16x32_bf16 v[124:127], v[140:143], v[206:209], v[124:127]
	v_mfma_f32_16x16x32_bf16 v[128:131], v[148:151], v[206:209], v[128:131]
	v_mfma_f32_16x16x32_bf16 v[112:115], v[140:143], v[216:219], v[112:115]
	v_mfma_f32_16x16x32_bf16 v[108:111], v[148:151], v[216:219], v[108:111]
	v_mfma_f32_16x16x32_bf16 v[96:99], v[140:143], v[224:227], v[96:99]
	v_mfma_f32_16x16x32_bf16 v[92:95], v[148:151], v[224:227], v[92:95]
	v_mfma_f32_16x16x32_bf16 v[80:83], v[140:143], v[232:235], v[80:83]
	v_mfma_f32_16x16x32_bf16 v[76:79], v[148:151], v[232:235], v[76:79]
	v_mfma_f32_16x16x32_bf16 v[120:123], v[152:155], v[194:197], v[120:123]
	v_mfma_f32_16x16x32_bf16 v[116:119], v[186:189], v[194:197], v[116:119]
	v_mfma_f32_16x16x32_bf16 v[104:107], v[152:155], v[210:213], v[104:107]
	v_mfma_f32_16x16x32_bf16 v[100:103], v[186:189], v[210:213], v[100:103]
	v_mfma_f32_16x16x32_bf16 v[88:91], v[152:155], v[220:223], v[88:91]
	v_mfma_f32_16x16x32_bf16 v[84:87], v[186:189], v[220:223], v[84:87]
	v_mfma_f32_16x16x32_bf16 v[72:75], v[152:155], v[228:231], v[72:75]
	v_mfma_f32_16x16x32_bf16 v[68:71], v[186:189], v[228:231], v[68:71]
	v_mfma_f32_16x16x32_bf16 v[120:123], v[182:185], v[206:209], v[120:123]
	v_mfma_f32_16x16x32_bf16 v[116:119], v[190:193], v[206:209], v[116:119]
	v_mfma_f32_16x16x32_bf16 v[104:107], v[182:185], v[216:219], v[104:107]
	v_mfma_f32_16x16x32_bf16 v[100:103], v[190:193], v[216:219], v[100:103]
	v_mfma_f32_16x16x32_bf16 v[88:91], v[182:185], v[224:227], v[88:91]
	v_mfma_f32_16x16x32_bf16 v[84:87], v[190:193], v[224:227], v[84:87]
	v_mfma_f32_16x16x32_bf16 v[72:75], v[182:185], v[232:235], v[72:75]
	v_mfma_f32_16x16x32_bf16 v[68:71], v[190:193], v[232:235], v[68:71]
	s_setprio 0
	s_barrier
	s_mov_b32 m0, s59
	v_lshl_add_u64 v[236:237], v[214:215], 0, v[166:167]
	ds_read_b128 v[194:197], v203 offset:16384
	ds_read_b128 v[206:209], v203 offset:17408
	ds_read_b128 v[210:213], v203 offset:18432
	ds_read_b128 v[216:219], v203 offset:19456
	ds_read_b128 v[220:223], v203 offset:20480
	ds_read_b128 v[224:227], v203 offset:21504
	ds_read_b128 v[228:231], v203 offset:22528
	ds_read_b128 v[232:235], v203 offset:23552
	global_load_lds_dwordx4 v[236:237], off
	v_lshl_add_u64 v[238:239], v[214:215], 0, v[170:171]
	s_mov_b32 m0, s60
	v_lshl_add_u64 v[214:215], v[214:215], 0, s[14:15]
	s_add_i32 s13, s56, s30
	global_load_lds_dwordx4 v[238:239], off
	v_lshl_add_u64 v[240:241], v[214:215], 0, v[166:167]
	s_mov_b32 m0, s13
	v_lshl_add_u64 v[214:215], v[214:215], 0, v[170:171]
	global_load_lds_dwordx4 v[240:241], off
	s_add_i32 m0, s13, 0x2000
	v_lshl_add_u64 v[242:243], v[198:199], 0, v[164:165]
	global_load_lds_dwordx4 v[214:215], off
	s_mov_b32 m0, s31
	v_lshl_add_u64 v[244:245], v[198:199], 0, v[168:169]
	global_load_lds_dwordx4 v[242:243], off
	s_mov_b32 m0, s34
	s_nop 0
	global_load_lds_dwordx4 v[244:245], off
	s_waitcnt vmcnt(8)
	s_waitcnt lgkmcnt(0)
	s_setprio 1
	s_barrier
; #define PG8_STAGE(bufoff, gbase, voff) do { _Pragma("unroll") for (int _i = 0; _i < 2; ++_i) \
;         __builtin_amdgcn_global_load_lds((const unsigned*)((const char*)(gbase) + (voff)[_i]), (PG8_LAS unsigned*)(lds + (bufoff) + ldsw + _i * 8192), 16, 0, 0); } while (0)
; #define PG8_LDA(dst, b, h) do { _Pragma("unroll") for (int m = 0; m < 4; ++m) _Pragma("unroll") for (int k = 0; k < 2; ++k) dst[m][k] = *(const PG8_LAS bf16x8*)(lds + PG8_SA(b, h) + aoff + m * 2048 + k * 1024); } while (0)
; #define PG8_LDB(dst, b, h) do { _Pragma("unroll") for (int n = 0; n < 2; ++n) _Pragma("unroll") for (int k = 0; k < 2; ++k) dst[n][k] = *(const PG8_LAS bf16x8*)(lds + PG8_SB(b, h) + boff + n * 2048 + k * 1024); } while (0)
; #define PG8_MMA(ai, bj, At, Bt) do { __builtin_amdgcn_s_setprio(1); _Pragma("unroll") for (int m = 0; m < 4; ++m) _Pragma("unroll") for (int n = 0; n < 2; ++n) _Pragma("unroll") for (int k = 0; k < 2; ++k) \
;         acc[ai][bj][m][n] = __builtin_amdgcn_mfma_f32_16x16x32_bf16(Bt[n][k], At[m][k], acc[ai][bj][m][n], 0, 0, 0); __builtin_amdgcn_s_setprio(0); } while (0)
; #define PG8_WAIT_V(n) asm volatile("s_waitcnt vmcnt(" #n ")" ::: "memory")
; #define PG8_WAIT_L(n) asm volatile("s_waitcnt lgkmcnt(" #n ")" ::: "memory")
; #define PG8_BAR __builtin_amdgcn_s_barrier()
; #define PG8_SCHED __builtin_amdgcn_sched_barrier(0)
; template <class Epi, class Sched, bool ALIGN_EPI = false, bool SP2 = false>
; __device__ __forceinline__ void gemm_phase(PG8_LAS unsigned char* lds, const Gemm g, const Sched& S, const Epi& E) {
;     ...
;             PG8_WAIT_V(8); PG8_WAIT_L(0); PG8_BAR; PG8_MMA(1, 0, At, B0); PG8_MMA(1, 1, At, B1); PG8_BAR; PG8_SCHED;
;             PG8_LDB(B0, 1, 0); PG8_LDB(B1, 1, 1); PG8_SCHED; PG8_LDA(At, 1, 0); PG8_STAGE(PG8_SA(0, 1), a2 + hstep, voffA);
;             PG8_WAIT_V(8); PG8_WAIT_L(0); PG8_BAR; PG8_MMA(0, 0, At, B0); PG8_MMA(0, 1, At, B1); PG8_BAR; PG8_SCHED;
	v_mfma_f32_16x16x32_bf16 v[64:67], v[136:139], v[194:197], v[64:67]
	v_mfma_f32_16x16x32_bf16 v[60:63], v[144:147], v[194:197], v[60:63]
	v_mfma_f32_16x16x32_bf16 v[48:51], v[136:139], v[210:213], v[48:51]
	v_mfma_f32_16x16x32_bf16 v[44:47], v[144:147], v[210:213], v[44:47]
	v_mfma_f32_16x16x32_bf16 v[32:35], v[136:139], v[220:223], v[32:35]
	v_mfma_f32_16x16x32_bf16 v[28:31], v[144:147], v[220:223], v[28:31]
	v_mfma_f32_16x16x32_bf16 v[16:19], v[136:139], v[228:231], v[16:19]
	v_mfma_f32_16x16x32_bf16 v[12:15], v[144:147], v[228:231], v[12:15]
	v_mfma_f32_16x16x32_bf16 v[64:67], v[140:143], v[206:209], v[64:67]
	v_mfma_f32_16x16x32_bf16 v[60:63], v[148:151], v[206:209], v[60:63]
	v_mfma_f32_16x16x32_bf16 v[48:51], v[140:143], v[216:219], v[48:51]
	v_mfma_f32_16x16x32_bf16 v[44:47], v[148:151], v[216:219], v[44:47]
	v_mfma_f32_16x16x32_bf16 v[32:35], v[140:143], v[224:227], v[32:35]
	v_mfma_f32_16x16x32_bf16 v[28:31], v[148:151], v[224:227], v[28:31]
	v_mfma_f32_16x16x32_bf16 v[16:19], v[140:143], v[232:235], v[16:19]
	v_mfma_f32_16x16x32_bf16 v[12:15], v[148:151], v[232:235], v[12:15]
	v_mfma_f32_16x16x32_bf16 v[56:59], v[152:155], v[194:197], v[56:59]
	v_mfma_f32_16x16x32_bf16 v[52:55], v[186:189], v[194:197], v[52:55]
	v_mfma_f32_16x16x32_bf16 v[40:43], v[152:155], v[210:213], v[40:43]
	v_mfma_f32_16x16x32_bf16 v[36:39], v[186:189], v[210:213], v[36:39]
	v_mfma_f32_16x16x32_bf16 v[24:27], v[152:155], v[220:223], v[24:27]
	v_mfma_f32_16x16x32_bf16 v[20:23], v[186:189], v[220:223], v[20:23]
	v_mfma_f32_16x16x32_bf16 v[8:11], v[152:155], v[228:231], v[8:11]
	v_mfma_f32_16x16x32_bf16 v[4:7], v[186:189], v[228:231], v[4:7]
	v_mfma_f32_16x16x32_bf16 v[56:59], v[182:185], v[206:209], v[56:59]
	v_mfma_f32_16x16x32_bf16 v[52:55], v[190:193], v[206:209], v[52:55]
	v_mfma_f32_16x16x32_bf16 v[40:43], v[182:185], v[216:219], v[40:43]
	v_mfma_f32_16x16x32_bf16 v[36:39], v[190:193], v[216:219], v[36:39]
	v_mfma_f32_16x16x32_bf16 v[24:27], v[182:185], v[224:227], v[24:27]
	v_mfma_f32_16x16x32_bf16 v[20:23], v[190:193], v[224:227], v[20:23]
	v_mfma_f32_16x16x32_bf16 v[8:11], v[182:185], v[232:235], v[8:11]
	v_mfma_f32_16x16x32_bf16 v[4:7], v[190:193], v[232:235], v[4:7]
	s_setprio 0
	s_barrier
	s_add_i32 s13, 0, 0x18000
	s_add_i32 s29, 0, 0x1c000
	v_add_u32_e32 v148, s13, v201
	v_add_u32_e32 v190, s29, v201
	ds_read_b128 v[136:139], v148
	ds_read_b128 v[140:143], v148 offset:1024
	ds_read_b128 v[144:147], v148 offset:2048
	ds_read_b128 v[148:151], v148 offset:3072
	ds_read_b128 v[152:155], v190
	ds_read_b128 v[182:185], v190 offset:1024
	ds_read_b128 v[186:189], v190 offset:2048
	ds_read_b128 v[190:193], v190 offset:3072
	v_lshl_add_u64 v[198:199], v[198:199], 0, s[14:15]
	s_mov_b32 m0, s35
	v_lshl_add_u64 v[246:247], v[198:199], 0, v[164:165]
	ds_read_b128 v[194:197], v203 offset:32768
	ds_read_b128 v[206:209], v203 offset:33792
	ds_read_b128 v[210:213], v203 offset:34816
	ds_read_b128 v[216:219], v203 offset:35840
	ds_read_b128 v[220:223], v203 offset:36864
	ds_read_b128 v[224:227], v203 offset:37888
	ds_read_b128 v[228:231], v203 offset:38912
	ds_read_b128 v[232:235], v203 offset:39936
	global_load_lds_dwordx4 v[246:247], off
	s_mov_b32 m0, s36
	v_lshl_add_u64 v[198:199], v[198:199], 0, v[168:169]
	global_load_lds_dwordx4 v[198:199], off
	s_waitcnt vmcnt(8)
	s_waitcnt lgkmcnt(0)
	s_setprio 1
	s_barrier
	v_mfma_f32_16x16x32_bf16 v[124:127], v[136:139], v[194:197], v[124:127]
	v_mfma_f32_16x16x32_bf16 v[128:131], v[144:147], v[194:197], v[128:131]
	v_mfma_f32_16x16x32_bf16 v[112:115], v[136:139], v[210:213], v[112:115]
	v_mfma_f32_16x16x32_bf16 v[108:111], v[144:147], v[210:213], v[108:111]
	v_mfma_f32_16x16x32_bf16 v[96:99], v[136:139], v[220:223], v[96:99]
	v_mfma_f32_16x16x32_bf16 v[92:95], v[144:147], v[220:223], v[92:95]
	v_mfma_f32_16x16x32_bf16 v[80:83], v[136:139], v[228:231], v[80:83]
	v_mfma_f32_16x16x32_bf16 v[76:79], v[144:147], v[228:231], v[76:79]
	v_mfma_f32_16x16x32_bf16 v[124:127], v[140:143], v[206:209], v[124:127]
	v_mfma_f32_16x16x32_bf16 v[128:131], v[148:151], v[206:209], v[128:131]
	v_mfma_f32_16x16x32_bf16 v[112:115], v[140:143], v[216:219], v[112:115]
	v_mfma_f32_16x16x32_bf16 v[108:111], v[148:151], v[216:219], v[108:111]
	v_mfma_f32_16x16x32_bf16 v[96:99], v[140:143], v[224:227], v[96:99]
	v_mfma_f32_16x16x32_bf16 v[92:95], v[148:151], v[224:227], v[92:95]
	v_mfma_f32_16x16x32_bf16 v[80:83], v[140:143], v[232:235], v[80:83]
	v_mfma_f32_16x16x32_bf16 v[76:79], v[148:151], v[232:235], v[76:79]
	v_mfma_f32_16x16x32_bf16 v[120:123], v[152:155], v[194:197], v[120:123]
	v_mfma_f32_16x16x32_bf16 v[116:119], v[186:189], v[194:197], v[116:119]
	v_mfma_f32_16x16x32_bf16 v[104:107], v[152:155], v[210:213], v[104:107]
	v_mfma_f32_16x16x32_bf16 v[100:103], v[186:189], v[210:213], v[100:103]
	v_mfma_f32_16x16x32_bf16 v[88:91], v[152:155], v[220:223], v[88:91]
	v_mfma_f32_16x16x32_bf16 v[84:87], v[186:189], v[220:223], v[84:87]
	v_mfma_f32_16x16x32_bf16 v[72:75], v[152:155], v[228:231], v[72:75]
	v_mfma_f32_16x16x32_bf16 v[68:71], v[186:189], v[228:231], v[68:71]
	v_mfma_f32_16x16x32_bf16 v[120:123], v[182:185], v[206:209], v[120:123]
	v_mfma_f32_16x16x32_bf16 v[116:119], v[190:193], v[206:209], v[116:119]
	v_mfma_f32_16x16x32_bf16 v[104:107], v[182:185], v[216:219], v[104:107]
	v_mfma_f32_16x16x32_bf16 v[100:103], v[190:193], v[216:219], v[100:103]
	v_mfma_f32_16x16x32_bf16 v[88:91], v[182:185], v[224:227], v[88:91]
	v_mfma_f32_16x16x32_bf16 v[84:87], v[190:193], v[224:227], v[84:87]
	v_mfma_f32_16x16x32_bf16 v[72:75], v[182:185], v[232:235], v[72:75]
	v_mfma_f32_16x16x32_bf16 v[68:71], v[190:193], v[232:235], v[68:71]
	s_setprio 0
	s_barrier
; #define PG8_STAGE(bufoff, gbase, voff) do { _Pragma("unroll") for (int _i = 0; _i < 2; ++_i) \
;         __builtin_amdgcn_global_load_lds((const unsigned*)((const char*)(gbase) + (voff)[_i]), (PG8_LAS unsigned*)(lds + (bufoff) + ldsw + _i * 8192), 16, 0, 0); } while (0)
; #define PG8_LDA(dst, b, h) do { _Pragma("unroll") for (int m = 0; m < 4; ++m) _Pragma("unroll") for (int k = 0; k < 2; ++k) dst[m][k] = *(const PG8_LAS bf16x8*)(lds + PG8_SA(b, h) + aoff + m * 2048 + k * 1024); } while (0)
; #define PG8_MMA(ai, bj, At, Bt) do { __builtin_amdgcn_s_setprio(1); _Pragma("unroll") for (int m = 0; m < 4; ++m) _Pragma("unroll") for (int n = 0; n < 2; ++n) _Pragma("unroll") for (int k = 0; k < 2; ++k) \
;         acc[ai][bj][m][n] = __builtin_amdgcn_mfma_f32_16x16x32_bf16(Bt[n][k], At[m][k], acc[ai][bj][m][n], 0, 0, 0); __builtin_amdgcn_s_setprio(0); } while (0)
; #define PG8_WAIT_V(n) asm volatile("s_waitcnt vmcnt(" #n ")" ::: "memory")
; #define PG8_WAIT_L(n) asm volatile("s_waitcnt lgkmcnt(" #n ")" ::: "memory")
; #define PG8_BAR __builtin_amdgcn_s_barrier()
; #define PG8_SCHED __builtin_amdgcn_sched_barrier(0)
; template <class Epi, class Sched, bool ALIGN_EPI = false, bool SP2 = false>
; __device__ __forceinline__ void gemm_phase(PG8_LAS unsigned char* lds, const Gemm g, const Sched& S, const Epi& E) {
;     ...
;         for (int t = 0; t < nt; t += 2) {
;     ...
;             PG8_LDA(At, 1, 1); PG8_STAGE(PG8_SB(1, 0), b3, voffB); PG8_STAGE(PG8_SB(1, 1), b3 + hstep, voffB); PG8_STAGE(PG8_SA(1, 0), a3, voffA);
;             PG8_WAIT_V(8); PG8_WAIT_L(0); PG8_BAR; PG8_MMA(1, 0, At, B0); PG8_MMA(1, 1, At, B1); PG8_BAR; PG8_SCHED;
	s_add_i32 s13, s13, s30
	v_lshl_add_u64 v[198:199], v[236:237], 0, s[22:23]
	s_mov_b32 m0, s13
	ds_read_b128 v[194:197], v203 offset:49152
	ds_read_b128 v[206:209], v203 offset:50176
	ds_read_b128 v[210:213], v203 offset:51200
	ds_read_b128 v[216:219], v203 offset:52224
	ds_read_b128 v[220:223], v203 offset:53248
	ds_read_b128 v[224:227], v203 offset:54272
	ds_read_b128 v[228:231], v203 offset:55296
	ds_read_b128 v[232:235], v203 offset:56320
	global_load_lds_dwordx4 v[198:199], off
	v_lshl_add_u64 v[198:199], v[238:239], 0, s[22:23]
	s_add_i32 m0, s13, 0x2000
	s_add_i32 s13, s29, s30
	global_load_lds_dwordx4 v[198:199], off
	s_mov_b32 m0, s13
	v_lshl_add_u64 v[198:199], v[240:241], 0, s[22:23]
	global_load_lds_dwordx4 v[198:199], off
	s_add_i32 m0, s13, 0x2000
	v_lshl_add_u64 v[198:199], v[214:215], 0, s[22:23]
	global_load_lds_dwordx4 v[198:199], off
	s_mov_b32 m0, s37
	v_lshl_add_u64 v[198:199], v[242:243], 0, s[22:23]
	global_load_lds_dwordx4 v[198:199], off
	s_mov_b32 m0, s41
	v_lshl_add_u64 v[198:199], v[244:245], 0, s[22:23]
	global_load_lds_dwordx4 v[198:199], off
	s_waitcnt vmcnt(8)
	s_waitcnt lgkmcnt(0)
	s_setprio 1
	s_barrier
	v_mfma_f32_16x16x32_bf16 v[64:67], v[136:139], v[194:197], v[64:67]
	v_mfma_f32_16x16x32_bf16 v[60:63], v[144:147], v[194:197], v[60:63]
	v_mfma_f32_16x16x32_bf16 v[48:51], v[136:139], v[210:213], v[48:51]
	v_mfma_f32_16x16x32_bf16 v[44:47], v[144:147], v[210:213], v[44:47]
	v_mfma_f32_16x16x32_bf16 v[32:35], v[136:139], v[220:223], v[32:35]
	v_mfma_f32_16x16x32_bf16 v[28:31], v[144:147], v[220:223], v[28:31]
	v_mfma_f32_16x16x32_bf16 v[16:19], v[136:139], v[228:231], v[16:19]
	v_mfma_f32_16x16x32_bf16 v[12:15], v[144:147], v[228:231], v[12:15]
	v_mfma_f32_16x16x32_bf16 v[64:67], v[140:143], v[206:209], v[64:67]
	v_mfma_f32_16x16x32_bf16 v[60:63], v[148:151], v[206:209], v[60:63]
	v_mfma_f32_16x16x32_bf16 v[48:51], v[140:143], v[216:219], v[48:51]
	v_mfma_f32_16x16x32_bf16 v[44:47], v[148:151], v[216:219], v[44:47]
	v_mfma_f32_16x16x32_bf16 v[32:35], v[140:143], v[224:227], v[32:35]
	v_mfma_f32_16x16x32_bf16 v[28:31], v[148:151], v[224:227], v[28:31]
	v_mfma_f32_16x16x32_bf16 v[16:19], v[140:143], v[232:235], v[16:19]
	v_mfma_f32_16x16x32_bf16 v[12:15], v[148:151], v[232:235], v[12:15]
	v_mfma_f32_16x16x32_bf16 v[56:59], v[152:155], v[194:197], v[56:59]
	v_mfma_f32_16x16x32_bf16 v[52:55], v[186:189], v[194:197], v[52:55]
	v_mfma_f32_16x16x32_bf16 v[40:43], v[152:155], v[210:213], v[40:43]
	v_mfma_f32_16x16x32_bf16 v[36:39], v[186:189], v[210:213], v[36:39]
	v_mfma_f32_16x16x32_bf16 v[24:27], v[152:155], v[220:223], v[24:27]
	v_mfma_f32_16x16x32_bf16 v[20:23], v[186:189], v[220:223], v[20:23]
	v_mfma_f32_16x16x32_bf16 v[8:11], v[152:155], v[228:231], v[8:11]
	v_mfma_f32_16x16x32_bf16 v[4:7], v[186:189], v[228:231], v[4:7]
	v_mfma_f32_16x16x32_bf16 v[56:59], v[182:185], v[206:209], v[56:59]
	v_mfma_f32_16x16x32_bf16 v[52:55], v[190:193], v[206:209], v[52:55]
	v_mfma_f32_16x16x32_bf16 v[40:43], v[182:185], v[216:219], v[40:43]
	v_mfma_f32_16x16x32_bf16 v[36:39], v[190:193], v[216:219], v[36:39]
	v_mfma_f32_16x16x32_bf16 v[24:27], v[182:185], v[224:227], v[24:27]
	v_mfma_f32_16x16x32_bf16 v[20:23], v[190:193], v[224:227], v[20:23]
	v_mfma_f32_16x16x32_bf16 v[8:11], v[182:185], v[232:235], v[8:11]
	v_mfma_f32_16x16x32_bf16 v[4:7], v[190:193], v[232:235], v[4:7]
	s_setprio 0
	s_barrier
	v_lshl_add_u64 v[132:133], v[132:133], 0, s[26:27]
	s_cmp_ge_i32 s12, s47
	v_lshl_add_u64 v[134:135], v[134:135], 0, s[26:27]
	s_cbranch_scc0 .LBB0_1340

; #define PG8_STAGE(bufoff, gbase, voff) do { _Pragma("unroll") for (int _i = 0; _i < 2; ++_i) \
;         __builtin_amdgcn_global_load_lds((const unsigned*)((const char*)(gbase) + (voff)[_i]), (PG8_LAS unsigned*)(lds + (bufoff) + ldsw + _i * 8192), 16, 0, 0); } while (0)
; #define PG8_LDA(dst, b, h) do { _Pragma("unroll") for (int m = 0; m < 4; ++m) _Pragma("unroll") for (int k = 0; k < 2; ++k) dst[m][k] = *(const PG8_LAS bf16x8*)(lds + PG8_SA(b, h) + aoff + m * 2048 + k * 1024); } while (0)
; #define PG8_LDB(dst, b, h) do { _Pragma("unroll") for (int n = 0; n < 2; ++n) _Pragma("unroll") for (int k = 0; k < 2; ++k) dst[n][k] = *(const PG8_LAS bf16x8*)(lds + PG8_SB(b, h) + boff + n * 2048 + k * 1024); } while (0)
; #define PG8_MMA(ai, bj, At, Bt) do { __builtin_amdgcn_s_setprio(1); _Pragma("unroll") for (int m = 0; m < 4; ++m) _Pragma("unroll") for (int n = 0; n < 2; ++n) _Pragma("unroll") for (int k = 0; k < 2; ++k) \
;         acc[ai][bj][m][n] = __builtin_amdgcn_mfma_f32_16x16x32_bf16(Bt[n][k], At[m][k], acc[ai][bj][m][n], 0, 0, 0); __builtin_amdgcn_s_setprio(0); } while (0)
; #define PG8_WAIT_V(n) asm volatile("s_waitcnt vmcnt(" #n ")" ::: "memory")
; #define PG8_WAIT_L(n) asm volatile("s_waitcnt lgkmcnt(" #n ")" ::: "memory")
; #define PG8_BAR __builtin_amdgcn_s_barrier()
; #define PG8_SCHED __builtin_amdgcn_sched_barrier(0)
; template <class Epi, class Sched, bool ALIGN_EPI = false, bool SP2 = false>
; __device__ __forceinline__ void gemm_phase(PG8_LAS unsigned char* lds, const Gemm g, const Sched& S, const Epi& E) {
;     ...
;             PG8_LDB(B0, 0, 0); PG8_LDB(B1, 0, 1); PG8_SCHED; PG8_LDA(At, 0, 0); PG8_STAGE(PG8_SA(1, 1), a1 + hstep, voffA);
;             PG8_WAIT_V(8); PG8_WAIT_L(0); PG8_BAR; PG8_MMA(0, 0, At, B0); PG8_MMA(0, 1, At, B1); PG8_BAR; PG8_SCHED;
.LBB0_1423:
	v_add_u32_e32 v152, s81, v169
	v_add_u32_e32 v165, s82, v169
	ds_read_b128 v[132:135], v152
	ds_read_b128 v[136:139], v152 offset:1024
	ds_read_b128 v[174:177], v152 offset:2048
	ds_read_b128 v[178:181], v152 offset:3072
	ds_read_b128 v[182:185], v165
	ds_read_b128 v[186:189], v165 offset:1024
	ds_read_b128 v[190:193], v165 offset:2048
	ds_read_b128 v[194:197], v165 offset:3072
	s_cmp_eq_u32 s74, s10
	v_lshl_add_u64 v[198:199], v[130:131], 0, s[26:27]
	s_cselect_b64 vcc, -1, 0
	s_add_i32 s10, s10, 2
	v_cndmask_b32_e32 v211, v199, v171, vcc
	v_cndmask_b32_e32 v210, v198, v170, vcc
	v_cndmask_b32_e32 v215, v129, v173, vcc
	v_cndmask_b32_e32 v214, v128, v172, vcc
	v_lshl_add_u64 v[240:241], v[130:131], 0, v[160:161]
	s_add_i32 m0, s47, 0xc000
	ds_read_b128 v[198:201], v213
	ds_read_b128 v[202:205], v213 offset:1024
	ds_read_b128 v[206:209], v213 offset:2048
	ds_read_b128 v[220:223], v213 offset:3072
	ds_read_b128 v[224:227], v213 offset:4096
	ds_read_b128 v[228:231], v213 offset:5120
	ds_read_b128 v[232:235], v213 offset:6144
	ds_read_b128 v[236:239], v213 offset:7168
	global_load_lds_dwordx4 v[240:241], off
	s_add_i32 m0, s47, 0xe000
	v_lshl_add_u64 v[240:241], v[130:131], 0, v[158:159]
	global_load_lds_dwordx4 v[240:241], off
	s_waitcnt vmcnt(8)
	s_waitcnt lgkmcnt(0)
	s_setprio 1
	s_barrier
	v_mfma_f32_16x16x32_bf16 v[124:127], v[132:135], v[198:201], v[124:127]
	v_mfma_f32_16x16x32_bf16 v[120:123], v[174:177], v[198:201], v[120:123]
	v_mfma_f32_16x16x32_bf16 v[108:111], v[132:135], v[206:209], v[108:111]
	v_mfma_f32_16x16x32_bf16 v[104:107], v[174:177], v[206:209], v[104:107]
	v_mfma_f32_16x16x32_bf16 v[92:95], v[132:135], v[224:227], v[92:95]
	v_mfma_f32_16x16x32_bf16 v[88:91], v[174:177], v[224:227], v[88:91]
	v_mfma_f32_16x16x32_bf16 v[76:79], v[132:135], v[232:235], v[76:79]
	v_mfma_f32_16x16x32_bf16 v[72:75], v[174:177], v[232:235], v[72:75]
	v_mfma_f32_16x16x32_bf16 v[124:127], v[136:139], v[202:205], v[124:127]
	v_mfma_f32_16x16x32_bf16 v[120:123], v[178:181], v[202:205], v[120:123]
	v_mfma_f32_16x16x32_bf16 v[108:111], v[136:139], v[220:223], v[108:111]
	v_mfma_f32_16x16x32_bf16 v[104:107], v[178:181], v[220:223], v[104:107]
	v_mfma_f32_16x16x32_bf16 v[92:95], v[136:139], v[228:231], v[92:95]
	v_mfma_f32_16x16x32_bf16 v[88:91], v[178:181], v[228:231], v[88:91]
	v_mfma_f32_16x16x32_bf16 v[76:79], v[136:139], v[236:239], v[76:79]
	v_mfma_f32_16x16x32_bf16 v[72:75], v[178:181], v[236:239], v[72:75]
	s_cmp_eq_u32 s22, 12
	s_cbranch_scc1 .Lio_skipk0
	v_mfma_f32_16x16x32_bf16 v[116:119], v[182:185], v[198:201], v[116:119]
	v_mfma_f32_16x16x32_bf16 v[112:115], v[190:193], v[198:201], v[112:115]
	v_mfma_f32_16x16x32_bf16 v[100:103], v[182:185], v[206:209], v[100:103]
	v_mfma_f32_16x16x32_bf16 v[96:99], v[190:193], v[206:209], v[96:99]
	v_mfma_f32_16x16x32_bf16 v[84:87], v[182:185], v[224:227], v[84:87]
	v_mfma_f32_16x16x32_bf16 v[80:83], v[190:193], v[224:227], v[80:83]
	v_mfma_f32_16x16x32_bf16 v[68:71], v[182:185], v[232:235], v[68:71]
	v_mfma_f32_16x16x32_bf16 v[64:67], v[190:193], v[232:235], v[64:67]
	v_mfma_f32_16x16x32_bf16 v[116:119], v[186:189], v[202:205], v[116:119]
	v_mfma_f32_16x16x32_bf16 v[112:115], v[194:197], v[202:205], v[112:115]
	v_mfma_f32_16x16x32_bf16 v[100:103], v[186:189], v[220:223], v[100:103]
	v_mfma_f32_16x16x32_bf16 v[96:99], v[194:197], v[220:223], v[96:99]
	v_mfma_f32_16x16x32_bf16 v[84:87], v[186:189], v[228:231], v[84:87]
	v_mfma_f32_16x16x32_bf16 v[80:83], v[194:197], v[228:231], v[80:83]
	v_mfma_f32_16x16x32_bf16 v[68:71], v[186:189], v[236:239], v[68:71]
	v_mfma_f32_16x16x32_bf16 v[64:67], v[194:197], v[236:239], v[64:67]

; #define PG8_STAGE(bufoff, gbase, voff) do { _Pragma("unroll") for (int _i = 0; _i < 2; ++_i) \
;         __builtin_amdgcn_global_load_lds((const unsigned*)((const char*)(gbase) + (voff)[_i]), (PG8_LAS unsigned*)(lds + (bufoff) + ldsw + _i * 8192), 16, 0, 0); } while (0)
; #define PG8_LDA(dst, b, h) do { _Pragma("unroll") for (int m = 0; m < 4; ++m) _Pragma("unroll") for (int k = 0; k < 2; ++k) dst[m][k] = *(const PG8_LAS bf16x8*)(lds + PG8_SA(b, h) + aoff + m * 2048 + k * 1024); } while (0)
; #define PG8_LDB(dst, b, h) do { _Pragma("unroll") for (int n = 0; n < 2; ++n) _Pragma("unroll") for (int k = 0; k < 2; ++k) dst[n][k] = *(const PG8_LAS bf16x8*)(lds + PG8_SB(b, h) + boff + n * 2048 + k * 1024); } while (0)
; #define PG8_MMA(ai, bj, At, Bt) do { __builtin_amdgcn_s_setprio(1); _Pragma("unroll") for (int m = 0; m < 4; ++m) _Pragma("unroll") for (int n = 0; n < 2; ++n) _Pragma("unroll") for (int k = 0; k < 2; ++k) \
;         acc[ai][bj][m][n] = __builtin_amdgcn_mfma_f32_16x16x32_bf16(Bt[n][k], At[m][k], acc[ai][bj][m][n], 0, 0, 0); __builtin_amdgcn_s_setprio(0); } while (0)
; #define PG8_WAIT_V(n) asm volatile("s_waitcnt vmcnt(" #n ")" ::: "memory")
; #define PG8_WAIT_L(n) asm volatile("s_waitcnt lgkmcnt(" #n ")" ::: "memory")
; #define PG8_BAR __builtin_amdgcn_s_barrier()
; #define PG8_SCHED __builtin_amdgcn_sched_barrier(0)
; template <class Epi, class Sched, bool ALIGN_EPI = false, bool SP2 = false>
; __device__ __forceinline__ void gemm_phase(PG8_LAS unsigned char* lds, const Gemm g, const Sched& S, const Epi& E) {
;     ...
;             PG8_LDB(B0, 1, 0); PG8_LDB(B1, 1, 1); PG8_SCHED; PG8_LDA(At, 1, 0); PG8_STAGE(PG8_SA(0, 1), a2 + hstep, voffA);
;             PG8_WAIT_V(8); PG8_WAIT_L(0); PG8_BAR; PG8_MMA(0, 0, At, B0); PG8_MMA(0, 1, At, B1); PG8_BAR; PG8_SCHED;
;             PG8_LDA(At, 1, 1); PG8_STAGE(PG8_SB(1, 0), b3, voffB); PG8_STAGE(PG8_SB(1, 1), b3 + hstep, voffB); PG8_STAGE(PG8_SA(1, 0), a3, voffA);
;             PG8_WAIT_V(8); PG8_WAIT_L(0); PG8_BAR; PG8_MMA(1, 0, At, B0); PG8_MMA(1, 1, At, B1); PG8_BAR; PG8_SCHED;
.Lio_skipk1:
	s_setprio 0
	s_barrier
	s_add_i32 s11, 0, 0x18000
	v_add_u32_e32 v152, s11, v169
	s_add_i32 s13, 0, 0x1c000
	ds_read_b128 v[132:135], v152
	ds_read_b128 v[136:139], v152 offset:1024
	ds_read_b128 v[174:177], v152 offset:2048
	ds_read_b128 v[178:181], v152 offset:3072
	v_add_u32_e32 v152, s13, v169
	ds_read_b128 v[182:185], v152
	ds_read_b128 v[186:189], v152 offset:1024
	ds_read_b128 v[190:193], v152 offset:2048
	ds_read_b128 v[194:197], v152 offset:3072
	v_lshl_add_u64 v[210:211], v[210:211], 0, s[18:19]
	s_mov_b32 m0, s57
	v_lshl_add_u64 v[250:251], v[210:211], 0, v[144:145]
	ds_read_b128 v[198:201], v213 offset:32768
	ds_read_b128 v[202:205], v213 offset:33792
	ds_read_b128 v[206:209], v213 offset:34816
	ds_read_b128 v[220:223], v213 offset:35840
	ds_read_b128 v[224:227], v213 offset:36864
	ds_read_b128 v[228:231], v213 offset:37888
	ds_read_b128 v[232:235], v213 offset:38912
	ds_read_b128 v[236:239], v213 offset:39936
	global_load_lds_dwordx4 v[250:251], off
	s_mov_b32 m0, s59
	v_lshl_add_u64 v[210:211], v[210:211], 0, v[148:149]
	global_load_lds_dwordx4 v[210:211], off
	s_waitcnt vmcnt(8)
	s_waitcnt lgkmcnt(0)
	s_setprio 1
	s_barrier
	v_mfma_f32_16x16x32_bf16 v[124:127], v[132:135], v[198:201], v[124:127]
	v_mfma_f32_16x16x32_bf16 v[120:123], v[174:177], v[198:201], v[120:123]
	v_mfma_f32_16x16x32_bf16 v[108:111], v[132:135], v[206:209], v[108:111]
	v_mfma_f32_16x16x32_bf16 v[104:107], v[174:177], v[206:209], v[104:107]
	v_mfma_f32_16x16x32_bf16 v[92:95], v[132:135], v[224:227], v[92:95]
	v_mfma_f32_16x16x32_bf16 v[88:91], v[174:177], v[224:227], v[88:91]
	v_mfma_f32_16x16x32_bf16 v[76:79], v[132:135], v[232:235], v[76:79]
	v_mfma_f32_16x16x32_bf16 v[72:75], v[174:177], v[232:235], v[72:75]
	v_mfma_f32_16x16x32_bf16 v[124:127], v[136:139], v[202:205], v[124:127]
	v_mfma_f32_16x16x32_bf16 v[120:123], v[178:181], v[202:205], v[120:123]
	v_mfma_f32_16x16x32_bf16 v[108:111], v[136:139], v[220:223], v[108:111]
	v_mfma_f32_16x16x32_bf16 v[104:107], v[178:181], v[220:223], v[104:107]
	v_mfma_f32_16x16x32_bf16 v[92:95], v[136:139], v[228:231], v[92:95]
	v_mfma_f32_16x16x32_bf16 v[88:91], v[178:181], v[228:231], v[88:91]
	v_mfma_f32_16x16x32_bf16 v[76:79], v[136:139], v[236:239], v[76:79]
	v_mfma_f32_16x16x32_bf16 v[72:75], v[178:181], v[236:239], v[72:75]
	s_cmp_eq_u32 s22, 12
	s_cbranch_scc1 .Lio_skipk2
	v_mfma_f32_16x16x32_bf16 v[116:119], v[182:185], v[198:201], v[116:119]
	v_mfma_f32_16x16x32_bf16 v[112:115], v[190:193], v[198:201], v[112:115]
	v_mfma_f32_16x16x32_bf16 v[100:103], v[182:185], v[206:209], v[100:103]
	v_mfma_f32_16x16x32_bf16 v[96:99], v[190:193], v[206:209], v[96:99]
	v_mfma_f32_16x16x32_bf16 v[84:87], v[182:185], v[224:227], v[84:87]
	v_mfma_f32_16x16x32_bf16 v[80:83], v[190:193], v[224:227], v[80:83]
	v_mfma_f32_16x16x32_bf16 v[68:71], v[182:185], v[232:235], v[68:71]
	v_mfma_f32_16x16x32_bf16 v[64:67], v[190:193], v[232:235], v[64:67]
	v_mfma_f32_16x16x32_bf16 v[116:119], v[186:189], v[202:205], v[116:119]
	v_mfma_f32_16x16x32_bf16 v[112:115], v[194:197], v[202:205], v[112:115]
	v_mfma_f32_16x16x32_bf16 v[100:103], v[186:189], v[220:223], v[100:103]
	v_mfma_f32_16x16x32_bf16 v[96:99], v[194:197], v[220:223], v[96:99]
	v_mfma_f32_16x16x32_bf16 v[84:87], v[186:189], v[228:231], v[84:87]
	v_mfma_f32_16x16x32_bf16 v[80:83], v[194:197], v[228:231], v[80:83]
	v_mfma_f32_16x16x32_bf16 v[68:71], v[186:189], v[236:239], v[68:71]
	v_mfma_f32_16x16x32_bf16 v[64:67], v[194:197], v[236:239], v[64:67]
.Lio_skipk2:
	s_setprio 0
	s_barrier
	s_add_i32 s11, s11, s41
	v_lshl_add_u64 v[210:211], v[240:241], 0, s[26:27]
	s_mov_b32 m0, s11
	ds_read_b128 v[198:201], v213 offset:49152
	ds_read_b128 v[202:205], v213 offset:50176
	ds_read_b128 v[206:209], v213 offset:51200
	ds_read_b128 v[220:223], v213 offset:52224
	ds_read_b128 v[224:227], v213 offset:53248
	ds_read_b128 v[228:231], v213 offset:54272
	ds_read_b128 v[232:235], v213 offset:55296
	ds_read_b128 v[236:239], v213 offset:56320
	global_load_lds_dwordx4 v[210:211], off
	v_lshl_add_u64 v[210:211], v[242:243], 0, s[26:27]
	s_add_i32 m0, s11, 0x2000
	s_add_i32 s11, s13, s41
	global_load_lds_dwordx4 v[210:211], off
	s_mov_b32 m0, s11
	v_lshl_add_u64 v[210:211], v[244:245], 0, s[26:27]
	global_load_lds_dwordx4 v[210:211], off
	s_add_i32 m0, s11, 0x2000
	v_lshl_add_u64 v[210:211], v[214:215], 0, s[26:27]
	global_load_lds_dwordx4 v[210:211], off
	s_mov_b32 m0, s69
	v_lshl_add_u64 v[210:211], v[246:247], 0, s[26:27]
	global_load_lds_dwordx4 v[210:211], off
	s_mov_b32 m0, s70
	v_lshl_add_u64 v[210:211], v[248:249], 0, s[26:27]
	global_load_lds_dwordx4 v[210:211], off
	s_waitcnt vmcnt(8)
	s_waitcnt lgkmcnt(0)
	s_setprio 1
	s_barrier
	v_mfma_f32_16x16x32_bf16 v[60:63], v[132:135], v[198:201], v[60:63]
	v_mfma_f32_16x16x32_bf16 v[56:59], v[174:177], v[198:201], v[56:59]
	v_mfma_f32_16x16x32_bf16 v[44:47], v[132:135], v[206:209], v[44:47]
	v_mfma_f32_16x16x32_bf16 v[40:43], v[174:177], v[206:209], v[40:43]
	v_mfma_f32_16x16x32_bf16 v[28:31], v[132:135], v[224:227], v[28:31]
	v_mfma_f32_16x16x32_bf16 v[24:27], v[174:177], v[224:227], v[24:27]
	v_mfma_f32_16x16x32_bf16 v[12:15], v[132:135], v[232:235], v[12:15]
	v_mfma_f32_16x16x32_bf16 v[8:11], v[174:177], v[232:235], v[8:11]
	v_mfma_f32_16x16x32_bf16 v[60:63], v[136:139], v[202:205], v[60:63]
	v_mfma_f32_16x16x32_bf16 v[56:59], v[178:181], v[202:205], v[56:59]
	v_mfma_f32_16x16x32_bf16 v[44:47], v[136:139], v[220:223], v[44:47]
	v_mfma_f32_16x16x32_bf16 v[40:43], v[178:181], v[220:223], v[40:43]
	v_mfma_f32_16x16x32_bf16 v[28:31], v[136:139], v[228:231], v[28:31]
	v_mfma_f32_16x16x32_bf16 v[24:27], v[178:181], v[228:231], v[24:27]
	v_mfma_f32_16x16x32_bf16 v[12:15], v[136:139], v[236:239], v[12:15]
	v_mfma_f32_16x16x32_bf16 v[8:11], v[178:181], v[236:239], v[8:11]
	s_cmp_eq_u32 s22, 12
	s_cbranch_scc1 .Lio_skipk3
	v_mfma_f32_16x16x32_bf16 v[52:55], v[182:185], v[198:201], v[52:55]
	v_mfma_f32_16x16x32_bf16 v[48:51], v[190:193], v[198:201], v[48:51]
	v_mfma_f32_16x16x32_bf16 v[36:39], v[182:185], v[206:209], v[36:39]
	v_mfma_f32_16x16x32_bf16 v[32:35], v[190:193], v[206:209], v[32:35]
	v_mfma_f32_16x16x32_bf16 v[20:23], v[182:185], v[224:227], v[20:23]
	v_mfma_f32_16x16x32_bf16 v[16:19], v[190:193], v[224:227], v[16:19]
	v_mfma_f32_16x16x32_bf16 v[4:7], v[182:185], v[232:235], v[4:7]
	v_mfma_f32_16x16x32_bf16 v[0:3], v[190:193], v[232:235], v[0:3]
	v_mfma_f32_16x16x32_bf16 v[52:55], v[186:189], v[202:205], v[52:55]
	v_mfma_f32_16x16x32_bf16 v[48:51], v[194:197], v[202:205], v[48:51]
	v_mfma_f32_16x16x32_bf16 v[36:39], v[186:189], v[220:223], v[36:39]
	v_mfma_f32_16x16x32_bf16 v[32:35], v[194:197], v[220:223], v[32:35]
	v_mfma_f32_16x16x32_bf16 v[20:23], v[186:189], v[228:231], v[20:23]
	v_mfma_f32_16x16x32_bf16 v[16:19], v[194:197], v[228:231], v[16:19]
	v_mfma_f32_16x16x32_bf16 v[4:7], v[186:189], v[236:239], v[4:7]
	v_mfma_f32_16x16x32_bf16 v[0:3], v[194:197], v[236:239], v[0:3]

; #define PG8_STAGE(bufoff, gbase, voff) do { _Pragma("unroll") for (int _i = 0; _i < 2; ++_i) \
;         __builtin_amdgcn_global_load_lds((const unsigned*)((const char*)(gbase) + (voff)[_i]), (PG8_LAS unsigned*)(lds + (bufoff) + ldsw + _i * 8192), 16, 0, 0); } while (0)
; #define PG8_LDA(dst, b, h) do { _Pragma("unroll") for (int m = 0; m < 4; ++m) _Pragma("unroll") for (int k = 0; k < 2; ++k) dst[m][k] = *(const PG8_LAS bf16x8*)(lds + PG8_SA(b, h) + aoff + m * 2048 + k * 1024); } while (0)
; #define PG8_LDB(dst, b, h) do { _Pragma("unroll") for (int n = 0; n < 2; ++n) _Pragma("unroll") for (int k = 0; k < 2; ++k) dst[n][k] = *(const PG8_LAS bf16x8*)(lds + PG8_SB(b, h) + boff + n * 2048 + k * 1024); } while (0)
; #define PG8_MMA(ai, bj, At, Bt) do { __builtin_amdgcn_s_setprio(1); _Pragma("unroll") for (int m = 0; m < 4; ++m) _Pragma("unroll") for (int n = 0; n < 2; ++n) _Pragma("unroll") for (int k = 0; k < 2; ++k) \
;         acc[ai][bj][m][n] = __builtin_amdgcn_mfma_f32_16x16x32_bf16(Bt[n][k], At[m][k], acc[ai][bj][m][n], 0, 0, 0); __builtin_amdgcn_s_setprio(0); } while (0)
; #define PG8_WAIT_V(n) asm volatile("s_waitcnt vmcnt(" #n ")" ::: "memory")
; #define PG8_WAIT_L(n) asm volatile("s_waitcnt lgkmcnt(" #n ")" ::: "memory")
; template <class Epi, class Sched, bool ALIGN_EPI = false, bool SP2 = false>
; __device__ __forceinline__ void gemm_phase(PG8_LAS unsigned char* lds, const Gemm g, const Sched& S, const Epi& E) {
;     ...
;             const bool last = (t == nt - 2);
;             const char* a1 = cA + (size_t)(t + 1) * kstep;
;             const char* a2 = last ? nA : cA + (size_t)(t + 2) * kstep; const char* b2 = last ? nB : cB + (size_t)(t + 2) * kstep;
;             const char* a3 = a2 + kstep; const char* b3 = b2 + kstep;
;             if (last && has_next) S.a_ready(nxt);
;             if constexpr (SP2) {
;             PG8_LDB(B0, 0, 0); PG8_LDB(B1, 0, 1); PG8_SCHED; PG8_LDA(At, 0, 0); PG8_STAGE(PG8_SA(1, 1), a1 + hstep, voffA);
;             PG8_WAIT_V(8); PG8_WAIT_L(0); PG8_BAR; PG8_MMA(0, 0, At, B0); PG8_MMA(0, 1, At, B1); PG8_BAR; PG8_SCHED;
;             PG8_LDA(At, 0, 1); PG8_STAGE(PG8_SB(0, 0), b2, voffB); PG8_STAGE(PG8_SB(0, 1), b2 + hstep, voffB); PG8_STAGE(PG8_SA(0, 0), a2, voffA);
;             PG8_WAIT_V(8); PG8_WAIT_L(0); PG8_BAR; PG8_MMA(1, 0, At, B0); PG8_MMA(1, 1, At, B1); PG8_BAR; PG8_SCHED;
.LBB0_1695:
	v_add_u32_e32 v188, s54, v199
	ds_read_b128 v[132:135], v201
	ds_read_b128 v[136:139], v201 offset:1024
	ds_read_b128 v[140:143], v201 offset:2048
	ds_read_b128 v[144:147], v201 offset:3072
	ds_read_b128 v[148:151], v188
	ds_read_b128 v[180:183], v188 offset:1024
	ds_read_b128 v[184:187], v188 offset:2048
	ds_read_b128 v[188:191], v188 offset:3072
	s_cmp_eq_u32 s48, s12
	v_lshl_add_u64 v[192:193], v[130:131], 0, s[22:23]
	s_cselect_b64 vcc, -1, 0
	s_add_i32 s12, s12, 2
	v_cndmask_b32_e32 v197, v193, v177, vcc
	v_cndmask_b32_e32 v196, v192, v176, vcc
	v_cndmask_b32_e32 v213, v129, v179, vcc
	v_cndmask_b32_e32 v212, v128, v178, vcc
	s_mov_b32 m0, s55
	v_lshl_add_u64 v[214:215], v[130:131], 0, v[172:173]
	ds_read_b128 v[192:195], v202
	ds_read_b128 v[204:207], v202 offset:1024
	ds_read_b128 v[208:211], v202 offset:2048
	ds_read_b128 v[216:219], v202 offset:3072
	ds_read_b128 v[220:223], v202 offset:4096
	ds_read_b128 v[224:227], v202 offset:5120
	ds_read_b128 v[228:231], v202 offset:6144
	ds_read_b128 v[232:235], v202 offset:7168
	global_load_lds_dwordx4 v[214:215], off
	s_mov_b32 m0, s56
	v_lshl_add_u64 v[214:215], v[130:131], 0, v[170:171]
	global_load_lds_dwordx4 v[214:215], off
	s_waitcnt vmcnt(8)
	s_waitcnt lgkmcnt(0)
	s_setprio 1
	s_barrier
	v_mfma_f32_16x16x32_bf16 v[120:123], v[132:135], v[192:195], v[120:123]
	v_mfma_f32_16x16x32_bf16 v[124:127], v[140:143], v[192:195], v[124:127]
	v_mfma_f32_16x16x32_bf16 v[108:111], v[132:135], v[208:211], v[108:111]
	v_mfma_f32_16x16x32_bf16 v[104:107], v[140:143], v[208:211], v[104:107]
	v_mfma_f32_16x16x32_bf16 v[92:95], v[132:135], v[220:223], v[92:95]
	v_mfma_f32_16x16x32_bf16 v[88:91], v[140:143], v[220:223], v[88:91]
	v_mfma_f32_16x16x32_bf16 v[76:79], v[132:135], v[228:231], v[76:79]
	v_mfma_f32_16x16x32_bf16 v[72:75], v[140:143], v[228:231], v[72:75]
	v_mfma_f32_16x16x32_bf16 v[120:123], v[136:139], v[204:207], v[120:123]
	v_mfma_f32_16x16x32_bf16 v[124:127], v[144:147], v[204:207], v[124:127]
	v_mfma_f32_16x16x32_bf16 v[108:111], v[136:139], v[216:219], v[108:111]
	v_mfma_f32_16x16x32_bf16 v[104:107], v[144:147], v[216:219], v[104:107]
	v_mfma_f32_16x16x32_bf16 v[92:95], v[136:139], v[224:227], v[92:95]
	v_mfma_f32_16x16x32_bf16 v[88:91], v[144:147], v[224:227], v[88:91]
	v_mfma_f32_16x16x32_bf16 v[76:79], v[136:139], v[232:235], v[76:79]
	v_mfma_f32_16x16x32_bf16 v[72:75], v[144:147], v[232:235], v[72:75]
	v_mfma_f32_16x16x32_bf16 v[116:119], v[148:151], v[192:195], v[116:119]
	v_mfma_f32_16x16x32_bf16 v[112:115], v[184:187], v[192:195], v[112:115]
	v_mfma_f32_16x16x32_bf16 v[100:103], v[148:151], v[208:211], v[100:103]
	v_mfma_f32_16x16x32_bf16 v[96:99], v[184:187], v[208:211], v[96:99]
	v_mfma_f32_16x16x32_bf16 v[84:87], v[148:151], v[220:223], v[84:87]
	v_mfma_f32_16x16x32_bf16 v[80:83], v[184:187], v[220:223], v[80:83]
	v_mfma_f32_16x16x32_bf16 v[68:71], v[148:151], v[228:231], v[68:71]
	v_mfma_f32_16x16x32_bf16 v[64:67], v[184:187], v[228:231], v[64:67]
	v_mfma_f32_16x16x32_bf16 v[116:119], v[180:183], v[204:207], v[116:119]
	v_mfma_f32_16x16x32_bf16 v[112:115], v[188:191], v[204:207], v[112:115]
	v_mfma_f32_16x16x32_bf16 v[100:103], v[180:183], v[216:219], v[100:103]
	v_mfma_f32_16x16x32_bf16 v[96:99], v[188:191], v[216:219], v[96:99]
	v_mfma_f32_16x16x32_bf16 v[84:87], v[180:183], v[224:227], v[84:87]
	v_mfma_f32_16x16x32_bf16 v[80:83], v[188:191], v[224:227], v[80:83]
	v_mfma_f32_16x16x32_bf16 v[68:71], v[180:183], v[232:235], v[68:71]
	v_mfma_f32_16x16x32_bf16 v[64:67], v[188:191], v[232:235], v[64:67]
	s_setprio 0
	s_barrier
	s_mov_b32 m0, s57
	v_lshl_add_u64 v[214:215], v[212:213], 0, v[164:165]
	ds_read_b128 v[192:195], v202 offset:16384
	ds_read_b128 v[204:207], v202 offset:17408
	ds_read_b128 v[208:211], v202 offset:18432
	ds_read_b128 v[216:219], v202 offset:19456
	ds_read_b128 v[220:223], v202 offset:20480
	ds_read_b128 v[224:227], v202 offset:21504
	ds_read_b128 v[228:231], v202 offset:22528
	ds_read_b128 v[232:235], v202 offset:23552
	global_load_lds_dwordx4 v[214:215], off
	v_lshl_add_u64 v[236:237], v[212:213], 0, v[168:169]
	s_mov_b32 m0, s58
	v_lshl_add_u64 v[212:213], v[212:213], 0, s[14:15]
	s_add_i32 s13, s54, s30
	global_load_lds_dwordx4 v[236:237], off
	v_lshl_add_u64 v[238:239], v[212:213], 0, v[164:165]
	s_mov_b32 m0, s13
	v_lshl_add_u64 v[212:213], v[212:213], 0, v[168:169]
	global_load_lds_dwordx4 v[238:239], off
	s_add_i32 m0, s13, 0x2000
	v_lshl_add_u64 v[240:241], v[196:197], 0, v[162:163]
	global_load_lds_dwordx4 v[212:213], off
	s_mov_b32 m0, s31
	v_lshl_add_u64 v[242:243], v[196:197], 0, v[166:167]
	global_load_lds_dwordx4 v[240:241], off
	s_mov_b32 m0, s34
	s_nop 0
	global_load_lds_dwordx4 v[242:243], off
	s_waitcnt vmcnt(8)
	s_waitcnt lgkmcnt(0)
	s_setprio 1
	s_barrier
; #define PG8_STAGE(bufoff, gbase, voff) do { _Pragma("unroll") for (int _i = 0; _i < 2; ++_i) \
;         __builtin_amdgcn_global_load_lds((const unsigned*)((const char*)(gbase) + (voff)[_i]), (PG8_LAS unsigned*)(lds + (bufoff) + ldsw + _i * 8192), 16, 0, 0); } while (0)
; #define PG8_LDA(dst, b, h) do { _Pragma("unroll") for (int m = 0; m < 4; ++m) _Pragma("unroll") for (int k = 0; k < 2; ++k) dst[m][k] = *(const PG8_LAS bf16x8*)(lds + PG8_SA(b, h) + aoff + m * 2048 + k * 1024); } while (0)
; #define PG8_LDB(dst, b, h) do { _Pragma("unroll") for (int n = 0; n < 2; ++n) _Pragma("unroll") for (int k = 0; k < 2; ++k) dst[n][k] = *(const PG8_LAS bf16x8*)(lds + PG8_SB(b, h) + boff + n * 2048 + k * 1024); } while (0)
; #define PG8_MMA(ai, bj, At, Bt) do { __builtin_amdgcn_s_setprio(1); _Pragma("unroll") for (int m = 0; m < 4; ++m) _Pragma("unroll") for (int n = 0; n < 2; ++n) _Pragma("unroll") for (int k = 0; k < 2; ++k) \
;         acc[ai][bj][m][n] = __builtin_amdgcn_mfma_f32_16x16x32_bf16(Bt[n][k], At[m][k], acc[ai][bj][m][n], 0, 0, 0); __builtin_amdgcn_s_setprio(0); } while (0)
; #define PG8_WAIT_V(n) asm volatile("s_waitcnt vmcnt(" #n ")" ::: "memory")
; #define PG8_WAIT_L(n) asm volatile("s_waitcnt lgkmcnt(" #n ")" ::: "memory")
; #define PG8_BAR __builtin_amdgcn_s_barrier()
; #define PG8_SCHED __builtin_amdgcn_sched_barrier(0)
; template <class Epi, class Sched, bool ALIGN_EPI = false, bool SP2 = false>
; __device__ __forceinline__ void gemm_phase(PG8_LAS unsigned char* lds, const Gemm g, const Sched& S, const Epi& E) {
;     ...
;             PG8_WAIT_V(8); PG8_WAIT_L(0); PG8_BAR; PG8_MMA(1, 0, At, B0); PG8_MMA(1, 1, At, B1); PG8_BAR; PG8_SCHED;
;             PG8_LDB(B0, 1, 0); PG8_LDB(B1, 1, 1); PG8_SCHED; PG8_LDA(At, 1, 0); PG8_STAGE(PG8_SA(0, 1), a2 + hstep, voffA);
;             PG8_WAIT_V(8); PG8_WAIT_L(0); PG8_BAR; PG8_MMA(0, 0, At, B0); PG8_MMA(0, 1, At, B1); PG8_BAR; PG8_SCHED;
	v_mfma_f32_16x16x32_bf16 v[60:63], v[132:135], v[192:195], v[60:63]
	v_mfma_f32_16x16x32_bf16 v[56:59], v[140:143], v[192:195], v[56:59]
	v_mfma_f32_16x16x32_bf16 v[44:47], v[132:135], v[208:211], v[44:47]
	v_mfma_f32_16x16x32_bf16 v[40:43], v[140:143], v[208:211], v[40:43]
	v_mfma_f32_16x16x32_bf16 v[28:31], v[132:135], v[220:223], v[28:31]
	v_mfma_f32_16x16x32_bf16 v[24:27], v[140:143], v[220:223], v[24:27]
	v_mfma_f32_16x16x32_bf16 v[12:15], v[132:135], v[228:231], v[12:15]
	v_mfma_f32_16x16x32_bf16 v[8:11], v[140:143], v[228:231], v[8:11]
	v_mfma_f32_16x16x32_bf16 v[60:63], v[136:139], v[204:207], v[60:63]
	v_mfma_f32_16x16x32_bf16 v[56:59], v[144:147], v[204:207], v[56:59]
	v_mfma_f32_16x16x32_bf16 v[44:47], v[136:139], v[216:219], v[44:47]
	v_mfma_f32_16x16x32_bf16 v[40:43], v[144:147], v[216:219], v[40:43]
	v_mfma_f32_16x16x32_bf16 v[28:31], v[136:139], v[224:227], v[28:31]
	v_mfma_f32_16x16x32_bf16 v[24:27], v[144:147], v[224:227], v[24:27]
	v_mfma_f32_16x16x32_bf16 v[12:15], v[136:139], v[232:235], v[12:15]
	v_mfma_f32_16x16x32_bf16 v[8:11], v[144:147], v[232:235], v[8:11]
	v_mfma_f32_16x16x32_bf16 v[52:55], v[148:151], v[192:195], v[52:55]
	v_mfma_f32_16x16x32_bf16 v[48:51], v[184:187], v[192:195], v[48:51]
	v_mfma_f32_16x16x32_bf16 v[36:39], v[148:151], v[208:211], v[36:39]
	v_mfma_f32_16x16x32_bf16 v[32:35], v[184:187], v[208:211], v[32:35]
	v_mfma_f32_16x16x32_bf16 v[20:23], v[148:151], v[220:223], v[20:23]
	v_mfma_f32_16x16x32_bf16 v[16:19], v[184:187], v[220:223], v[16:19]
	v_mfma_f32_16x16x32_bf16 v[4:7], v[148:151], v[228:231], v[4:7]
	v_mfma_f32_16x16x32_bf16 v[0:3], v[184:187], v[228:231], v[0:3]
	v_mfma_f32_16x16x32_bf16 v[52:55], v[180:183], v[204:207], v[52:55]
	v_mfma_f32_16x16x32_bf16 v[48:51], v[188:191], v[204:207], v[48:51]
	v_mfma_f32_16x16x32_bf16 v[36:39], v[180:183], v[216:219], v[36:39]
	v_mfma_f32_16x16x32_bf16 v[32:35], v[188:191], v[216:219], v[32:35]
	v_mfma_f32_16x16x32_bf16 v[20:23], v[180:183], v[224:227], v[20:23]
	v_mfma_f32_16x16x32_bf16 v[16:19], v[188:191], v[224:227], v[16:19]
	v_mfma_f32_16x16x32_bf16 v[4:7], v[180:183], v[232:235], v[4:7]
	v_mfma_f32_16x16x32_bf16 v[0:3], v[188:191], v[232:235], v[0:3]
	s_setprio 0
	s_barrier
	s_add_i32 s13, 0, 0x18000
	s_add_i32 s29, 0, 0x1c000
	v_add_u32_e32 v144, s13, v199
	v_add_u32_e32 v188, s29, v199
	ds_read_b128 v[132:135], v144
	ds_read_b128 v[136:139], v144 offset:1024
	ds_read_b128 v[140:143], v144 offset:2048
	ds_read_b128 v[144:147], v144 offset:3072
	ds_read_b128 v[148:151], v188
	ds_read_b128 v[180:183], v188 offset:1024
	ds_read_b128 v[184:187], v188 offset:2048
	ds_read_b128 v[188:191], v188 offset:3072
	v_lshl_add_u64 v[196:197], v[196:197], 0, s[14:15]
	s_mov_b32 m0, s35
	v_lshl_add_u64 v[244:245], v[196:197], 0, v[162:163]
	ds_read_b128 v[192:195], v202 offset:32768
	ds_read_b128 v[204:207], v202 offset:33792
	ds_read_b128 v[208:211], v202 offset:34816
	ds_read_b128 v[216:219], v202 offset:35840
	ds_read_b128 v[220:223], v202 offset:36864
	ds_read_b128 v[224:227], v202 offset:37888
	ds_read_b128 v[228:231], v202 offset:38912
	ds_read_b128 v[232:235], v202 offset:39936
	global_load_lds_dwordx4 v[244:245], off
	s_mov_b32 m0, s36
	v_lshl_add_u64 v[196:197], v[196:197], 0, v[166:167]
	global_load_lds_dwordx4 v[196:197], off
	s_waitcnt vmcnt(8)
	s_waitcnt lgkmcnt(0)
	s_setprio 1
	s_barrier
	v_mfma_f32_16x16x32_bf16 v[120:123], v[132:135], v[192:195], v[120:123]
	v_mfma_f32_16x16x32_bf16 v[124:127], v[140:143], v[192:195], v[124:127]
	v_mfma_f32_16x16x32_bf16 v[108:111], v[132:135], v[208:211], v[108:111]
	v_mfma_f32_16x16x32_bf16 v[104:107], v[140:143], v[208:211], v[104:107]
	v_mfma_f32_16x16x32_bf16 v[92:95], v[132:135], v[220:223], v[92:95]
	v_mfma_f32_16x16x32_bf16 v[88:91], v[140:143], v[220:223], v[88:91]
	v_mfma_f32_16x16x32_bf16 v[76:79], v[132:135], v[228:231], v[76:79]
	v_mfma_f32_16x16x32_bf16 v[72:75], v[140:143], v[228:231], v[72:75]
	v_mfma_f32_16x16x32_bf16 v[120:123], v[136:139], v[204:207], v[120:123]
	v_mfma_f32_16x16x32_bf16 v[124:127], v[144:147], v[204:207], v[124:127]
	v_mfma_f32_16x16x32_bf16 v[108:111], v[136:139], v[216:219], v[108:111]
	v_mfma_f32_16x16x32_bf16 v[104:107], v[144:147], v[216:219], v[104:107]
	v_mfma_f32_16x16x32_bf16 v[92:95], v[136:139], v[224:227], v[92:95]
	v_mfma_f32_16x16x32_bf16 v[88:91], v[144:147], v[224:227], v[88:91]
	v_mfma_f32_16x16x32_bf16 v[76:79], v[136:139], v[232:235], v[76:79]
	v_mfma_f32_16x16x32_bf16 v[72:75], v[144:147], v[232:235], v[72:75]
	v_mfma_f32_16x16x32_bf16 v[116:119], v[148:151], v[192:195], v[116:119]
	v_mfma_f32_16x16x32_bf16 v[112:115], v[184:187], v[192:195], v[112:115]
	v_mfma_f32_16x16x32_bf16 v[100:103], v[148:151], v[208:211], v[100:103]
	v_mfma_f32_16x16x32_bf16 v[96:99], v[184:187], v[208:211], v[96:99]
	v_mfma_f32_16x16x32_bf16 v[84:87], v[148:151], v[220:223], v[84:87]
	v_mfma_f32_16x16x32_bf16 v[80:83], v[184:187], v[220:223], v[80:83]
	v_mfma_f32_16x16x32_bf16 v[68:71], v[148:151], v[228:231], v[68:71]
	v_mfma_f32_16x16x32_bf16 v[64:67], v[184:187], v[228:231], v[64:67]
	v_mfma_f32_16x16x32_bf16 v[116:119], v[180:183], v[204:207], v[116:119]
	v_mfma_f32_16x16x32_bf16 v[112:115], v[188:191], v[204:207], v[112:115]
	v_mfma_f32_16x16x32_bf16 v[100:103], v[180:183], v[216:219], v[100:103]
	v_mfma_f32_16x16x32_bf16 v[96:99], v[188:191], v[216:219], v[96:99]
	v_mfma_f32_16x16x32_bf16 v[84:87], v[180:183], v[224:227], v[84:87]
	v_mfma_f32_16x16x32_bf16 v[80:83], v[188:191], v[224:227], v[80:83]
	v_mfma_f32_16x16x32_bf16 v[68:71], v[180:183], v[232:235], v[68:71]
	v_mfma_f32_16x16x32_bf16 v[64:67], v[188:191], v[232:235], v[64:67]
	s_setprio 0
	s_barrier
; #define PG8_STAGE(bufoff, gbase, voff) do { _Pragma("unroll") for (int _i = 0; _i < 2; ++_i) \
;         __builtin_amdgcn_global_load_lds((const unsigned*)((const char*)(gbase) + (voff)[_i]), (PG8_LAS unsigned*)(lds + (bufoff) + ldsw + _i * 8192), 16, 0, 0); } while (0)
; #define PG8_LDA(dst, b, h) do { _Pragma("unroll") for (int m = 0; m < 4; ++m) _Pragma("unroll") for (int k = 0; k < 2; ++k) dst[m][k] = *(const PG8_LAS bf16x8*)(lds + PG8_SA(b, h) + aoff + m * 2048 + k * 1024); } while (0)
; #define PG8_MMA(ai, bj, At, Bt) do { __builtin_amdgcn_s_setprio(1); _Pragma("unroll") for (int m = 0; m < 4; ++m) _Pragma("unroll") for (int n = 0; n < 2; ++n) _Pragma("unroll") for (int k = 0; k < 2; ++k) \
;         acc[ai][bj][m][n] = __builtin_amdgcn_mfma_f32_16x16x32_bf16(Bt[n][k], At[m][k], acc[ai][bj][m][n], 0, 0, 0); __builtin_amdgcn_s_setprio(0); } while (0)
; #define PG8_WAIT_V(n) asm volatile("s_waitcnt vmcnt(" #n ")" ::: "memory")
; #define PG8_WAIT_L(n) asm volatile("s_waitcnt lgkmcnt(" #n ")" ::: "memory")
; #define PG8_BAR __builtin_amdgcn_s_barrier()
; #define PG8_SCHED __builtin_amdgcn_sched_barrier(0)
; template <class Epi, class Sched, bool ALIGN_EPI = false, bool SP2 = false>
; __device__ __forceinline__ void gemm_phase(PG8_LAS unsigned char* lds, const Gemm g, const Sched& S, const Epi& E) {
;     ...
;             PG8_LDA(At, 1, 1); PG8_STAGE(PG8_SB(1, 0), b3, voffB); PG8_STAGE(PG8_SB(1, 1), b3 + hstep, voffB); PG8_STAGE(PG8_SA(1, 0), a3, voffA);
;             PG8_WAIT_V(8); PG8_WAIT_L(0); PG8_BAR; PG8_MMA(1, 0, At, B0); PG8_MMA(1, 1, At, B1); PG8_BAR; PG8_SCHED;
	s_add_i32 s13, s13, s30
	v_lshl_add_u64 v[196:197], v[214:215], 0, s[22:23]
	s_mov_b32 m0, s13
	ds_read_b128 v[192:195], v202 offset:49152
	ds_read_b128 v[204:207], v202 offset:50176
	ds_read_b128 v[208:211], v202 offset:51200
	ds_read_b128 v[216:219], v202 offset:52224
	ds_read_b128 v[220:223], v202 offset:53248
	ds_read_b128 v[224:227], v202 offset:54272
	ds_read_b128 v[228:231], v202 offset:55296
	ds_read_b128 v[232:235], v202 offset:56320
	global_load_lds_dwordx4 v[196:197], off
	v_lshl_add_u64 v[196:197], v[236:237], 0, s[22:23]
	s_add_i32 m0, s13, 0x2000
	s_add_i32 s13, s29, s30
	global_load_lds_dwordx4 v[196:197], off
	s_mov_b32 m0, s13
	v_lshl_add_u64 v[196:197], v[238:239], 0, s[22:23]
	global_load_lds_dwordx4 v[196:197], off
	s_add_i32 m0, s13, 0x2000
	v_lshl_add_u64 v[196:197], v[212:213], 0, s[22:23]
	global_load_lds_dwordx4 v[196:197], off
	s_mov_b32 m0, s37
	v_lshl_add_u64 v[196:197], v[240:241], 0, s[22:23]
	global_load_lds_dwordx4 v[196:197], off
	s_mov_b32 m0, s41
	v_lshl_add_u64 v[196:197], v[242:243], 0, s[22:23]
	global_load_lds_dwordx4 v[196:197], off
	s_waitcnt vmcnt(8)
	s_waitcnt lgkmcnt(0)
	s_setprio 1
	s_barrier
	v_mfma_f32_16x16x32_bf16 v[60:63], v[132:135], v[192:195], v[60:63]
	v_mfma_f32_16x16x32_bf16 v[56:59], v[140:143], v[192:195], v[56:59]
	v_mfma_f32_16x16x32_bf16 v[44:47], v[132:135], v[208:211], v[44:47]
	v_mfma_f32_16x16x32_bf16 v[40:43], v[140:143], v[208:211], v[40:43]
	v_mfma_f32_16x16x32_bf16 v[28:31], v[132:135], v[220:223], v[28:31]
	v_mfma_f32_16x16x32_bf16 v[24:27], v[140:143], v[220:223], v[24:27]
	v_mfma_f32_16x16x32_bf16 v[12:15], v[132:135], v[228:231], v[12:15]
	v_mfma_f32_16x16x32_bf16 v[8:11], v[140:143], v[228:231], v[8:11]
	v_mfma_f32_16x16x32_bf16 v[60:63], v[136:139], v[204:207], v[60:63]
	v_mfma_f32_16x16x32_bf16 v[56:59], v[144:147], v[204:207], v[56:59]
	v_mfma_f32_16x16x32_bf16 v[44:47], v[136:139], v[216:219], v[44:47]
	v_mfma_f32_16x16x32_bf16 v[40:43], v[144:147], v[216:219], v[40:43]
	v_mfma_f32_16x16x32_bf16 v[28:31], v[136:139], v[224:227], v[28:31]
	v_mfma_f32_16x16x32_bf16 v[24:27], v[144:147], v[224:227], v[24:27]
	v_mfma_f32_16x16x32_bf16 v[12:15], v[136:139], v[232:235], v[12:15]
	v_mfma_f32_16x16x32_bf16 v[8:11], v[144:147], v[232:235], v[8:11]
	v_mfma_f32_16x16x32_bf16 v[52:55], v[148:151], v[192:195], v[52:55]
	v_mfma_f32_16x16x32_bf16 v[48:51], v[184:187], v[192:195], v[48:51]
	v_mfma_f32_16x16x32_bf16 v[36:39], v[148:151], v[208:211], v[36:39]
	v_mfma_f32_16x16x32_bf16 v[32:35], v[184:187], v[208:211], v[32:35]
	v_mfma_f32_16x16x32_bf16 v[20:23], v[148:151], v[220:223], v[20:23]
	v_mfma_f32_16x16x32_bf16 v[16:19], v[184:187], v[220:223], v[16:19]
	v_mfma_f32_16x16x32_bf16 v[4:7], v[148:151], v[228:231], v[4:7]
	v_mfma_f32_16x16x32_bf16 v[0:3], v[184:187], v[228:231], v[0:3]
	v_mfma_f32_16x16x32_bf16 v[52:55], v[180:183], v[204:207], v[52:55]
	v_mfma_f32_16x16x32_bf16 v[48:51], v[188:191], v[204:207], v[48:51]
	v_mfma_f32_16x16x32_bf16 v[36:39], v[180:183], v[216:219], v[36:39]
	v_mfma_f32_16x16x32_bf16 v[32:35], v[188:191], v[216:219], v[32:35]
	v_mfma_f32_16x16x32_bf16 v[20:23], v[180:183], v[224:227], v[20:23]
	v_mfma_f32_16x16x32_bf16 v[16:19], v[188:191], v[224:227], v[16:19]
	v_mfma_f32_16x16x32_bf16 v[4:7], v[180:183], v[232:235], v[4:7]
	v_mfma_f32_16x16x32_bf16 v[0:3], v[188:191], v[232:235], v[0:3]
	s_setprio 0
	s_barrier
	v_lshl_add_u64 v[128:129], v[128:129], 0, s[26:27]
	s_cmp_ge_i32 s12, s47
	v_lshl_add_u64 v[130:131], v[130:131], 0, s[26:27]
	s_cbranch_scc0 .LBB0_1695

; #define PG8_STAGE(bufoff, gbase, voff) do { _Pragma("unroll") for (int _i = 0; _i < 2; ++_i) \
;         __builtin_amdgcn_global_load_lds((const unsigned*)((const char*)(gbase) + (voff)[_i]), (PG8_LAS unsigned*)(lds + (bufoff) + ldsw + _i * 8192), 16, 0, 0); } while (0)
; #define PG8_LDA(dst, b, h) do { _Pragma("unroll") for (int m = 0; m < 4; ++m) _Pragma("unroll") for (int k = 0; k < 2; ++k) dst[m][k] = *(const PG8_LAS bf16x8*)(lds + PG8_SA(b, h) + aoff + m * 2048 + k * 1024); } while (0)
; #define PG8_LDB(dst, b, h) do { _Pragma("unroll") for (int n = 0; n < 2; ++n) _Pragma("unroll") for (int k = 0; k < 2; ++k) dst[n][k] = *(const PG8_LAS bf16x8*)(lds + PG8_SB(b, h) + boff + n * 2048 + k * 1024); } while (0)
; #define PG8_MMA(ai, bj, At, Bt) do { __builtin_amdgcn_s_setprio(1); _Pragma("unroll") for (int m = 0; m < 4; ++m) _Pragma("unroll") for (int n = 0; n < 2; ++n) _Pragma("unroll") for (int k = 0; k < 2; ++k) \
;         acc[ai][bj][m][n] = __builtin_amdgcn_mfma_f32_16x16x32_bf16(Bt[n][k], At[m][k], acc[ai][bj][m][n], 0, 0, 0); __builtin_amdgcn_s_setprio(0); } while (0)
; #define PG8_WAIT_V(n) asm volatile("s_waitcnt vmcnt(" #n ")" ::: "memory")
; #define PG8_WAIT_L(n) asm volatile("s_waitcnt lgkmcnt(" #n ")" ::: "memory")
; template <class Epi, class Sched, bool ALIGN_EPI = false, bool SP2 = false>
; __device__ __forceinline__ void gemm_phase(PG8_LAS unsigned char* lds, const Gemm g, const Sched& S, const Epi& E) {
;     ...
;             const bool last = (t == nt - 2);
;             const char* a1 = cA + (size_t)(t + 1) * kstep;
;             const char* a2 = last ? nA : cA + (size_t)(t + 2) * kstep; const char* b2 = last ? nB : cB + (size_t)(t + 2) * kstep;
;             const char* a3 = a2 + kstep; const char* b3 = b2 + kstep;
;             if (last && has_next) S.a_ready(nxt);
;             if constexpr (SP2) {
;             PG8_LDB(B0, 0, 0); PG8_LDB(B1, 0, 1); PG8_SCHED; PG8_LDA(At, 0, 0); PG8_STAGE(PG8_SA(1, 1), a1 + hstep, voffA);
;             PG8_WAIT_V(8); PG8_WAIT_L(0); PG8_BAR; PG8_MMA(0, 0, At, B0); PG8_MMA(0, 1, At, B1); PG8_BAR; PG8_SCHED;
;             PG8_LDA(At, 0, 1); PG8_STAGE(PG8_SB(0, 0), b2, voffB); PG8_STAGE(PG8_SB(0, 1), b2 + hstep, voffB); PG8_STAGE(PG8_SA(0, 0), a2, voffA);
;             PG8_WAIT_V(8); PG8_WAIT_L(0); PG8_BAR; PG8_MMA(1, 0, At, B0); PG8_MMA(1, 1, At, B1); PG8_BAR; PG8_SCHED;
.LBB0_1776:
	v_add_u32_e32 v166, s54, v169
	v_add_u32_e32 v168, s55, v169
	ds_read_b128 v[162:165], v166
	ds_read_b128 v[182:185], v166 offset:1024
	ds_read_b128 v[186:189], v166 offset:2048
	ds_read_b128 v[190:193], v166 offset:3072
	ds_read_b128 v[194:197], v168
	ds_read_b128 v[198:201], v168 offset:1024
	ds_read_b128 v[202:205], v168 offset:2048
	ds_read_b128 v[206:209], v168 offset:3072
	s_cmp_eq_u32 s53, s10
	v_lshl_add_u64 v[172:173], v[160:161], 0, s[22:23]
	s_cselect_b64 vcc, -1, 0
	s_add_i32 s10, s10, 2
	v_cndmask_b32_e32 v173, v173, v153, vcc
	v_cndmask_b32_e32 v172, v172, v152, vcc
	v_cndmask_b32_e32 v215, v159, v155, vcc
	v_cndmask_b32_e32 v214, v158, v154, vcc
	s_mov_b32 m0, s56
	v_lshl_add_u64 v[244:245], v[160:161], 0, v[148:149]
	ds_read_b128 v[210:213], v179
	ds_read_b128 v[216:219], v179 offset:1024
	ds_read_b128 v[220:223], v179 offset:2048
	ds_read_b128 v[224:227], v179 offset:3072
	ds_read_b128 v[228:231], v179 offset:4096
	ds_read_b128 v[232:235], v179 offset:5120
	ds_read_b128 v[236:239], v179 offset:6144
	ds_read_b128 v[240:243], v179 offset:7168
	global_load_lds_dwordx4 v[244:245], off
	s_mov_b32 m0, s57
	v_lshl_add_u64 v[244:245], v[160:161], 0, v[146:147]
	global_load_lds_dwordx4 v[244:245], off
	s_waitcnt vmcnt(8)
	s_waitcnt lgkmcnt(0)
	s_setprio 1
	s_barrier
	v_mfma_f32_16x16x32_bf16 v[124:127], v[162:165], v[210:213], v[124:127]
	v_mfma_f32_16x16x32_bf16 v[116:119], v[186:189], v[210:213], v[116:119]
	v_mfma_f32_16x16x32_bf16 v[108:111], v[162:165], v[220:223], v[108:111]
	v_mfma_f32_16x16x32_bf16 v[100:103], v[186:189], v[220:223], v[100:103]
	v_mfma_f32_16x16x32_bf16 v[92:95], v[162:165], v[228:231], v[92:95]
	v_mfma_f32_16x16x32_bf16 v[84:87], v[186:189], v[228:231], v[84:87]
	v_mfma_f32_16x16x32_bf16 v[76:79], v[162:165], v[236:239], v[76:79]
	v_mfma_f32_16x16x32_bf16 v[68:71], v[186:189], v[236:239], v[68:71]
	v_mfma_f32_16x16x32_bf16 v[124:127], v[182:185], v[216:219], v[124:127]
	v_mfma_f32_16x16x32_bf16 v[116:119], v[190:193], v[216:219], v[116:119]
	v_mfma_f32_16x16x32_bf16 v[108:111], v[182:185], v[224:227], v[108:111]
	v_mfma_f32_16x16x32_bf16 v[100:103], v[190:193], v[224:227], v[100:103]
	v_mfma_f32_16x16x32_bf16 v[92:95], v[182:185], v[232:235], v[92:95]
	v_mfma_f32_16x16x32_bf16 v[84:87], v[190:193], v[232:235], v[84:87]
	v_mfma_f32_16x16x32_bf16 v[76:79], v[182:185], v[240:243], v[76:79]
	v_mfma_f32_16x16x32_bf16 v[68:71], v[190:193], v[240:243], v[68:71]
	v_mfma_f32_16x16x32_bf16 v[120:123], v[194:197], v[210:213], v[120:123]
	v_mfma_f32_16x16x32_bf16 v[112:115], v[202:205], v[210:213], v[112:115]
	v_mfma_f32_16x16x32_bf16 v[104:107], v[194:197], v[220:223], v[104:107]
	v_mfma_f32_16x16x32_bf16 v[96:99], v[202:205], v[220:223], v[96:99]
	v_mfma_f32_16x16x32_bf16 v[88:91], v[194:197], v[228:231], v[88:91]
	v_mfma_f32_16x16x32_bf16 v[80:83], v[202:205], v[228:231], v[80:83]
	v_mfma_f32_16x16x32_bf16 v[72:75], v[194:197], v[236:239], v[72:75]
	v_mfma_f32_16x16x32_bf16 v[64:67], v[202:205], v[236:239], v[64:67]
	v_mfma_f32_16x16x32_bf16 v[120:123], v[198:201], v[216:219], v[120:123]
	v_mfma_f32_16x16x32_bf16 v[112:115], v[206:209], v[216:219], v[112:115]
	v_mfma_f32_16x16x32_bf16 v[104:107], v[198:201], v[224:227], v[104:107]
	v_mfma_f32_16x16x32_bf16 v[96:99], v[206:209], v[224:227], v[96:99]
	v_mfma_f32_16x16x32_bf16 v[88:91], v[198:201], v[232:235], v[88:91]
	v_mfma_f32_16x16x32_bf16 v[80:83], v[206:209], v[232:235], v[80:83]
	v_mfma_f32_16x16x32_bf16 v[72:75], v[198:201], v[240:243], v[72:75]
	v_mfma_f32_16x16x32_bf16 v[64:67], v[206:209], v[240:243], v[64:67]
	s_setprio 0
	s_barrier
	s_mov_b32 m0, s60
	v_lshl_add_u64 v[244:245], v[214:215], 0, v[138:139]
	ds_read_b128 v[210:213], v179 offset:16384
	ds_read_b128 v[216:219], v179 offset:17408
	ds_read_b128 v[220:223], v179 offset:18432
	ds_read_b128 v[224:227], v179 offset:19456
	ds_read_b128 v[228:231], v179 offset:20480
	ds_read_b128 v[232:235], v179 offset:21504
	ds_read_b128 v[236:239], v179 offset:22528
	ds_read_b128 v[240:243], v179 offset:23552
	global_load_lds_dwordx4 v[244:245], off
	v_lshl_add_u64 v[246:247], v[214:215], 0, v[134:135]
	s_mov_b32 m0, s61
	v_lshl_add_u64 v[214:215], v[214:215], 0, s[14:15]
	global_load_lds_dwordx4 v[246:247], off
	v_lshl_add_u64 v[248:249], v[214:215], 0, v[138:139]
	s_mov_b32 m0, s62
	v_lshl_add_u64 v[214:215], v[214:215], 0, v[134:135]
	global_load_lds_dwordx4 v[248:249], off
	s_add_i32 m0, s62, 0x2000
	v_lshl_add_u64 v[250:251], v[172:173], 0, v[140:141]
	global_load_lds_dwordx4 v[214:215], off
	s_mov_b32 m0, s46
	v_lshl_add_u64 v[252:253], v[172:173], 0, v[136:137]
	global_load_lds_dwordx4 v[250:251], off
	s_mov_b32 m0, s47
	s_nop 0
	global_load_lds_dwordx4 v[252:253], off
	s_waitcnt vmcnt(8)
	s_waitcnt lgkmcnt(0)
	s_setprio 1
	s_barrier
; #define PG8_STAGE(bufoff, gbase, voff) do { _Pragma("unroll") for (int _i = 0; _i < 2; ++_i) \
;         __builtin_amdgcn_global_load_lds((const unsigned*)((const char*)(gbase) + (voff)[_i]), (PG8_LAS unsigned*)(lds + (bufoff) + ldsw + _i * 8192), 16, 0, 0); } while (0)
; #define PG8_LDA(dst, b, h) do { _Pragma("unroll") for (int m = 0; m < 4; ++m) _Pragma("unroll") for (int k = 0; k < 2; ++k) dst[m][k] = *(const PG8_LAS bf16x8*)(lds + PG8_SA(b, h) + aoff + m * 2048 + k * 1024); } while (0)
; #define PG8_LDB(dst, b, h) do { _Pragma("unroll") for (int n = 0; n < 2; ++n) _Pragma("unroll") for (int k = 0; k < 2; ++k) dst[n][k] = *(const PG8_LAS bf16x8*)(lds + PG8_SB(b, h) + boff + n * 2048 + k * 1024); } while (0)
; #define PG8_MMA(ai, bj, At, Bt) do { __builtin_amdgcn_s_setprio(1); _Pragma("unroll") for (int m = 0; m < 4; ++m) _Pragma("unroll") for (int n = 0; n < 2; ++n) _Pragma("unroll") for (int k = 0; k < 2; ++k) \
;         acc[ai][bj][m][n] = __builtin_amdgcn_mfma_f32_16x16x32_bf16(Bt[n][k], At[m][k], acc[ai][bj][m][n], 0, 0, 0); __builtin_amdgcn_s_setprio(0); } while (0)
; #define PG8_WAIT_V(n) asm volatile("s_waitcnt vmcnt(" #n ")" ::: "memory")
; #define PG8_WAIT_L(n) asm volatile("s_waitcnt lgkmcnt(" #n ")" ::: "memory")
; #define PG8_BAR __builtin_amdgcn_s_barrier()
; #define PG8_SCHED __builtin_amdgcn_sched_barrier(0)
; template <class Epi, class Sched, bool ALIGN_EPI = false, bool SP2 = false>
; __device__ __forceinline__ void gemm_phase(PG8_LAS unsigned char* lds, const Gemm g, const Sched& S, const Epi& E) {
;     ...
;             PG8_WAIT_V(8); PG8_WAIT_L(0); PG8_BAR; PG8_MMA(1, 0, At, B0); PG8_MMA(1, 1, At, B1); PG8_BAR; PG8_SCHED;
;             PG8_LDB(B0, 1, 0); PG8_LDB(B1, 1, 1); PG8_SCHED; PG8_LDA(At, 1, 0); PG8_STAGE(PG8_SA(0, 1), a2 + hstep, voffA);
;             PG8_WAIT_V(8); PG8_WAIT_L(0); PG8_BAR; PG8_MMA(0, 0, At, B0); PG8_MMA(0, 1, At, B1); PG8_BAR; PG8_SCHED;
	v_mfma_f32_16x16x32_bf16 v[60:63], v[162:165], v[210:213], v[60:63]
	v_mfma_f32_16x16x32_bf16 v[52:55], v[186:189], v[210:213], v[52:55]
	v_mfma_f32_16x16x32_bf16 v[44:47], v[162:165], v[220:223], v[44:47]
	v_mfma_f32_16x16x32_bf16 v[36:39], v[186:189], v[220:223], v[36:39]
	v_mfma_f32_16x16x32_bf16 v[28:31], v[162:165], v[228:231], v[28:31]
	v_mfma_f32_16x16x32_bf16 v[20:23], v[186:189], v[228:231], v[20:23]
	v_mfma_f32_16x16x32_bf16 v[12:15], v[162:165], v[236:239], v[12:15]
	v_mfma_f32_16x16x32_bf16 v[4:7], v[186:189], v[236:239], v[4:7]
	v_mfma_f32_16x16x32_bf16 v[60:63], v[182:185], v[216:219], v[60:63]
	v_mfma_f32_16x16x32_bf16 v[52:55], v[190:193], v[216:219], v[52:55]
	v_mfma_f32_16x16x32_bf16 v[44:47], v[182:185], v[224:227], v[44:47]
	v_mfma_f32_16x16x32_bf16 v[36:39], v[190:193], v[224:227], v[36:39]
	v_mfma_f32_16x16x32_bf16 v[28:31], v[182:185], v[232:235], v[28:31]
	v_mfma_f32_16x16x32_bf16 v[20:23], v[190:193], v[232:235], v[20:23]
	v_mfma_f32_16x16x32_bf16 v[12:15], v[182:185], v[240:243], v[12:15]
	v_mfma_f32_16x16x32_bf16 v[4:7], v[190:193], v[240:243], v[4:7]
	v_mfma_f32_16x16x32_bf16 v[56:59], v[194:197], v[210:213], v[56:59]
	v_mfma_f32_16x16x32_bf16 v[48:51], v[202:205], v[210:213], v[48:51]
	v_mfma_f32_16x16x32_bf16 v[40:43], v[194:197], v[220:223], v[40:43]
	v_mfma_f32_16x16x32_bf16 v[32:35], v[202:205], v[220:223], v[32:35]
	v_mfma_f32_16x16x32_bf16 v[24:27], v[194:197], v[228:231], v[24:27]
	v_mfma_f32_16x16x32_bf16 v[16:19], v[202:205], v[228:231], v[16:19]
	v_mfma_f32_16x16x32_bf16 v[8:11], v[194:197], v[236:239], v[8:11]
	v_mfma_f32_16x16x32_bf16 v[0:3], v[202:205], v[236:239], v[0:3]
	v_mfma_f32_16x16x32_bf16 v[56:59], v[198:201], v[216:219], v[56:59]
	v_mfma_f32_16x16x32_bf16 v[48:51], v[206:209], v[216:219], v[48:51]
	v_mfma_f32_16x16x32_bf16 v[40:43], v[198:201], v[224:227], v[40:43]
	v_mfma_f32_16x16x32_bf16 v[32:35], v[206:209], v[224:227], v[32:35]
	v_mfma_f32_16x16x32_bf16 v[24:27], v[198:201], v[232:235], v[24:27]
	v_mfma_f32_16x16x32_bf16 v[16:19], v[206:209], v[232:235], v[16:19]
	v_mfma_f32_16x16x32_bf16 v[8:11], v[198:201], v[240:243], v[8:11]
	v_mfma_f32_16x16x32_bf16 v[0:3], v[206:209], v[240:243], v[0:3]
	s_setprio 0
	s_barrier
	s_add_i32 s11, 0, 0x18000
	v_add_u32_e32 v166, s11, v169
	s_add_i32 s13, 0, 0x1c000
	ds_read_b128 v[162:165], v166
	ds_read_b128 v[182:185], v166 offset:1024
	ds_read_b128 v[186:189], v166 offset:2048
	ds_read_b128 v[190:193], v166 offset:3072
	v_add_u32_e32 v166, s13, v169
	ds_read_b128 v[194:197], v166
	ds_read_b128 v[198:201], v166 offset:1024
	ds_read_b128 v[202:205], v166 offset:2048
	ds_read_b128 v[206:209], v166 offset:3072
	v_lshl_add_u64 v[172:173], v[172:173], 0, s[14:15]
	s_mov_b32 m0, s48
	v_lshl_add_u64 v[170:171], v[172:173], 0, v[140:141]
	ds_read_b128 v[210:213], v179 offset:32768
	ds_read_b128 v[216:219], v179 offset:33792
	ds_read_b128 v[220:223], v179 offset:34816
	ds_read_b128 v[224:227], v179 offset:35840
	ds_read_b128 v[228:231], v179 offset:36864
	ds_read_b128 v[232:235], v179 offset:37888
	ds_read_b128 v[236:239], v179 offset:38912
	ds_read_b128 v[240:243], v179 offset:39936
	global_load_lds_dwordx4 v[170:171], off
	s_mov_b32 m0, s49
	v_lshl_add_u64 v[170:171], v[172:173], 0, v[136:137]
	global_load_lds_dwordx4 v[170:171], off
	s_waitcnt vmcnt(8)
	s_waitcnt lgkmcnt(0)
	s_setprio 1
	s_barrier
	v_mfma_f32_16x16x32_bf16 v[124:127], v[162:165], v[210:213], v[124:127]
	v_mfma_f32_16x16x32_bf16 v[116:119], v[186:189], v[210:213], v[116:119]
	v_mfma_f32_16x16x32_bf16 v[108:111], v[162:165], v[220:223], v[108:111]
	v_mfma_f32_16x16x32_bf16 v[100:103], v[186:189], v[220:223], v[100:103]
	v_mfma_f32_16x16x32_bf16 v[92:95], v[162:165], v[228:231], v[92:95]
	v_mfma_f32_16x16x32_bf16 v[84:87], v[186:189], v[228:231], v[84:87]
	v_mfma_f32_16x16x32_bf16 v[76:79], v[162:165], v[236:239], v[76:79]
	v_mfma_f32_16x16x32_bf16 v[68:71], v[186:189], v[236:239], v[68:71]
	v_mfma_f32_16x16x32_bf16 v[124:127], v[182:185], v[216:219], v[124:127]
	v_mfma_f32_16x16x32_bf16 v[116:119], v[190:193], v[216:219], v[116:119]
	v_mfma_f32_16x16x32_bf16 v[108:111], v[182:185], v[224:227], v[108:111]
	v_mfma_f32_16x16x32_bf16 v[100:103], v[190:193], v[224:227], v[100:103]
	v_mfma_f32_16x16x32_bf16 v[92:95], v[182:185], v[232:235], v[92:95]
	v_mfma_f32_16x16x32_bf16 v[84:87], v[190:193], v[232:235], v[84:87]
	v_mfma_f32_16x16x32_bf16 v[76:79], v[182:185], v[240:243], v[76:79]
	v_mfma_f32_16x16x32_bf16 v[68:71], v[190:193], v[240:243], v[68:71]
	v_mfma_f32_16x16x32_bf16 v[120:123], v[194:197], v[210:213], v[120:123]
	v_mfma_f32_16x16x32_bf16 v[112:115], v[202:205], v[210:213], v[112:115]
	v_mfma_f32_16x16x32_bf16 v[104:107], v[194:197], v[220:223], v[104:107]
	v_mfma_f32_16x16x32_bf16 v[96:99], v[202:205], v[220:223], v[96:99]
	v_mfma_f32_16x16x32_bf16 v[88:91], v[194:197], v[228:231], v[88:91]
	v_mfma_f32_16x16x32_bf16 v[80:83], v[202:205], v[228:231], v[80:83]
	v_mfma_f32_16x16x32_bf16 v[72:75], v[194:197], v[236:239], v[72:75]
	v_mfma_f32_16x16x32_bf16 v[64:67], v[202:205], v[236:239], v[64:67]
	v_mfma_f32_16x16x32_bf16 v[120:123], v[198:201], v[216:219], v[120:123]
	v_mfma_f32_16x16x32_bf16 v[112:115], v[206:209], v[216:219], v[112:115]
	v_mfma_f32_16x16x32_bf16 v[104:107], v[198:201], v[224:227], v[104:107]
	v_mfma_f32_16x16x32_bf16 v[96:99], v[206:209], v[224:227], v[96:99]
	v_mfma_f32_16x16x32_bf16 v[88:91], v[198:201], v[232:235], v[88:91]
	v_mfma_f32_16x16x32_bf16 v[80:83], v[206:209], v[232:235], v[80:83]
	v_mfma_f32_16x16x32_bf16 v[72:75], v[198:201], v[240:243], v[72:75]
	v_mfma_f32_16x16x32_bf16 v[64:67], v[206:209], v[240:243], v[64:67]
	s_setprio 0
	s_barrier
; #define PG8_STAGE(bufoff, gbase, voff) do { _Pragma("unroll") for (int _i = 0; _i < 2; ++_i) \
;         __builtin_amdgcn_global_load_lds((const unsigned*)((const char*)(gbase) + (voff)[_i]), (PG8_LAS unsigned*)(lds + (bufoff) + ldsw + _i * 8192), 16, 0, 0); } while (0)
; #define PG8_LDA(dst, b, h) do { _Pragma("unroll") for (int m = 0; m < 4; ++m) _Pragma("unroll") for (int k = 0; k < 2; ++k) dst[m][k] = *(const PG8_LAS bf16x8*)(lds + PG8_SA(b, h) + aoff + m * 2048 + k * 1024); } while (0)
; #define PG8_MMA(ai, bj, At, Bt) do { __builtin_amdgcn_s_setprio(1); _Pragma("unroll") for (int m = 0; m < 4; ++m) _Pragma("unroll") for (int n = 0; n < 2; ++n) _Pragma("unroll") for (int k = 0; k < 2; ++k) \
;         acc[ai][bj][m][n] = __builtin_amdgcn_mfma_f32_16x16x32_bf16(Bt[n][k], At[m][k], acc[ai][bj][m][n], 0, 0, 0); __builtin_amdgcn_s_setprio(0); } while (0)
; #define PG8_WAIT_V(n) asm volatile("s_waitcnt vmcnt(" #n ")" ::: "memory")
; #define PG8_WAIT_L(n) asm volatile("s_waitcnt lgkmcnt(" #n ")" ::: "memory")
; #define PG8_BAR __builtin_amdgcn_s_barrier()
; #define PG8_SCHED __builtin_amdgcn_sched_barrier(0)
; template <class Epi, class Sched, bool ALIGN_EPI = false, bool SP2 = false>
; __device__ __forceinline__ void gemm_phase(PG8_LAS unsigned char* lds, const Gemm g, const Sched& S, const Epi& E) {
;     ...
;             PG8_LDA(At, 1, 1); PG8_STAGE(PG8_SB(1, 0), b3, voffB); PG8_STAGE(PG8_SB(1, 1), b3 + hstep, voffB); PG8_STAGE(PG8_SA(1, 0), a3, voffA);
;             PG8_WAIT_V(8); PG8_WAIT_L(0); PG8_BAR; PG8_MMA(1, 0, At, B0); PG8_MMA(1, 1, At, B1); PG8_BAR; PG8_SCHED;
	s_add_i32 s11, s11, s29
	v_lshl_add_u64 v[170:171], v[244:245], 0, s[22:23]
	s_mov_b32 m0, s11
	ds_read_b128 v[210:213], v179 offset:49152
	ds_read_b128 v[216:219], v179 offset:50176
	ds_read_b128 v[220:223], v179 offset:51200
	ds_read_b128 v[224:227], v179 offset:52224
	ds_read_b128 v[228:231], v179 offset:53248
	ds_read_b128 v[232:235], v179 offset:54272
	ds_read_b128 v[236:239], v179 offset:55296
	ds_read_b128 v[240:243], v179 offset:56320
	global_load_lds_dwordx4 v[170:171], off
	v_lshl_add_u64 v[170:171], v[246:247], 0, s[22:23]
	s_add_i32 m0, s11, 0x2000
	s_add_i32 s11, s13, s29
	global_load_lds_dwordx4 v[170:171], off
	s_mov_b32 m0, s11
	v_lshl_add_u64 v[170:171], v[248:249], 0, s[22:23]
	global_load_lds_dwordx4 v[170:171], off
	s_add_i32 m0, s11, 0x2000
	v_lshl_add_u64 v[170:171], v[214:215], 0, s[22:23]
	global_load_lds_dwordx4 v[170:171], off
	s_mov_b32 m0, s50
	v_lshl_add_u64 v[170:171], v[250:251], 0, s[22:23]
	global_load_lds_dwordx4 v[170:171], off
	s_mov_b32 m0, s51
	v_lshl_add_u64 v[170:171], v[252:253], 0, s[22:23]
	global_load_lds_dwordx4 v[170:171], off
	s_waitcnt vmcnt(8)
	s_waitcnt lgkmcnt(0)
	s_setprio 1
	s_barrier
	v_mfma_f32_16x16x32_bf16 v[60:63], v[162:165], v[210:213], v[60:63]
	v_mfma_f32_16x16x32_bf16 v[52:55], v[186:189], v[210:213], v[52:55]
	v_mfma_f32_16x16x32_bf16 v[44:47], v[162:165], v[220:223], v[44:47]
	v_mfma_f32_16x16x32_bf16 v[36:39], v[186:189], v[220:223], v[36:39]
	v_mfma_f32_16x16x32_bf16 v[28:31], v[162:165], v[228:231], v[28:31]
	v_mfma_f32_16x16x32_bf16 v[20:23], v[186:189], v[228:231], v[20:23]
	v_mfma_f32_16x16x32_bf16 v[12:15], v[162:165], v[236:239], v[12:15]
	v_mfma_f32_16x16x32_bf16 v[4:7], v[186:189], v[236:239], v[4:7]
	v_mfma_f32_16x16x32_bf16 v[60:63], v[182:185], v[216:219], v[60:63]
	v_mfma_f32_16x16x32_bf16 v[52:55], v[190:193], v[216:219], v[52:55]
	v_mfma_f32_16x16x32_bf16 v[44:47], v[182:185], v[224:227], v[44:47]
	v_mfma_f32_16x16x32_bf16 v[36:39], v[190:193], v[224:227], v[36:39]
	v_mfma_f32_16x16x32_bf16 v[28:31], v[182:185], v[232:235], v[28:31]
	v_mfma_f32_16x16x32_bf16 v[20:23], v[190:193], v[232:235], v[20:23]
	v_mfma_f32_16x16x32_bf16 v[12:15], v[182:185], v[240:243], v[12:15]
	v_mfma_f32_16x16x32_bf16 v[4:7], v[190:193], v[240:243], v[4:7]
	v_mfma_f32_16x16x32_bf16 v[56:59], v[194:197], v[210:213], v[56:59]
	v_mfma_f32_16x16x32_bf16 v[48:51], v[202:205], v[210:213], v[48:51]
	v_mfma_f32_16x16x32_bf16 v[40:43], v[194:197], v[220:223], v[40:43]
	v_mfma_f32_16x16x32_bf16 v[32:35], v[202:205], v[220:223], v[32:35]
	v_mfma_f32_16x16x32_bf16 v[24:27], v[194:197], v[228:231], v[24:27]
	v_mfma_f32_16x16x32_bf16 v[16:19], v[202:205], v[228:231], v[16:19]
	v_mfma_f32_16x16x32_bf16 v[8:11], v[194:197], v[236:239], v[8:11]
	v_mfma_f32_16x16x32_bf16 v[0:3], v[202:205], v[236:239], v[0:3]
	v_mfma_f32_16x16x32_bf16 v[56:59], v[198:201], v[216:219], v[56:59]
	v_mfma_f32_16x16x32_bf16 v[48:51], v[206:209], v[216:219], v[48:51]
	v_mfma_f32_16x16x32_bf16 v[40:43], v[198:201], v[224:227], v[40:43]
	v_mfma_f32_16x16x32_bf16 v[32:35], v[206:209], v[224:227], v[32:35]
	v_mfma_f32_16x16x32_bf16 v[24:27], v[198:201], v[232:235], v[24:27]
	v_mfma_f32_16x16x32_bf16 v[16:19], v[206:209], v[232:235], v[16:19]
	v_mfma_f32_16x16x32_bf16 v[8:11], v[198:201], v[240:243], v[8:11]
	v_mfma_f32_16x16x32_bf16 v[0:3], v[206:209], v[240:243], v[0:3]
	s_setprio 0
	s_barrier
	v_lshl_add_u64 v[158:159], v[158:159], 0, s[26:27]
	s_cmp_ge_i32 s10, s52
	v_lshl_add_u64 v[160:161], v[160:161], 0, s[26:27]
	s_cbranch_scc0 .LBB0_1776

; #define PG8_STAGE(bufoff, gbase, voff) do { _Pragma("unroll") for (int _i = 0; _i < 2; ++_i) \
;         __builtin_amdgcn_global_load_lds((const unsigned*)((const char*)(gbase) + (voff)[_i]), (PG8_LAS unsigned*)(lds + (bufoff) + ldsw + _i * 8192), 16, 0, 0); } while (0)
; #define PG8_LDA(dst, b, h) do { _Pragma("unroll") for (int m = 0; m < 4; ++m) _Pragma("unroll") for (int k = 0; k < 2; ++k) dst[m][k] = *(const PG8_LAS bf16x8*)(lds + PG8_SA(b, h) + aoff + m * 2048 + k * 1024); } while (0)
; #define PG8_LDB(dst, b, h) do { _Pragma("unroll") for (int n = 0; n < 2; ++n) _Pragma("unroll") for (int k = 0; k < 2; ++k) dst[n][k] = *(const PG8_LAS bf16x8*)(lds + PG8_SB(b, h) + boff + n * 2048 + k * 1024); } while (0)
; #define PG8_MMA(ai, bj, At, Bt) do { __builtin_amdgcn_s_setprio(1); _Pragma("unroll") for (int m = 0; m < 4; ++m) _Pragma("unroll") for (int n = 0; n < 2; ++n) _Pragma("unroll") for (int k = 0; k < 2; ++k) \
;         acc[ai][bj][m][n] = __builtin_amdgcn_mfma_f32_16x16x32_bf16(Bt[n][k], At[m][k], acc[ai][bj][m][n], 0, 0, 0); __builtin_amdgcn_s_setprio(0); } while (0)
; #define PG8_WAIT_V(n) asm volatile("s_waitcnt vmcnt(" #n ")" ::: "memory")
; #define PG8_WAIT_L(n) asm volatile("s_waitcnt lgkmcnt(" #n ")" ::: "memory")
; template <class Epi, class Sched, bool ALIGN_EPI = false, bool SP2 = false>
; __device__ __forceinline__ void gemm_phase(PG8_LAS unsigned char* lds, const Gemm g, const Sched& S, const Epi& E) {
;     ...
;             const bool last = (t == nt - 2);
;             const char* a1 = cA + (size_t)(t + 1) * kstep;
;             const char* a2 = last ? nA : cA + (size_t)(t + 2) * kstep; const char* b2 = last ? nB : cB + (size_t)(t + 2) * kstep;
;             const char* a3 = a2 + kstep; const char* b3 = b2 + kstep;
;             if (last && has_next) S.a_ready(nxt);
;             if constexpr (SP2) {
;             PG8_LDB(B0, 0, 0); PG8_LDB(B1, 0, 1); PG8_SCHED; PG8_LDA(At, 0, 0); PG8_STAGE(PG8_SA(1, 1), a1 + hstep, voffA);
;             PG8_WAIT_V(8); PG8_WAIT_L(0); PG8_BAR; PG8_MMA(0, 0, At, B0); PG8_MMA(0, 1, At, B1); PG8_BAR; PG8_SCHED;
;             PG8_LDA(At, 0, 1); PG8_STAGE(PG8_SB(0, 0), b2, voffB); PG8_STAGE(PG8_SB(0, 1), b2 + hstep, voffB); PG8_STAGE(PG8_SA(0, 0), a2, voffA);
;             PG8_WAIT_V(8); PG8_WAIT_L(0); PG8_BAR; PG8_MMA(1, 0, At, B0); PG8_MMA(1, 1, At, B1); PG8_BAR; PG8_SCHED;
.LBB0_1924:
	v_add_u32_e32 v192, s50, v161
	ds_read_b128 v[164:167], v162
	ds_read_b128 v[168:171], v162 offset:1024
	ds_read_b128 v[172:175], v162 offset:2048
	ds_read_b128 v[176:179], v162 offset:3072
	ds_read_b128 v[180:183], v192
	ds_read_b128 v[184:187], v192 offset:1024
	ds_read_b128 v[188:191], v192 offset:2048
	ds_read_b128 v[192:195], v192 offset:3072
	s_cmp_eq_u32 s49, s10
	v_lshl_add_u64 v[196:197], v[158:159], 0, s[24:25]
	s_cselect_b64 vcc, -1, 0
	s_add_i32 s10, s10, 2
	v_cndmask_b32_e32 v213, v197, v151, vcc
	v_cndmask_b32_e32 v212, v196, v150, vcc
	v_cndmask_b32_e32 v215, v155, v153, vcc
	v_cndmask_b32_e32 v214, v154, v152, vcc
	s_mov_b32 m0, s51
	v_lshl_add_u64 v[232:233], v[158:159], 0, v[146:147]
	ds_read_b128 v[196:199], v163
	ds_read_b128 v[200:203], v163 offset:1024
	ds_read_b128 v[204:207], v163 offset:2048
	ds_read_b128 v[208:211], v163 offset:3072
	ds_read_b128 v[216:219], v163 offset:4096
	ds_read_b128 v[220:223], v163 offset:5120
	ds_read_b128 v[224:227], v163 offset:6144
	ds_read_b128 v[228:231], v163 offset:7168
	global_load_lds_dwordx4 v[232:233], off
	s_mov_b32 m0, s52
	v_lshl_add_u64 v[232:233], v[158:159], 0, v[144:145]
	global_load_lds_dwordx4 v[232:233], off
	s_waitcnt vmcnt(8)
	s_waitcnt lgkmcnt(0)
	s_setprio 1
	s_barrier
	v_mfma_f32_16x16x32_bf16 v[124:127], v[164:167], v[196:199], v[124:127]
	v_mfma_f32_16x16x32_bf16 v[120:123], v[172:175], v[196:199], v[120:123]
	v_mfma_f32_16x16x32_bf16 v[108:111], v[164:167], v[204:207], v[108:111]
	v_mfma_f32_16x16x32_bf16 v[104:107], v[172:175], v[204:207], v[104:107]
	v_mfma_f32_16x16x32_bf16 v[92:95], v[164:167], v[216:219], v[92:95]
	v_mfma_f32_16x16x32_bf16 v[88:91], v[172:175], v[216:219], v[88:91]
	v_mfma_f32_16x16x32_bf16 v[76:79], v[164:167], v[224:227], v[76:79]
	v_mfma_f32_16x16x32_bf16 v[72:75], v[172:175], v[224:227], v[72:75]
	v_mfma_f32_16x16x32_bf16 v[124:127], v[168:171], v[200:203], v[124:127]
	v_mfma_f32_16x16x32_bf16 v[120:123], v[176:179], v[200:203], v[120:123]
	v_mfma_f32_16x16x32_bf16 v[108:111], v[168:171], v[208:211], v[108:111]
	v_mfma_f32_16x16x32_bf16 v[104:107], v[176:179], v[208:211], v[104:107]
	v_mfma_f32_16x16x32_bf16 v[92:95], v[168:171], v[220:223], v[92:95]
	v_mfma_f32_16x16x32_bf16 v[88:91], v[176:179], v[220:223], v[88:91]
	v_mfma_f32_16x16x32_bf16 v[76:79], v[168:171], v[228:231], v[76:79]
	v_mfma_f32_16x16x32_bf16 v[72:75], v[176:179], v[228:231], v[72:75]
	v_mfma_f32_16x16x32_bf16 v[116:119], v[180:183], v[196:199], v[116:119]
	v_mfma_f32_16x16x32_bf16 v[112:115], v[188:191], v[196:199], v[112:115]
	v_mfma_f32_16x16x32_bf16 v[100:103], v[180:183], v[204:207], v[100:103]
	v_mfma_f32_16x16x32_bf16 v[96:99], v[188:191], v[204:207], v[96:99]
	v_mfma_f32_16x16x32_bf16 v[84:87], v[180:183], v[216:219], v[84:87]
	v_mfma_f32_16x16x32_bf16 v[80:83], v[188:191], v[216:219], v[80:83]
	v_mfma_f32_16x16x32_bf16 v[68:71], v[180:183], v[224:227], v[68:71]
	v_mfma_f32_16x16x32_bf16 v[64:67], v[188:191], v[224:227], v[64:67]
	v_mfma_f32_16x16x32_bf16 v[116:119], v[184:187], v[200:203], v[116:119]
	v_mfma_f32_16x16x32_bf16 v[112:115], v[192:195], v[200:203], v[112:115]
	v_mfma_f32_16x16x32_bf16 v[100:103], v[184:187], v[208:211], v[100:103]
	v_mfma_f32_16x16x32_bf16 v[96:99], v[192:195], v[208:211], v[96:99]
	v_mfma_f32_16x16x32_bf16 v[84:87], v[184:187], v[220:223], v[84:87]
	v_mfma_f32_16x16x32_bf16 v[80:83], v[192:195], v[220:223], v[80:83]
	v_mfma_f32_16x16x32_bf16 v[68:71], v[184:187], v[228:231], v[68:71]
	v_mfma_f32_16x16x32_bf16 v[64:67], v[192:195], v[228:231], v[64:67]
	s_setprio 0
	s_barrier
	s_mov_b32 m0, s53
	v_lshl_add_u64 v[232:233], v[214:215], 0, v[138:139]
	ds_read_b128 v[196:199], v163 offset:16384
	ds_read_b128 v[200:203], v163 offset:17408
	ds_read_b128 v[204:207], v163 offset:18432
	ds_read_b128 v[208:211], v163 offset:19456
	ds_read_b128 v[216:219], v163 offset:20480
	ds_read_b128 v[220:223], v163 offset:21504
	ds_read_b128 v[224:227], v163 offset:22528
	ds_read_b128 v[228:231], v163 offset:23552
	global_load_lds_dwordx4 v[232:233], off
	v_lshl_add_u64 v[234:235], v[214:215], 0, v[134:135]
	s_mov_b32 m0, s54
	v_lshl_add_u64 v[214:215], v[214:215], 0, s[14:15]
	global_load_lds_dwordx4 v[234:235], off
	v_lshl_add_u64 v[236:237], v[214:215], 0, v[138:139]
	s_mov_b32 m0, s55
	v_lshl_add_u64 v[214:215], v[214:215], 0, v[134:135]
	global_load_lds_dwordx4 v[236:237], off
	s_mov_b32 m0, s56
	v_lshl_add_u64 v[238:239], v[212:213], 0, v[140:141]
	global_load_lds_dwordx4 v[214:215], off
	s_mov_b32 m0, s37
	v_lshl_add_u64 v[240:241], v[212:213], 0, v[136:137]
	global_load_lds_dwordx4 v[238:239], off
	s_mov_b32 m0, s41
	s_nop 0
	global_load_lds_dwordx4 v[240:241], off
	s_waitcnt vmcnt(8)
	s_waitcnt lgkmcnt(0)
	s_setprio 1
	s_barrier
; #define PG8_STAGE(bufoff, gbase, voff) do { _Pragma("unroll") for (int _i = 0; _i < 2; ++_i) \
;         __builtin_amdgcn_global_load_lds((const unsigned*)((const char*)(gbase) + (voff)[_i]), (PG8_LAS unsigned*)(lds + (bufoff) + ldsw + _i * 8192), 16, 0, 0); } while (0)
; #define PG8_LDA(dst, b, h) do { _Pragma("unroll") for (int m = 0; m < 4; ++m) _Pragma("unroll") for (int k = 0; k < 2; ++k) dst[m][k] = *(const PG8_LAS bf16x8*)(lds + PG8_SA(b, h) + aoff + m * 2048 + k * 1024); } while (0)
; #define PG8_LDB(dst, b, h) do { _Pragma("unroll") for (int n = 0; n < 2; ++n) _Pragma("unroll") for (int k = 0; k < 2; ++k) dst[n][k] = *(const PG8_LAS bf16x8*)(lds + PG8_SB(b, h) + boff + n * 2048 + k * 1024); } while (0)
; #define PG8_MMA(ai, bj, At, Bt) do { __builtin_amdgcn_s_setprio(1); _Pragma("unroll") for (int m = 0; m < 4; ++m) _Pragma("unroll") for (int n = 0; n < 2; ++n) _Pragma("unroll") for (int k = 0; k < 2; ++k) \
;         acc[ai][bj][m][n] = __builtin_amdgcn_mfma_f32_16x16x32_bf16(Bt[n][k], At[m][k], acc[ai][bj][m][n], 0, 0, 0); __builtin_amdgcn_s_setprio(0); } while (0)
; #define PG8_WAIT_V(n) asm volatile("s_waitcnt vmcnt(" #n ")" ::: "memory")
; #define PG8_WAIT_L(n) asm volatile("s_waitcnt lgkmcnt(" #n ")" ::: "memory")
; #define PG8_BAR __builtin_amdgcn_s_barrier()
; #define PG8_SCHED __builtin_amdgcn_sched_barrier(0)
; template <class Epi, class Sched, bool ALIGN_EPI = false, bool SP2 = false>
; __device__ __forceinline__ void gemm_phase(PG8_LAS unsigned char* lds, const Gemm g, const Sched& S, const Epi& E) {
;     ...
;             PG8_WAIT_V(8); PG8_WAIT_L(0); PG8_BAR; PG8_MMA(1, 0, At, B0); PG8_MMA(1, 1, At, B1); PG8_BAR; PG8_SCHED;
;             PG8_LDB(B0, 1, 0); PG8_LDB(B1, 1, 1); PG8_SCHED; PG8_LDA(At, 1, 0); PG8_STAGE(PG8_SA(0, 1), a2 + hstep, voffA);
;             PG8_WAIT_V(8); PG8_WAIT_L(0); PG8_BAR; PG8_MMA(0, 0, At, B0); PG8_MMA(0, 1, At, B1); PG8_BAR; PG8_SCHED;
	v_mfma_f32_16x16x32_bf16 v[60:63], v[164:167], v[196:199], v[60:63]
	v_mfma_f32_16x16x32_bf16 v[56:59], v[172:175], v[196:199], v[56:59]
	v_mfma_f32_16x16x32_bf16 v[44:47], v[164:167], v[204:207], v[44:47]
	v_mfma_f32_16x16x32_bf16 v[40:43], v[172:175], v[204:207], v[40:43]
	v_mfma_f32_16x16x32_bf16 v[28:31], v[164:167], v[216:219], v[28:31]
	v_mfma_f32_16x16x32_bf16 v[24:27], v[172:175], v[216:219], v[24:27]
	v_mfma_f32_16x16x32_bf16 v[12:15], v[164:167], v[224:227], v[12:15]
	v_mfma_f32_16x16x32_bf16 v[8:11], v[172:175], v[224:227], v[8:11]
	v_mfma_f32_16x16x32_bf16 v[60:63], v[168:171], v[200:203], v[60:63]
	v_mfma_f32_16x16x32_bf16 v[56:59], v[176:179], v[200:203], v[56:59]
	v_mfma_f32_16x16x32_bf16 v[44:47], v[168:171], v[208:211], v[44:47]
	v_mfma_f32_16x16x32_bf16 v[40:43], v[176:179], v[208:211], v[40:43]
	v_mfma_f32_16x16x32_bf16 v[28:31], v[168:171], v[220:223], v[28:31]
	v_mfma_f32_16x16x32_bf16 v[24:27], v[176:179], v[220:223], v[24:27]
	v_mfma_f32_16x16x32_bf16 v[12:15], v[168:171], v[228:231], v[12:15]
	v_mfma_f32_16x16x32_bf16 v[8:11], v[176:179], v[228:231], v[8:11]
	v_mfma_f32_16x16x32_bf16 v[52:55], v[180:183], v[196:199], v[52:55]
	v_mfma_f32_16x16x32_bf16 v[48:51], v[188:191], v[196:199], v[48:51]
	v_mfma_f32_16x16x32_bf16 v[36:39], v[180:183], v[204:207], v[36:39]
	v_mfma_f32_16x16x32_bf16 v[32:35], v[188:191], v[204:207], v[32:35]
	v_mfma_f32_16x16x32_bf16 v[20:23], v[180:183], v[216:219], v[20:23]
	v_mfma_f32_16x16x32_bf16 v[16:19], v[188:191], v[216:219], v[16:19]
	v_mfma_f32_16x16x32_bf16 v[4:7], v[180:183], v[224:227], v[4:7]
	v_mfma_f32_16x16x32_bf16 v[0:3], v[188:191], v[224:227], v[0:3]
	v_mfma_f32_16x16x32_bf16 v[52:55], v[184:187], v[200:203], v[52:55]
	v_mfma_f32_16x16x32_bf16 v[48:51], v[192:195], v[200:203], v[48:51]
	v_mfma_f32_16x16x32_bf16 v[36:39], v[184:187], v[208:211], v[36:39]
	v_mfma_f32_16x16x32_bf16 v[32:35], v[192:195], v[208:211], v[32:35]
	v_mfma_f32_16x16x32_bf16 v[20:23], v[184:187], v[220:223], v[20:23]
	v_mfma_f32_16x16x32_bf16 v[16:19], v[192:195], v[220:223], v[16:19]
	v_mfma_f32_16x16x32_bf16 v[4:7], v[184:187], v[228:231], v[4:7]
	v_mfma_f32_16x16x32_bf16 v[0:3], v[192:195], v[228:231], v[0:3]
	s_setprio 0
	s_barrier
	v_add_u32_e32 v176, s57, v161
	v_add_u32_e32 v192, s58, v161
	ds_read_b128 v[164:167], v176
	ds_read_b128 v[168:171], v176 offset:1024
	ds_read_b128 v[172:175], v176 offset:2048
	ds_read_b128 v[176:179], v176 offset:3072
	ds_read_b128 v[180:183], v192
	ds_read_b128 v[184:187], v192 offset:1024
	ds_read_b128 v[188:191], v192 offset:2048
	ds_read_b128 v[192:195], v192 offset:3072
	v_lshl_add_u64 v[212:213], v[212:213], 0, s[14:15]
	s_mov_b32 m0, s44
	v_lshl_add_u64 v[242:243], v[212:213], 0, v[140:141]
	ds_read_b128 v[196:199], v163 offset:32768
	ds_read_b128 v[200:203], v163 offset:33792
	ds_read_b128 v[204:207], v163 offset:34816
	ds_read_b128 v[208:211], v163 offset:35840
	ds_read_b128 v[216:219], v163 offset:36864
	ds_read_b128 v[220:223], v163 offset:37888
	ds_read_b128 v[224:227], v163 offset:38912
	ds_read_b128 v[228:231], v163 offset:39936
	global_load_lds_dwordx4 v[242:243], off
	s_mov_b32 m0, s45
	v_lshl_add_u64 v[212:213], v[212:213], 0, v[136:137]
	global_load_lds_dwordx4 v[212:213], off
	s_waitcnt vmcnt(8)
	s_waitcnt lgkmcnt(0)
	s_setprio 1
	s_barrier
	v_mfma_f32_16x16x32_bf16 v[124:127], v[164:167], v[196:199], v[124:127]
	v_mfma_f32_16x16x32_bf16 v[120:123], v[172:175], v[196:199], v[120:123]
	v_mfma_f32_16x16x32_bf16 v[108:111], v[164:167], v[204:207], v[108:111]
	v_mfma_f32_16x16x32_bf16 v[104:107], v[172:175], v[204:207], v[104:107]
	v_mfma_f32_16x16x32_bf16 v[92:95], v[164:167], v[216:219], v[92:95]
	v_mfma_f32_16x16x32_bf16 v[88:91], v[172:175], v[216:219], v[88:91]
	v_mfma_f32_16x16x32_bf16 v[76:79], v[164:167], v[224:227], v[76:79]
	v_mfma_f32_16x16x32_bf16 v[72:75], v[172:175], v[224:227], v[72:75]
	v_mfma_f32_16x16x32_bf16 v[124:127], v[168:171], v[200:203], v[124:127]
	v_mfma_f32_16x16x32_bf16 v[120:123], v[176:179], v[200:203], v[120:123]
	v_mfma_f32_16x16x32_bf16 v[108:111], v[168:171], v[208:211], v[108:111]
	v_mfma_f32_16x16x32_bf16 v[104:107], v[176:179], v[208:211], v[104:107]
	v_mfma_f32_16x16x32_bf16 v[92:95], v[168:171], v[220:223], v[92:95]
	v_mfma_f32_16x16x32_bf16 v[88:91], v[176:179], v[220:223], v[88:91]
	v_mfma_f32_16x16x32_bf16 v[76:79], v[168:171], v[228:231], v[76:79]
	v_mfma_f32_16x16x32_bf16 v[72:75], v[176:179], v[228:231], v[72:75]
	v_mfma_f32_16x16x32_bf16 v[116:119], v[180:183], v[196:199], v[116:119]
	v_mfma_f32_16x16x32_bf16 v[112:115], v[188:191], v[196:199], v[112:115]
	v_mfma_f32_16x16x32_bf16 v[100:103], v[180:183], v[204:207], v[100:103]
	v_mfma_f32_16x16x32_bf16 v[96:99], v[188:191], v[204:207], v[96:99]
	v_mfma_f32_16x16x32_bf16 v[84:87], v[180:183], v[216:219], v[84:87]
	v_mfma_f32_16x16x32_bf16 v[80:83], v[188:191], v[216:219], v[80:83]
	v_mfma_f32_16x16x32_bf16 v[68:71], v[180:183], v[224:227], v[68:71]
	v_mfma_f32_16x16x32_bf16 v[64:67], v[188:191], v[224:227], v[64:67]
	v_mfma_f32_16x16x32_bf16 v[116:119], v[184:187], v[200:203], v[116:119]
	v_mfma_f32_16x16x32_bf16 v[112:115], v[192:195], v[200:203], v[112:115]
	v_mfma_f32_16x16x32_bf16 v[100:103], v[184:187], v[208:211], v[100:103]
	v_mfma_f32_16x16x32_bf16 v[96:99], v[192:195], v[208:211], v[96:99]
	v_mfma_f32_16x16x32_bf16 v[84:87], v[184:187], v[220:223], v[84:87]
	v_mfma_f32_16x16x32_bf16 v[80:83], v[192:195], v[220:223], v[80:83]
	v_mfma_f32_16x16x32_bf16 v[68:71], v[184:187], v[228:231], v[68:71]
	v_mfma_f32_16x16x32_bf16 v[64:67], v[192:195], v[228:231], v[64:67]
	s_setprio 0
	s_barrier
; #define PG8_STAGE(bufoff, gbase, voff) do { _Pragma("unroll") for (int _i = 0; _i < 2; ++_i) \
;         __builtin_amdgcn_global_load_lds((const unsigned*)((const char*)(gbase) + (voff)[_i]), (PG8_LAS unsigned*)(lds + (bufoff) + ldsw + _i * 8192), 16, 0, 0); } while (0)
; #define PG8_LDA(dst, b, h) do { _Pragma("unroll") for (int m = 0; m < 4; ++m) _Pragma("unroll") for (int k = 0; k < 2; ++k) dst[m][k] = *(const PG8_LAS bf16x8*)(lds + PG8_SA(b, h) + aoff + m * 2048 + k * 1024); } while (0)
; #define PG8_MMA(ai, bj, At, Bt) do { __builtin_amdgcn_s_setprio(1); _Pragma("unroll") for (int m = 0; m < 4; ++m) _Pragma("unroll") for (int n = 0; n < 2; ++n) _Pragma("unroll") for (int k = 0; k < 2; ++k) \
;         acc[ai][bj][m][n] = __builtin_amdgcn_mfma_f32_16x16x32_bf16(Bt[n][k], At[m][k], acc[ai][bj][m][n], 0, 0, 0); __builtin_amdgcn_s_setprio(0); } while (0)
; #define PG8_WAIT_V(n) asm volatile("s_waitcnt vmcnt(" #n ")" ::: "memory")
; #define PG8_WAIT_L(n) asm volatile("s_waitcnt lgkmcnt(" #n ")" ::: "memory")
; #define PG8_BAR __builtin_amdgcn_s_barrier()
; #define PG8_SCHED __builtin_amdgcn_sched_barrier(0)
; template <class Epi, class Sched, bool ALIGN_EPI = false, bool SP2 = false>
; __device__ __forceinline__ void gemm_phase(PG8_LAS unsigned char* lds, const Gemm g, const Sched& S, const Epi& E) {
;     ...
;             PG8_LDA(At, 1, 1); PG8_STAGE(PG8_SB(1, 0), b3, voffB); PG8_STAGE(PG8_SB(1, 1), b3 + hstep, voffB); PG8_STAGE(PG8_SA(1, 0), a3, voffA);
;             PG8_WAIT_V(8); PG8_WAIT_L(0); PG8_BAR; PG8_MMA(1, 0, At, B0); PG8_MMA(1, 1, At, B1); PG8_BAR; PG8_SCHED;
	s_mov_b32 m0, s59
	v_lshl_add_u64 v[212:213], v[232:233], 0, s[24:25]
	ds_read_b128 v[196:199], v163 offset:49152
	ds_read_b128 v[200:203], v163 offset:50176
	ds_read_b128 v[204:207], v163 offset:51200
	ds_read_b128 v[208:211], v163 offset:52224
	ds_read_b128 v[216:219], v163 offset:53248
	ds_read_b128 v[220:223], v163 offset:54272
	ds_read_b128 v[224:227], v163 offset:55296
	ds_read_b128 v[228:231], v163 offset:56320
	global_load_lds_dwordx4 v[212:213], off
	s_mov_b32 m0, s60
	v_lshl_add_u64 v[212:213], v[234:235], 0, s[24:25]
	global_load_lds_dwordx4 v[212:213], off
	s_mov_b32 m0, s61
	v_lshl_add_u64 v[212:213], v[236:237], 0, s[24:25]
	global_load_lds_dwordx4 v[212:213], off
	s_mov_b32 m0, s62
	v_lshl_add_u64 v[212:213], v[214:215], 0, s[24:25]
	global_load_lds_dwordx4 v[212:213], off
	s_mov_b32 m0, s46
	v_lshl_add_u64 v[212:213], v[238:239], 0, s[24:25]
	global_load_lds_dwordx4 v[212:213], off
	s_mov_b32 m0, s47
	v_lshl_add_u64 v[212:213], v[240:241], 0, s[24:25]
	global_load_lds_dwordx4 v[212:213], off
	s_waitcnt vmcnt(8)
	s_waitcnt lgkmcnt(0)
	s_setprio 1
	s_barrier
	v_mfma_f32_16x16x32_bf16 v[60:63], v[164:167], v[196:199], v[60:63]
	v_mfma_f32_16x16x32_bf16 v[56:59], v[172:175], v[196:199], v[56:59]
	v_mfma_f32_16x16x32_bf16 v[44:47], v[164:167], v[204:207], v[44:47]
	v_mfma_f32_16x16x32_bf16 v[40:43], v[172:175], v[204:207], v[40:43]
	v_mfma_f32_16x16x32_bf16 v[28:31], v[164:167], v[216:219], v[28:31]
	v_mfma_f32_16x16x32_bf16 v[24:27], v[172:175], v[216:219], v[24:27]
	v_mfma_f32_16x16x32_bf16 v[12:15], v[164:167], v[224:227], v[12:15]
	v_mfma_f32_16x16x32_bf16 v[8:11], v[172:175], v[224:227], v[8:11]
	v_mfma_f32_16x16x32_bf16 v[60:63], v[168:171], v[200:203], v[60:63]
	v_mfma_f32_16x16x32_bf16 v[56:59], v[176:179], v[200:203], v[56:59]
	v_mfma_f32_16x16x32_bf16 v[44:47], v[168:171], v[208:211], v[44:47]
	v_mfma_f32_16x16x32_bf16 v[40:43], v[176:179], v[208:211], v[40:43]
	v_mfma_f32_16x16x32_bf16 v[28:31], v[168:171], v[220:223], v[28:31]
	v_mfma_f32_16x16x32_bf16 v[24:27], v[176:179], v[220:223], v[24:27]
	v_mfma_f32_16x16x32_bf16 v[12:15], v[168:171], v[228:231], v[12:15]
	v_mfma_f32_16x16x32_bf16 v[8:11], v[176:179], v[228:231], v[8:11]
	v_mfma_f32_16x16x32_bf16 v[52:55], v[180:183], v[196:199], v[52:55]
	v_mfma_f32_16x16x32_bf16 v[48:51], v[188:191], v[196:199], v[48:51]
	v_mfma_f32_16x16x32_bf16 v[36:39], v[180:183], v[204:207], v[36:39]
	v_mfma_f32_16x16x32_bf16 v[32:35], v[188:191], v[204:207], v[32:35]
	v_mfma_f32_16x16x32_bf16 v[20:23], v[180:183], v[216:219], v[20:23]
	v_mfma_f32_16x16x32_bf16 v[16:19], v[188:191], v[216:219], v[16:19]
	v_mfma_f32_16x16x32_bf16 v[4:7], v[180:183], v[224:227], v[4:7]
	v_mfma_f32_16x16x32_bf16 v[0:3], v[188:191], v[224:227], v[0:3]
	v_mfma_f32_16x16x32_bf16 v[52:55], v[184:187], v[200:203], v[52:55]
	v_mfma_f32_16x16x32_bf16 v[48:51], v[192:195], v[200:203], v[48:51]
	v_mfma_f32_16x16x32_bf16 v[36:39], v[184:187], v[208:211], v[36:39]
	v_mfma_f32_16x16x32_bf16 v[32:35], v[192:195], v[208:211], v[32:35]
	v_mfma_f32_16x16x32_bf16 v[20:23], v[184:187], v[220:223], v[20:23]
	v_mfma_f32_16x16x32_bf16 v[16:19], v[192:195], v[220:223], v[16:19]
	v_mfma_f32_16x16x32_bf16 v[4:7], v[184:187], v[228:231], v[4:7]
	v_mfma_f32_16x16x32_bf16 v[0:3], v[192:195], v[228:231], v[0:3]
	s_setprio 0
	s_barrier
	v_lshl_add_u64 v[154:155], v[154:155], 0, s[28:29]
	s_cmp_ge_i32 s10, s48
	v_lshl_add_u64 v[158:159], v[158:159], 0, s[28:29]
	s_cbranch_scc0 .LBB0_1924

; #define PG8_STAGE(bufoff, gbase, voff) do { _Pragma("unroll") for (int _i = 0; _i < 2; ++_i) \
;         __builtin_amdgcn_global_load_lds((const unsigned*)((const char*)(gbase) + (voff)[_i]), (PG8_LAS unsigned*)(lds + (bufoff) + ldsw + _i * 8192), 16, 0, 0); } while (0)
; #define PG8_LDA(dst, b, h) do { _Pragma("unroll") for (int m = 0; m < 4; ++m) _Pragma("unroll") for (int k = 0; k < 2; ++k) dst[m][k] = *(const PG8_LAS bf16x8*)(lds + PG8_SA(b, h) + aoff + m * 2048 + k * 1024); } while (0)
; #define PG8_LDB(dst, b, h) do { _Pragma("unroll") for (int n = 0; n < 2; ++n) _Pragma("unroll") for (int k = 0; k < 2; ++k) dst[n][k] = *(const PG8_LAS bf16x8*)(lds + PG8_SB(b, h) + boff + n * 2048 + k * 1024); } while (0)
; #define PG8_MMA(ai, bj, At, Bt) do { __builtin_amdgcn_s_setprio(1); _Pragma("unroll") for (int m = 0; m < 4; ++m) _Pragma("unroll") for (int n = 0; n < 2; ++n) _Pragma("unroll") for (int k = 0; k < 2; ++k) \
;         acc[ai][bj][m][n] = __builtin_amdgcn_mfma_f32_16x16x32_bf16(Bt[n][k], At[m][k], acc[ai][bj][m][n], 0, 0, 0); __builtin_amdgcn_s_setprio(0); } while (0)
; #define PG8_WAIT_V(n) asm volatile("s_waitcnt vmcnt(" #n ")" ::: "memory")
; #define PG8_WAIT_L(n) asm volatile("s_waitcnt lgkmcnt(" #n ")" ::: "memory")
; template <class Epi, class Sched, bool ALIGN_EPI = false, bool SP2 = false>
; __device__ __forceinline__ void gemm_phase(PG8_LAS unsigned char* lds, const Gemm g, const Sched& S, const Epi& E) {
;     ...
;             const bool last = (t == nt - 2);
;             const char* a1 = cA + (size_t)(t + 1) * kstep;
;             const char* a2 = last ? nA : cA + (size_t)(t + 2) * kstep; const char* b2 = last ? nB : cB + (size_t)(t + 2) * kstep;
;             const char* a3 = a2 + kstep; const char* b3 = b2 + kstep;
;             if (last && has_next) S.a_ready(nxt);
;             if constexpr (SP2) {
;             PG8_LDB(B0, 0, 0); PG8_LDB(B1, 0, 1); PG8_SCHED; PG8_LDA(At, 0, 0); PG8_STAGE(PG8_SA(1, 1), a1 + hstep, voffA);
;             PG8_WAIT_V(8); PG8_WAIT_L(0); PG8_BAR; PG8_MMA(0, 0, At, B0); PG8_MMA(0, 1, At, B1); PG8_BAR; PG8_SCHED;
;             PG8_LDA(At, 0, 1); PG8_STAGE(PG8_SB(0, 0), b2, voffB); PG8_STAGE(PG8_SB(0, 1), b2 + hstep, voffB); PG8_STAGE(PG8_SA(0, 0), a2, voffA);
;             PG8_WAIT_V(8); PG8_WAIT_L(0); PG8_BAR; PG8_MMA(1, 0, At, B0); PG8_MMA(1, 1, At, B1); PG8_BAR; PG8_SCHED;
.LBB0_1947:
	v_add_u32_e32 v178, s53, v216
	v_add_u32_e32 v194, s54, v216
	ds_read_b128 v[138:141], v178
	ds_read_b128 v[142:145], v178 offset:1024
	ds_read_b128 v[146:149], v178 offset:2048
	ds_read_b128 v[178:181], v178 offset:3072
	ds_read_b128 v[182:185], v194
	ds_read_b128 v[186:189], v194 offset:1024
	ds_read_b128 v[190:193], v194 offset:2048
	ds_read_b128 v[194:197], v194 offset:3072
	s_cmp_eq_u32 s47, s10
	v_lshl_add_u64 v[198:199], v[136:137], 0, s[20:21]
	s_cselect_b64 vcc, -1, 0
	s_add_i32 s10, s10, 2
	v_cndmask_b32_e32 v215, v199, v175, vcc
	v_cndmask_b32_e32 v214, v198, v174, vcc
	v_cndmask_b32_e32 v237, v135, v177, vcc
	v_cndmask_b32_e32 v236, v134, v176, vcc
	v_lshl_add_u64 v[238:239], v[136:137], 0, v[168:169]
	s_add_i32 m0, s34, 0xc000
	ds_read_b128 v[198:201], v218
	ds_read_b128 v[202:205], v218 offset:1024
	ds_read_b128 v[206:209], v218 offset:2048
	ds_read_b128 v[210:213], v218 offset:3072
	ds_read_b128 v[220:223], v218 offset:4096
	ds_read_b128 v[224:227], v218 offset:5120
	ds_read_b128 v[228:231], v218 offset:6144
	ds_read_b128 v[232:235], v218 offset:7168
	global_load_lds_dwordx4 v[238:239], off
	s_add_i32 m0, s34, 0xe000
	v_lshl_add_u64 v[238:239], v[136:137], 0, v[166:167]
	global_load_lds_dwordx4 v[238:239], off
	s_waitcnt vmcnt(8)
	s_waitcnt lgkmcnt(0)
	s_setprio 1
	s_barrier
	v_mfma_f32_16x16x32_bf16 v[130:133], v[138:141], v[198:201], v[130:133]
	v_mfma_f32_16x16x32_bf16 v[126:129], v[146:149], v[198:201], v[126:129]
	v_mfma_f32_16x16x32_bf16 v[114:117], v[138:141], v[206:209], v[114:117]
	v_mfma_f32_16x16x32_bf16 v[110:113], v[146:149], v[206:209], v[110:113]
	v_mfma_f32_16x16x32_bf16 v[98:101], v[138:141], v[220:223], v[98:101]
	v_mfma_f32_16x16x32_bf16 v[94:97], v[146:149], v[220:223], v[94:97]
	v_mfma_f32_16x16x32_bf16 v[82:85], v[138:141], v[228:231], v[82:85]
	v_mfma_f32_16x16x32_bf16 v[78:81], v[146:149], v[228:231], v[78:81]
	v_mfma_f32_16x16x32_bf16 v[130:133], v[142:145], v[202:205], v[130:133]
	v_mfma_f32_16x16x32_bf16 v[126:129], v[178:181], v[202:205], v[126:129]
	v_mfma_f32_16x16x32_bf16 v[114:117], v[142:145], v[210:213], v[114:117]
	v_mfma_f32_16x16x32_bf16 v[110:113], v[178:181], v[210:213], v[110:113]
	v_mfma_f32_16x16x32_bf16 v[98:101], v[142:145], v[224:227], v[98:101]
	v_mfma_f32_16x16x32_bf16 v[94:97], v[178:181], v[224:227], v[94:97]
	v_mfma_f32_16x16x32_bf16 v[82:85], v[142:145], v[232:235], v[82:85]
	v_mfma_f32_16x16x32_bf16 v[78:81], v[178:181], v[232:235], v[78:81]
	v_mfma_f32_16x16x32_bf16 v[122:125], v[182:185], v[198:201], v[122:125]
	v_mfma_f32_16x16x32_bf16 v[118:121], v[190:193], v[198:201], v[118:121]
	v_mfma_f32_16x16x32_bf16 v[106:109], v[182:185], v[206:209], v[106:109]
	v_mfma_f32_16x16x32_bf16 v[102:105], v[190:193], v[206:209], v[102:105]
	v_mfma_f32_16x16x32_bf16 v[90:93], v[182:185], v[220:223], v[90:93]
	v_mfma_f32_16x16x32_bf16 v[86:89], v[190:193], v[220:223], v[86:89]
	v_mfma_f32_16x16x32_bf16 v[74:77], v[182:185], v[228:231], v[74:77]
	v_mfma_f32_16x16x32_bf16 v[70:73], v[190:193], v[228:231], v[70:73]
	v_mfma_f32_16x16x32_bf16 v[122:125], v[186:189], v[202:205], v[122:125]
	v_mfma_f32_16x16x32_bf16 v[118:121], v[194:197], v[202:205], v[118:121]
	v_mfma_f32_16x16x32_bf16 v[106:109], v[186:189], v[210:213], v[106:109]
	v_mfma_f32_16x16x32_bf16 v[102:105], v[194:197], v[210:213], v[102:105]
	v_mfma_f32_16x16x32_bf16 v[90:93], v[186:189], v[224:227], v[90:93]
	v_mfma_f32_16x16x32_bf16 v[86:89], v[194:197], v[224:227], v[86:89]
	v_mfma_f32_16x16x32_bf16 v[74:77], v[186:189], v[232:235], v[74:77]
	v_mfma_f32_16x16x32_bf16 v[70:73], v[194:197], v[232:235], v[70:73]
	s_setprio 0
	s_barrier
	s_add_i32 s11, s53, s29
	v_lshl_add_u64 v[238:239], v[236:237], 0, v[158:159]
	s_mov_b32 m0, s11
	ds_read_b128 v[198:201], v218 offset:16384
	ds_read_b128 v[202:205], v218 offset:17408
	ds_read_b128 v[206:209], v218 offset:18432
	ds_read_b128 v[210:213], v218 offset:19456
	ds_read_b128 v[220:223], v218 offset:20480
	ds_read_b128 v[224:227], v218 offset:21504
	ds_read_b128 v[228:231], v218 offset:22528
	ds_read_b128 v[232:235], v218 offset:23552
	global_load_lds_dwordx4 v[238:239], off
	v_lshl_add_u64 v[240:241], v[236:237], 0, v[162:163]
	s_add_i32 m0, s11, 0x2000
	v_lshl_add_u64 v[236:237], v[236:237], 0, s[12:13]
	s_add_i32 s11, s54, s29
	global_load_lds_dwordx4 v[240:241], off
	v_lshl_add_u64 v[242:243], v[236:237], 0, v[158:159]
	s_mov_b32 m0, s11
	v_lshl_add_u64 v[236:237], v[236:237], 0, v[162:163]
	global_load_lds_dwordx4 v[242:243], off
	s_add_i32 m0, s11, 0x2000
	v_lshl_add_u64 v[244:245], v[214:215], 0, v[154:155]
	global_load_lds_dwordx4 v[236:237], off
	s_mov_b32 m0, s34
	v_lshl_add_u64 v[246:247], v[214:215], 0, v[160:161]
	global_load_lds_dwordx4 v[244:245], off
	s_mov_b32 m0, s35
	s_nop 0
	global_load_lds_dwordx4 v[246:247], off
	s_waitcnt vmcnt(8)
	s_waitcnt lgkmcnt(0)
	s_setprio 1
	s_barrier
; #define PG8_STAGE(bufoff, gbase, voff) do { _Pragma("unroll") for (int _i = 0; _i < 2; ++_i) \
;         __builtin_amdgcn_global_load_lds((const unsigned*)((const char*)(gbase) + (voff)[_i]), (PG8_LAS unsigned*)(lds + (bufoff) + ldsw + _i * 8192), 16, 0, 0); } while (0)
; #define PG8_LDA(dst, b, h) do { _Pragma("unroll") for (int m = 0; m < 4; ++m) _Pragma("unroll") for (int k = 0; k < 2; ++k) dst[m][k] = *(const PG8_LAS bf16x8*)(lds + PG8_SA(b, h) + aoff + m * 2048 + k * 1024); } while (0)
; #define PG8_LDB(dst, b, h) do { _Pragma("unroll") for (int n = 0; n < 2; ++n) _Pragma("unroll") for (int k = 0; k < 2; ++k) dst[n][k] = *(const PG8_LAS bf16x8*)(lds + PG8_SB(b, h) + boff + n * 2048 + k * 1024); } while (0)
; #define PG8_MMA(ai, bj, At, Bt) do { __builtin_amdgcn_s_setprio(1); _Pragma("unroll") for (int m = 0; m < 4; ++m) _Pragma("unroll") for (int n = 0; n < 2; ++n) _Pragma("unroll") for (int k = 0; k < 2; ++k) \
;         acc[ai][bj][m][n] = __builtin_amdgcn_mfma_f32_16x16x32_bf16(Bt[n][k], At[m][k], acc[ai][bj][m][n], 0, 0, 0); __builtin_amdgcn_s_setprio(0); } while (0)
; #define PG8_WAIT_V(n) asm volatile("s_waitcnt vmcnt(" #n ")" ::: "memory")
; #define PG8_WAIT_L(n) asm volatile("s_waitcnt lgkmcnt(" #n ")" ::: "memory")
; #define PG8_BAR __builtin_amdgcn_s_barrier()
; #define PG8_SCHED __builtin_amdgcn_sched_barrier(0)
; template <class Epi, class Sched, bool ALIGN_EPI = false, bool SP2 = false>
; __device__ __forceinline__ void gemm_phase(PG8_LAS unsigned char* lds, const Gemm g, const Sched& S, const Epi& E) {
;     ...
;             PG8_WAIT_V(8); PG8_WAIT_L(0); PG8_BAR; PG8_MMA(1, 0, At, B0); PG8_MMA(1, 1, At, B1); PG8_BAR; PG8_SCHED;
;             PG8_LDB(B0, 1, 0); PG8_LDB(B1, 1, 1); PG8_SCHED; PG8_LDA(At, 1, 0); PG8_STAGE(PG8_SA(0, 1), a2 + hstep, voffA);
;             PG8_WAIT_V(8); PG8_WAIT_L(0); PG8_BAR; PG8_MMA(0, 0, At, B0); PG8_MMA(0, 1, At, B1); PG8_BAR; PG8_SCHED;
	v_mfma_f32_16x16x32_bf16 v[66:69], v[138:141], v[198:201], v[66:69]
	v_mfma_f32_16x16x32_bf16 v[62:65], v[146:149], v[198:201], v[62:65]
	v_mfma_f32_16x16x32_bf16 v[50:53], v[138:141], v[206:209], v[50:53]
	v_mfma_f32_16x16x32_bf16 v[46:49], v[146:149], v[206:209], v[46:49]
	v_mfma_f32_16x16x32_bf16 v[34:37], v[138:141], v[220:223], v[34:37]
	v_mfma_f32_16x16x32_bf16 v[30:33], v[146:149], v[220:223], v[30:33]
	v_mfma_f32_16x16x32_bf16 v[18:21], v[138:141], v[228:231], v[18:21]
	v_mfma_f32_16x16x32_bf16 v[14:17], v[146:149], v[228:231], v[14:17]
	v_mfma_f32_16x16x32_bf16 v[66:69], v[142:145], v[202:205], v[66:69]
	v_mfma_f32_16x16x32_bf16 v[62:65], v[178:181], v[202:205], v[62:65]
	v_mfma_f32_16x16x32_bf16 v[50:53], v[142:145], v[210:213], v[50:53]
	v_mfma_f32_16x16x32_bf16 v[46:49], v[178:181], v[210:213], v[46:49]
	v_mfma_f32_16x16x32_bf16 v[34:37], v[142:145], v[224:227], v[34:37]
	v_mfma_f32_16x16x32_bf16 v[30:33], v[178:181], v[224:227], v[30:33]
	v_mfma_f32_16x16x32_bf16 v[18:21], v[142:145], v[232:235], v[18:21]
	v_mfma_f32_16x16x32_bf16 v[14:17], v[178:181], v[232:235], v[14:17]
	v_mfma_f32_16x16x32_bf16 v[58:61], v[182:185], v[198:201], v[58:61]
	v_mfma_f32_16x16x32_bf16 v[54:57], v[190:193], v[198:201], v[54:57]
	v_mfma_f32_16x16x32_bf16 v[42:45], v[182:185], v[206:209], v[42:45]
	v_mfma_f32_16x16x32_bf16 v[38:41], v[190:193], v[206:209], v[38:41]
	v_mfma_f32_16x16x32_bf16 v[26:29], v[182:185], v[220:223], v[26:29]
	v_mfma_f32_16x16x32_bf16 v[22:25], v[190:193], v[220:223], v[22:25]
	v_mfma_f32_16x16x32_bf16 v[10:13], v[182:185], v[228:231], v[10:13]
	v_mfma_f32_16x16x32_bf16 v[6:9], v[190:193], v[228:231], v[6:9]
	v_mfma_f32_16x16x32_bf16 v[58:61], v[186:189], v[202:205], v[58:61]
	v_mfma_f32_16x16x32_bf16 v[54:57], v[194:197], v[202:205], v[54:57]
	v_mfma_f32_16x16x32_bf16 v[42:45], v[186:189], v[210:213], v[42:45]
	v_mfma_f32_16x16x32_bf16 v[38:41], v[194:197], v[210:213], v[38:41]
	v_mfma_f32_16x16x32_bf16 v[26:29], v[186:189], v[224:227], v[26:29]
	v_mfma_f32_16x16x32_bf16 v[22:25], v[194:197], v[224:227], v[22:25]
	v_mfma_f32_16x16x32_bf16 v[10:13], v[186:189], v[232:235], v[10:13]
	v_mfma_f32_16x16x32_bf16 v[6:9], v[194:197], v[232:235], v[6:9]
	s_setprio 0
	s_barrier
	s_add_i32 s11, 0, 0x18000
	s_add_i32 s31, 0, 0x1c000
	v_add_u32_e32 v178, s11, v216
	v_add_u32_e32 v194, s31, v216
	ds_read_b128 v[138:141], v178
	ds_read_b128 v[142:145], v178 offset:1024
	ds_read_b128 v[146:149], v178 offset:2048
	ds_read_b128 v[178:181], v178 offset:3072
	ds_read_b128 v[182:185], v194
	ds_read_b128 v[186:189], v194 offset:1024
	ds_read_b128 v[190:193], v194 offset:2048
	ds_read_b128 v[194:197], v194 offset:3072
	v_lshl_add_u64 v[214:215], v[214:215], 0, s[12:13]
	s_mov_b32 m0, s36
	v_lshl_add_u64 v[248:249], v[214:215], 0, v[154:155]
	ds_read_b128 v[198:201], v218 offset:32768
	ds_read_b128 v[202:205], v218 offset:33792
	ds_read_b128 v[206:209], v218 offset:34816
	ds_read_b128 v[210:213], v218 offset:35840
	ds_read_b128 v[220:223], v218 offset:36864
	ds_read_b128 v[224:227], v218 offset:37888
	ds_read_b128 v[228:231], v218 offset:38912
	ds_read_b128 v[232:235], v218 offset:39936
	global_load_lds_dwordx4 v[248:249], off
	s_mov_b32 m0, s37
	v_lshl_add_u64 v[214:215], v[214:215], 0, v[160:161]
	global_load_lds_dwordx4 v[214:215], off
	s_waitcnt vmcnt(8)
	s_waitcnt lgkmcnt(0)
	s_setprio 1
	s_barrier
	v_mfma_f32_16x16x32_bf16 v[130:133], v[138:141], v[198:201], v[130:133]
	v_mfma_f32_16x16x32_bf16 v[126:129], v[146:149], v[198:201], v[126:129]
	v_mfma_f32_16x16x32_bf16 v[114:117], v[138:141], v[206:209], v[114:117]
	v_mfma_f32_16x16x32_bf16 v[110:113], v[146:149], v[206:209], v[110:113]
	v_mfma_f32_16x16x32_bf16 v[98:101], v[138:141], v[220:223], v[98:101]
	v_mfma_f32_16x16x32_bf16 v[94:97], v[146:149], v[220:223], v[94:97]
	v_mfma_f32_16x16x32_bf16 v[82:85], v[138:141], v[228:231], v[82:85]
	v_mfma_f32_16x16x32_bf16 v[78:81], v[146:149], v[228:231], v[78:81]
	v_mfma_f32_16x16x32_bf16 v[130:133], v[142:145], v[202:205], v[130:133]
	v_mfma_f32_16x16x32_bf16 v[126:129], v[178:181], v[202:205], v[126:129]
	v_mfma_f32_16x16x32_bf16 v[114:117], v[142:145], v[210:213], v[114:117]
	v_mfma_f32_16x16x32_bf16 v[110:113], v[178:181], v[210:213], v[110:113]
	v_mfma_f32_16x16x32_bf16 v[98:101], v[142:145], v[224:227], v[98:101]
	v_mfma_f32_16x16x32_bf16 v[94:97], v[178:181], v[224:227], v[94:97]
	v_mfma_f32_16x16x32_bf16 v[82:85], v[142:145], v[232:235], v[82:85]
	v_mfma_f32_16x16x32_bf16 v[78:81], v[178:181], v[232:235], v[78:81]
	v_mfma_f32_16x16x32_bf16 v[122:125], v[182:185], v[198:201], v[122:125]
	v_mfma_f32_16x16x32_bf16 v[118:121], v[190:193], v[198:201], v[118:121]
	v_mfma_f32_16x16x32_bf16 v[106:109], v[182:185], v[206:209], v[106:109]
	v_mfma_f32_16x16x32_bf16 v[102:105], v[190:193], v[206:209], v[102:105]
	v_mfma_f32_16x16x32_bf16 v[90:93], v[182:185], v[220:223], v[90:93]
	v_mfma_f32_16x16x32_bf16 v[86:89], v[190:193], v[220:223], v[86:89]
	v_mfma_f32_16x16x32_bf16 v[74:77], v[182:185], v[228:231], v[74:77]
	v_mfma_f32_16x16x32_bf16 v[70:73], v[190:193], v[228:231], v[70:73]
	v_mfma_f32_16x16x32_bf16 v[122:125], v[186:189], v[202:205], v[122:125]
	v_mfma_f32_16x16x32_bf16 v[118:121], v[194:197], v[202:205], v[118:121]
	v_mfma_f32_16x16x32_bf16 v[106:109], v[186:189], v[210:213], v[106:109]
	v_mfma_f32_16x16x32_bf16 v[102:105], v[194:197], v[210:213], v[102:105]
	v_mfma_f32_16x16x32_bf16 v[90:93], v[186:189], v[224:227], v[90:93]
	v_mfma_f32_16x16x32_bf16 v[86:89], v[194:197], v[224:227], v[86:89]
	v_mfma_f32_16x16x32_bf16 v[74:77], v[186:189], v[232:235], v[74:77]
	v_mfma_f32_16x16x32_bf16 v[70:73], v[194:197], v[232:235], v[70:73]
	s_setprio 0
	s_barrier
; #define PG8_STAGE(bufoff, gbase, voff) do { _Pragma("unroll") for (int _i = 0; _i < 2; ++_i) \
;         __builtin_amdgcn_global_load_lds((const unsigned*)((const char*)(gbase) + (voff)[_i]), (PG8_LAS unsigned*)(lds + (bufoff) + ldsw + _i * 8192), 16, 0, 0); } while (0)
; #define PG8_LDA(dst, b, h) do { _Pragma("unroll") for (int m = 0; m < 4; ++m) _Pragma("unroll") for (int k = 0; k < 2; ++k) dst[m][k] = *(const PG8_LAS bf16x8*)(lds + PG8_SA(b, h) + aoff + m * 2048 + k * 1024); } while (0)
; #define PG8_MMA(ai, bj, At, Bt) do { __builtin_amdgcn_s_setprio(1); _Pragma("unroll") for (int m = 0; m < 4; ++m) _Pragma("unroll") for (int n = 0; n < 2; ++n) _Pragma("unroll") for (int k = 0; k < 2; ++k) \
;         acc[ai][bj][m][n] = __builtin_amdgcn_mfma_f32_16x16x32_bf16(Bt[n][k], At[m][k], acc[ai][bj][m][n], 0, 0, 0); __builtin_amdgcn_s_setprio(0); } while (0)
; #define PG8_WAIT_V(n) asm volatile("s_waitcnt vmcnt(" #n ")" ::: "memory")
; #define PG8_WAIT_L(n) asm volatile("s_waitcnt lgkmcnt(" #n ")" ::: "memory")
; #define PG8_BAR __builtin_amdgcn_s_barrier()
; #define PG8_SCHED __builtin_amdgcn_sched_barrier(0)
; template <class Epi, class Sched, bool ALIGN_EPI = false, bool SP2 = false>
; __device__ __forceinline__ void gemm_phase(PG8_LAS unsigned char* lds, const Gemm g, const Sched& S, const Epi& E) {
;     ...
;             PG8_LDA(At, 1, 1); PG8_STAGE(PG8_SB(1, 0), b3, voffB); PG8_STAGE(PG8_SB(1, 1), b3 + hstep, voffB); PG8_STAGE(PG8_SA(1, 0), a3, voffA);
;             PG8_WAIT_V(8); PG8_WAIT_L(0); PG8_BAR; PG8_MMA(1, 0, At, B0); PG8_MMA(1, 1, At, B1); PG8_BAR; PG8_SCHED;
	s_add_i32 s11, s11, s29
	v_lshl_add_u64 v[214:215], v[238:239], 0, s[20:21]
	s_mov_b32 m0, s11
	ds_read_b128 v[198:201], v218 offset:49152
	ds_read_b128 v[202:205], v218 offset:50176
	ds_read_b128 v[206:209], v218 offset:51200
	ds_read_b128 v[210:213], v218 offset:52224
	ds_read_b128 v[220:223], v218 offset:53248
	ds_read_b128 v[224:227], v218 offset:54272
	ds_read_b128 v[228:231], v218 offset:55296
	ds_read_b128 v[232:235], v218 offset:56320
	global_load_lds_dwordx4 v[214:215], off
	v_lshl_add_u64 v[214:215], v[240:241], 0, s[20:21]
	s_add_i32 m0, s11, 0x2000
	s_add_i32 s11, s31, s29
	global_load_lds_dwordx4 v[214:215], off
	s_mov_b32 m0, s11
	v_lshl_add_u64 v[214:215], v[242:243], 0, s[20:21]
	global_load_lds_dwordx4 v[214:215], off
	s_add_i32 m0, s11, 0x2000
	v_lshl_add_u64 v[214:215], v[236:237], 0, s[20:21]
	global_load_lds_dwordx4 v[214:215], off
	s_mov_b32 m0, s41
	v_lshl_add_u64 v[214:215], v[244:245], 0, s[20:21]
	global_load_lds_dwordx4 v[214:215], off
	s_mov_b32 m0, s44
	v_lshl_add_u64 v[214:215], v[246:247], 0, s[20:21]
	global_load_lds_dwordx4 v[214:215], off
	s_waitcnt vmcnt(8)
	s_waitcnt lgkmcnt(0)
	s_setprio 1
	s_barrier
	v_mfma_f32_16x16x32_bf16 v[66:69], v[138:141], v[198:201], v[66:69]
	v_mfma_f32_16x16x32_bf16 v[62:65], v[146:149], v[198:201], v[62:65]
	v_mfma_f32_16x16x32_bf16 v[50:53], v[138:141], v[206:209], v[50:53]
	v_mfma_f32_16x16x32_bf16 v[46:49], v[146:149], v[206:209], v[46:49]
	v_mfma_f32_16x16x32_bf16 v[34:37], v[138:141], v[220:223], v[34:37]
	v_mfma_f32_16x16x32_bf16 v[30:33], v[146:149], v[220:223], v[30:33]
	v_mfma_f32_16x16x32_bf16 v[18:21], v[138:141], v[228:231], v[18:21]
	v_mfma_f32_16x16x32_bf16 v[14:17], v[146:149], v[228:231], v[14:17]
	v_mfma_f32_16x16x32_bf16 v[66:69], v[142:145], v[202:205], v[66:69]
	v_mfma_f32_16x16x32_bf16 v[62:65], v[178:181], v[202:205], v[62:65]
	v_mfma_f32_16x16x32_bf16 v[50:53], v[142:145], v[210:213], v[50:53]
	v_mfma_f32_16x16x32_bf16 v[46:49], v[178:181], v[210:213], v[46:49]
	v_mfma_f32_16x16x32_bf16 v[34:37], v[142:145], v[224:227], v[34:37]
	v_mfma_f32_16x16x32_bf16 v[30:33], v[178:181], v[224:227], v[30:33]
	v_mfma_f32_16x16x32_bf16 v[18:21], v[142:145], v[232:235], v[18:21]
	v_mfma_f32_16x16x32_bf16 v[14:17], v[178:181], v[232:235], v[14:17]
	v_mfma_f32_16x16x32_bf16 v[58:61], v[182:185], v[198:201], v[58:61]
	v_mfma_f32_16x16x32_bf16 v[54:57], v[190:193], v[198:201], v[54:57]
	v_mfma_f32_16x16x32_bf16 v[42:45], v[182:185], v[206:209], v[42:45]
	v_mfma_f32_16x16x32_bf16 v[38:41], v[190:193], v[206:209], v[38:41]
	v_mfma_f32_16x16x32_bf16 v[26:29], v[182:185], v[220:223], v[26:29]
	v_mfma_f32_16x16x32_bf16 v[22:25], v[190:193], v[220:223], v[22:25]
	v_mfma_f32_16x16x32_bf16 v[10:13], v[182:185], v[228:231], v[10:13]
	v_mfma_f32_16x16x32_bf16 v[6:9], v[190:193], v[228:231], v[6:9]
	v_mfma_f32_16x16x32_bf16 v[58:61], v[186:189], v[202:205], v[58:61]
	v_mfma_f32_16x16x32_bf16 v[54:57], v[194:197], v[202:205], v[54:57]
	v_mfma_f32_16x16x32_bf16 v[42:45], v[186:189], v[210:213], v[42:45]
	v_mfma_f32_16x16x32_bf16 v[38:41], v[194:197], v[210:213], v[38:41]
	v_mfma_f32_16x16x32_bf16 v[26:29], v[186:189], v[224:227], v[26:29]
	v_mfma_f32_16x16x32_bf16 v[22:25], v[194:197], v[224:227], v[22:25]
	v_mfma_f32_16x16x32_bf16 v[10:13], v[186:189], v[232:235], v[10:13]
	v_mfma_f32_16x16x32_bf16 v[6:9], v[194:197], v[232:235], v[6:9]
	s_setprio 0
	s_barrier
	v_lshl_add_u64 v[134:135], v[134:135], 0, s[26:27]
	s_cmp_ge_i32 s10, s46
	v_lshl_add_u64 v[136:137], v[136:137], 0, s[26:27]
	s_cbranch_scc0 .LBB0_1947
